# v18 + GEMM loops: s_setprio flips removed; MFMAs reordered accumulator-major (k0,k1 of each accumulator back to back, accumulate chain forwarding)
# speedup vs baseline: 1.0178x; 1.0178x over previous
; #define PG8_STAGE(bufoff, gbase, voff) do { _Pragma("unroll") for (int _i = 0; _i < 2; ++_i) \
;         __builtin_amdgcn_global_load_lds((const unsigned*)((const char*)(gbase) + (voff)[_i]), (LAS unsigned*)(lds + (bufoff) + ldsw + _i * 8192), 16, 0, 0); } while (0)
; #define PG8_LDA(dst, b, h) do { _Pragma("unroll") for (int m = 0; m < 4; ++m) _Pragma("unroll") for (int k = 0; k < 2; ++k) dst[m][k] = *(const LAS bf16x8*)(lds + PG8_SA(b, h) + aoff + m * 2048 + k * 1024); } while (0)
; #define PG8_LDB(dst, b, h) do { _Pragma("unroll") for (int n = 0; n < 2; ++n) _Pragma("unroll") for (int k = 0; k < 2; ++k) dst[n][k] = *(const LAS bf16x8*)(lds + PG8_SB(b, h) + boff + n * 2048 + k * 1024); } while (0)
; #define PG8_MMA(ai, bj, At, Bt) do { __builtin_amdgcn_s_setprio(1); _Pragma("unroll") for (int m = 0; m < 4; ++m) _Pragma("unroll") for (int n = 0; n < 2; ++n) _Pragma("unroll") for (int k = 0; k < 2; ++k) \
;         acc[ai][bj][m][n] = __builtin_amdgcn_mfma_f32_16x16x32_bf16(Bt[n][k], At[m][k], acc[ai][bj][m][n], 0, 0, 0); __builtin_amdgcn_s_setprio(0); } while (0)
; #define PG8_WAIT_V(n) asm volatile("s_waitcnt vmcnt(" #n ")" ::: "memory")
; #define PG8_WAIT_L(n) asm volatile("s_waitcnt lgkmcnt(" #n ")" ::: "memory")
; #define PG8_BAR __builtin_amdgcn_s_barrier()
; #define PG8_SCHED __builtin_amdgcn_sched_barrier(0)
; template <class Epi>
; __device__ __forceinline__ void gemm_phase(LAS unsigned char* lds, const Gemm g, const Order& S, const Epi& E, const int wid) {
;     ...
;             PG8_LDB(B0, 0, 0); PG8_LDB(B1, 0, 1); PG8_SCHED; PG8_LDA(At, 0, 0); PG8_STAGE(PG8_SA(1, 1), a1 + hA, voffA);
;             PG8_WAIT_V(8); PG8_WAIT_L(0); PG8_BAR; PG8_MMA(0, 0, At, B0); PG8_MMA(0, 1, At, B1); PG8_BAR; PG8_SCHED;
;             PG8_LDA(At, 0, 1); PG8_STAGE(PG8_SB(0, 0), b2, voffB); PG8_STAGE(PG8_SB(0, 1), b2 + hB, voffB); PG8_STAGE(PG8_SA(0, 0), a2, voffA);
.LBB0_225:
	ds_read_b128 v[144:147], v142
	ds_read_b128 v[148:151], v142 offset:1024
	ds_read_b128 v[158:161], v142 offset:2048
	ds_read_b128 v[162:165], v142 offset:3072
	ds_read_b128 v[166:169], v143
	ds_read_b128 v[170:173], v143 offset:1024
	ds_read_b128 v[174:177], v143 offset:2048
	ds_read_b128 v[178:181], v143 offset:3072
	s_add_u32 s26, s58, 0xfff00080
	s_addc_u32 s27, s59, -1
	s_cmp_eq_u32 s25, 60
	s_cselect_b32 s65, s0, s27
	s_cselect_b32 s64, s1, s26
	s_cselect_b32 s63, s6, s24
	s_cselect_b32 s62, s22, s23
	v_lshl_add_u64 v[214:215], s[58:59], 0, v[132:133]
	s_add_i32 m0, s70, 0xc000
	ds_read_b128 v[182:185], v141
	ds_read_b128 v[186:189], v141 offset:1024
	ds_read_b128 v[190:193], v141 offset:2048
	ds_read_b128 v[194:197], v141 offset:3072
	ds_read_b128 v[198:201], v141 offset:4096
	ds_read_b128 v[202:205], v141 offset:5120
	ds_read_b128 v[206:209], v141 offset:6144
	ds_read_b128 v[210:213], v141 offset:7168
	global_load_lds_dwordx4 v[214:215], off
	v_lshl_add_u64 v[214:215], s[58:59], 0, v[138:139]
	s_add_i32 m0, s70, 0xe000
	s_nop 0
	global_load_lds_dwordx4 v[214:215], off
	s_waitcnt vmcnt(8)
	s_waitcnt lgkmcnt(0)
	s_barrier
	s_waitcnt lgkmcnt(0)
	v_mfma_f32_16x16x32_bf16 v[124:127], v[144:147], v[182:185], v[124:127]
	v_mfma_f32_16x16x32_bf16 v[124:127], v[148:151], v[186:189], v[124:127]
	v_mfma_f32_16x16x32_bf16 v[120:123], v[158:161], v[182:185], v[120:123]
	v_mfma_f32_16x16x32_bf16 v[120:123], v[162:165], v[186:189], v[120:123]
	v_mfma_f32_16x16x32_bf16 v[108:111], v[144:147], v[190:193], v[108:111]
	v_mfma_f32_16x16x32_bf16 v[108:111], v[148:151], v[194:197], v[108:111]
	v_mfma_f32_16x16x32_bf16 v[104:107], v[158:161], v[190:193], v[104:107]
	v_mfma_f32_16x16x32_bf16 v[104:107], v[162:165], v[194:197], v[104:107]
	v_mfma_f32_16x16x32_bf16 v[92:95], v[144:147], v[198:201], v[92:95]
	v_mfma_f32_16x16x32_bf16 v[92:95], v[148:151], v[202:205], v[92:95]
	v_mfma_f32_16x16x32_bf16 v[88:91], v[158:161], v[198:201], v[88:91]
	v_mfma_f32_16x16x32_bf16 v[88:91], v[162:165], v[202:205], v[88:91]
	v_mfma_f32_16x16x32_bf16 v[76:79], v[144:147], v[206:209], v[76:79]
	v_mfma_f32_16x16x32_bf16 v[76:79], v[148:151], v[210:213], v[76:79]
	v_mfma_f32_16x16x32_bf16 v[72:75], v[158:161], v[206:209], v[72:75]
	v_mfma_f32_16x16x32_bf16 v[72:75], v[162:165], v[210:213], v[72:75]
	v_mfma_f32_16x16x32_bf16 v[116:119], v[166:169], v[182:185], v[116:119]
	v_mfma_f32_16x16x32_bf16 v[116:119], v[170:173], v[186:189], v[116:119]
	v_mfma_f32_16x16x32_bf16 v[112:115], v[174:177], v[182:185], v[112:115]
	v_mfma_f32_16x16x32_bf16 v[112:115], v[178:181], v[186:189], v[112:115]
	v_mfma_f32_16x16x32_bf16 v[100:103], v[166:169], v[190:193], v[100:103]
	v_mfma_f32_16x16x32_bf16 v[100:103], v[170:173], v[194:197], v[100:103]
	v_mfma_f32_16x16x32_bf16 v[96:99], v[174:177], v[190:193], v[96:99]
	v_mfma_f32_16x16x32_bf16 v[96:99], v[178:181], v[194:197], v[96:99]
	v_mfma_f32_16x16x32_bf16 v[84:87], v[166:169], v[198:201], v[84:87]
	v_mfma_f32_16x16x32_bf16 v[84:87], v[170:173], v[202:205], v[84:87]
	v_mfma_f32_16x16x32_bf16 v[80:83], v[174:177], v[198:201], v[80:83]
	v_mfma_f32_16x16x32_bf16 v[80:83], v[178:181], v[202:205], v[80:83]
	v_mfma_f32_16x16x32_bf16 v[68:71], v[166:169], v[206:209], v[68:71]
	v_mfma_f32_16x16x32_bf16 v[68:71], v[170:173], v[210:213], v[68:71]
	v_mfma_f32_16x16x32_bf16 v[64:67], v[174:177], v[206:209], v[64:67]
	v_mfma_f32_16x16x32_bf16 v[64:67], v[178:181], v[210:213], v[64:67]
	s_barrier
	s_add_i32 s26, s12, s69
	v_lshl_add_u64 v[214:215], s[62:63], 0, v[128:129]
	s_mov_b32 m0, s26
	ds_read_b128 v[182:185], v141 offset:16384
	ds_read_b128 v[186:189], v141 offset:17408
	ds_read_b128 v[190:193], v141 offset:18432
	ds_read_b128 v[194:197], v141 offset:19456
	ds_read_b128 v[198:201], v141 offset:20480
	ds_read_b128 v[202:205], v141 offset:21504
	ds_read_b128 v[206:209], v141 offset:22528
	ds_read_b128 v[210:213], v141 offset:23552
	global_load_lds_dwordx4 v[214:215], off
	s_add_i32 m0, s26, 0x2000
	s_add_u32 s26, s62, 0x100000
	v_lshl_add_u64 v[216:217], s[62:63], 0, v[130:131]
	s_addc_u32 s27, s63, 0
	s_add_i32 s28, s13, s69
	global_load_lds_dwordx4 v[216:217], off
	v_lshl_add_u64 v[218:219], s[26:27], 0, v[128:129]
	s_mov_b32 m0, s28
	v_lshl_add_u64 v[220:221], s[64:65], 0, v[138:139]
	global_load_lds_dwordx4 v[218:219], off
	v_lshl_add_u64 v[218:219], s[26:27], 0, v[130:131]
	s_add_i32 m0, s28, 0x2000
	s_nop 0
	global_load_lds_dwordx4 v[218:219], off
	v_lshl_add_u64 v[218:219], s[64:65], 0, v[132:133]
	s_mov_b32 m0, s70
	s_nop 0
	global_load_lds_dwordx4 v[218:219], off
	s_mov_b32 m0, s71
	s_nop 0
	global_load_lds_dwordx4 v[220:221], off
	s_waitcnt vmcnt(8)
	s_waitcnt lgkmcnt(0)
	s_barrier
; #define PG8_STAGE(bufoff, gbase, voff) do { _Pragma("unroll") for (int _i = 0; _i < 2; ++_i) \
;         __builtin_amdgcn_global_load_lds((const unsigned*)((const char*)(gbase) + (voff)[_i]), (LAS unsigned*)(lds + (bufoff) + ldsw + _i * 8192), 16, 0, 0); } while (0)
; #define PG8_LDA(dst, b, h) do { _Pragma("unroll") for (int m = 0; m < 4; ++m) _Pragma("unroll") for (int k = 0; k < 2; ++k) dst[m][k] = *(const LAS bf16x8*)(lds + PG8_SA(b, h) + aoff + m * 2048 + k * 1024); } while (0)
; #define PG8_LDB(dst, b, h) do { _Pragma("unroll") for (int n = 0; n < 2; ++n) _Pragma("unroll") for (int k = 0; k < 2; ++k) dst[n][k] = *(const LAS bf16x8*)(lds + PG8_SB(b, h) + boff + n * 2048 + k * 1024); } while (0)
; #define PG8_MMA(ai, bj, At, Bt) do { __builtin_amdgcn_s_setprio(1); _Pragma("unroll") for (int m = 0; m < 4; ++m) _Pragma("unroll") for (int n = 0; n < 2; ++n) _Pragma("unroll") for (int k = 0; k < 2; ++k) \
;         acc[ai][bj][m][n] = __builtin_amdgcn_mfma_f32_16x16x32_bf16(Bt[n][k], At[m][k], acc[ai][bj][m][n], 0, 0, 0); __builtin_amdgcn_s_setprio(0); } while (0)
; #define PG8_WAIT_V(n) asm volatile("s_waitcnt vmcnt(" #n ")" ::: "memory")
; #define PG8_WAIT_L(n) asm volatile("s_waitcnt lgkmcnt(" #n ")" ::: "memory")
; #define PG8_BAR __builtin_amdgcn_s_barrier()
; #define PG8_SCHED __builtin_amdgcn_sched_barrier(0)
; template <class Epi>
; __device__ __forceinline__ void gemm_phase(LAS unsigned char* lds, const Gemm g, const Order& S, const Epi& E, const int wid) {
;     ...
;             PG8_LDA(At, 0, 1); PG8_STAGE(PG8_SB(0, 0), b2, voffB); PG8_STAGE(PG8_SB(0, 1), b2 + hB, voffB); PG8_STAGE(PG8_SA(0, 0), a2, voffA);
;             PG8_WAIT_V(8); PG8_WAIT_L(0); PG8_BAR; PG8_MMA(1, 0, At, B0); PG8_MMA(1, 1, At, B1); PG8_BAR; PG8_SCHED;
;             PG8_LDB(B0, 1, 0); PG8_LDB(B1, 1, 1); PG8_SCHED; PG8_LDA(At, 1, 0); PG8_STAGE(PG8_SA(0, 1), a2 + hA, voffA);
;             PG8_WAIT_V(8); PG8_WAIT_L(0); PG8_BAR; PG8_MMA(0, 0, At, B0); PG8_MMA(0, 1, At, B1); PG8_BAR; PG8_SCHED;
	s_waitcnt lgkmcnt(0)
	v_mfma_f32_16x16x32_bf16 v[60:63], v[144:147], v[182:185], v[60:63]
	v_mfma_f32_16x16x32_bf16 v[60:63], v[148:151], v[186:189], v[60:63]
	v_mfma_f32_16x16x32_bf16 v[56:59], v[158:161], v[182:185], v[56:59]
	v_mfma_f32_16x16x32_bf16 v[56:59], v[162:165], v[186:189], v[56:59]
	v_mfma_f32_16x16x32_bf16 v[44:47], v[144:147], v[190:193], v[44:47]
	v_mfma_f32_16x16x32_bf16 v[44:47], v[148:151], v[194:197], v[44:47]
	v_mfma_f32_16x16x32_bf16 v[40:43], v[158:161], v[190:193], v[40:43]
	v_mfma_f32_16x16x32_bf16 v[40:43], v[162:165], v[194:197], v[40:43]
	v_mfma_f32_16x16x32_bf16 v[28:31], v[144:147], v[198:201], v[28:31]
	v_mfma_f32_16x16x32_bf16 v[28:31], v[148:151], v[202:205], v[28:31]
	v_mfma_f32_16x16x32_bf16 v[24:27], v[158:161], v[198:201], v[24:27]
	v_mfma_f32_16x16x32_bf16 v[24:27], v[162:165], v[202:205], v[24:27]
	v_mfma_f32_16x16x32_bf16 v[12:15], v[144:147], v[206:209], v[12:15]
	v_mfma_f32_16x16x32_bf16 v[12:15], v[148:151], v[210:213], v[12:15]
	v_mfma_f32_16x16x32_bf16 v[8:11], v[158:161], v[206:209], v[8:11]
	v_mfma_f32_16x16x32_bf16 v[8:11], v[162:165], v[210:213], v[8:11]
	v_mfma_f32_16x16x32_bf16 v[52:55], v[166:169], v[182:185], v[52:55]
	v_mfma_f32_16x16x32_bf16 v[52:55], v[170:173], v[186:189], v[52:55]
	v_mfma_f32_16x16x32_bf16 v[48:51], v[174:177], v[182:185], v[48:51]
	v_mfma_f32_16x16x32_bf16 v[48:51], v[178:181], v[186:189], v[48:51]
	v_mfma_f32_16x16x32_bf16 v[36:39], v[166:169], v[190:193], v[36:39]
	v_mfma_f32_16x16x32_bf16 v[36:39], v[170:173], v[194:197], v[36:39]
	v_mfma_f32_16x16x32_bf16 v[32:35], v[174:177], v[190:193], v[32:35]
	v_mfma_f32_16x16x32_bf16 v[32:35], v[178:181], v[194:197], v[32:35]
	v_mfma_f32_16x16x32_bf16 v[20:23], v[166:169], v[198:201], v[20:23]
	v_mfma_f32_16x16x32_bf16 v[20:23], v[170:173], v[202:205], v[20:23]
	v_mfma_f32_16x16x32_bf16 v[16:19], v[174:177], v[198:201], v[16:19]
	v_mfma_f32_16x16x32_bf16 v[16:19], v[178:181], v[202:205], v[16:19]
	v_mfma_f32_16x16x32_bf16 v[4:7], v[166:169], v[206:209], v[4:7]
	v_mfma_f32_16x16x32_bf16 v[4:7], v[170:173], v[210:213], v[4:7]
	v_mfma_f32_16x16x32_bf16 v[0:3], v[174:177], v[206:209], v[0:3]
	v_mfma_f32_16x16x32_bf16 v[0:3], v[178:181], v[210:213], v[0:3]
	s_barrier
	s_add_i32 s28, 0, 0x18000
	v_add_u32_e32 v157, s28, v140
	s_add_i32 s29, 0, 0x1c000
	ds_read_b128 v[144:147], v157
	ds_read_b128 v[148:151], v157 offset:1024
	ds_read_b128 v[158:161], v157 offset:2048
	ds_read_b128 v[162:165], v157 offset:3072
	v_add_u32_e32 v157, s29, v140
	ds_read_b128 v[166:169], v157
	ds_read_b128 v[170:173], v157 offset:1024
	ds_read_b128 v[174:177], v157 offset:2048
	ds_read_b128 v[178:181], v157 offset:3072
	s_add_u32 s26, s64, 0x100000
	s_addc_u32 s27, s65, 0
	s_mov_b32 m0, s76
	v_lshl_add_u64 v[222:223], s[26:27], 0, v[132:133]
	ds_read_b128 v[182:185], v141 offset:32768
	ds_read_b128 v[186:189], v141 offset:33792
	ds_read_b128 v[190:193], v141 offset:34816
	ds_read_b128 v[194:197], v141 offset:35840
	ds_read_b128 v[198:201], v141 offset:36864
	ds_read_b128 v[202:205], v141 offset:37888
	ds_read_b128 v[206:209], v141 offset:38912
	ds_read_b128 v[210:213], v141 offset:39936
	global_load_lds_dwordx4 v[222:223], off
	v_lshl_add_u64 v[222:223], s[26:27], 0, v[138:139]
	s_mov_b32 m0, s77
	s_nop 0
	global_load_lds_dwordx4 v[222:223], off
	s_waitcnt vmcnt(8)
	s_waitcnt lgkmcnt(0)
	s_barrier
	s_waitcnt lgkmcnt(0)
	v_mfma_f32_16x16x32_bf16 v[124:127], v[144:147], v[182:185], v[124:127]
	v_mfma_f32_16x16x32_bf16 v[124:127], v[148:151], v[186:189], v[124:127]
	v_mfma_f32_16x16x32_bf16 v[120:123], v[158:161], v[182:185], v[120:123]
	v_mfma_f32_16x16x32_bf16 v[120:123], v[162:165], v[186:189], v[120:123]
	v_mfma_f32_16x16x32_bf16 v[108:111], v[144:147], v[190:193], v[108:111]
	v_mfma_f32_16x16x32_bf16 v[108:111], v[148:151], v[194:197], v[108:111]
	v_mfma_f32_16x16x32_bf16 v[104:107], v[158:161], v[190:193], v[104:107]
	v_mfma_f32_16x16x32_bf16 v[104:107], v[162:165], v[194:197], v[104:107]
	v_mfma_f32_16x16x32_bf16 v[92:95], v[144:147], v[198:201], v[92:95]
	v_mfma_f32_16x16x32_bf16 v[92:95], v[148:151], v[202:205], v[92:95]
	v_mfma_f32_16x16x32_bf16 v[88:91], v[158:161], v[198:201], v[88:91]
	v_mfma_f32_16x16x32_bf16 v[88:91], v[162:165], v[202:205], v[88:91]
	v_mfma_f32_16x16x32_bf16 v[76:79], v[144:147], v[206:209], v[76:79]
	v_mfma_f32_16x16x32_bf16 v[76:79], v[148:151], v[210:213], v[76:79]
	v_mfma_f32_16x16x32_bf16 v[72:75], v[158:161], v[206:209], v[72:75]
	v_mfma_f32_16x16x32_bf16 v[72:75], v[162:165], v[210:213], v[72:75]
	v_mfma_f32_16x16x32_bf16 v[116:119], v[166:169], v[182:185], v[116:119]
	v_mfma_f32_16x16x32_bf16 v[116:119], v[170:173], v[186:189], v[116:119]
	v_mfma_f32_16x16x32_bf16 v[112:115], v[174:177], v[182:185], v[112:115]
	v_mfma_f32_16x16x32_bf16 v[112:115], v[178:181], v[186:189], v[112:115]
	v_mfma_f32_16x16x32_bf16 v[100:103], v[166:169], v[190:193], v[100:103]
	v_mfma_f32_16x16x32_bf16 v[100:103], v[170:173], v[194:197], v[100:103]
	v_mfma_f32_16x16x32_bf16 v[96:99], v[174:177], v[190:193], v[96:99]
	v_mfma_f32_16x16x32_bf16 v[96:99], v[178:181], v[194:197], v[96:99]
	v_mfma_f32_16x16x32_bf16 v[84:87], v[166:169], v[198:201], v[84:87]
	v_mfma_f32_16x16x32_bf16 v[84:87], v[170:173], v[202:205], v[84:87]
	v_mfma_f32_16x16x32_bf16 v[80:83], v[174:177], v[198:201], v[80:83]
	v_mfma_f32_16x16x32_bf16 v[80:83], v[178:181], v[202:205], v[80:83]
	v_mfma_f32_16x16x32_bf16 v[68:71], v[166:169], v[206:209], v[68:71]
	v_mfma_f32_16x16x32_bf16 v[68:71], v[170:173], v[210:213], v[68:71]
	v_mfma_f32_16x16x32_bf16 v[64:67], v[174:177], v[206:209], v[64:67]
	v_mfma_f32_16x16x32_bf16 v[64:67], v[178:181], v[210:213], v[64:67]
	s_barrier
; #define PG8_STAGE(bufoff, gbase, voff) do { _Pragma("unroll") for (int _i = 0; _i < 2; ++_i) \
;         __builtin_amdgcn_global_load_lds((const unsigned*)((const char*)(gbase) + (voff)[_i]), (LAS unsigned*)(lds + (bufoff) + ldsw + _i * 8192), 16, 0, 0); } while (0)
; #define PG8_LDA(dst, b, h) do { _Pragma("unroll") for (int m = 0; m < 4; ++m) _Pragma("unroll") for (int k = 0; k < 2; ++k) dst[m][k] = *(const LAS bf16x8*)(lds + PG8_SA(b, h) + aoff + m * 2048 + k * 1024); } while (0)
; #define PG8_MMA(ai, bj, At, Bt) do { __builtin_amdgcn_s_setprio(1); _Pragma("unroll") for (int m = 0; m < 4; ++m) _Pragma("unroll") for (int n = 0; n < 2; ++n) _Pragma("unroll") for (int k = 0; k < 2; ++k) \
;         acc[ai][bj][m][n] = __builtin_amdgcn_mfma_f32_16x16x32_bf16(Bt[n][k], At[m][k], acc[ai][bj][m][n], 0, 0, 0); __builtin_amdgcn_s_setprio(0); } while (0)
; #define PG8_WAIT_V(n) asm volatile("s_waitcnt vmcnt(" #n ")" ::: "memory")
; #define PG8_WAIT_L(n) asm volatile("s_waitcnt lgkmcnt(" #n ")" ::: "memory")
; #define PG8_BAR __builtin_amdgcn_s_barrier()
; #define PG8_SCHED __builtin_amdgcn_sched_barrier(0)
; template <class Epi>
; __device__ __forceinline__ void gemm_phase(LAS unsigned char* lds, const Gemm g, const Order& S, const Epi& E, const int wid) {
;     ...
;             PG8_LDA(At, 1, 1); PG8_STAGE(PG8_SB(1, 0), b3, voffB); PG8_STAGE(PG8_SB(1, 1), b3 + hB, voffB); PG8_STAGE(PG8_SA(1, 0), a3, voffA);
;             PG8_WAIT_V(8); PG8_WAIT_L(0); PG8_BAR; PG8_MMA(1, 0, At, B0); PG8_MMA(1, 1, At, B1); PG8_BAR; PG8_SCHED;
	s_add_i32 s26, s28, s69
	v_lshl_add_u64 v[214:215], v[214:215], 0, s[36:37]
	s_mov_b32 m0, s26
	ds_read_b128 v[182:185], v141 offset:49152
	ds_read_b128 v[186:189], v141 offset:50176
	ds_read_b128 v[190:193], v141 offset:51200
	ds_read_b128 v[194:197], v141 offset:52224
	ds_read_b128 v[198:201], v141 offset:53248
	ds_read_b128 v[202:205], v141 offset:54272
	ds_read_b128 v[206:209], v141 offset:55296
	ds_read_b128 v[210:213], v141 offset:56320
	global_load_lds_dwordx4 v[214:215], off
	s_add_i32 m0, s26, 0x2000
	s_add_u32 s26, s62, 0x100080
	v_lshl_add_u64 v[214:215], v[216:217], 0, s[36:37]
	s_addc_u32 s27, s63, 0
	s_add_i32 s28, s29, s69
	global_load_lds_dwordx4 v[214:215], off
	v_lshl_add_u64 v[214:215], s[26:27], 0, v[128:129]
	s_mov_b32 m0, s28
	s_nop 0
	global_load_lds_dwordx4 v[214:215], off
	v_lshl_add_u64 v[214:215], s[26:27], 0, v[130:131]
	s_add_i32 m0, s28, 0x2000
	s_nop 0
	global_load_lds_dwordx4 v[214:215], off
	v_lshl_add_u64 v[214:215], v[218:219], 0, s[36:37]
	s_mov_b32 m0, s75
	s_nop 0
	global_load_lds_dwordx4 v[214:215], off
	v_lshl_add_u64 v[214:215], v[220:221], 0, s[36:37]
	s_mov_b32 m0, s79
	s_nop 0
	global_load_lds_dwordx4 v[214:215], off
	s_waitcnt vmcnt(8)
	s_waitcnt lgkmcnt(0)
	s_barrier
	s_waitcnt lgkmcnt(0)
	v_mfma_f32_16x16x32_bf16 v[60:63], v[144:147], v[182:185], v[60:63]
	v_mfma_f32_16x16x32_bf16 v[60:63], v[148:151], v[186:189], v[60:63]
	v_mfma_f32_16x16x32_bf16 v[56:59], v[158:161], v[182:185], v[56:59]
	v_mfma_f32_16x16x32_bf16 v[56:59], v[162:165], v[186:189], v[56:59]
	v_mfma_f32_16x16x32_bf16 v[44:47], v[144:147], v[190:193], v[44:47]
	v_mfma_f32_16x16x32_bf16 v[44:47], v[148:151], v[194:197], v[44:47]
	v_mfma_f32_16x16x32_bf16 v[40:43], v[158:161], v[190:193], v[40:43]
	v_mfma_f32_16x16x32_bf16 v[40:43], v[162:165], v[194:197], v[40:43]
	v_mfma_f32_16x16x32_bf16 v[28:31], v[144:147], v[198:201], v[28:31]
	v_mfma_f32_16x16x32_bf16 v[28:31], v[148:151], v[202:205], v[28:31]
	v_mfma_f32_16x16x32_bf16 v[24:27], v[158:161], v[198:201], v[24:27]
	v_mfma_f32_16x16x32_bf16 v[24:27], v[162:165], v[202:205], v[24:27]
	v_mfma_f32_16x16x32_bf16 v[12:15], v[144:147], v[206:209], v[12:15]
	v_mfma_f32_16x16x32_bf16 v[12:15], v[148:151], v[210:213], v[12:15]
	v_mfma_f32_16x16x32_bf16 v[8:11], v[158:161], v[206:209], v[8:11]
	v_mfma_f32_16x16x32_bf16 v[8:11], v[162:165], v[210:213], v[8:11]
	v_mfma_f32_16x16x32_bf16 v[52:55], v[166:169], v[182:185], v[52:55]
	v_mfma_f32_16x16x32_bf16 v[52:55], v[170:173], v[186:189], v[52:55]
	v_mfma_f32_16x16x32_bf16 v[48:51], v[174:177], v[182:185], v[48:51]
	v_mfma_f32_16x16x32_bf16 v[48:51], v[178:181], v[186:189], v[48:51]
	v_mfma_f32_16x16x32_bf16 v[36:39], v[166:169], v[190:193], v[36:39]
	v_mfma_f32_16x16x32_bf16 v[36:39], v[170:173], v[194:197], v[36:39]
	v_mfma_f32_16x16x32_bf16 v[32:35], v[174:177], v[190:193], v[32:35]
	v_mfma_f32_16x16x32_bf16 v[32:35], v[178:181], v[194:197], v[32:35]
	v_mfma_f32_16x16x32_bf16 v[20:23], v[166:169], v[198:201], v[20:23]
	v_mfma_f32_16x16x32_bf16 v[20:23], v[170:173], v[202:205], v[20:23]
	v_mfma_f32_16x16x32_bf16 v[16:19], v[174:177], v[198:201], v[16:19]
	v_mfma_f32_16x16x32_bf16 v[16:19], v[178:181], v[202:205], v[16:19]
	v_mfma_f32_16x16x32_bf16 v[4:7], v[166:169], v[206:209], v[4:7]
	v_mfma_f32_16x16x32_bf16 v[4:7], v[170:173], v[210:213], v[4:7]
	v_mfma_f32_16x16x32_bf16 v[0:3], v[174:177], v[206:209], v[0:3]
	v_mfma_f32_16x16x32_bf16 v[0:3], v[178:181], v[210:213], v[0:3]
	s_barrier
	s_add_i32 s25, s25, 2
	s_add_u32 s58, s58, 0x100
	s_addc_u32 s59, s59, 0
	s_add_u32 s23, s23, 0x100
	s_addc_u32 s24, s24, 0
	s_cmp_gt_u32 s25, 61
	s_cbranch_scc0 .LBB0_225
	s_and_b64 vcc, exec, s[14:15]
	s_cbranch_vccz .LBB0_228
	s_barrier

; #define PG8_STAGE(bufoff, gbase, voff) do { _Pragma("unroll") for (int _i = 0; _i < 2; ++_i) \
;         __builtin_amdgcn_global_load_lds((const unsigned*)((const char*)(gbase) + (voff)[_i]), (LAS unsigned*)(lds + (bufoff) + ldsw + _i * 8192), 16, 0, 0); } while (0)
; #define PG8_LDA(dst, b, h) do { _Pragma("unroll") for (int m = 0; m < 4; ++m) _Pragma("unroll") for (int k = 0; k < 2; ++k) dst[m][k] = *(const LAS bf16x8*)(lds + PG8_SA(b, h) + aoff + m * 2048 + k * 1024); } while (0)
; #define PG8_LDB(dst, b, h) do { _Pragma("unroll") for (int n = 0; n < 2; ++n) _Pragma("unroll") for (int k = 0; k < 2; ++k) dst[n][k] = *(const LAS bf16x8*)(lds + PG8_SB(b, h) + boff + n * 2048 + k * 1024); } while (0)
; #define PG8_MMA(ai, bj, At, Bt) do { __builtin_amdgcn_s_setprio(1); _Pragma("unroll") for (int m = 0; m < 4; ++m) _Pragma("unroll") for (int n = 0; n < 2; ++n) _Pragma("unroll") for (int k = 0; k < 2; ++k) \
;         acc[ai][bj][m][n] = __builtin_amdgcn_mfma_f32_16x16x32_bf16(Bt[n][k], At[m][k], acc[ai][bj][m][n], 0, 0, 0); __builtin_amdgcn_s_setprio(0); } while (0)
; #define PG8_WAIT_V(n) asm volatile("s_waitcnt vmcnt(" #n ")" ::: "memory")
; #define PG8_WAIT_L(n) asm volatile("s_waitcnt lgkmcnt(" #n ")" ::: "memory")
; #define PG8_BAR __builtin_amdgcn_s_barrier()
; #define PG8_SCHED __builtin_amdgcn_sched_barrier(0)
; template <class Epi>
; __device__ __forceinline__ void gemm_phase(LAS unsigned char* lds, const Gemm g, const Order& S, const Epi& E, const int wid) {
;     ...
;             PG8_LDB(B0, 0, 0); PG8_LDB(B1, 0, 1); PG8_SCHED; PG8_LDA(At, 0, 0); PG8_STAGE(PG8_SA(1, 1), a1 + hA, voffA);
;             PG8_WAIT_V(8); PG8_WAIT_L(0); PG8_BAR; PG8_MMA(0, 0, At, B0); PG8_MMA(0, 1, At, B1); PG8_BAR; PG8_SCHED;
;             PG8_LDA(At, 0, 1); PG8_STAGE(PG8_SB(0, 0), b2, voffB); PG8_STAGE(PG8_SB(0, 1), b2 + hB, voffB); PG8_STAGE(PG8_SA(0, 0), a2, voffA);
.LBB0_344:
	ds_read_b128 v[144:147], v141
	ds_read_b128 v[152:155], v141 offset:1024
	ds_read_b128 v[156:159], v141 offset:2048
	ds_read_b128 v[160:163], v141 offset:3072
	ds_read_b128 v[164:167], v142
	ds_read_b128 v[168:171], v142 offset:1024
	ds_read_b128 v[172:175], v142 offset:2048
	ds_read_b128 v[176:179], v142 offset:3072
	s_add_u32 s10, s8, 0xfffc0080
	s_addc_u32 s11, s9, -1
	s_cmp_eq_u32 s75, 12
	s_cselect_b32 s13, s7, s11
	s_cselect_b32 s12, s40, s10
	s_cselect_b32 s11, s47, s74
	s_cselect_b32 s10, s55, s73
	v_lshl_add_u64 v[212:213], s[8:9], 0, v[128:129]
	s_add_i32 m0, s29, 0xc000
	ds_read_b128 v[180:183], v143
	ds_read_b128 v[184:187], v143 offset:1024
	ds_read_b128 v[188:191], v143 offset:2048
	ds_read_b128 v[192:195], v143 offset:3072
	ds_read_b128 v[196:199], v143 offset:4096
	ds_read_b128 v[200:203], v143 offset:5120
	ds_read_b128 v[204:207], v143 offset:6144
	ds_read_b128 v[208:211], v143 offset:7168
	global_load_lds_dwordx4 v[212:213], off
	v_lshl_add_u64 v[212:213], s[8:9], 0, v[138:139]
	s_add_i32 m0, s29, 0xe000
	s_nop 0
	global_load_lds_dwordx4 v[212:213], off
	s_waitcnt vmcnt(8)
	s_waitcnt lgkmcnt(0)
	s_barrier
	s_waitcnt lgkmcnt(0)
	v_mfma_f32_16x16x32_bf16 v[124:127], v[144:147], v[180:183], v[124:127]
	v_mfma_f32_16x16x32_bf16 v[124:127], v[152:155], v[184:187], v[124:127]
	v_mfma_f32_16x16x32_bf16 v[120:123], v[156:159], v[180:183], v[120:123]
	v_mfma_f32_16x16x32_bf16 v[120:123], v[160:163], v[184:187], v[120:123]
	v_mfma_f32_16x16x32_bf16 v[112:115], v[144:147], v[188:191], v[112:115]
	v_mfma_f32_16x16x32_bf16 v[112:115], v[152:155], v[192:195], v[112:115]
	v_mfma_f32_16x16x32_bf16 v[104:107], v[156:159], v[188:191], v[104:107]
	v_mfma_f32_16x16x32_bf16 v[104:107], v[160:163], v[192:195], v[104:107]
	v_mfma_f32_16x16x32_bf16 v[96:99], v[144:147], v[196:199], v[96:99]
	v_mfma_f32_16x16x32_bf16 v[96:99], v[152:155], v[200:203], v[96:99]
	v_mfma_f32_16x16x32_bf16 v[88:91], v[156:159], v[196:199], v[88:91]
	v_mfma_f32_16x16x32_bf16 v[88:91], v[160:163], v[200:203], v[88:91]
	v_mfma_f32_16x16x32_bf16 v[80:83], v[144:147], v[204:207], v[80:83]
	v_mfma_f32_16x16x32_bf16 v[80:83], v[152:155], v[208:211], v[80:83]
	v_mfma_f32_16x16x32_bf16 v[72:75], v[156:159], v[204:207], v[72:75]
	v_mfma_f32_16x16x32_bf16 v[72:75], v[160:163], v[208:211], v[72:75]
	v_mfma_f32_16x16x32_bf16 v[116:119], v[164:167], v[180:183], v[116:119]
	v_mfma_f32_16x16x32_bf16 v[116:119], v[168:171], v[184:187], v[116:119]
	v_mfma_f32_16x16x32_bf16 v[108:111], v[172:175], v[180:183], v[108:111]
	v_mfma_f32_16x16x32_bf16 v[108:111], v[176:179], v[184:187], v[108:111]
	v_mfma_f32_16x16x32_bf16 v[100:103], v[164:167], v[188:191], v[100:103]
	v_mfma_f32_16x16x32_bf16 v[100:103], v[168:171], v[192:195], v[100:103]
	v_mfma_f32_16x16x32_bf16 v[92:95], v[172:175], v[188:191], v[92:95]
	v_mfma_f32_16x16x32_bf16 v[92:95], v[176:179], v[192:195], v[92:95]
	v_mfma_f32_16x16x32_bf16 v[84:87], v[164:167], v[196:199], v[84:87]
	v_mfma_f32_16x16x32_bf16 v[84:87], v[168:171], v[200:203], v[84:87]
	v_mfma_f32_16x16x32_bf16 v[76:79], v[172:175], v[196:199], v[76:79]
	v_mfma_f32_16x16x32_bf16 v[76:79], v[176:179], v[200:203], v[76:79]
	v_mfma_f32_16x16x32_bf16 v[68:71], v[164:167], v[204:207], v[68:71]
	v_mfma_f32_16x16x32_bf16 v[68:71], v[168:171], v[208:211], v[68:71]
	v_mfma_f32_16x16x32_bf16 v[64:67], v[172:175], v[204:207], v[64:67]
	v_mfma_f32_16x16x32_bf16 v[64:67], v[176:179], v[208:211], v[64:67]
	s_barrier
	s_add_i32 s76, s65, s0
	v_lshl_add_u64 v[212:213], s[10:11], 0, v[134:135]
	s_mov_b32 m0, s76
	ds_read_b128 v[180:183], v143 offset:16384
	ds_read_b128 v[184:187], v143 offset:17408
	ds_read_b128 v[188:191], v143 offset:18432
	ds_read_b128 v[192:195], v143 offset:19456
	ds_read_b128 v[196:199], v143 offset:20480
	ds_read_b128 v[200:203], v143 offset:21504
	ds_read_b128 v[204:207], v143 offset:22528
	ds_read_b128 v[208:211], v143 offset:23552
	global_load_lds_dwordx4 v[212:213], off
	s_add_i32 m0, s76, 0x2000
	s_add_u32 s76, s10, 0x40000
	v_lshl_add_u64 v[214:215], s[10:11], 0, v[136:137]
	s_addc_u32 s77, s11, 0
	s_add_i32 s78, s66, s0
	global_load_lds_dwordx4 v[214:215], off
	v_lshl_add_u64 v[216:217], s[76:77], 0, v[134:135]
	s_mov_b32 m0, s78
	v_lshl_add_u64 v[218:219], s[12:13], 0, v[138:139]
	global_load_lds_dwordx4 v[216:217], off
	v_lshl_add_u64 v[216:217], s[76:77], 0, v[136:137]
	s_add_i32 m0, s78, 0x2000
	s_nop 0
	global_load_lds_dwordx4 v[216:217], off
	v_lshl_add_u64 v[216:217], s[12:13], 0, v[128:129]
	s_mov_b32 m0, s29
	s_nop 0
	global_load_lds_dwordx4 v[216:217], off
	s_mov_b32 m0, s30
	s_nop 0
	global_load_lds_dwordx4 v[218:219], off
	s_waitcnt vmcnt(8)
	s_waitcnt lgkmcnt(0)
	s_barrier
; #define PG8_STAGE(bufoff, gbase, voff) do { _Pragma("unroll") for (int _i = 0; _i < 2; ++_i) \
;         __builtin_amdgcn_global_load_lds((const unsigned*)((const char*)(gbase) + (voff)[_i]), (LAS unsigned*)(lds + (bufoff) + ldsw + _i * 8192), 16, 0, 0); } while (0)
; #define PG8_LDA(dst, b, h) do { _Pragma("unroll") for (int m = 0; m < 4; ++m) _Pragma("unroll") for (int k = 0; k < 2; ++k) dst[m][k] = *(const LAS bf16x8*)(lds + PG8_SA(b, h) + aoff + m * 2048 + k * 1024); } while (0)
; #define PG8_LDB(dst, b, h) do { _Pragma("unroll") for (int n = 0; n < 2; ++n) _Pragma("unroll") for (int k = 0; k < 2; ++k) dst[n][k] = *(const LAS bf16x8*)(lds + PG8_SB(b, h) + boff + n * 2048 + k * 1024); } while (0)
; #define PG8_MMA(ai, bj, At, Bt) do { __builtin_amdgcn_s_setprio(1); _Pragma("unroll") for (int m = 0; m < 4; ++m) _Pragma("unroll") for (int n = 0; n < 2; ++n) _Pragma("unroll") for (int k = 0; k < 2; ++k) \
;         acc[ai][bj][m][n] = __builtin_amdgcn_mfma_f32_16x16x32_bf16(Bt[n][k], At[m][k], acc[ai][bj][m][n], 0, 0, 0); __builtin_amdgcn_s_setprio(0); } while (0)
; #define PG8_WAIT_V(n) asm volatile("s_waitcnt vmcnt(" #n ")" ::: "memory")
; #define PG8_WAIT_L(n) asm volatile("s_waitcnt lgkmcnt(" #n ")" ::: "memory")
; #define PG8_BAR __builtin_amdgcn_s_barrier()
; #define PG8_SCHED __builtin_amdgcn_sched_barrier(0)
; template <class Epi>
; __device__ __forceinline__ void gemm_phase(LAS unsigned char* lds, const Gemm g, const Order& S, const Epi& E, const int wid) {
;     ...
;             PG8_LDA(At, 0, 1); PG8_STAGE(PG8_SB(0, 0), b2, voffB); PG8_STAGE(PG8_SB(0, 1), b2 + hB, voffB); PG8_STAGE(PG8_SA(0, 0), a2, voffA);
;             PG8_WAIT_V(8); PG8_WAIT_L(0); PG8_BAR; PG8_MMA(1, 0, At, B0); PG8_MMA(1, 1, At, B1); PG8_BAR; PG8_SCHED;
;             PG8_LDB(B0, 1, 0); PG8_LDB(B1, 1, 1); PG8_SCHED; PG8_LDA(At, 1, 0); PG8_STAGE(PG8_SA(0, 1), a2 + hA, voffA);
;             PG8_WAIT_V(8); PG8_WAIT_L(0); PG8_BAR; PG8_MMA(0, 0, At, B0); PG8_MMA(0, 1, At, B1); PG8_BAR; PG8_SCHED;
	s_waitcnt lgkmcnt(0)
	v_mfma_f32_16x16x32_bf16 v[60:63], v[144:147], v[180:183], v[60:63]
	v_mfma_f32_16x16x32_bf16 v[60:63], v[152:155], v[184:187], v[60:63]
	v_mfma_f32_16x16x32_bf16 v[56:59], v[156:159], v[180:183], v[56:59]
	v_mfma_f32_16x16x32_bf16 v[56:59], v[160:163], v[184:187], v[56:59]
	v_mfma_f32_16x16x32_bf16 v[48:51], v[144:147], v[188:191], v[48:51]
	v_mfma_f32_16x16x32_bf16 v[48:51], v[152:155], v[192:195], v[48:51]
	v_mfma_f32_16x16x32_bf16 v[40:43], v[156:159], v[188:191], v[40:43]
	v_mfma_f32_16x16x32_bf16 v[40:43], v[160:163], v[192:195], v[40:43]
	v_mfma_f32_16x16x32_bf16 v[32:35], v[144:147], v[196:199], v[32:35]
	v_mfma_f32_16x16x32_bf16 v[32:35], v[152:155], v[200:203], v[32:35]
	v_mfma_f32_16x16x32_bf16 v[24:27], v[156:159], v[196:199], v[24:27]
	v_mfma_f32_16x16x32_bf16 v[24:27], v[160:163], v[200:203], v[24:27]
	v_mfma_f32_16x16x32_bf16 v[16:19], v[144:147], v[204:207], v[16:19]
	v_mfma_f32_16x16x32_bf16 v[16:19], v[152:155], v[208:211], v[16:19]
	v_mfma_f32_16x16x32_bf16 v[8:11], v[156:159], v[204:207], v[8:11]
	v_mfma_f32_16x16x32_bf16 v[8:11], v[160:163], v[208:211], v[8:11]
	v_mfma_f32_16x16x32_bf16 v[52:55], v[164:167], v[180:183], v[52:55]
	v_mfma_f32_16x16x32_bf16 v[52:55], v[168:171], v[184:187], v[52:55]
	v_mfma_f32_16x16x32_bf16 v[44:47], v[172:175], v[180:183], v[44:47]
	v_mfma_f32_16x16x32_bf16 v[44:47], v[176:179], v[184:187], v[44:47]
	v_mfma_f32_16x16x32_bf16 v[36:39], v[164:167], v[188:191], v[36:39]
	v_mfma_f32_16x16x32_bf16 v[36:39], v[168:171], v[192:195], v[36:39]
	v_mfma_f32_16x16x32_bf16 v[28:31], v[172:175], v[188:191], v[28:31]
	v_mfma_f32_16x16x32_bf16 v[28:31], v[176:179], v[192:195], v[28:31]
	v_mfma_f32_16x16x32_bf16 v[20:23], v[164:167], v[196:199], v[20:23]
	v_mfma_f32_16x16x32_bf16 v[20:23], v[168:171], v[200:203], v[20:23]
	v_mfma_f32_16x16x32_bf16 v[12:15], v[172:175], v[196:199], v[12:15]
	v_mfma_f32_16x16x32_bf16 v[12:15], v[176:179], v[200:203], v[12:15]
	v_mfma_f32_16x16x32_bf16 v[4:7], v[164:167], v[204:207], v[4:7]
	v_mfma_f32_16x16x32_bf16 v[4:7], v[168:171], v[208:211], v[4:7]
	v_mfma_f32_16x16x32_bf16 v[0:3], v[172:175], v[204:207], v[0:3]
	v_mfma_f32_16x16x32_bf16 v[0:3], v[176:179], v[208:211], v[0:3]
	s_barrier
	s_add_i32 s76, 0, 0x18000
	s_add_i32 s77, 0, 0x1c000
	v_add_u32_e32 v160, s76, v140
	v_add_u32_e32 v176, s77, v140
	ds_read_b128 v[144:147], v160
	ds_read_b128 v[152:155], v160 offset:1024
	ds_read_b128 v[156:159], v160 offset:2048
	ds_read_b128 v[160:163], v160 offset:3072
	ds_read_b128 v[164:167], v176
	ds_read_b128 v[168:171], v176 offset:1024
	ds_read_b128 v[172:175], v176 offset:2048
	ds_read_b128 v[176:179], v176 offset:3072
	s_add_u32 s12, s12, 0x40000
	s_addc_u32 s13, s13, 0
	s_mov_b32 m0, s31
	v_lshl_add_u64 v[220:221], s[12:13], 0, v[128:129]
	ds_read_b128 v[180:183], v143 offset:32768
	ds_read_b128 v[184:187], v143 offset:33792
	ds_read_b128 v[188:191], v143 offset:34816
	ds_read_b128 v[192:195], v143 offset:35840
	ds_read_b128 v[196:199], v143 offset:36864
	ds_read_b128 v[200:203], v143 offset:37888
	ds_read_b128 v[204:207], v143 offset:38912
	ds_read_b128 v[208:211], v143 offset:39936
	global_load_lds_dwordx4 v[220:221], off
	v_lshl_add_u64 v[220:221], s[12:13], 0, v[138:139]
	s_mov_b32 m0, s33
	s_nop 0
	global_load_lds_dwordx4 v[220:221], off
	s_waitcnt vmcnt(8)
	s_waitcnt lgkmcnt(0)
	s_barrier
	s_waitcnt lgkmcnt(0)
	v_mfma_f32_16x16x32_bf16 v[124:127], v[144:147], v[180:183], v[124:127]
	v_mfma_f32_16x16x32_bf16 v[124:127], v[152:155], v[184:187], v[124:127]
	v_mfma_f32_16x16x32_bf16 v[120:123], v[156:159], v[180:183], v[120:123]
	v_mfma_f32_16x16x32_bf16 v[120:123], v[160:163], v[184:187], v[120:123]
	v_mfma_f32_16x16x32_bf16 v[112:115], v[144:147], v[188:191], v[112:115]
	v_mfma_f32_16x16x32_bf16 v[112:115], v[152:155], v[192:195], v[112:115]
	v_mfma_f32_16x16x32_bf16 v[104:107], v[156:159], v[188:191], v[104:107]
	v_mfma_f32_16x16x32_bf16 v[104:107], v[160:163], v[192:195], v[104:107]
	v_mfma_f32_16x16x32_bf16 v[96:99], v[144:147], v[196:199], v[96:99]
	v_mfma_f32_16x16x32_bf16 v[96:99], v[152:155], v[200:203], v[96:99]
	v_mfma_f32_16x16x32_bf16 v[88:91], v[156:159], v[196:199], v[88:91]
	v_mfma_f32_16x16x32_bf16 v[88:91], v[160:163], v[200:203], v[88:91]
	v_mfma_f32_16x16x32_bf16 v[80:83], v[144:147], v[204:207], v[80:83]
	v_mfma_f32_16x16x32_bf16 v[80:83], v[152:155], v[208:211], v[80:83]
	v_mfma_f32_16x16x32_bf16 v[72:75], v[156:159], v[204:207], v[72:75]
	v_mfma_f32_16x16x32_bf16 v[72:75], v[160:163], v[208:211], v[72:75]
	v_mfma_f32_16x16x32_bf16 v[116:119], v[164:167], v[180:183], v[116:119]
	v_mfma_f32_16x16x32_bf16 v[116:119], v[168:171], v[184:187], v[116:119]
	v_mfma_f32_16x16x32_bf16 v[108:111], v[172:175], v[180:183], v[108:111]
	v_mfma_f32_16x16x32_bf16 v[108:111], v[176:179], v[184:187], v[108:111]
	v_mfma_f32_16x16x32_bf16 v[100:103], v[164:167], v[188:191], v[100:103]
	v_mfma_f32_16x16x32_bf16 v[100:103], v[168:171], v[192:195], v[100:103]
	v_mfma_f32_16x16x32_bf16 v[92:95], v[172:175], v[188:191], v[92:95]
	v_mfma_f32_16x16x32_bf16 v[92:95], v[176:179], v[192:195], v[92:95]
	v_mfma_f32_16x16x32_bf16 v[84:87], v[164:167], v[196:199], v[84:87]
	v_mfma_f32_16x16x32_bf16 v[84:87], v[168:171], v[200:203], v[84:87]
	v_mfma_f32_16x16x32_bf16 v[76:79], v[172:175], v[196:199], v[76:79]
	v_mfma_f32_16x16x32_bf16 v[76:79], v[176:179], v[200:203], v[76:79]
	v_mfma_f32_16x16x32_bf16 v[68:71], v[164:167], v[204:207], v[68:71]
	v_mfma_f32_16x16x32_bf16 v[68:71], v[168:171], v[208:211], v[68:71]
	v_mfma_f32_16x16x32_bf16 v[64:67], v[172:175], v[204:207], v[64:67]
	v_mfma_f32_16x16x32_bf16 v[64:67], v[176:179], v[208:211], v[64:67]
	s_barrier
; #define PG8_STAGE(bufoff, gbase, voff) do { _Pragma("unroll") for (int _i = 0; _i < 2; ++_i) \
;         __builtin_amdgcn_global_load_lds((const unsigned*)((const char*)(gbase) + (voff)[_i]), (LAS unsigned*)(lds + (bufoff) + ldsw + _i * 8192), 16, 0, 0); } while (0)
; #define PG8_LDA(dst, b, h) do { _Pragma("unroll") for (int m = 0; m < 4; ++m) _Pragma("unroll") for (int k = 0; k < 2; ++k) dst[m][k] = *(const LAS bf16x8*)(lds + PG8_SA(b, h) + aoff + m * 2048 + k * 1024); } while (0)
; #define PG8_MMA(ai, bj, At, Bt) do { __builtin_amdgcn_s_setprio(1); _Pragma("unroll") for (int m = 0; m < 4; ++m) _Pragma("unroll") for (int n = 0; n < 2; ++n) _Pragma("unroll") for (int k = 0; k < 2; ++k) \
;         acc[ai][bj][m][n] = __builtin_amdgcn_mfma_f32_16x16x32_bf16(Bt[n][k], At[m][k], acc[ai][bj][m][n], 0, 0, 0); __builtin_amdgcn_s_setprio(0); } while (0)
; #define PG8_WAIT_V(n) asm volatile("s_waitcnt vmcnt(" #n ")" ::: "memory")
; #define PG8_WAIT_L(n) asm volatile("s_waitcnt lgkmcnt(" #n ")" ::: "memory")
; #define PG8_BAR __builtin_amdgcn_s_barrier()
; #define PG8_SCHED __builtin_amdgcn_sched_barrier(0)
; template <class Epi>
; __device__ __forceinline__ void gemm_phase(LAS unsigned char* lds, const Gemm g, const Order& S, const Epi& E, const int wid) {
;     ...
;             PG8_LDA(At, 1, 1); PG8_STAGE(PG8_SB(1, 0), b3, voffB); PG8_STAGE(PG8_SB(1, 1), b3 + hB, voffB); PG8_STAGE(PG8_SA(1, 0), a3, voffA);
;             PG8_WAIT_V(8); PG8_WAIT_L(0); PG8_BAR; PG8_MMA(1, 0, At, B0); PG8_MMA(1, 1, At, B1); PG8_BAR; PG8_SCHED;
	s_add_i32 s12, s76, s0
	v_lshl_add_u64 v[212:213], v[212:213], 0, s[44:45]
	s_mov_b32 m0, s12
	ds_read_b128 v[180:183], v143 offset:49152
	ds_read_b128 v[184:187], v143 offset:50176
	ds_read_b128 v[188:191], v143 offset:51200
	ds_read_b128 v[192:195], v143 offset:52224
	ds_read_b128 v[196:199], v143 offset:53248
	ds_read_b128 v[200:203], v143 offset:54272
	ds_read_b128 v[204:207], v143 offset:55296
	ds_read_b128 v[208:211], v143 offset:56320
	global_load_lds_dwordx4 v[212:213], off
	s_add_i32 m0, s12, 0x2000
	s_add_u32 s10, s10, 0x40080
	v_lshl_add_u64 v[212:213], v[214:215], 0, s[44:45]
	s_addc_u32 s11, s11, 0
	s_add_i32 s12, s77, s0
	global_load_lds_dwordx4 v[212:213], off
	v_lshl_add_u64 v[212:213], s[10:11], 0, v[134:135]
	s_mov_b32 m0, s12
	s_nop 0
	global_load_lds_dwordx4 v[212:213], off
	v_lshl_add_u64 v[212:213], s[10:11], 0, v[136:137]
	s_add_i32 m0, s12, 0x2000
	s_nop 0
	global_load_lds_dwordx4 v[212:213], off
	v_lshl_add_u64 v[212:213], v[216:217], 0, s[44:45]
	s_mov_b32 m0, s63
	s_nop 0
	global_load_lds_dwordx4 v[212:213], off
	v_lshl_add_u64 v[212:213], v[218:219], 0, s[44:45]
	s_mov_b32 m0, s64
	s_nop 0
	global_load_lds_dwordx4 v[212:213], off
	s_waitcnt vmcnt(8)
	s_waitcnt lgkmcnt(0)
	s_barrier
	s_waitcnt lgkmcnt(0)
	v_mfma_f32_16x16x32_bf16 v[60:63], v[144:147], v[180:183], v[60:63]
	v_mfma_f32_16x16x32_bf16 v[60:63], v[152:155], v[184:187], v[60:63]
	v_mfma_f32_16x16x32_bf16 v[56:59], v[156:159], v[180:183], v[56:59]
	v_mfma_f32_16x16x32_bf16 v[56:59], v[160:163], v[184:187], v[56:59]
	v_mfma_f32_16x16x32_bf16 v[48:51], v[144:147], v[188:191], v[48:51]
	v_mfma_f32_16x16x32_bf16 v[48:51], v[152:155], v[192:195], v[48:51]
	v_mfma_f32_16x16x32_bf16 v[40:43], v[156:159], v[188:191], v[40:43]
	v_mfma_f32_16x16x32_bf16 v[40:43], v[160:163], v[192:195], v[40:43]
	v_mfma_f32_16x16x32_bf16 v[32:35], v[144:147], v[196:199], v[32:35]
	v_mfma_f32_16x16x32_bf16 v[32:35], v[152:155], v[200:203], v[32:35]
	v_mfma_f32_16x16x32_bf16 v[24:27], v[156:159], v[196:199], v[24:27]
	v_mfma_f32_16x16x32_bf16 v[24:27], v[160:163], v[200:203], v[24:27]
	v_mfma_f32_16x16x32_bf16 v[16:19], v[144:147], v[204:207], v[16:19]
	v_mfma_f32_16x16x32_bf16 v[16:19], v[152:155], v[208:211], v[16:19]
	v_mfma_f32_16x16x32_bf16 v[8:11], v[156:159], v[204:207], v[8:11]
	v_mfma_f32_16x16x32_bf16 v[8:11], v[160:163], v[208:211], v[8:11]
	v_mfma_f32_16x16x32_bf16 v[52:55], v[164:167], v[180:183], v[52:55]
	v_mfma_f32_16x16x32_bf16 v[52:55], v[168:171], v[184:187], v[52:55]
	v_mfma_f32_16x16x32_bf16 v[44:47], v[172:175], v[180:183], v[44:47]
	v_mfma_f32_16x16x32_bf16 v[44:47], v[176:179], v[184:187], v[44:47]
	v_mfma_f32_16x16x32_bf16 v[36:39], v[164:167], v[188:191], v[36:39]
	v_mfma_f32_16x16x32_bf16 v[36:39], v[168:171], v[192:195], v[36:39]
	v_mfma_f32_16x16x32_bf16 v[28:31], v[172:175], v[188:191], v[28:31]
	v_mfma_f32_16x16x32_bf16 v[28:31], v[176:179], v[192:195], v[28:31]
	v_mfma_f32_16x16x32_bf16 v[20:23], v[164:167], v[196:199], v[20:23]
	v_mfma_f32_16x16x32_bf16 v[20:23], v[168:171], v[200:203], v[20:23]
	v_mfma_f32_16x16x32_bf16 v[12:15], v[172:175], v[196:199], v[12:15]
	v_mfma_f32_16x16x32_bf16 v[12:15], v[176:179], v[200:203], v[12:15]
	v_mfma_f32_16x16x32_bf16 v[4:7], v[164:167], v[204:207], v[4:7]
	v_mfma_f32_16x16x32_bf16 v[4:7], v[168:171], v[208:211], v[4:7]
	v_mfma_f32_16x16x32_bf16 v[0:3], v[172:175], v[204:207], v[0:3]
	v_mfma_f32_16x16x32_bf16 v[0:3], v[176:179], v[208:211], v[0:3]
	s_barrier
	s_add_i32 s75, s75, 2
	s_add_u32 s8, s8, 0x100
	s_addc_u32 s9, s9, 0
	s_add_u32 s73, s73, 0x100
	s_addc_u32 s74, s74, 0
	s_cmp_gt_u32 s75, 13
	s_cbranch_scc0 .LBB0_344
	s_and_b64 vcc, exec, s[94:95]
	s_cbranch_vccz .LBB0_347
	s_barrier

; #define PG8_STAGE(bufoff, gbase, voff) do { _Pragma("unroll") for (int _i = 0; _i < 2; ++_i) \
;         __builtin_amdgcn_global_load_lds((const unsigned*)((const char*)(gbase) + (voff)[_i]), (LAS unsigned*)(lds + (bufoff) + ldsw + _i * 8192), 16, 0, 0); } while (0)
; #define PG8_LDA(dst, b, h) do { _Pragma("unroll") for (int m = 0; m < 4; ++m) _Pragma("unroll") for (int k = 0; k < 2; ++k) dst[m][k] = *(const LAS bf16x8*)(lds + PG8_SA(b, h) + aoff + m * 2048 + k * 1024); } while (0)
; #define PG8_LDB(dst, b, h) do { _Pragma("unroll") for (int n = 0; n < 2; ++n) _Pragma("unroll") for (int k = 0; k < 2; ++k) dst[n][k] = *(const LAS bf16x8*)(lds + PG8_SB(b, h) + boff + n * 2048 + k * 1024); } while (0)
; #define PG8_MMA(ai, bj, At, Bt) do { __builtin_amdgcn_s_setprio(1); _Pragma("unroll") for (int m = 0; m < 4; ++m) _Pragma("unroll") for (int n = 0; n < 2; ++n) _Pragma("unroll") for (int k = 0; k < 2; ++k) \
;         acc[ai][bj][m][n] = __builtin_amdgcn_mfma_f32_16x16x32_bf16(Bt[n][k], At[m][k], acc[ai][bj][m][n], 0, 0, 0); __builtin_amdgcn_s_setprio(0); } while (0)
; #define PG8_WAIT_V(n) asm volatile("s_waitcnt vmcnt(" #n ")" ::: "memory")
; #define PG8_WAIT_L(n) asm volatile("s_waitcnt lgkmcnt(" #n ")" ::: "memory")
; #define PG8_BAR __builtin_amdgcn_s_barrier()
; #define PG8_SCHED __builtin_amdgcn_sched_barrier(0)
; template <class Epi>
; __device__ __forceinline__ void gemm_phase(LAS unsigned char* lds, const Gemm g, const Order& S, const Epi& E, const int wid) {
;     ...
;             PG8_LDB(B0, 0, 0); PG8_LDB(B1, 0, 1); PG8_SCHED; PG8_LDA(At, 0, 0); PG8_STAGE(PG8_SA(1, 1), a1 + hA, voffA);
;             PG8_WAIT_V(8); PG8_WAIT_L(0); PG8_BAR; PG8_MMA(0, 0, At, B0); PG8_MMA(0, 1, At, B1); PG8_BAR; PG8_SCHED;
;             PG8_LDA(At, 0, 1); PG8_STAGE(PG8_SB(0, 0), b2, voffB); PG8_STAGE(PG8_SB(0, 1), b2 + hB, voffB); PG8_STAGE(PG8_SA(0, 0), a2, voffA);
.LBB0_379:
	ds_read_b128 v[146:149], v141
	ds_read_b128 v[150:153], v141 offset:1024
	ds_read_b128 v[154:157], v141 offset:2048
	ds_read_b128 v[158:161], v141 offset:3072
	ds_read_b128 v[162:165], v144
	ds_read_b128 v[166:169], v144 offset:1024
	ds_read_b128 v[170:173], v144 offset:2048
	ds_read_b128 v[174:177], v144 offset:3072
	s_add_u32 s44, s42, 0xfffe0080
	s_addc_u32 s45, s43, -1
	s_cmp_eq_u32 s63, 4
	s_cselect_b32 s47, s13, s45
	s_cselect_b32 s46, s59, s44
	s_cselect_b32 s45, s21, s62
	s_cselect_b32 s44, s60, s61
	v_lshl_add_u64 v[210:211], s[42:43], 0, v[128:129]
	s_add_i32 m0, s22, 0xc000
	ds_read_b128 v[178:181], v145
	ds_read_b128 v[182:185], v145 offset:1024
	ds_read_b128 v[186:189], v145 offset:2048
	ds_read_b128 v[190:193], v145 offset:3072
	ds_read_b128 v[194:197], v145 offset:4096
	ds_read_b128 v[198:201], v145 offset:5120
	ds_read_b128 v[202:205], v145 offset:6144
	ds_read_b128 v[206:209], v145 offset:7168
	global_load_lds_dwordx4 v[210:211], off
	v_lshl_add_u64 v[210:211], s[42:43], 0, v[138:139]
	s_add_i32 m0, s22, 0xe000
	s_nop 0
	global_load_lds_dwordx4 v[210:211], off
	s_waitcnt vmcnt(8)
	s_waitcnt lgkmcnt(0)
	s_barrier
	s_waitcnt lgkmcnt(0)
	v_mfma_f32_16x16x32_bf16 v[124:127], v[146:149], v[178:181], v[124:127]
	v_mfma_f32_16x16x32_bf16 v[124:127], v[150:153], v[182:185], v[124:127]
	v_mfma_f32_16x16x32_bf16 v[120:123], v[154:157], v[178:181], v[120:123]
	v_mfma_f32_16x16x32_bf16 v[120:123], v[158:161], v[182:185], v[120:123]
	v_mfma_f32_16x16x32_bf16 v[108:111], v[146:149], v[186:189], v[108:111]
	v_mfma_f32_16x16x32_bf16 v[108:111], v[150:153], v[190:193], v[108:111]
	v_mfma_f32_16x16x32_bf16 v[104:107], v[154:157], v[186:189], v[104:107]
	v_mfma_f32_16x16x32_bf16 v[104:107], v[158:161], v[190:193], v[104:107]
	v_mfma_f32_16x16x32_bf16 v[92:95], v[146:149], v[194:197], v[92:95]
	v_mfma_f32_16x16x32_bf16 v[92:95], v[150:153], v[198:201], v[92:95]
	v_mfma_f32_16x16x32_bf16 v[88:91], v[154:157], v[194:197], v[88:91]
	v_mfma_f32_16x16x32_bf16 v[88:91], v[158:161], v[198:201], v[88:91]
	v_mfma_f32_16x16x32_bf16 v[76:79], v[146:149], v[202:205], v[76:79]
	v_mfma_f32_16x16x32_bf16 v[76:79], v[150:153], v[206:209], v[76:79]
	v_mfma_f32_16x16x32_bf16 v[72:75], v[154:157], v[202:205], v[72:75]
	v_mfma_f32_16x16x32_bf16 v[72:75], v[158:161], v[206:209], v[72:75]
	v_mfma_f32_16x16x32_bf16 v[116:119], v[162:165], v[178:181], v[116:119]
	v_mfma_f32_16x16x32_bf16 v[116:119], v[166:169], v[182:185], v[116:119]
	v_mfma_f32_16x16x32_bf16 v[112:115], v[170:173], v[178:181], v[112:115]
	v_mfma_f32_16x16x32_bf16 v[112:115], v[174:177], v[182:185], v[112:115]
	v_mfma_f32_16x16x32_bf16 v[100:103], v[162:165], v[186:189], v[100:103]
	v_mfma_f32_16x16x32_bf16 v[100:103], v[166:169], v[190:193], v[100:103]
	v_mfma_f32_16x16x32_bf16 v[96:99], v[170:173], v[186:189], v[96:99]
	v_mfma_f32_16x16x32_bf16 v[96:99], v[174:177], v[190:193], v[96:99]
	v_mfma_f32_16x16x32_bf16 v[84:87], v[162:165], v[194:197], v[84:87]
	v_mfma_f32_16x16x32_bf16 v[84:87], v[166:169], v[198:201], v[84:87]
	v_mfma_f32_16x16x32_bf16 v[80:83], v[170:173], v[194:197], v[80:83]
	v_mfma_f32_16x16x32_bf16 v[80:83], v[174:177], v[198:201], v[80:83]
	v_mfma_f32_16x16x32_bf16 v[68:71], v[162:165], v[202:205], v[68:71]
	v_mfma_f32_16x16x32_bf16 v[68:71], v[166:169], v[206:209], v[68:71]
	v_mfma_f32_16x16x32_bf16 v[64:67], v[170:173], v[202:205], v[64:67]
	v_mfma_f32_16x16x32_bf16 v[64:67], v[174:177], v[206:209], v[64:67]
	s_barrier
	s_add_i32 s64, s56, s0
	v_lshl_add_u64 v[210:211], s[44:45], 0, v[134:135]
	s_mov_b32 m0, s64
	ds_read_b128 v[178:181], v145 offset:16384
	ds_read_b128 v[182:185], v145 offset:17408
	ds_read_b128 v[186:189], v145 offset:18432
	ds_read_b128 v[190:193], v145 offset:19456
	ds_read_b128 v[194:197], v145 offset:20480
	ds_read_b128 v[198:201], v145 offset:21504
	ds_read_b128 v[202:205], v145 offset:22528
	ds_read_b128 v[206:209], v145 offset:23552
	global_load_lds_dwordx4 v[210:211], off
	s_add_i32 m0, s64, 0x2000
	s_add_u32 s64, s44, 0x20000
	v_lshl_add_u64 v[212:213], s[44:45], 0, v[136:137]
	s_addc_u32 s65, s45, 0
	s_add_i32 s66, s57, s0
	global_load_lds_dwordx4 v[212:213], off
	v_lshl_add_u64 v[214:215], s[64:65], 0, v[134:135]
	s_mov_b32 m0, s66
	v_lshl_add_u64 v[216:217], s[46:47], 0, v[138:139]
	global_load_lds_dwordx4 v[214:215], off
	v_lshl_add_u64 v[214:215], s[64:65], 0, v[136:137]
	s_add_i32 m0, s66, 0x2000
	s_nop 0
	global_load_lds_dwordx4 v[214:215], off
	v_lshl_add_u64 v[214:215], s[46:47], 0, v[128:129]
	s_mov_b32 m0, s22
	s_nop 0
	global_load_lds_dwordx4 v[214:215], off
	s_mov_b32 m0, s23
	s_nop 0
	global_load_lds_dwordx4 v[216:217], off
	s_waitcnt vmcnt(8)
	s_waitcnt lgkmcnt(0)
	s_barrier
; #define PG8_STAGE(bufoff, gbase, voff) do { _Pragma("unroll") for (int _i = 0; _i < 2; ++_i) \
;         __builtin_amdgcn_global_load_lds((const unsigned*)((const char*)(gbase) + (voff)[_i]), (LAS unsigned*)(lds + (bufoff) + ldsw + _i * 8192), 16, 0, 0); } while (0)
; #define PG8_LDA(dst, b, h) do { _Pragma("unroll") for (int m = 0; m < 4; ++m) _Pragma("unroll") for (int k = 0; k < 2; ++k) dst[m][k] = *(const LAS bf16x8*)(lds + PG8_SA(b, h) + aoff + m * 2048 + k * 1024); } while (0)
; #define PG8_LDB(dst, b, h) do { _Pragma("unroll") for (int n = 0; n < 2; ++n) _Pragma("unroll") for (int k = 0; k < 2; ++k) dst[n][k] = *(const LAS bf16x8*)(lds + PG8_SB(b, h) + boff + n * 2048 + k * 1024); } while (0)
; #define PG8_MMA(ai, bj, At, Bt) do { __builtin_amdgcn_s_setprio(1); _Pragma("unroll") for (int m = 0; m < 4; ++m) _Pragma("unroll") for (int n = 0; n < 2; ++n) _Pragma("unroll") for (int k = 0; k < 2; ++k) \
;         acc[ai][bj][m][n] = __builtin_amdgcn_mfma_f32_16x16x32_bf16(Bt[n][k], At[m][k], acc[ai][bj][m][n], 0, 0, 0); __builtin_amdgcn_s_setprio(0); } while (0)
; #define PG8_WAIT_V(n) asm volatile("s_waitcnt vmcnt(" #n ")" ::: "memory")
; #define PG8_WAIT_L(n) asm volatile("s_waitcnt lgkmcnt(" #n ")" ::: "memory")
; #define PG8_BAR __builtin_amdgcn_s_barrier()
; #define PG8_SCHED __builtin_amdgcn_sched_barrier(0)
; template <class Epi>
; __device__ __forceinline__ void gemm_phase(LAS unsigned char* lds, const Gemm g, const Order& S, const Epi& E, const int wid) {
;     ...
;             PG8_LDA(At, 0, 1); PG8_STAGE(PG8_SB(0, 0), b2, voffB); PG8_STAGE(PG8_SB(0, 1), b2 + hB, voffB); PG8_STAGE(PG8_SA(0, 0), a2, voffA);
;             PG8_WAIT_V(8); PG8_WAIT_L(0); PG8_BAR; PG8_MMA(1, 0, At, B0); PG8_MMA(1, 1, At, B1); PG8_BAR; PG8_SCHED;
;             PG8_LDB(B0, 1, 0); PG8_LDB(B1, 1, 1); PG8_SCHED; PG8_LDA(At, 1, 0); PG8_STAGE(PG8_SA(0, 1), a2 + hA, voffA);
;             PG8_WAIT_V(8); PG8_WAIT_L(0); PG8_BAR; PG8_MMA(0, 0, At, B0); PG8_MMA(0, 1, At, B1); PG8_BAR; PG8_SCHED;
	s_waitcnt lgkmcnt(0)
	v_mfma_f32_16x16x32_bf16 v[60:63], v[146:149], v[178:181], v[60:63]
	v_mfma_f32_16x16x32_bf16 v[60:63], v[150:153], v[182:185], v[60:63]
	v_mfma_f32_16x16x32_bf16 v[56:59], v[154:157], v[178:181], v[56:59]
	v_mfma_f32_16x16x32_bf16 v[56:59], v[158:161], v[182:185], v[56:59]
	v_mfma_f32_16x16x32_bf16 v[44:47], v[146:149], v[186:189], v[44:47]
	v_mfma_f32_16x16x32_bf16 v[44:47], v[150:153], v[190:193], v[44:47]
	v_mfma_f32_16x16x32_bf16 v[40:43], v[154:157], v[186:189], v[40:43]
	v_mfma_f32_16x16x32_bf16 v[40:43], v[158:161], v[190:193], v[40:43]
	v_mfma_f32_16x16x32_bf16 v[28:31], v[146:149], v[194:197], v[28:31]
	v_mfma_f32_16x16x32_bf16 v[28:31], v[150:153], v[198:201], v[28:31]
	v_mfma_f32_16x16x32_bf16 v[24:27], v[154:157], v[194:197], v[24:27]
	v_mfma_f32_16x16x32_bf16 v[24:27], v[158:161], v[198:201], v[24:27]
	v_mfma_f32_16x16x32_bf16 v[12:15], v[146:149], v[202:205], v[12:15]
	v_mfma_f32_16x16x32_bf16 v[12:15], v[150:153], v[206:209], v[12:15]
	v_mfma_f32_16x16x32_bf16 v[8:11], v[154:157], v[202:205], v[8:11]
	v_mfma_f32_16x16x32_bf16 v[8:11], v[158:161], v[206:209], v[8:11]
	v_mfma_f32_16x16x32_bf16 v[52:55], v[162:165], v[178:181], v[52:55]
	v_mfma_f32_16x16x32_bf16 v[52:55], v[166:169], v[182:185], v[52:55]
	v_mfma_f32_16x16x32_bf16 v[48:51], v[170:173], v[178:181], v[48:51]
	v_mfma_f32_16x16x32_bf16 v[48:51], v[174:177], v[182:185], v[48:51]
	v_mfma_f32_16x16x32_bf16 v[36:39], v[162:165], v[186:189], v[36:39]
	v_mfma_f32_16x16x32_bf16 v[36:39], v[166:169], v[190:193], v[36:39]
	v_mfma_f32_16x16x32_bf16 v[32:35], v[170:173], v[186:189], v[32:35]
	v_mfma_f32_16x16x32_bf16 v[32:35], v[174:177], v[190:193], v[32:35]
	v_mfma_f32_16x16x32_bf16 v[20:23], v[162:165], v[194:197], v[20:23]
	v_mfma_f32_16x16x32_bf16 v[20:23], v[166:169], v[198:201], v[20:23]
	v_mfma_f32_16x16x32_bf16 v[16:19], v[170:173], v[194:197], v[16:19]
	v_mfma_f32_16x16x32_bf16 v[16:19], v[174:177], v[198:201], v[16:19]
	v_mfma_f32_16x16x32_bf16 v[4:7], v[162:165], v[202:205], v[4:7]
	v_mfma_f32_16x16x32_bf16 v[4:7], v[166:169], v[206:209], v[4:7]
	v_mfma_f32_16x16x32_bf16 v[0:3], v[170:173], v[202:205], v[0:3]
	v_mfma_f32_16x16x32_bf16 v[0:3], v[174:177], v[206:209], v[0:3]
	s_barrier
	s_add_i32 s64, 0, 0x18000
	s_add_i32 s65, 0, 0x1c000
	v_add_u32_e32 v158, s64, v140
	v_add_u32_e32 v174, s65, v140
	ds_read_b128 v[146:149], v158
	ds_read_b128 v[150:153], v158 offset:1024
	ds_read_b128 v[154:157], v158 offset:2048
	ds_read_b128 v[158:161], v158 offset:3072
	ds_read_b128 v[162:165], v174
	ds_read_b128 v[166:169], v174 offset:1024
	ds_read_b128 v[170:173], v174 offset:2048
	ds_read_b128 v[174:177], v174 offset:3072
	s_add_u32 s46, s46, 0x20000
	s_addc_u32 s47, s47, 0
	s_mov_b32 m0, s29
	v_lshl_add_u64 v[218:219], s[46:47], 0, v[128:129]
	ds_read_b128 v[178:181], v145 offset:32768
	ds_read_b128 v[182:185], v145 offset:33792
	ds_read_b128 v[186:189], v145 offset:34816
	ds_read_b128 v[190:193], v145 offset:35840
	ds_read_b128 v[194:197], v145 offset:36864
	ds_read_b128 v[198:201], v145 offset:37888
	ds_read_b128 v[202:205], v145 offset:38912
	ds_read_b128 v[206:209], v145 offset:39936
	global_load_lds_dwordx4 v[218:219], off
	v_lshl_add_u64 v[218:219], s[46:47], 0, v[138:139]
	s_mov_b32 m0, s30
	s_nop 0
	global_load_lds_dwordx4 v[218:219], off
	s_waitcnt vmcnt(8)
	s_waitcnt lgkmcnt(0)
	s_barrier
	s_waitcnt lgkmcnt(0)
	v_mfma_f32_16x16x32_bf16 v[124:127], v[146:149], v[178:181], v[124:127]
	v_mfma_f32_16x16x32_bf16 v[124:127], v[150:153], v[182:185], v[124:127]
	v_mfma_f32_16x16x32_bf16 v[120:123], v[154:157], v[178:181], v[120:123]
	v_mfma_f32_16x16x32_bf16 v[120:123], v[158:161], v[182:185], v[120:123]
	v_mfma_f32_16x16x32_bf16 v[108:111], v[146:149], v[186:189], v[108:111]
	v_mfma_f32_16x16x32_bf16 v[108:111], v[150:153], v[190:193], v[108:111]
	v_mfma_f32_16x16x32_bf16 v[104:107], v[154:157], v[186:189], v[104:107]
	v_mfma_f32_16x16x32_bf16 v[104:107], v[158:161], v[190:193], v[104:107]
	v_mfma_f32_16x16x32_bf16 v[92:95], v[146:149], v[194:197], v[92:95]
	v_mfma_f32_16x16x32_bf16 v[92:95], v[150:153], v[198:201], v[92:95]
	v_mfma_f32_16x16x32_bf16 v[88:91], v[154:157], v[194:197], v[88:91]
	v_mfma_f32_16x16x32_bf16 v[88:91], v[158:161], v[198:201], v[88:91]
	v_mfma_f32_16x16x32_bf16 v[76:79], v[146:149], v[202:205], v[76:79]
	v_mfma_f32_16x16x32_bf16 v[76:79], v[150:153], v[206:209], v[76:79]
	v_mfma_f32_16x16x32_bf16 v[72:75], v[154:157], v[202:205], v[72:75]
	v_mfma_f32_16x16x32_bf16 v[72:75], v[158:161], v[206:209], v[72:75]
	v_mfma_f32_16x16x32_bf16 v[116:119], v[162:165], v[178:181], v[116:119]
	v_mfma_f32_16x16x32_bf16 v[116:119], v[166:169], v[182:185], v[116:119]
	v_mfma_f32_16x16x32_bf16 v[112:115], v[170:173], v[178:181], v[112:115]
	v_mfma_f32_16x16x32_bf16 v[112:115], v[174:177], v[182:185], v[112:115]
	v_mfma_f32_16x16x32_bf16 v[100:103], v[162:165], v[186:189], v[100:103]
	v_mfma_f32_16x16x32_bf16 v[100:103], v[166:169], v[190:193], v[100:103]
	v_mfma_f32_16x16x32_bf16 v[96:99], v[170:173], v[186:189], v[96:99]
	v_mfma_f32_16x16x32_bf16 v[96:99], v[174:177], v[190:193], v[96:99]
	v_mfma_f32_16x16x32_bf16 v[84:87], v[162:165], v[194:197], v[84:87]
	v_mfma_f32_16x16x32_bf16 v[84:87], v[166:169], v[198:201], v[84:87]
	v_mfma_f32_16x16x32_bf16 v[80:83], v[170:173], v[194:197], v[80:83]
	v_mfma_f32_16x16x32_bf16 v[80:83], v[174:177], v[198:201], v[80:83]
	v_mfma_f32_16x16x32_bf16 v[68:71], v[162:165], v[202:205], v[68:71]
	v_mfma_f32_16x16x32_bf16 v[68:71], v[166:169], v[206:209], v[68:71]
	v_mfma_f32_16x16x32_bf16 v[64:67], v[170:173], v[202:205], v[64:67]
	v_mfma_f32_16x16x32_bf16 v[64:67], v[174:177], v[206:209], v[64:67]
	s_barrier
; #define PG8_STAGE(bufoff, gbase, voff) do { _Pragma("unroll") for (int _i = 0; _i < 2; ++_i) \
;         __builtin_amdgcn_global_load_lds((const unsigned*)((const char*)(gbase) + (voff)[_i]), (LAS unsigned*)(lds + (bufoff) + ldsw + _i * 8192), 16, 0, 0); } while (0)
; #define PG8_LDA(dst, b, h) do { _Pragma("unroll") for (int m = 0; m < 4; ++m) _Pragma("unroll") for (int k = 0; k < 2; ++k) dst[m][k] = *(const LAS bf16x8*)(lds + PG8_SA(b, h) + aoff + m * 2048 + k * 1024); } while (0)
; #define PG8_MMA(ai, bj, At, Bt) do { __builtin_amdgcn_s_setprio(1); _Pragma("unroll") for (int m = 0; m < 4; ++m) _Pragma("unroll") for (int n = 0; n < 2; ++n) _Pragma("unroll") for (int k = 0; k < 2; ++k) \
;         acc[ai][bj][m][n] = __builtin_amdgcn_mfma_f32_16x16x32_bf16(Bt[n][k], At[m][k], acc[ai][bj][m][n], 0, 0, 0); __builtin_amdgcn_s_setprio(0); } while (0)
; #define PG8_WAIT_V(n) asm volatile("s_waitcnt vmcnt(" #n ")" ::: "memory")
; #define PG8_WAIT_L(n) asm volatile("s_waitcnt lgkmcnt(" #n ")" ::: "memory")
; #define PG8_BAR __builtin_amdgcn_s_barrier()
; #define PG8_SCHED __builtin_amdgcn_sched_barrier(0)
; template <class Epi>
; __device__ __forceinline__ void gemm_phase(LAS unsigned char* lds, const Gemm g, const Order& S, const Epi& E, const int wid) {
;     ...
;             PG8_LDA(At, 1, 1); PG8_STAGE(PG8_SB(1, 0), b3, voffB); PG8_STAGE(PG8_SB(1, 1), b3 + hB, voffB); PG8_STAGE(PG8_SA(1, 0), a3, voffA);
;             PG8_WAIT_V(8); PG8_WAIT_L(0); PG8_BAR; PG8_MMA(1, 0, At, B0); PG8_MMA(1, 1, At, B1); PG8_BAR; PG8_SCHED;
	s_add_i32 s46, s64, s0
	v_lshl_add_u64 v[210:211], v[210:211], 0, s[10:11]
	s_mov_b32 m0, s46
	ds_read_b128 v[178:181], v145 offset:49152
	ds_read_b128 v[182:185], v145 offset:50176
	ds_read_b128 v[186:189], v145 offset:51200
	ds_read_b128 v[190:193], v145 offset:52224
	ds_read_b128 v[194:197], v145 offset:53248
	ds_read_b128 v[198:201], v145 offset:54272
	ds_read_b128 v[202:205], v145 offset:55296
	ds_read_b128 v[206:209], v145 offset:56320
	global_load_lds_dwordx4 v[210:211], off
	s_add_i32 m0, s46, 0x2000
	s_add_u32 s44, s44, 0x20080
	v_lshl_add_u64 v[210:211], v[212:213], 0, s[10:11]
	s_addc_u32 s45, s45, 0
	s_add_i32 s46, s65, s0
	global_load_lds_dwordx4 v[210:211], off
	v_lshl_add_u64 v[210:211], s[44:45], 0, v[134:135]
	s_mov_b32 m0, s46
	s_nop 0
	global_load_lds_dwordx4 v[210:211], off
	v_lshl_add_u64 v[210:211], s[44:45], 0, v[136:137]
	s_add_i32 m0, s46, 0x2000
	s_nop 0
	global_load_lds_dwordx4 v[210:211], off
	v_lshl_add_u64 v[210:211], v[214:215], 0, s[10:11]
	s_mov_b32 m0, s51
	s_nop 0
	global_load_lds_dwordx4 v[210:211], off
	v_lshl_add_u64 v[210:211], v[216:217], 0, s[10:11]
	s_mov_b32 m0, s54
	s_nop 0
	global_load_lds_dwordx4 v[210:211], off
	s_waitcnt vmcnt(8)
	s_waitcnt lgkmcnt(0)
	s_barrier
	s_waitcnt lgkmcnt(0)
	v_mfma_f32_16x16x32_bf16 v[60:63], v[146:149], v[178:181], v[60:63]
	v_mfma_f32_16x16x32_bf16 v[60:63], v[150:153], v[182:185], v[60:63]
	v_mfma_f32_16x16x32_bf16 v[56:59], v[154:157], v[178:181], v[56:59]
	v_mfma_f32_16x16x32_bf16 v[56:59], v[158:161], v[182:185], v[56:59]
	v_mfma_f32_16x16x32_bf16 v[44:47], v[146:149], v[186:189], v[44:47]
	v_mfma_f32_16x16x32_bf16 v[44:47], v[150:153], v[190:193], v[44:47]
	v_mfma_f32_16x16x32_bf16 v[40:43], v[154:157], v[186:189], v[40:43]
	v_mfma_f32_16x16x32_bf16 v[40:43], v[158:161], v[190:193], v[40:43]
	v_mfma_f32_16x16x32_bf16 v[28:31], v[146:149], v[194:197], v[28:31]
	v_mfma_f32_16x16x32_bf16 v[28:31], v[150:153], v[198:201], v[28:31]
	v_mfma_f32_16x16x32_bf16 v[24:27], v[154:157], v[194:197], v[24:27]
	v_mfma_f32_16x16x32_bf16 v[24:27], v[158:161], v[198:201], v[24:27]
	v_mfma_f32_16x16x32_bf16 v[12:15], v[146:149], v[202:205], v[12:15]
	v_mfma_f32_16x16x32_bf16 v[12:15], v[150:153], v[206:209], v[12:15]
	v_mfma_f32_16x16x32_bf16 v[8:11], v[154:157], v[202:205], v[8:11]
	v_mfma_f32_16x16x32_bf16 v[8:11], v[158:161], v[206:209], v[8:11]
	v_mfma_f32_16x16x32_bf16 v[52:55], v[162:165], v[178:181], v[52:55]
	v_mfma_f32_16x16x32_bf16 v[52:55], v[166:169], v[182:185], v[52:55]
	v_mfma_f32_16x16x32_bf16 v[48:51], v[170:173], v[178:181], v[48:51]
	v_mfma_f32_16x16x32_bf16 v[48:51], v[174:177], v[182:185], v[48:51]
	v_mfma_f32_16x16x32_bf16 v[36:39], v[162:165], v[186:189], v[36:39]
	v_mfma_f32_16x16x32_bf16 v[36:39], v[166:169], v[190:193], v[36:39]
	v_mfma_f32_16x16x32_bf16 v[32:35], v[170:173], v[186:189], v[32:35]
	v_mfma_f32_16x16x32_bf16 v[32:35], v[174:177], v[190:193], v[32:35]
	v_mfma_f32_16x16x32_bf16 v[20:23], v[162:165], v[194:197], v[20:23]
	v_mfma_f32_16x16x32_bf16 v[20:23], v[166:169], v[198:201], v[20:23]
	v_mfma_f32_16x16x32_bf16 v[16:19], v[170:173], v[194:197], v[16:19]
	v_mfma_f32_16x16x32_bf16 v[16:19], v[174:177], v[198:201], v[16:19]
	v_mfma_f32_16x16x32_bf16 v[4:7], v[162:165], v[202:205], v[4:7]
	v_mfma_f32_16x16x32_bf16 v[4:7], v[166:169], v[206:209], v[4:7]
	v_mfma_f32_16x16x32_bf16 v[0:3], v[170:173], v[202:205], v[0:3]
	v_mfma_f32_16x16x32_bf16 v[0:3], v[174:177], v[206:209], v[0:3]
	s_barrier
	s_add_i32 s63, s63, 2
	s_add_u32 s42, s42, 0x100
	s_addc_u32 s43, s43, 0
	s_add_u32 s61, s61, 0x100
	s_addc_u32 s62, s62, 0
	s_cmp_gt_u32 s63, 5
	s_cbranch_scc0 .LBB0_379
	s_and_b64 vcc, exec, s[94:95]
	s_cbranch_vccz .LBB0_382
	s_barrier

; #define PG8_STAGE(bufoff, gbase, voff) do { _Pragma("unroll") for (int _i = 0; _i < 2; ++_i) \
;         __builtin_amdgcn_global_load_lds((const unsigned*)((const char*)(gbase) + (voff)[_i]), (LAS unsigned*)(lds + (bufoff) + ldsw + _i * 8192), 16, 0, 0); } while (0)
; #define PG8_LDA(dst, b, h) do { _Pragma("unroll") for (int m = 0; m < 4; ++m) _Pragma("unroll") for (int k = 0; k < 2; ++k) dst[m][k] = *(const LAS bf16x8*)(lds + PG8_SA(b, h) + aoff + m * 2048 + k * 1024); } while (0)
; #define PG8_LDB(dst, b, h) do { _Pragma("unroll") for (int n = 0; n < 2; ++n) _Pragma("unroll") for (int k = 0; k < 2; ++k) dst[n][k] = *(const LAS bf16x8*)(lds + PG8_SB(b, h) + boff + n * 2048 + k * 1024); } while (0)
; #define PG8_MMA(ai, bj, At, Bt) do { __builtin_amdgcn_s_setprio(1); _Pragma("unroll") for (int m = 0; m < 4; ++m) _Pragma("unroll") for (int n = 0; n < 2; ++n) _Pragma("unroll") for (int k = 0; k < 2; ++k) \
;         acc[ai][bj][m][n] = __builtin_amdgcn_mfma_f32_16x16x32_bf16(Bt[n][k], At[m][k], acc[ai][bj][m][n], 0, 0, 0); __builtin_amdgcn_s_setprio(0); } while (0)
; #define PG8_WAIT_V(n) asm volatile("s_waitcnt vmcnt(" #n ")" ::: "memory")
; #define PG8_WAIT_L(n) asm volatile("s_waitcnt lgkmcnt(" #n ")" ::: "memory")
; #define PG8_BAR __builtin_amdgcn_s_barrier()
; #define PG8_SCHED __builtin_amdgcn_sched_barrier(0)
; template <class Epi>
; __device__ __forceinline__ void gemm_phase(LAS unsigned char* lds, const Gemm g, const Order& S, const Epi& E, const int wid) {
;     ...
;             const bool last = (t == nt - 2);
;             const char* a1 = cA + (size_t)(t + 1) * kstep;
;             const char* a2 = last ? nA : cA + (size_t)(t + 2) * kstep; const char* b2 = last ? nB : cB + (size_t)(t + 2) * kstep;
;             const char* a3 = a2 + kstep; const char* b3 = b2 + kstep;
;     ...
;             PG8_LDB(B0, 0, 0); PG8_LDB(B1, 0, 1); PG8_SCHED; PG8_LDA(At, 0, 0); PG8_STAGE(PG8_SA(1, 1), a1 + hA, voffA);
;             PG8_WAIT_V(8); PG8_WAIT_L(0); PG8_BAR; PG8_MMA(0, 0, At, B0); PG8_MMA(0, 1, At, B1); PG8_BAR; PG8_SCHED;
;             PG8_LDA(At, 0, 1); PG8_STAGE(PG8_SB(0, 0), b2, voffB); PG8_STAGE(PG8_SB(0, 1), b2 + hB, voffB); PG8_STAGE(PG8_SA(0, 0), a2, voffA);
.LBB0_492:
	s_add_u32 s19, s46, s5
	s_addc_u32 s21, s47, 0
	s_add_u32 s24, s19, 0x100
	s_addc_u32 s25, s21, 0
	s_and_b64 s[22:23], s[56:57], exec
	s_cselect_b32 s61, s37, s25
	s_cselect_b32 s60, s36, s24
	s_add_u32 s5, s40, s5
	s_addc_u32 s22, s41, 0
	s_add_u32 s5, s5, 0x100
	s_addc_u32 s24, s22, 0
	s_and_b64 s[22:23], s[56:57], exec
	s_cselect_b32 s63, s39, s24
	s_cselect_b32 s62, s38, s5
	s_add_u32 s66, s19, 0x80080
	s_addc_u32 s67, s21, 0
	s_add_i32 s28, s1, s77
	ds_read_b128 v[146:149], v139
	s_waitcnt vmcnt(0)
	ds_read_b128 v[150:153], v139 offset:1024
	ds_read_b128 v[154:157], v139 offset:2048
	ds_read_b128 v[158:161], v139 offset:3072
	ds_read_b128 v[162:165], v140
	ds_read_b128 v[166:169], v140 offset:1024
	ds_read_b128 v[170:173], v140 offset:2048
	ds_read_b128 v[174:177], v140 offset:3072
	s_add_i32 m0, s43, 0xc000
	s_add_i32 s29, s43, 0xe000
	s_add_i32 s25, s28, 0x2000
	s_add_u32 s64, s62, 0x80000
	s_addc_u32 s65, s63, 0
	s_add_i32 s27, s73, s77
	s_add_i32 s26, s27, 0x2000
	s_add_i32 s24, 0, 0x18000
	s_add_i32 s23, 0, 0x1c000
	s_add_u32 s58, s60, 0x80000
	s_addc_u32 s59, s61, 0
	s_add_i32 s22, s24, s77
	s_add_i32 s19, s22, 0x2000
	s_add_u32 s56, s62, 0x80080
	s_addc_u32 s57, s63, 0
	s_add_i32 s21, s23, s77
	s_add_i32 s5, s21, 0x2000
	v_lshl_add_u64 v[142:143], s[66:67], 0, v[128:129]
	ds_read_b128 v[178:181], v141
	ds_read_b128 v[182:185], v141 offset:1024
	ds_read_b128 v[186:189], v141 offset:2048
	ds_read_b128 v[190:193], v141 offset:3072
	ds_read_b128 v[194:197], v141 offset:4096
	ds_read_b128 v[198:201], v141 offset:5120
	ds_read_b128 v[202:205], v141 offset:6144
	ds_read_b128 v[206:209], v141 offset:7168
	global_load_lds_dwordx4 v[142:143], off
	v_lshl_add_u64 v[142:143], s[66:67], 0, v[136:137]
	s_mov_b32 m0, s29
	s_nop 0
	global_load_lds_dwordx4 v[142:143], off
	s_waitcnt vmcnt(8)
	s_waitcnt lgkmcnt(0)
	s_barrier
	s_waitcnt lgkmcnt(0)
	v_mfma_f32_16x16x32_bf16 v[124:127], v[146:149], v[178:181], v[124:127]
	v_mfma_f32_16x16x32_bf16 v[124:127], v[150:153], v[182:185], v[124:127]
	v_mfma_f32_16x16x32_bf16 v[120:123], v[154:157], v[178:181], v[120:123]
	v_mfma_f32_16x16x32_bf16 v[120:123], v[158:161], v[182:185], v[120:123]
	v_mfma_f32_16x16x32_bf16 v[108:111], v[146:149], v[186:189], v[108:111]
	v_mfma_f32_16x16x32_bf16 v[108:111], v[150:153], v[190:193], v[108:111]
	v_mfma_f32_16x16x32_bf16 v[104:107], v[154:157], v[186:189], v[104:107]
	v_mfma_f32_16x16x32_bf16 v[104:107], v[158:161], v[190:193], v[104:107]
	v_mfma_f32_16x16x32_bf16 v[92:95], v[146:149], v[194:197], v[92:95]
	v_mfma_f32_16x16x32_bf16 v[92:95], v[150:153], v[198:201], v[92:95]
	v_mfma_f32_16x16x32_bf16 v[88:91], v[154:157], v[194:197], v[88:91]
	v_mfma_f32_16x16x32_bf16 v[88:91], v[158:161], v[198:201], v[88:91]
	v_mfma_f32_16x16x32_bf16 v[76:79], v[146:149], v[202:205], v[76:79]
	v_mfma_f32_16x16x32_bf16 v[76:79], v[150:153], v[206:209], v[76:79]
	v_mfma_f32_16x16x32_bf16 v[72:75], v[154:157], v[202:205], v[72:75]
	v_mfma_f32_16x16x32_bf16 v[72:75], v[158:161], v[206:209], v[72:75]
	v_mfma_f32_16x16x32_bf16 v[116:119], v[162:165], v[178:181], v[116:119]
	v_mfma_f32_16x16x32_bf16 v[116:119], v[166:169], v[182:185], v[116:119]
	v_mfma_f32_16x16x32_bf16 v[112:115], v[170:173], v[178:181], v[112:115]
	v_mfma_f32_16x16x32_bf16 v[112:115], v[174:177], v[182:185], v[112:115]
	v_mfma_f32_16x16x32_bf16 v[100:103], v[162:165], v[186:189], v[100:103]
	v_mfma_f32_16x16x32_bf16 v[100:103], v[166:169], v[190:193], v[100:103]
	v_mfma_f32_16x16x32_bf16 v[96:99], v[170:173], v[186:189], v[96:99]
	v_mfma_f32_16x16x32_bf16 v[96:99], v[174:177], v[190:193], v[96:99]
	v_mfma_f32_16x16x32_bf16 v[84:87], v[162:165], v[194:197], v[84:87]
	v_mfma_f32_16x16x32_bf16 v[84:87], v[166:169], v[198:201], v[84:87]
	v_mfma_f32_16x16x32_bf16 v[80:83], v[170:173], v[194:197], v[80:83]
	v_mfma_f32_16x16x32_bf16 v[80:83], v[174:177], v[198:201], v[80:83]
	v_mfma_f32_16x16x32_bf16 v[68:71], v[162:165], v[202:205], v[68:71]
	v_mfma_f32_16x16x32_bf16 v[68:71], v[166:169], v[206:209], v[68:71]
	v_mfma_f32_16x16x32_bf16 v[64:67], v[170:173], v[202:205], v[64:67]
	v_mfma_f32_16x16x32_bf16 v[64:67], v[174:177], v[206:209], v[64:67]
	s_barrier
	s_mov_b32 m0, s28
	v_lshl_add_u64 v[142:143], s[62:63], 0, v[132:133]
	ds_read_b128 v[178:181], v141 offset:16384
	ds_read_b128 v[182:185], v141 offset:17408
	ds_read_b128 v[186:189], v141 offset:18432
	ds_read_b128 v[190:193], v141 offset:19456
	ds_read_b128 v[194:197], v141 offset:20480
	ds_read_b128 v[198:201], v141 offset:21504
	ds_read_b128 v[202:205], v141 offset:22528
	ds_read_b128 v[206:209], v141 offset:23552
	global_load_lds_dwordx4 v[142:143], off
	v_lshl_add_u64 v[210:211], s[62:63], 0, v[134:135]
	s_mov_b32 m0, s25
	v_lshl_add_u64 v[212:213], s[64:65], 0, v[132:133]
	global_load_lds_dwordx4 v[210:211], off
	s_mov_b32 m0, s27
	v_lshl_add_u64 v[214:215], s[60:61], 0, v[136:137]
	global_load_lds_dwordx4 v[212:213], off
	v_lshl_add_u64 v[212:213], s[64:65], 0, v[134:135]
	s_mov_b32 m0, s26
	s_nop 0
	global_load_lds_dwordx4 v[212:213], off
	v_lshl_add_u64 v[212:213], s[60:61], 0, v[128:129]
	s_mov_b32 m0, s43
	s_nop 0
	global_load_lds_dwordx4 v[212:213], off
	s_mov_b32 m0, s45
	s_nop 0
	global_load_lds_dwordx4 v[214:215], off
	s_waitcnt vmcnt(8)
	s_waitcnt lgkmcnt(0)
	s_barrier
; #define PG8_STAGE(bufoff, gbase, voff) do { _Pragma("unroll") for (int _i = 0; _i < 2; ++_i) \
;         __builtin_amdgcn_global_load_lds((const unsigned*)((const char*)(gbase) + (voff)[_i]), (LAS unsigned*)(lds + (bufoff) + ldsw + _i * 8192), 16, 0, 0); } while (0)
; #define PG8_LDA(dst, b, h) do { _Pragma("unroll") for (int m = 0; m < 4; ++m) _Pragma("unroll") for (int k = 0; k < 2; ++k) dst[m][k] = *(const LAS bf16x8*)(lds + PG8_SA(b, h) + aoff + m * 2048 + k * 1024); } while (0)
; #define PG8_LDB(dst, b, h) do { _Pragma("unroll") for (int n = 0; n < 2; ++n) _Pragma("unroll") for (int k = 0; k < 2; ++k) dst[n][k] = *(const LAS bf16x8*)(lds + PG8_SB(b, h) + boff + n * 2048 + k * 1024); } while (0)
; #define PG8_MMA(ai, bj, At, Bt) do { __builtin_amdgcn_s_setprio(1); _Pragma("unroll") for (int m = 0; m < 4; ++m) _Pragma("unroll") for (int n = 0; n < 2; ++n) _Pragma("unroll") for (int k = 0; k < 2; ++k) \
;         acc[ai][bj][m][n] = __builtin_amdgcn_mfma_f32_16x16x32_bf16(Bt[n][k], At[m][k], acc[ai][bj][m][n], 0, 0, 0); __builtin_amdgcn_s_setprio(0); } while (0)
; #define PG8_WAIT_V(n) asm volatile("s_waitcnt vmcnt(" #n ")" ::: "memory")
; #define PG8_WAIT_L(n) asm volatile("s_waitcnt lgkmcnt(" #n ")" ::: "memory")
; #define PG8_BAR __builtin_amdgcn_s_barrier()
; #define PG8_SCHED __builtin_amdgcn_sched_barrier(0)
; template <class Epi>
; __device__ __forceinline__ void gemm_phase(LAS unsigned char* lds, const Gemm g, const Order& S, const Epi& E, const int wid) {
;     ...
;             PG8_LDA(At, 0, 1); PG8_STAGE(PG8_SB(0, 0), b2, voffB); PG8_STAGE(PG8_SB(0, 1), b2 + hB, voffB); PG8_STAGE(PG8_SA(0, 0), a2, voffA);
;             PG8_WAIT_V(8); PG8_WAIT_L(0); PG8_BAR; PG8_MMA(1, 0, At, B0); PG8_MMA(1, 1, At, B1); PG8_BAR; PG8_SCHED;
;             PG8_LDB(B0, 1, 0); PG8_LDB(B1, 1, 1); PG8_SCHED; PG8_LDA(At, 1, 0); PG8_STAGE(PG8_SA(0, 1), a2 + hA, voffA);
;             PG8_WAIT_V(8); PG8_WAIT_L(0); PG8_BAR; PG8_MMA(0, 0, At, B0); PG8_MMA(0, 1, At, B1); PG8_BAR; PG8_SCHED;
	s_waitcnt lgkmcnt(0)
	v_mfma_f32_16x16x32_bf16 v[60:63], v[146:149], v[178:181], v[60:63]
	v_mfma_f32_16x16x32_bf16 v[60:63], v[150:153], v[182:185], v[60:63]
	v_mfma_f32_16x16x32_bf16 v[56:59], v[154:157], v[178:181], v[56:59]
	v_mfma_f32_16x16x32_bf16 v[56:59], v[158:161], v[182:185], v[56:59]
	v_mfma_f32_16x16x32_bf16 v[44:47], v[146:149], v[186:189], v[44:47]
	v_mfma_f32_16x16x32_bf16 v[44:47], v[150:153], v[190:193], v[44:47]
	v_mfma_f32_16x16x32_bf16 v[40:43], v[154:157], v[186:189], v[40:43]
	v_mfma_f32_16x16x32_bf16 v[40:43], v[158:161], v[190:193], v[40:43]
	v_mfma_f32_16x16x32_bf16 v[28:31], v[146:149], v[194:197], v[28:31]
	v_mfma_f32_16x16x32_bf16 v[28:31], v[150:153], v[198:201], v[28:31]
	v_mfma_f32_16x16x32_bf16 v[24:27], v[154:157], v[194:197], v[24:27]
	v_mfma_f32_16x16x32_bf16 v[24:27], v[158:161], v[198:201], v[24:27]
	v_mfma_f32_16x16x32_bf16 v[12:15], v[146:149], v[202:205], v[12:15]
	v_mfma_f32_16x16x32_bf16 v[12:15], v[150:153], v[206:209], v[12:15]
	v_mfma_f32_16x16x32_bf16 v[8:11], v[154:157], v[202:205], v[8:11]
	v_mfma_f32_16x16x32_bf16 v[8:11], v[158:161], v[206:209], v[8:11]
	v_mfma_f32_16x16x32_bf16 v[52:55], v[162:165], v[178:181], v[52:55]
	v_mfma_f32_16x16x32_bf16 v[52:55], v[166:169], v[182:185], v[52:55]
	v_mfma_f32_16x16x32_bf16 v[48:51], v[170:173], v[178:181], v[48:51]
	v_mfma_f32_16x16x32_bf16 v[48:51], v[174:177], v[182:185], v[48:51]
	v_mfma_f32_16x16x32_bf16 v[36:39], v[162:165], v[186:189], v[36:39]
	v_mfma_f32_16x16x32_bf16 v[36:39], v[166:169], v[190:193], v[36:39]
	v_mfma_f32_16x16x32_bf16 v[32:35], v[170:173], v[186:189], v[32:35]
	v_mfma_f32_16x16x32_bf16 v[32:35], v[174:177], v[190:193], v[32:35]
	v_mfma_f32_16x16x32_bf16 v[20:23], v[162:165], v[194:197], v[20:23]
	v_mfma_f32_16x16x32_bf16 v[20:23], v[166:169], v[198:201], v[20:23]
	v_mfma_f32_16x16x32_bf16 v[16:19], v[170:173], v[194:197], v[16:19]
	v_mfma_f32_16x16x32_bf16 v[16:19], v[174:177], v[198:201], v[16:19]
	v_mfma_f32_16x16x32_bf16 v[4:7], v[162:165], v[202:205], v[4:7]
	v_mfma_f32_16x16x32_bf16 v[4:7], v[166:169], v[206:209], v[4:7]
	v_mfma_f32_16x16x32_bf16 v[0:3], v[170:173], v[202:205], v[0:3]
	v_mfma_f32_16x16x32_bf16 v[0:3], v[174:177], v[206:209], v[0:3]
	s_barrier
	v_add_u32_e32 v144, s24, v138
	ds_read_b128 v[146:149], v144
	ds_read_b128 v[150:153], v144 offset:1024
	ds_read_b128 v[154:157], v144 offset:2048
	ds_read_b128 v[158:161], v144 offset:3072
	v_add_u32_e32 v144, s23, v138
	ds_read_b128 v[162:165], v144
	ds_read_b128 v[166:169], v144 offset:1024
	ds_read_b128 v[170:173], v144 offset:2048
	ds_read_b128 v[174:177], v144 offset:3072
	s_mov_b32 m0, s78
	v_lshl_add_u64 v[216:217], s[58:59], 0, v[128:129]
	ds_read_b128 v[178:181], v141 offset:32768
	ds_read_b128 v[182:185], v141 offset:33792
	ds_read_b128 v[186:189], v141 offset:34816
	ds_read_b128 v[190:193], v141 offset:35840
	ds_read_b128 v[194:197], v141 offset:36864
	ds_read_b128 v[198:201], v141 offset:37888
	ds_read_b128 v[202:205], v141 offset:38912
	ds_read_b128 v[206:209], v141 offset:39936
	global_load_lds_dwordx4 v[216:217], off
	v_lshl_add_u64 v[216:217], s[58:59], 0, v[136:137]
	s_mov_b32 m0, s79
	s_nop 0
	global_load_lds_dwordx4 v[216:217], off
	s_waitcnt vmcnt(8)
	s_waitcnt lgkmcnt(0)
	s_barrier
	s_waitcnt lgkmcnt(0)
	v_mfma_f32_16x16x32_bf16 v[124:127], v[146:149], v[178:181], v[124:127]
	v_mfma_f32_16x16x32_bf16 v[124:127], v[150:153], v[182:185], v[124:127]
	v_mfma_f32_16x16x32_bf16 v[120:123], v[154:157], v[178:181], v[120:123]
	v_mfma_f32_16x16x32_bf16 v[120:123], v[158:161], v[182:185], v[120:123]
	v_mfma_f32_16x16x32_bf16 v[108:111], v[146:149], v[186:189], v[108:111]
	v_mfma_f32_16x16x32_bf16 v[108:111], v[150:153], v[190:193], v[108:111]
	v_mfma_f32_16x16x32_bf16 v[104:107], v[154:157], v[186:189], v[104:107]
	v_mfma_f32_16x16x32_bf16 v[104:107], v[158:161], v[190:193], v[104:107]
	v_mfma_f32_16x16x32_bf16 v[92:95], v[146:149], v[194:197], v[92:95]
	v_mfma_f32_16x16x32_bf16 v[92:95], v[150:153], v[198:201], v[92:95]
	v_mfma_f32_16x16x32_bf16 v[88:91], v[154:157], v[194:197], v[88:91]
	v_mfma_f32_16x16x32_bf16 v[88:91], v[158:161], v[198:201], v[88:91]
	v_mfma_f32_16x16x32_bf16 v[76:79], v[146:149], v[202:205], v[76:79]
	v_mfma_f32_16x16x32_bf16 v[76:79], v[150:153], v[206:209], v[76:79]
	v_mfma_f32_16x16x32_bf16 v[72:75], v[154:157], v[202:205], v[72:75]
	v_mfma_f32_16x16x32_bf16 v[72:75], v[158:161], v[206:209], v[72:75]
	v_mfma_f32_16x16x32_bf16 v[116:119], v[162:165], v[178:181], v[116:119]
	v_mfma_f32_16x16x32_bf16 v[116:119], v[166:169], v[182:185], v[116:119]
	v_mfma_f32_16x16x32_bf16 v[112:115], v[170:173], v[178:181], v[112:115]
	v_mfma_f32_16x16x32_bf16 v[112:115], v[174:177], v[182:185], v[112:115]
	v_mfma_f32_16x16x32_bf16 v[100:103], v[162:165], v[186:189], v[100:103]
	v_mfma_f32_16x16x32_bf16 v[100:103], v[166:169], v[190:193], v[100:103]
	v_mfma_f32_16x16x32_bf16 v[96:99], v[170:173], v[186:189], v[96:99]
	v_mfma_f32_16x16x32_bf16 v[96:99], v[174:177], v[190:193], v[96:99]
	v_mfma_f32_16x16x32_bf16 v[84:87], v[162:165], v[194:197], v[84:87]
	v_mfma_f32_16x16x32_bf16 v[84:87], v[166:169], v[198:201], v[84:87]
	v_mfma_f32_16x16x32_bf16 v[80:83], v[170:173], v[194:197], v[80:83]
	v_mfma_f32_16x16x32_bf16 v[80:83], v[174:177], v[198:201], v[80:83]
	v_mfma_f32_16x16x32_bf16 v[68:71], v[162:165], v[202:205], v[68:71]
	v_mfma_f32_16x16x32_bf16 v[68:71], v[166:169], v[206:209], v[68:71]
	v_mfma_f32_16x16x32_bf16 v[64:67], v[170:173], v[202:205], v[64:67]
	v_mfma_f32_16x16x32_bf16 v[64:67], v[174:177], v[206:209], v[64:67]
	s_barrier
; #define PG8_STAGE(bufoff, gbase, voff) do { _Pragma("unroll") for (int _i = 0; _i < 2; ++_i) \
;         __builtin_amdgcn_global_load_lds((const unsigned*)((const char*)(gbase) + (voff)[_i]), (LAS unsigned*)(lds + (bufoff) + ldsw + _i * 8192), 16, 0, 0); } while (0)
; #define PG8_LDA(dst, b, h) do { _Pragma("unroll") for (int m = 0; m < 4; ++m) _Pragma("unroll") for (int k = 0; k < 2; ++k) dst[m][k] = *(const LAS bf16x8*)(lds + PG8_SA(b, h) + aoff + m * 2048 + k * 1024); } while (0)
; #define PG8_MMA(ai, bj, At, Bt) do { __builtin_amdgcn_s_setprio(1); _Pragma("unroll") for (int m = 0; m < 4; ++m) _Pragma("unroll") for (int n = 0; n < 2; ++n) _Pragma("unroll") for (int k = 0; k < 2; ++k) \
;         acc[ai][bj][m][n] = __builtin_amdgcn_mfma_f32_16x16x32_bf16(Bt[n][k], At[m][k], acc[ai][bj][m][n], 0, 0, 0); __builtin_amdgcn_s_setprio(0); } while (0)
; #define PG8_WAIT_V(n) asm volatile("s_waitcnt vmcnt(" #n ")" ::: "memory")
; #define PG8_WAIT_L(n) asm volatile("s_waitcnt lgkmcnt(" #n ")" ::: "memory")
; #define PG8_BAR __builtin_amdgcn_s_barrier()
; #define PG8_SCHED __builtin_amdgcn_sched_barrier(0)
; template <class Epi>
; __device__ __forceinline__ void gemm_phase(LAS unsigned char* lds, const Gemm g, const Order& S, const Epi& E, const int wid) {
;     ...
;         for (int t = 0; t < nt; t += 2) {
;     ...
;             PG8_LDA(At, 1, 1); PG8_STAGE(PG8_SB(1, 0), b3, voffB); PG8_STAGE(PG8_SB(1, 1), b3 + hB, voffB); PG8_STAGE(PG8_SA(1, 0), a3, voffA);
;             PG8_WAIT_V(8); PG8_WAIT_L(0); PG8_BAR; PG8_MMA(1, 0, At, B0); PG8_MMA(1, 1, At, B1); PG8_BAR; PG8_SCHED;
	s_mov_b32 m0, s22
	v_lshl_add_u64 v[142:143], v[142:143], 0, s[16:17]
	ds_read_b128 v[178:181], v141 offset:49152
	ds_read_b128 v[182:185], v141 offset:50176
	ds_read_b128 v[186:189], v141 offset:51200
	ds_read_b128 v[190:193], v141 offset:52224
	ds_read_b128 v[194:197], v141 offset:53248
	ds_read_b128 v[198:201], v141 offset:54272
	ds_read_b128 v[202:205], v141 offset:55296
	ds_read_b128 v[206:209], v141 offset:56320
	global_load_lds_dwordx4 v[142:143], off
	v_lshl_add_u64 v[142:143], v[210:211], 0, s[16:17]
	s_mov_b32 m0, s19
	s_nop 0
	global_load_lds_dwordx4 v[142:143], off
	v_lshl_add_u64 v[142:143], s[56:57], 0, v[132:133]
	s_mov_b32 m0, s21
	s_nop 0
	global_load_lds_dwordx4 v[142:143], off
	v_lshl_add_u64 v[142:143], s[56:57], 0, v[134:135]
	s_mov_b32 m0, s5
	s_nop 0
	global_load_lds_dwordx4 v[142:143], off
	v_lshl_add_u64 v[142:143], v[212:213], 0, s[16:17]
	s_mov_b32 m0, s96
	s_nop 0
	global_load_lds_dwordx4 v[142:143], off
	v_lshl_add_u64 v[142:143], v[214:215], 0, s[16:17]
	s_mov_b32 m0, s97
	s_nop 0
	global_load_lds_dwordx4 v[142:143], off
	s_waitcnt vmcnt(8)
	s_waitcnt lgkmcnt(0)
	s_barrier
	s_waitcnt lgkmcnt(0)
	v_mfma_f32_16x16x32_bf16 v[60:63], v[146:149], v[178:181], v[60:63]
	v_mfma_f32_16x16x32_bf16 v[60:63], v[150:153], v[182:185], v[60:63]
	v_mfma_f32_16x16x32_bf16 v[56:59], v[154:157], v[178:181], v[56:59]
	v_mfma_f32_16x16x32_bf16 v[56:59], v[158:161], v[182:185], v[56:59]
	v_mfma_f32_16x16x32_bf16 v[44:47], v[146:149], v[186:189], v[44:47]
	v_mfma_f32_16x16x32_bf16 v[44:47], v[150:153], v[190:193], v[44:47]
	v_mfma_f32_16x16x32_bf16 v[40:43], v[154:157], v[186:189], v[40:43]
	v_mfma_f32_16x16x32_bf16 v[40:43], v[158:161], v[190:193], v[40:43]
	v_mfma_f32_16x16x32_bf16 v[28:31], v[146:149], v[194:197], v[28:31]
	v_mfma_f32_16x16x32_bf16 v[28:31], v[150:153], v[198:201], v[28:31]
	v_mfma_f32_16x16x32_bf16 v[24:27], v[154:157], v[194:197], v[24:27]
	v_mfma_f32_16x16x32_bf16 v[24:27], v[158:161], v[198:201], v[24:27]
	v_mfma_f32_16x16x32_bf16 v[12:15], v[146:149], v[202:205], v[12:15]
	v_mfma_f32_16x16x32_bf16 v[12:15], v[150:153], v[206:209], v[12:15]
	v_mfma_f32_16x16x32_bf16 v[8:11], v[154:157], v[202:205], v[8:11]
	v_mfma_f32_16x16x32_bf16 v[8:11], v[158:161], v[206:209], v[8:11]
	v_mfma_f32_16x16x32_bf16 v[52:55], v[162:165], v[178:181], v[52:55]
	v_mfma_f32_16x16x32_bf16 v[52:55], v[166:169], v[182:185], v[52:55]
	v_mfma_f32_16x16x32_bf16 v[48:51], v[170:173], v[178:181], v[48:51]
	v_mfma_f32_16x16x32_bf16 v[48:51], v[174:177], v[182:185], v[48:51]
	v_mfma_f32_16x16x32_bf16 v[36:39], v[162:165], v[186:189], v[36:39]
	v_mfma_f32_16x16x32_bf16 v[36:39], v[166:169], v[190:193], v[36:39]
	v_mfma_f32_16x16x32_bf16 v[32:35], v[170:173], v[186:189], v[32:35]
	v_mfma_f32_16x16x32_bf16 v[32:35], v[174:177], v[190:193], v[32:35]
	v_mfma_f32_16x16x32_bf16 v[20:23], v[162:165], v[194:197], v[20:23]
	v_mfma_f32_16x16x32_bf16 v[20:23], v[166:169], v[198:201], v[20:23]
	v_mfma_f32_16x16x32_bf16 v[16:19], v[170:173], v[194:197], v[16:19]
	v_mfma_f32_16x16x32_bf16 v[16:19], v[174:177], v[198:201], v[16:19]
	v_mfma_f32_16x16x32_bf16 v[4:7], v[162:165], v[202:205], v[4:7]
	v_mfma_f32_16x16x32_bf16 v[4:7], v[166:169], v[206:209], v[4:7]
	v_mfma_f32_16x16x32_bf16 v[0:3], v[170:173], v[202:205], v[0:3]
	v_mfma_f32_16x16x32_bf16 v[0:3], v[174:177], v[206:209], v[0:3]
	s_barrier
	s_movk_i32 s5, 0x100
	s_andn2_b64 vcc, exec, s[54:55]
	s_mov_b64 s[56:57], -1
	s_mov_b64 s[54:55], 0
	s_cbranch_vccz .LBB0_492
	s_and_b64 vcc, exec, s[12:13]
	s_cbranch_vccz .LBB0_495
	s_barrier

; #define PG8_STAGE(bufoff, gbase, voff) do { _Pragma("unroll") for (int _i = 0; _i < 2; ++_i) \
;         __builtin_amdgcn_global_load_lds((const unsigned*)((const char*)(gbase) + (voff)[_i]), (LAS unsigned*)(lds + (bufoff) + ldsw + _i * 8192), 16, 0, 0); } while (0)
; #define PG8_LDA(dst, b, h) do { _Pragma("unroll") for (int m = 0; m < 4; ++m) _Pragma("unroll") for (int k = 0; k < 2; ++k) dst[m][k] = *(const LAS bf16x8*)(lds + PG8_SA(b, h) + aoff + m * 2048 + k * 1024); } while (0)
; #define PG8_LDB(dst, b, h) do { _Pragma("unroll") for (int n = 0; n < 2; ++n) _Pragma("unroll") for (int k = 0; k < 2; ++k) dst[n][k] = *(const LAS bf16x8*)(lds + PG8_SB(b, h) + boff + n * 2048 + k * 1024); } while (0)
; #define PG8_MMA(ai, bj, At, Bt) do { __builtin_amdgcn_s_setprio(1); _Pragma("unroll") for (int m = 0; m < 4; ++m) _Pragma("unroll") for (int n = 0; n < 2; ++n) _Pragma("unroll") for (int k = 0; k < 2; ++k) \
;         acc[ai][bj][m][n] = __builtin_amdgcn_mfma_f32_16x16x32_bf16(Bt[n][k], At[m][k], acc[ai][bj][m][n], 0, 0, 0); __builtin_amdgcn_s_setprio(0); } while (0)
; #define PG8_WAIT_V(n) asm volatile("s_waitcnt vmcnt(" #n ")" ::: "memory")
; #define PG8_WAIT_L(n) asm volatile("s_waitcnt lgkmcnt(" #n ")" ::: "memory")
; #define PG8_BAR __builtin_amdgcn_s_barrier()
; #define PG8_SCHED __builtin_amdgcn_sched_barrier(0)
; template <class Epi>
; __device__ __forceinline__ void gemm_phase(LAS unsigned char* lds, const Gemm g, const Order& S, const Epi& E, const int wid) {
;     ...
;             PG8_LDB(B0, 0, 0); PG8_LDB(B1, 0, 1); PG8_SCHED; PG8_LDA(At, 0, 0); PG8_STAGE(PG8_SA(1, 1), a1 + hA, voffA);
;             PG8_WAIT_V(8); PG8_WAIT_L(0); PG8_BAR; PG8_MMA(0, 0, At, B0); PG8_MMA(0, 1, At, B1); PG8_BAR; PG8_SCHED;
;             PG8_LDA(At, 0, 1); PG8_STAGE(PG8_SB(0, 0), b2, voffB); PG8_STAGE(PG8_SB(0, 1), b2 + hB, voffB); PG8_STAGE(PG8_SA(0, 0), a2, voffA);
.LBB0_581:
	ds_read_b128 v[146:149], v142
	ds_read_b128 v[150:153], v142 offset:1024
	ds_read_b128 v[154:157], v142 offset:2048
	ds_read_b128 v[158:161], v142 offset:3072
	ds_read_b128 v[162:165], v143
	ds_read_b128 v[166:169], v143 offset:1024
	ds_read_b128 v[170:173], v143 offset:2048
	ds_read_b128 v[174:177], v143 offset:3072
	s_add_u32 s38, s36, 0xfff80080
	s_addc_u32 s39, s37, -1
	s_cmp_eq_u32 s58, 28
	s_cselect_b32 s41, s5, s39
	s_cselect_b32 s40, s4, s38
	s_cselect_b32 s39, s21, s19
	s_cselect_b32 s38, s20, s17
	v_lshl_add_u64 v[210:211], s[36:37], 0, v[128:129]
	s_add_i32 m0, s26, 0xc000
	ds_read_b128 v[178:181], v144
	ds_read_b128 v[182:185], v144 offset:1024
	ds_read_b128 v[186:189], v144 offset:2048
	ds_read_b128 v[190:193], v144 offset:3072
	ds_read_b128 v[194:197], v144 offset:4096
	ds_read_b128 v[198:201], v144 offset:5120
	ds_read_b128 v[202:205], v144 offset:6144
	ds_read_b128 v[206:209], v144 offset:7168
	global_load_lds_dwordx4 v[210:211], off
	v_lshl_add_u64 v[210:211], s[36:37], 0, v[138:139]
	s_add_i32 m0, s26, 0xe000
	s_nop 0
	global_load_lds_dwordx4 v[210:211], off
	s_waitcnt vmcnt(8)
	s_waitcnt lgkmcnt(0)
	s_barrier
	s_waitcnt lgkmcnt(0)
	v_mfma_f32_16x16x32_bf16 v[124:127], v[146:149], v[178:181], v[124:127]
	v_mfma_f32_16x16x32_bf16 v[124:127], v[150:153], v[182:185], v[124:127]
	v_mfma_f32_16x16x32_bf16 v[120:123], v[154:157], v[178:181], v[120:123]
	v_mfma_f32_16x16x32_bf16 v[120:123], v[158:161], v[182:185], v[120:123]
	v_mfma_f32_16x16x32_bf16 v[116:119], v[146:149], v[186:189], v[116:119]
	v_mfma_f32_16x16x32_bf16 v[116:119], v[150:153], v[190:193], v[116:119]
	v_mfma_f32_16x16x32_bf16 v[112:115], v[154:157], v[186:189], v[112:115]
	v_mfma_f32_16x16x32_bf16 v[112:115], v[158:161], v[190:193], v[112:115]
	v_mfma_f32_16x16x32_bf16 v[100:103], v[146:149], v[194:197], v[100:103]
	v_mfma_f32_16x16x32_bf16 v[100:103], v[150:153], v[198:201], v[100:103]
	v_mfma_f32_16x16x32_bf16 v[96:99], v[154:157], v[194:197], v[96:99]
	v_mfma_f32_16x16x32_bf16 v[96:99], v[158:161], v[198:201], v[96:99]
	v_mfma_f32_16x16x32_bf16 v[84:87], v[146:149], v[202:205], v[84:87]
	v_mfma_f32_16x16x32_bf16 v[84:87], v[150:153], v[206:209], v[84:87]
	v_mfma_f32_16x16x32_bf16 v[80:83], v[154:157], v[202:205], v[80:83]
	v_mfma_f32_16x16x32_bf16 v[80:83], v[158:161], v[206:209], v[80:83]
	v_mfma_f32_16x16x32_bf16 v[108:111], v[162:165], v[178:181], v[108:111]
	v_mfma_f32_16x16x32_bf16 v[108:111], v[166:169], v[182:185], v[108:111]
	v_mfma_f32_16x16x32_bf16 v[104:107], v[170:173], v[178:181], v[104:107]
	v_mfma_f32_16x16x32_bf16 v[104:107], v[174:177], v[182:185], v[104:107]
	v_mfma_f32_16x16x32_bf16 v[92:95], v[162:165], v[186:189], v[92:95]
	v_mfma_f32_16x16x32_bf16 v[92:95], v[166:169], v[190:193], v[92:95]
	v_mfma_f32_16x16x32_bf16 v[88:91], v[170:173], v[186:189], v[88:91]
	v_mfma_f32_16x16x32_bf16 v[88:91], v[174:177], v[190:193], v[88:91]
	v_mfma_f32_16x16x32_bf16 v[76:79], v[162:165], v[194:197], v[76:79]
	v_mfma_f32_16x16x32_bf16 v[76:79], v[166:169], v[198:201], v[76:79]
	v_mfma_f32_16x16x32_bf16 v[72:75], v[170:173], v[194:197], v[72:75]
	v_mfma_f32_16x16x32_bf16 v[72:75], v[174:177], v[198:201], v[72:75]
	v_mfma_f32_16x16x32_bf16 v[68:71], v[162:165], v[202:205], v[68:71]
	v_mfma_f32_16x16x32_bf16 v[68:71], v[166:169], v[206:209], v[68:71]
	v_mfma_f32_16x16x32_bf16 v[64:67], v[170:173], v[202:205], v[64:67]
	v_mfma_f32_16x16x32_bf16 v[64:67], v[174:177], v[206:209], v[64:67]
	s_barrier
	s_add_i32 s59, s50, s24
	v_lshl_add_u64 v[210:211], s[38:39], 0, v[134:135]
	s_mov_b32 m0, s59
	ds_read_b128 v[178:181], v144 offset:16384
	ds_read_b128 v[182:185], v144 offset:17408
	ds_read_b128 v[186:189], v144 offset:18432
	ds_read_b128 v[190:193], v144 offset:19456
	ds_read_b128 v[194:197], v144 offset:20480
	ds_read_b128 v[198:201], v144 offset:21504
	ds_read_b128 v[202:205], v144 offset:22528
	ds_read_b128 v[206:209], v144 offset:23552
	global_load_lds_dwordx4 v[210:211], off
	s_add_i32 m0, s59, 0x2000
	s_add_u32 s60, s38, 0x80000
	v_lshl_add_u64 v[212:213], s[38:39], 0, v[136:137]
	s_addc_u32 s61, s39, 0
	s_add_i32 s59, s51, s24
	global_load_lds_dwordx4 v[212:213], off
	v_lshl_add_u64 v[214:215], s[60:61], 0, v[134:135]
	s_mov_b32 m0, s59
	v_lshl_add_u64 v[216:217], s[40:41], 0, v[138:139]
	global_load_lds_dwordx4 v[214:215], off
	v_lshl_add_u64 v[214:215], s[60:61], 0, v[136:137]
	s_add_i32 m0, s59, 0x2000
	s_nop 0
	global_load_lds_dwordx4 v[214:215], off
	v_lshl_add_u64 v[214:215], s[40:41], 0, v[128:129]
	s_mov_b32 m0, s26
	s_nop 0
	global_load_lds_dwordx4 v[214:215], off
	s_mov_b32 m0, s27
	s_nop 0
	global_load_lds_dwordx4 v[216:217], off
	s_waitcnt vmcnt(8)
	s_waitcnt lgkmcnt(0)
	s_barrier
; #define PG8_STAGE(bufoff, gbase, voff) do { _Pragma("unroll") for (int _i = 0; _i < 2; ++_i) \
;         __builtin_amdgcn_global_load_lds((const unsigned*)((const char*)(gbase) + (voff)[_i]), (LAS unsigned*)(lds + (bufoff) + ldsw + _i * 8192), 16, 0, 0); } while (0)
; #define PG8_LDA(dst, b, h) do { _Pragma("unroll") for (int m = 0; m < 4; ++m) _Pragma("unroll") for (int k = 0; k < 2; ++k) dst[m][k] = *(const LAS bf16x8*)(lds + PG8_SA(b, h) + aoff + m * 2048 + k * 1024); } while (0)
; #define PG8_LDB(dst, b, h) do { _Pragma("unroll") for (int n = 0; n < 2; ++n) _Pragma("unroll") for (int k = 0; k < 2; ++k) dst[n][k] = *(const LAS bf16x8*)(lds + PG8_SB(b, h) + boff + n * 2048 + k * 1024); } while (0)
; #define PG8_MMA(ai, bj, At, Bt) do { __builtin_amdgcn_s_setprio(1); _Pragma("unroll") for (int m = 0; m < 4; ++m) _Pragma("unroll") for (int n = 0; n < 2; ++n) _Pragma("unroll") for (int k = 0; k < 2; ++k) \
;         acc[ai][bj][m][n] = __builtin_amdgcn_mfma_f32_16x16x32_bf16(Bt[n][k], At[m][k], acc[ai][bj][m][n], 0, 0, 0); __builtin_amdgcn_s_setprio(0); } while (0)
; #define PG8_WAIT_V(n) asm volatile("s_waitcnt vmcnt(" #n ")" ::: "memory")
; #define PG8_WAIT_L(n) asm volatile("s_waitcnt lgkmcnt(" #n ")" ::: "memory")
; #define PG8_BAR __builtin_amdgcn_s_barrier()
; #define PG8_SCHED __builtin_amdgcn_sched_barrier(0)
; template <class Epi>
; __device__ __forceinline__ void gemm_phase(LAS unsigned char* lds, const Gemm g, const Order& S, const Epi& E, const int wid) {
;     ...
;             PG8_LDA(At, 0, 1); PG8_STAGE(PG8_SB(0, 0), b2, voffB); PG8_STAGE(PG8_SB(0, 1), b2 + hB, voffB); PG8_STAGE(PG8_SA(0, 0), a2, voffA);
;             PG8_WAIT_V(8); PG8_WAIT_L(0); PG8_BAR; PG8_MMA(1, 0, At, B0); PG8_MMA(1, 1, At, B1); PG8_BAR; PG8_SCHED;
;             PG8_LDB(B0, 1, 0); PG8_LDB(B1, 1, 1); PG8_SCHED; PG8_LDA(At, 1, 0); PG8_STAGE(PG8_SA(0, 1), a2 + hA, voffA);
;             PG8_WAIT_V(8); PG8_WAIT_L(0); PG8_BAR; PG8_MMA(0, 0, At, B0); PG8_MMA(0, 1, At, B1); PG8_BAR; PG8_SCHED;
	s_waitcnt lgkmcnt(0)
	v_mfma_f32_16x16x32_bf16 v[60:63], v[146:149], v[178:181], v[60:63]
	v_mfma_f32_16x16x32_bf16 v[60:63], v[150:153], v[182:185], v[60:63]
	v_mfma_f32_16x16x32_bf16 v[56:59], v[154:157], v[178:181], v[56:59]
	v_mfma_f32_16x16x32_bf16 v[56:59], v[158:161], v[182:185], v[56:59]
	v_mfma_f32_16x16x32_bf16 v[52:55], v[146:149], v[186:189], v[52:55]
	v_mfma_f32_16x16x32_bf16 v[52:55], v[150:153], v[190:193], v[52:55]
	v_mfma_f32_16x16x32_bf16 v[48:51], v[154:157], v[186:189], v[48:51]
	v_mfma_f32_16x16x32_bf16 v[48:51], v[158:161], v[190:193], v[48:51]
	v_mfma_f32_16x16x32_bf16 v[36:39], v[146:149], v[194:197], v[36:39]
	v_mfma_f32_16x16x32_bf16 v[36:39], v[150:153], v[198:201], v[36:39]
	v_mfma_f32_16x16x32_bf16 v[32:35], v[154:157], v[194:197], v[32:35]
	v_mfma_f32_16x16x32_bf16 v[32:35], v[158:161], v[198:201], v[32:35]
	v_mfma_f32_16x16x32_bf16 v[20:23], v[146:149], v[202:205], v[20:23]
	v_mfma_f32_16x16x32_bf16 v[20:23], v[150:153], v[206:209], v[20:23]
	v_mfma_f32_16x16x32_bf16 v[16:19], v[154:157], v[202:205], v[16:19]
	v_mfma_f32_16x16x32_bf16 v[16:19], v[158:161], v[206:209], v[16:19]
	v_mfma_f32_16x16x32_bf16 v[44:47], v[162:165], v[178:181], v[44:47]
	v_mfma_f32_16x16x32_bf16 v[44:47], v[166:169], v[182:185], v[44:47]
	v_mfma_f32_16x16x32_bf16 v[40:43], v[170:173], v[178:181], v[40:43]
	v_mfma_f32_16x16x32_bf16 v[40:43], v[174:177], v[182:185], v[40:43]
	v_mfma_f32_16x16x32_bf16 v[28:31], v[162:165], v[186:189], v[28:31]
	v_mfma_f32_16x16x32_bf16 v[28:31], v[166:169], v[190:193], v[28:31]
	v_mfma_f32_16x16x32_bf16 v[24:27], v[170:173], v[186:189], v[24:27]
	v_mfma_f32_16x16x32_bf16 v[24:27], v[174:177], v[190:193], v[24:27]
	v_mfma_f32_16x16x32_bf16 v[12:15], v[162:165], v[194:197], v[12:15]
	v_mfma_f32_16x16x32_bf16 v[12:15], v[166:169], v[198:201], v[12:15]
	v_mfma_f32_16x16x32_bf16 v[8:11], v[170:173], v[194:197], v[8:11]
	v_mfma_f32_16x16x32_bf16 v[8:11], v[174:177], v[198:201], v[8:11]
	v_mfma_f32_16x16x32_bf16 v[4:7], v[162:165], v[202:205], v[4:7]
	v_mfma_f32_16x16x32_bf16 v[4:7], v[166:169], v[206:209], v[4:7]
	v_mfma_f32_16x16x32_bf16 v[0:3], v[170:173], v[202:205], v[0:3]
	v_mfma_f32_16x16x32_bf16 v[0:3], v[174:177], v[206:209], v[0:3]
	s_barrier
	s_add_i32 s59, 0, 0x18000
	v_add_u32_e32 v145, s59, v141
	s_add_i32 s60, 0, 0x1c000
	ds_read_b128 v[146:149], v145
	ds_read_b128 v[150:153], v145 offset:1024
	ds_read_b128 v[154:157], v145 offset:2048
	ds_read_b128 v[158:161], v145 offset:3072
	v_add_u32_e32 v145, s60, v141
	ds_read_b128 v[162:165], v145
	ds_read_b128 v[166:169], v145 offset:1024
	ds_read_b128 v[170:173], v145 offset:2048
	ds_read_b128 v[174:177], v145 offset:3072
	s_add_u32 s40, s40, 0x80000
	s_addc_u32 s41, s41, 0
	s_mov_b32 m0, s28
	v_lshl_add_u64 v[218:219], s[40:41], 0, v[128:129]
	ds_read_b128 v[178:181], v144 offset:32768
	ds_read_b128 v[182:185], v144 offset:33792
	ds_read_b128 v[186:189], v144 offset:34816
	ds_read_b128 v[190:193], v144 offset:35840
	ds_read_b128 v[194:197], v144 offset:36864
	ds_read_b128 v[198:201], v144 offset:37888
	ds_read_b128 v[202:205], v144 offset:38912
	ds_read_b128 v[206:209], v144 offset:39936
	global_load_lds_dwordx4 v[218:219], off
	v_lshl_add_u64 v[218:219], s[40:41], 0, v[138:139]
	s_mov_b32 m0, s29
	s_nop 0
	global_load_lds_dwordx4 v[218:219], off
	s_waitcnt vmcnt(8)
	s_waitcnt lgkmcnt(0)
	s_barrier
	s_waitcnt lgkmcnt(0)
	v_mfma_f32_16x16x32_bf16 v[124:127], v[146:149], v[178:181], v[124:127]
	v_mfma_f32_16x16x32_bf16 v[124:127], v[150:153], v[182:185], v[124:127]
	v_mfma_f32_16x16x32_bf16 v[120:123], v[154:157], v[178:181], v[120:123]
	v_mfma_f32_16x16x32_bf16 v[120:123], v[158:161], v[182:185], v[120:123]
	v_mfma_f32_16x16x32_bf16 v[116:119], v[146:149], v[186:189], v[116:119]
	v_mfma_f32_16x16x32_bf16 v[116:119], v[150:153], v[190:193], v[116:119]
	v_mfma_f32_16x16x32_bf16 v[112:115], v[154:157], v[186:189], v[112:115]
	v_mfma_f32_16x16x32_bf16 v[112:115], v[158:161], v[190:193], v[112:115]
	v_mfma_f32_16x16x32_bf16 v[100:103], v[146:149], v[194:197], v[100:103]
	v_mfma_f32_16x16x32_bf16 v[100:103], v[150:153], v[198:201], v[100:103]
	v_mfma_f32_16x16x32_bf16 v[96:99], v[154:157], v[194:197], v[96:99]
	v_mfma_f32_16x16x32_bf16 v[96:99], v[158:161], v[198:201], v[96:99]
	v_mfma_f32_16x16x32_bf16 v[84:87], v[146:149], v[202:205], v[84:87]
	v_mfma_f32_16x16x32_bf16 v[84:87], v[150:153], v[206:209], v[84:87]
	v_mfma_f32_16x16x32_bf16 v[80:83], v[154:157], v[202:205], v[80:83]
	v_mfma_f32_16x16x32_bf16 v[80:83], v[158:161], v[206:209], v[80:83]
	v_mfma_f32_16x16x32_bf16 v[108:111], v[162:165], v[178:181], v[108:111]
	v_mfma_f32_16x16x32_bf16 v[108:111], v[166:169], v[182:185], v[108:111]
	v_mfma_f32_16x16x32_bf16 v[104:107], v[170:173], v[178:181], v[104:107]
	v_mfma_f32_16x16x32_bf16 v[104:107], v[174:177], v[182:185], v[104:107]
	v_mfma_f32_16x16x32_bf16 v[92:95], v[162:165], v[186:189], v[92:95]
	v_mfma_f32_16x16x32_bf16 v[92:95], v[166:169], v[190:193], v[92:95]
	v_mfma_f32_16x16x32_bf16 v[88:91], v[170:173], v[186:189], v[88:91]
	v_mfma_f32_16x16x32_bf16 v[88:91], v[174:177], v[190:193], v[88:91]
	v_mfma_f32_16x16x32_bf16 v[76:79], v[162:165], v[194:197], v[76:79]
	v_mfma_f32_16x16x32_bf16 v[76:79], v[166:169], v[198:201], v[76:79]
	v_mfma_f32_16x16x32_bf16 v[72:75], v[170:173], v[194:197], v[72:75]
	v_mfma_f32_16x16x32_bf16 v[72:75], v[174:177], v[198:201], v[72:75]
	v_mfma_f32_16x16x32_bf16 v[68:71], v[162:165], v[202:205], v[68:71]
	v_mfma_f32_16x16x32_bf16 v[68:71], v[166:169], v[206:209], v[68:71]
	v_mfma_f32_16x16x32_bf16 v[64:67], v[170:173], v[202:205], v[64:67]
	v_mfma_f32_16x16x32_bf16 v[64:67], v[174:177], v[206:209], v[64:67]
	s_barrier
; #define PG8_STAGE(bufoff, gbase, voff) do { _Pragma("unroll") for (int _i = 0; _i < 2; ++_i) \
;         __builtin_amdgcn_global_load_lds((const unsigned*)((const char*)(gbase) + (voff)[_i]), (LAS unsigned*)(lds + (bufoff) + ldsw + _i * 8192), 16, 0, 0); } while (0)
; #define PG8_LDA(dst, b, h) do { _Pragma("unroll") for (int m = 0; m < 4; ++m) _Pragma("unroll") for (int k = 0; k < 2; ++k) dst[m][k] = *(const LAS bf16x8*)(lds + PG8_SA(b, h) + aoff + m * 2048 + k * 1024); } while (0)
; #define PG8_MMA(ai, bj, At, Bt) do { __builtin_amdgcn_s_setprio(1); _Pragma("unroll") for (int m = 0; m < 4; ++m) _Pragma("unroll") for (int n = 0; n < 2; ++n) _Pragma("unroll") for (int k = 0; k < 2; ++k) \
;         acc[ai][bj][m][n] = __builtin_amdgcn_mfma_f32_16x16x32_bf16(Bt[n][k], At[m][k], acc[ai][bj][m][n], 0, 0, 0); __builtin_amdgcn_s_setprio(0); } while (0)
; #define PG8_WAIT_V(n) asm volatile("s_waitcnt vmcnt(" #n ")" ::: "memory")
; #define PG8_WAIT_L(n) asm volatile("s_waitcnt lgkmcnt(" #n ")" ::: "memory")
; #define PG8_BAR __builtin_amdgcn_s_barrier()
; #define PG8_SCHED __builtin_amdgcn_sched_barrier(0)
; template <class Epi>
; __device__ __forceinline__ void gemm_phase(LAS unsigned char* lds, const Gemm g, const Order& S, const Epi& E, const int wid) {
;     ...
;             PG8_LDA(At, 1, 1); PG8_STAGE(PG8_SB(1, 0), b3, voffB); PG8_STAGE(PG8_SB(1, 1), b3 + hB, voffB); PG8_STAGE(PG8_SA(1, 0), a3, voffA);
;             PG8_WAIT_V(8); PG8_WAIT_L(0); PG8_BAR; PG8_MMA(1, 0, At, B0); PG8_MMA(1, 1, At, B1); PG8_BAR; PG8_SCHED;
	s_add_i32 s40, s59, s24
	v_lshl_add_u64 v[210:211], v[210:211], 0, s[12:13]
	s_mov_b32 m0, s40
	ds_read_b128 v[178:181], v144 offset:49152
	ds_read_b128 v[182:185], v144 offset:50176
	ds_read_b128 v[186:189], v144 offset:51200
	ds_read_b128 v[190:193], v144 offset:52224
	ds_read_b128 v[194:197], v144 offset:53248
	ds_read_b128 v[198:201], v144 offset:54272
	ds_read_b128 v[202:205], v144 offset:55296
	ds_read_b128 v[206:209], v144 offset:56320
	global_load_lds_dwordx4 v[210:211], off
	s_add_i32 m0, s40, 0x2000
	s_add_u32 s38, s38, 0x80080
	v_lshl_add_u64 v[210:211], v[212:213], 0, s[12:13]
	s_addc_u32 s39, s39, 0
	s_add_i32 s40, s60, s24
	global_load_lds_dwordx4 v[210:211], off
	v_lshl_add_u64 v[210:211], s[38:39], 0, v[134:135]
	s_mov_b32 m0, s40
	s_nop 0
	global_load_lds_dwordx4 v[210:211], off
	v_lshl_add_u64 v[210:211], s[38:39], 0, v[136:137]
	s_add_i32 m0, s40, 0x2000
	s_nop 0
	global_load_lds_dwordx4 v[210:211], off
	v_lshl_add_u64 v[210:211], v[214:215], 0, s[12:13]
	s_mov_b32 m0, s47
	s_nop 0
	global_load_lds_dwordx4 v[210:211], off
	v_lshl_add_u64 v[210:211], v[216:217], 0, s[12:13]
	s_mov_b32 m0, s48
	s_nop 0
	global_load_lds_dwordx4 v[210:211], off
	s_waitcnt vmcnt(8)
	s_waitcnt lgkmcnt(0)
	s_barrier
	s_waitcnt lgkmcnt(0)
	v_mfma_f32_16x16x32_bf16 v[60:63], v[146:149], v[178:181], v[60:63]
	v_mfma_f32_16x16x32_bf16 v[60:63], v[150:153], v[182:185], v[60:63]
	v_mfma_f32_16x16x32_bf16 v[56:59], v[154:157], v[178:181], v[56:59]
	v_mfma_f32_16x16x32_bf16 v[56:59], v[158:161], v[182:185], v[56:59]
	v_mfma_f32_16x16x32_bf16 v[52:55], v[146:149], v[186:189], v[52:55]
	v_mfma_f32_16x16x32_bf16 v[52:55], v[150:153], v[190:193], v[52:55]
	v_mfma_f32_16x16x32_bf16 v[48:51], v[154:157], v[186:189], v[48:51]
	v_mfma_f32_16x16x32_bf16 v[48:51], v[158:161], v[190:193], v[48:51]
	v_mfma_f32_16x16x32_bf16 v[36:39], v[146:149], v[194:197], v[36:39]
	v_mfma_f32_16x16x32_bf16 v[36:39], v[150:153], v[198:201], v[36:39]
	v_mfma_f32_16x16x32_bf16 v[32:35], v[154:157], v[194:197], v[32:35]
	v_mfma_f32_16x16x32_bf16 v[32:35], v[158:161], v[198:201], v[32:35]
	v_mfma_f32_16x16x32_bf16 v[20:23], v[146:149], v[202:205], v[20:23]
	v_mfma_f32_16x16x32_bf16 v[20:23], v[150:153], v[206:209], v[20:23]
	v_mfma_f32_16x16x32_bf16 v[16:19], v[154:157], v[202:205], v[16:19]
	v_mfma_f32_16x16x32_bf16 v[16:19], v[158:161], v[206:209], v[16:19]
	v_mfma_f32_16x16x32_bf16 v[44:47], v[162:165], v[178:181], v[44:47]
	v_mfma_f32_16x16x32_bf16 v[44:47], v[166:169], v[182:185], v[44:47]
	v_mfma_f32_16x16x32_bf16 v[40:43], v[170:173], v[178:181], v[40:43]
	v_mfma_f32_16x16x32_bf16 v[40:43], v[174:177], v[182:185], v[40:43]
	v_mfma_f32_16x16x32_bf16 v[28:31], v[162:165], v[186:189], v[28:31]
	v_mfma_f32_16x16x32_bf16 v[28:31], v[166:169], v[190:193], v[28:31]
	v_mfma_f32_16x16x32_bf16 v[24:27], v[170:173], v[186:189], v[24:27]
	v_mfma_f32_16x16x32_bf16 v[24:27], v[174:177], v[190:193], v[24:27]
	v_mfma_f32_16x16x32_bf16 v[12:15], v[162:165], v[194:197], v[12:15]
	v_mfma_f32_16x16x32_bf16 v[12:15], v[166:169], v[198:201], v[12:15]
	v_mfma_f32_16x16x32_bf16 v[8:11], v[170:173], v[194:197], v[8:11]
	v_mfma_f32_16x16x32_bf16 v[8:11], v[174:177], v[198:201], v[8:11]
	v_mfma_f32_16x16x32_bf16 v[4:7], v[162:165], v[202:205], v[4:7]
	v_mfma_f32_16x16x32_bf16 v[4:7], v[166:169], v[206:209], v[4:7]
	v_mfma_f32_16x16x32_bf16 v[0:3], v[170:173], v[202:205], v[0:3]
	v_mfma_f32_16x16x32_bf16 v[0:3], v[174:177], v[206:209], v[0:3]
	s_barrier
	s_add_i32 s58, s58, 2
	s_add_u32 s36, s36, 0x100
	s_addc_u32 s37, s37, 0
	s_add_u32 s17, s17, 0x100
	s_addc_u32 s19, s19, 0
	s_cmp_gt_u32 s58, 29
	s_cbranch_scc0 .LBB0_581
	s_and_b64 vcc, exec, s[10:11]
	s_cbranch_vccz .LBB0_584
	s_barrier

; #define PG8_STAGE(bufoff, gbase, voff) do { _Pragma("unroll") for (int _i = 0; _i < 2; ++_i) \
;         __builtin_amdgcn_global_load_lds((const unsigned*)((const char*)(gbase) + (voff)[_i]), (LAS unsigned*)(lds + (bufoff) + ldsw + _i * 8192), 16, 0, 0); } while (0)
; #define PG8_LDA(dst, b, h) do { _Pragma("unroll") for (int m = 0; m < 4; ++m) _Pragma("unroll") for (int k = 0; k < 2; ++k) dst[m][k] = *(const LAS bf16x8*)(lds + PG8_SA(b, h) + aoff + m * 2048 + k * 1024); } while (0)
; #define PG8_LDB(dst, b, h) do { _Pragma("unroll") for (int n = 0; n < 2; ++n) _Pragma("unroll") for (int k = 0; k < 2; ++k) dst[n][k] = *(const LAS bf16x8*)(lds + PG8_SB(b, h) + boff + n * 2048 + k * 1024); } while (0)
; #define PG8_MMA(ai, bj, At, Bt) do { __builtin_amdgcn_s_setprio(1); _Pragma("unroll") for (int m = 0; m < 4; ++m) _Pragma("unroll") for (int n = 0; n < 2; ++n) _Pragma("unroll") for (int k = 0; k < 2; ++k) \
;         acc[ai][bj][m][n] = __builtin_amdgcn_mfma_f32_16x16x32_bf16(Bt[n][k], At[m][k], acc[ai][bj][m][n], 0, 0, 0); __builtin_amdgcn_s_setprio(0); } while (0)
; #define PG8_WAIT_V(n) asm volatile("s_waitcnt vmcnt(" #n ")" ::: "memory")
; #define PG8_WAIT_L(n) asm volatile("s_waitcnt lgkmcnt(" #n ")" ::: "memory")
; #define PG8_BAR __builtin_amdgcn_s_barrier()
; #define PG8_SCHED __builtin_amdgcn_sched_barrier(0)
; template <class Epi>
; __device__ __forceinline__ void gemm_phase(LAS unsigned char* lds, const Gemm g, const Order& S, const Epi& E, const int wid) {
;     ...
;             PG8_LDB(B0, 0, 0); PG8_LDB(B1, 0, 1); PG8_SCHED; PG8_LDA(At, 0, 0); PG8_STAGE(PG8_SA(1, 1), a1 + hA, voffA);
;             PG8_WAIT_V(8); PG8_WAIT_L(0); PG8_BAR; PG8_MMA(0, 0, At, B0); PG8_MMA(0, 1, At, B1); PG8_BAR; PG8_SCHED;
;             PG8_LDA(At, 0, 1); PG8_STAGE(PG8_SB(0, 0), b2, voffB); PG8_STAGE(PG8_SB(0, 1), b2 + hB, voffB); PG8_STAGE(PG8_SA(0, 0), a2, voffA);
.LBB0_665:
	ds_read_b128 v[146:149], v142
	ds_read_b128 v[150:153], v142 offset:1024
	ds_read_b128 v[154:157], v142 offset:2048
	ds_read_b128 v[158:161], v142 offset:3072
	ds_read_b128 v[162:165], v143
	ds_read_b128 v[166:169], v143 offset:1024
	ds_read_b128 v[170:173], v143 offset:2048
	ds_read_b128 v[174:177], v143 offset:3072
	s_add_u32 s42, s40, 0xfff80080
	s_addc_u32 s43, s41, -1
	s_cmp_eq_u32 s60, 28
	s_cselect_b32 s45, s17, s43
	s_cselect_b32 s44, s56, s42
	s_cselect_b32 s43, s19, s59
	s_cselect_b32 s42, s57, s58
	v_lshl_add_u64 v[210:211], s[40:41], 0, v[128:129]
	s_add_i32 m0, s21, 0xc000
	ds_read_b128 v[178:181], v144
	ds_read_b128 v[182:185], v144 offset:1024
	ds_read_b128 v[186:189], v144 offset:2048
	ds_read_b128 v[190:193], v144 offset:3072
	ds_read_b128 v[194:197], v144 offset:4096
	ds_read_b128 v[198:201], v144 offset:5120
	ds_read_b128 v[202:205], v144 offset:6144
	ds_read_b128 v[206:209], v144 offset:7168
	global_load_lds_dwordx4 v[210:211], off
	v_lshl_add_u64 v[210:211], s[40:41], 0, v[138:139]
	s_add_i32 m0, s21, 0xe000
	s_nop 0
	global_load_lds_dwordx4 v[210:211], off
	s_waitcnt vmcnt(8)
	s_waitcnt lgkmcnt(0)
	s_barrier
	s_waitcnt lgkmcnt(0)
	v_mfma_f32_16x16x32_bf16 v[124:127], v[146:149], v[178:181], v[124:127]
	v_mfma_f32_16x16x32_bf16 v[124:127], v[150:153], v[182:185], v[124:127]
	v_mfma_f32_16x16x32_bf16 v[120:123], v[154:157], v[178:181], v[120:123]
	v_mfma_f32_16x16x32_bf16 v[120:123], v[158:161], v[182:185], v[120:123]
	v_mfma_f32_16x16x32_bf16 v[116:119], v[146:149], v[186:189], v[116:119]
	v_mfma_f32_16x16x32_bf16 v[116:119], v[150:153], v[190:193], v[116:119]
	v_mfma_f32_16x16x32_bf16 v[112:115], v[154:157], v[186:189], v[112:115]
	v_mfma_f32_16x16x32_bf16 v[112:115], v[158:161], v[190:193], v[112:115]
	v_mfma_f32_16x16x32_bf16 v[100:103], v[146:149], v[194:197], v[100:103]
	v_mfma_f32_16x16x32_bf16 v[100:103], v[150:153], v[198:201], v[100:103]
	v_mfma_f32_16x16x32_bf16 v[96:99], v[154:157], v[194:197], v[96:99]
	v_mfma_f32_16x16x32_bf16 v[96:99], v[158:161], v[198:201], v[96:99]
	v_mfma_f32_16x16x32_bf16 v[84:87], v[146:149], v[202:205], v[84:87]
	v_mfma_f32_16x16x32_bf16 v[84:87], v[150:153], v[206:209], v[84:87]
	v_mfma_f32_16x16x32_bf16 v[80:83], v[154:157], v[202:205], v[80:83]
	v_mfma_f32_16x16x32_bf16 v[80:83], v[158:161], v[206:209], v[80:83]
	v_mfma_f32_16x16x32_bf16 v[108:111], v[162:165], v[178:181], v[108:111]
	v_mfma_f32_16x16x32_bf16 v[108:111], v[166:169], v[182:185], v[108:111]
	v_mfma_f32_16x16x32_bf16 v[104:107], v[170:173], v[178:181], v[104:107]
	v_mfma_f32_16x16x32_bf16 v[104:107], v[174:177], v[182:185], v[104:107]
	v_mfma_f32_16x16x32_bf16 v[92:95], v[162:165], v[186:189], v[92:95]
	v_mfma_f32_16x16x32_bf16 v[92:95], v[166:169], v[190:193], v[92:95]
	v_mfma_f32_16x16x32_bf16 v[88:91], v[170:173], v[186:189], v[88:91]
	v_mfma_f32_16x16x32_bf16 v[88:91], v[174:177], v[190:193], v[88:91]
	v_mfma_f32_16x16x32_bf16 v[76:79], v[162:165], v[194:197], v[76:79]
	v_mfma_f32_16x16x32_bf16 v[76:79], v[166:169], v[198:201], v[76:79]
	v_mfma_f32_16x16x32_bf16 v[72:75], v[170:173], v[194:197], v[72:75]
	v_mfma_f32_16x16x32_bf16 v[72:75], v[174:177], v[198:201], v[72:75]
	v_mfma_f32_16x16x32_bf16 v[68:71], v[162:165], v[202:205], v[68:71]
	v_mfma_f32_16x16x32_bf16 v[68:71], v[166:169], v[206:209], v[68:71]
	v_mfma_f32_16x16x32_bf16 v[64:67], v[170:173], v[202:205], v[64:67]
	v_mfma_f32_16x16x32_bf16 v[64:67], v[174:177], v[206:209], v[64:67]
	s_barrier
	s_add_i32 s61, s51, s24
	v_lshl_add_u64 v[210:211], s[42:43], 0, v[134:135]
	s_mov_b32 m0, s61
	ds_read_b128 v[178:181], v144 offset:16384
	ds_read_b128 v[182:185], v144 offset:17408
	ds_read_b128 v[186:189], v144 offset:18432
	ds_read_b128 v[190:193], v144 offset:19456
	ds_read_b128 v[194:197], v144 offset:20480
	ds_read_b128 v[198:201], v144 offset:21504
	ds_read_b128 v[202:205], v144 offset:22528
	ds_read_b128 v[206:209], v144 offset:23552
	global_load_lds_dwordx4 v[210:211], off
	s_add_i32 m0, s61, 0x2000
	s_add_u32 s62, s42, 0x80000
	v_lshl_add_u64 v[212:213], s[42:43], 0, v[136:137]
	s_addc_u32 s63, s43, 0
	s_add_i32 s61, s54, s24
	global_load_lds_dwordx4 v[212:213], off
	v_lshl_add_u64 v[214:215], s[62:63], 0, v[134:135]
	s_mov_b32 m0, s61
	v_lshl_add_u64 v[216:217], s[44:45], 0, v[138:139]
	global_load_lds_dwordx4 v[214:215], off
	v_lshl_add_u64 v[214:215], s[62:63], 0, v[136:137]
	s_add_i32 m0, s61, 0x2000
	s_nop 0
	global_load_lds_dwordx4 v[214:215], off
	v_lshl_add_u64 v[214:215], s[44:45], 0, v[128:129]
	s_mov_b32 m0, s21
	s_nop 0
	global_load_lds_dwordx4 v[214:215], off
	s_mov_b32 m0, s26
	s_nop 0
	global_load_lds_dwordx4 v[216:217], off
	s_waitcnt vmcnt(8)
	s_waitcnt lgkmcnt(0)
	s_barrier
; #define PG8_STAGE(bufoff, gbase, voff) do { _Pragma("unroll") for (int _i = 0; _i < 2; ++_i) \
;         __builtin_amdgcn_global_load_lds((const unsigned*)((const char*)(gbase) + (voff)[_i]), (LAS unsigned*)(lds + (bufoff) + ldsw + _i * 8192), 16, 0, 0); } while (0)
; #define PG8_LDA(dst, b, h) do { _Pragma("unroll") for (int m = 0; m < 4; ++m) _Pragma("unroll") for (int k = 0; k < 2; ++k) dst[m][k] = *(const LAS bf16x8*)(lds + PG8_SA(b, h) + aoff + m * 2048 + k * 1024); } while (0)
; #define PG8_LDB(dst, b, h) do { _Pragma("unroll") for (int n = 0; n < 2; ++n) _Pragma("unroll") for (int k = 0; k < 2; ++k) dst[n][k] = *(const LAS bf16x8*)(lds + PG8_SB(b, h) + boff + n * 2048 + k * 1024); } while (0)
; #define PG8_MMA(ai, bj, At, Bt) do { __builtin_amdgcn_s_setprio(1); _Pragma("unroll") for (int m = 0; m < 4; ++m) _Pragma("unroll") for (int n = 0; n < 2; ++n) _Pragma("unroll") for (int k = 0; k < 2; ++k) \
;         acc[ai][bj][m][n] = __builtin_amdgcn_mfma_f32_16x16x32_bf16(Bt[n][k], At[m][k], acc[ai][bj][m][n], 0, 0, 0); __builtin_amdgcn_s_setprio(0); } while (0)
; #define PG8_WAIT_V(n) asm volatile("s_waitcnt vmcnt(" #n ")" ::: "memory")
; #define PG8_WAIT_L(n) asm volatile("s_waitcnt lgkmcnt(" #n ")" ::: "memory")
; #define PG8_BAR __builtin_amdgcn_s_barrier()
; #define PG8_SCHED __builtin_amdgcn_sched_barrier(0)
; template <class Epi>
; __device__ __forceinline__ void gemm_phase(LAS unsigned char* lds, const Gemm g, const Order& S, const Epi& E, const int wid) {
;     ...
;             PG8_LDA(At, 0, 1); PG8_STAGE(PG8_SB(0, 0), b2, voffB); PG8_STAGE(PG8_SB(0, 1), b2 + hB, voffB); PG8_STAGE(PG8_SA(0, 0), a2, voffA);
;             PG8_WAIT_V(8); PG8_WAIT_L(0); PG8_BAR; PG8_MMA(1, 0, At, B0); PG8_MMA(1, 1, At, B1); PG8_BAR; PG8_SCHED;
;             PG8_LDB(B0, 1, 0); PG8_LDB(B1, 1, 1); PG8_SCHED; PG8_LDA(At, 1, 0); PG8_STAGE(PG8_SA(0, 1), a2 + hA, voffA);
;             PG8_WAIT_V(8); PG8_WAIT_L(0); PG8_BAR; PG8_MMA(0, 0, At, B0); PG8_MMA(0, 1, At, B1); PG8_BAR; PG8_SCHED;
	s_waitcnt lgkmcnt(0)
	v_mfma_f32_16x16x32_bf16 v[60:63], v[146:149], v[178:181], v[60:63]
	v_mfma_f32_16x16x32_bf16 v[60:63], v[150:153], v[182:185], v[60:63]
	v_mfma_f32_16x16x32_bf16 v[56:59], v[154:157], v[178:181], v[56:59]
	v_mfma_f32_16x16x32_bf16 v[56:59], v[158:161], v[182:185], v[56:59]
	v_mfma_f32_16x16x32_bf16 v[52:55], v[146:149], v[186:189], v[52:55]
	v_mfma_f32_16x16x32_bf16 v[52:55], v[150:153], v[190:193], v[52:55]
	v_mfma_f32_16x16x32_bf16 v[48:51], v[154:157], v[186:189], v[48:51]
	v_mfma_f32_16x16x32_bf16 v[48:51], v[158:161], v[190:193], v[48:51]
	v_mfma_f32_16x16x32_bf16 v[36:39], v[146:149], v[194:197], v[36:39]
	v_mfma_f32_16x16x32_bf16 v[36:39], v[150:153], v[198:201], v[36:39]
	v_mfma_f32_16x16x32_bf16 v[32:35], v[154:157], v[194:197], v[32:35]
	v_mfma_f32_16x16x32_bf16 v[32:35], v[158:161], v[198:201], v[32:35]
	v_mfma_f32_16x16x32_bf16 v[20:23], v[146:149], v[202:205], v[20:23]
	v_mfma_f32_16x16x32_bf16 v[20:23], v[150:153], v[206:209], v[20:23]
	v_mfma_f32_16x16x32_bf16 v[16:19], v[154:157], v[202:205], v[16:19]
	v_mfma_f32_16x16x32_bf16 v[16:19], v[158:161], v[206:209], v[16:19]
	v_mfma_f32_16x16x32_bf16 v[44:47], v[162:165], v[178:181], v[44:47]
	v_mfma_f32_16x16x32_bf16 v[44:47], v[166:169], v[182:185], v[44:47]
	v_mfma_f32_16x16x32_bf16 v[40:43], v[170:173], v[178:181], v[40:43]
	v_mfma_f32_16x16x32_bf16 v[40:43], v[174:177], v[182:185], v[40:43]
	v_mfma_f32_16x16x32_bf16 v[28:31], v[162:165], v[186:189], v[28:31]
	v_mfma_f32_16x16x32_bf16 v[28:31], v[166:169], v[190:193], v[28:31]
	v_mfma_f32_16x16x32_bf16 v[24:27], v[170:173], v[186:189], v[24:27]
	v_mfma_f32_16x16x32_bf16 v[24:27], v[174:177], v[190:193], v[24:27]
	v_mfma_f32_16x16x32_bf16 v[12:15], v[162:165], v[194:197], v[12:15]
	v_mfma_f32_16x16x32_bf16 v[12:15], v[166:169], v[198:201], v[12:15]
	v_mfma_f32_16x16x32_bf16 v[8:11], v[170:173], v[194:197], v[8:11]
	v_mfma_f32_16x16x32_bf16 v[8:11], v[174:177], v[198:201], v[8:11]
	v_mfma_f32_16x16x32_bf16 v[4:7], v[162:165], v[202:205], v[4:7]
	v_mfma_f32_16x16x32_bf16 v[4:7], v[166:169], v[206:209], v[4:7]
	v_mfma_f32_16x16x32_bf16 v[0:3], v[170:173], v[202:205], v[0:3]
	v_mfma_f32_16x16x32_bf16 v[0:3], v[174:177], v[206:209], v[0:3]
	s_barrier
	s_add_i32 s61, 0, 0x18000
	v_add_u32_e32 v145, s61, v141
	s_add_i32 s62, 0, 0x1c000
	ds_read_b128 v[146:149], v145
	ds_read_b128 v[150:153], v145 offset:1024
	ds_read_b128 v[154:157], v145 offset:2048
	ds_read_b128 v[158:161], v145 offset:3072
	v_add_u32_e32 v145, s62, v141
	ds_read_b128 v[162:165], v145
	ds_read_b128 v[166:169], v145 offset:1024
	ds_read_b128 v[170:173], v145 offset:2048
	ds_read_b128 v[174:177], v145 offset:3072
	s_add_u32 s44, s44, 0x80000
	s_addc_u32 s45, s45, 0
	s_mov_b32 m0, s27
	v_lshl_add_u64 v[218:219], s[44:45], 0, v[128:129]
	ds_read_b128 v[178:181], v144 offset:32768
	ds_read_b128 v[182:185], v144 offset:33792
	ds_read_b128 v[186:189], v144 offset:34816
	ds_read_b128 v[190:193], v144 offset:35840
	ds_read_b128 v[194:197], v144 offset:36864
	ds_read_b128 v[198:201], v144 offset:37888
	ds_read_b128 v[202:205], v144 offset:38912
	ds_read_b128 v[206:209], v144 offset:39936
	global_load_lds_dwordx4 v[218:219], off
	v_lshl_add_u64 v[218:219], s[44:45], 0, v[138:139]
	s_mov_b32 m0, s28
	s_nop 0
	global_load_lds_dwordx4 v[218:219], off
	s_waitcnt vmcnt(8)
	s_waitcnt lgkmcnt(0)
	s_barrier
	s_waitcnt lgkmcnt(0)
	v_mfma_f32_16x16x32_bf16 v[124:127], v[146:149], v[178:181], v[124:127]
	v_mfma_f32_16x16x32_bf16 v[124:127], v[150:153], v[182:185], v[124:127]
	v_mfma_f32_16x16x32_bf16 v[120:123], v[154:157], v[178:181], v[120:123]
	v_mfma_f32_16x16x32_bf16 v[120:123], v[158:161], v[182:185], v[120:123]
	v_mfma_f32_16x16x32_bf16 v[116:119], v[146:149], v[186:189], v[116:119]
	v_mfma_f32_16x16x32_bf16 v[116:119], v[150:153], v[190:193], v[116:119]
	v_mfma_f32_16x16x32_bf16 v[112:115], v[154:157], v[186:189], v[112:115]
	v_mfma_f32_16x16x32_bf16 v[112:115], v[158:161], v[190:193], v[112:115]
	v_mfma_f32_16x16x32_bf16 v[100:103], v[146:149], v[194:197], v[100:103]
	v_mfma_f32_16x16x32_bf16 v[100:103], v[150:153], v[198:201], v[100:103]
	v_mfma_f32_16x16x32_bf16 v[96:99], v[154:157], v[194:197], v[96:99]
	v_mfma_f32_16x16x32_bf16 v[96:99], v[158:161], v[198:201], v[96:99]
	v_mfma_f32_16x16x32_bf16 v[84:87], v[146:149], v[202:205], v[84:87]
	v_mfma_f32_16x16x32_bf16 v[84:87], v[150:153], v[206:209], v[84:87]
	v_mfma_f32_16x16x32_bf16 v[80:83], v[154:157], v[202:205], v[80:83]
	v_mfma_f32_16x16x32_bf16 v[80:83], v[158:161], v[206:209], v[80:83]
	v_mfma_f32_16x16x32_bf16 v[108:111], v[162:165], v[178:181], v[108:111]
	v_mfma_f32_16x16x32_bf16 v[108:111], v[166:169], v[182:185], v[108:111]
	v_mfma_f32_16x16x32_bf16 v[104:107], v[170:173], v[178:181], v[104:107]
	v_mfma_f32_16x16x32_bf16 v[104:107], v[174:177], v[182:185], v[104:107]
	v_mfma_f32_16x16x32_bf16 v[92:95], v[162:165], v[186:189], v[92:95]
	v_mfma_f32_16x16x32_bf16 v[92:95], v[166:169], v[190:193], v[92:95]
	v_mfma_f32_16x16x32_bf16 v[88:91], v[170:173], v[186:189], v[88:91]
	v_mfma_f32_16x16x32_bf16 v[88:91], v[174:177], v[190:193], v[88:91]
	v_mfma_f32_16x16x32_bf16 v[76:79], v[162:165], v[194:197], v[76:79]
	v_mfma_f32_16x16x32_bf16 v[76:79], v[166:169], v[198:201], v[76:79]
	v_mfma_f32_16x16x32_bf16 v[72:75], v[170:173], v[194:197], v[72:75]
	v_mfma_f32_16x16x32_bf16 v[72:75], v[174:177], v[198:201], v[72:75]
	v_mfma_f32_16x16x32_bf16 v[68:71], v[162:165], v[202:205], v[68:71]
	v_mfma_f32_16x16x32_bf16 v[68:71], v[166:169], v[206:209], v[68:71]
	v_mfma_f32_16x16x32_bf16 v[64:67], v[170:173], v[202:205], v[64:67]
	v_mfma_f32_16x16x32_bf16 v[64:67], v[174:177], v[206:209], v[64:67]
	s_barrier
; #define PG8_STAGE(bufoff, gbase, voff) do { _Pragma("unroll") for (int _i = 0; _i < 2; ++_i) \
;         __builtin_amdgcn_global_load_lds((const unsigned*)((const char*)(gbase) + (voff)[_i]), (LAS unsigned*)(lds + (bufoff) + ldsw + _i * 8192), 16, 0, 0); } while (0)
; #define PG8_LDA(dst, b, h) do { _Pragma("unroll") for (int m = 0; m < 4; ++m) _Pragma("unroll") for (int k = 0; k < 2; ++k) dst[m][k] = *(const LAS bf16x8*)(lds + PG8_SA(b, h) + aoff + m * 2048 + k * 1024); } while (0)
; #define PG8_MMA(ai, bj, At, Bt) do { __builtin_amdgcn_s_setprio(1); _Pragma("unroll") for (int m = 0; m < 4; ++m) _Pragma("unroll") for (int n = 0; n < 2; ++n) _Pragma("unroll") for (int k = 0; k < 2; ++k) \
;         acc[ai][bj][m][n] = __builtin_amdgcn_mfma_f32_16x16x32_bf16(Bt[n][k], At[m][k], acc[ai][bj][m][n], 0, 0, 0); __builtin_amdgcn_s_setprio(0); } while (0)
; #define PG8_WAIT_V(n) asm volatile("s_waitcnt vmcnt(" #n ")" ::: "memory")
; #define PG8_WAIT_L(n) asm volatile("s_waitcnt lgkmcnt(" #n ")" ::: "memory")
; #define PG8_BAR __builtin_amdgcn_s_barrier()
; #define PG8_SCHED __builtin_amdgcn_sched_barrier(0)
; template <class Epi>
; __device__ __forceinline__ void gemm_phase(LAS unsigned char* lds, const Gemm g, const Order& S, const Epi& E, const int wid) {
;     ...
;             PG8_LDA(At, 1, 1); PG8_STAGE(PG8_SB(1, 0), b3, voffB); PG8_STAGE(PG8_SB(1, 1), b3 + hB, voffB); PG8_STAGE(PG8_SA(1, 0), a3, voffA);
;             PG8_WAIT_V(8); PG8_WAIT_L(0); PG8_BAR; PG8_MMA(1, 0, At, B0); PG8_MMA(1, 1, At, B1); PG8_BAR; PG8_SCHED;
	s_add_i32 s44, s61, s24
	v_lshl_add_u64 v[210:211], v[210:211], 0, s[12:13]
	s_mov_b32 m0, s44
	ds_read_b128 v[178:181], v144 offset:49152
	ds_read_b128 v[182:185], v144 offset:50176
	ds_read_b128 v[186:189], v144 offset:51200
	ds_read_b128 v[190:193], v144 offset:52224
	ds_read_b128 v[194:197], v144 offset:53248
	ds_read_b128 v[198:201], v144 offset:54272
	ds_read_b128 v[202:205], v144 offset:55296
	ds_read_b128 v[206:209], v144 offset:56320
	global_load_lds_dwordx4 v[210:211], off
	s_add_i32 m0, s44, 0x2000
	s_add_u32 s42, s42, 0x80080
	v_lshl_add_u64 v[210:211], v[212:213], 0, s[12:13]
	s_addc_u32 s43, s43, 0
	s_add_i32 s44, s62, s24
	global_load_lds_dwordx4 v[210:211], off
	v_lshl_add_u64 v[210:211], s[42:43], 0, v[134:135]
	s_mov_b32 m0, s44
	s_nop 0
	global_load_lds_dwordx4 v[210:211], off
	v_lshl_add_u64 v[210:211], s[42:43], 0, v[136:137]
	s_add_i32 m0, s44, 0x2000
	s_nop 0
	global_load_lds_dwordx4 v[210:211], off
	v_lshl_add_u64 v[210:211], v[214:215], 0, s[12:13]
	s_mov_b32 m0, s48
	s_nop 0
	global_load_lds_dwordx4 v[210:211], off
	v_lshl_add_u64 v[210:211], v[216:217], 0, s[12:13]
	s_mov_b32 m0, s49
	s_nop 0
	global_load_lds_dwordx4 v[210:211], off
	s_waitcnt vmcnt(8)
	s_waitcnt lgkmcnt(0)
	s_barrier
	s_waitcnt lgkmcnt(0)
	v_mfma_f32_16x16x32_bf16 v[60:63], v[146:149], v[178:181], v[60:63]
	v_mfma_f32_16x16x32_bf16 v[60:63], v[150:153], v[182:185], v[60:63]
	v_mfma_f32_16x16x32_bf16 v[56:59], v[154:157], v[178:181], v[56:59]
	v_mfma_f32_16x16x32_bf16 v[56:59], v[158:161], v[182:185], v[56:59]
	v_mfma_f32_16x16x32_bf16 v[52:55], v[146:149], v[186:189], v[52:55]
	v_mfma_f32_16x16x32_bf16 v[52:55], v[150:153], v[190:193], v[52:55]
	v_mfma_f32_16x16x32_bf16 v[48:51], v[154:157], v[186:189], v[48:51]
	v_mfma_f32_16x16x32_bf16 v[48:51], v[158:161], v[190:193], v[48:51]
	v_mfma_f32_16x16x32_bf16 v[36:39], v[146:149], v[194:197], v[36:39]
	v_mfma_f32_16x16x32_bf16 v[36:39], v[150:153], v[198:201], v[36:39]
	v_mfma_f32_16x16x32_bf16 v[32:35], v[154:157], v[194:197], v[32:35]
	v_mfma_f32_16x16x32_bf16 v[32:35], v[158:161], v[198:201], v[32:35]
	v_mfma_f32_16x16x32_bf16 v[20:23], v[146:149], v[202:205], v[20:23]
	v_mfma_f32_16x16x32_bf16 v[20:23], v[150:153], v[206:209], v[20:23]
	v_mfma_f32_16x16x32_bf16 v[16:19], v[154:157], v[202:205], v[16:19]
	v_mfma_f32_16x16x32_bf16 v[16:19], v[158:161], v[206:209], v[16:19]
	v_mfma_f32_16x16x32_bf16 v[44:47], v[162:165], v[178:181], v[44:47]
	v_mfma_f32_16x16x32_bf16 v[44:47], v[166:169], v[182:185], v[44:47]
	v_mfma_f32_16x16x32_bf16 v[40:43], v[170:173], v[178:181], v[40:43]
	v_mfma_f32_16x16x32_bf16 v[40:43], v[174:177], v[182:185], v[40:43]
	v_mfma_f32_16x16x32_bf16 v[28:31], v[162:165], v[186:189], v[28:31]
	v_mfma_f32_16x16x32_bf16 v[28:31], v[166:169], v[190:193], v[28:31]
	v_mfma_f32_16x16x32_bf16 v[24:27], v[170:173], v[186:189], v[24:27]
	v_mfma_f32_16x16x32_bf16 v[24:27], v[174:177], v[190:193], v[24:27]
	v_mfma_f32_16x16x32_bf16 v[12:15], v[162:165], v[194:197], v[12:15]
	v_mfma_f32_16x16x32_bf16 v[12:15], v[166:169], v[198:201], v[12:15]
	v_mfma_f32_16x16x32_bf16 v[8:11], v[170:173], v[194:197], v[8:11]
	v_mfma_f32_16x16x32_bf16 v[8:11], v[174:177], v[198:201], v[8:11]
	v_mfma_f32_16x16x32_bf16 v[4:7], v[162:165], v[202:205], v[4:7]
	v_mfma_f32_16x16x32_bf16 v[4:7], v[166:169], v[206:209], v[4:7]
	v_mfma_f32_16x16x32_bf16 v[0:3], v[170:173], v[202:205], v[0:3]
	v_mfma_f32_16x16x32_bf16 v[0:3], v[174:177], v[206:209], v[0:3]
	s_barrier
	s_add_i32 s60, s60, 2
	s_add_u32 s40, s40, 0x100
	s_addc_u32 s41, s41, 0
	s_add_u32 s58, s58, 0x100
	s_addc_u32 s59, s59, 0
	s_cmp_gt_u32 s60, 29
	s_cbranch_scc0 .LBB0_665
	s_and_b64 vcc, exec, s[10:11]
	s_cbranch_vccz .LBB0_668
	s_barrier

; #define PG8_STAGE(bufoff, gbase, voff) do { _Pragma("unroll") for (int _i = 0; _i < 2; ++_i) \
;         __builtin_amdgcn_global_load_lds((const unsigned*)((const char*)(gbase) + (voff)[_i]), (LAS unsigned*)(lds + (bufoff) + ldsw + _i * 8192), 16, 0, 0); } while (0)
; #define PG8_LDA(dst, b, h) do { _Pragma("unroll") for (int m = 0; m < 4; ++m) _Pragma("unroll") for (int k = 0; k < 2; ++k) dst[m][k] = *(const LAS bf16x8*)(lds + PG8_SA(b, h) + aoff + m * 2048 + k * 1024); } while (0)
; #define PG8_LDB(dst, b, h) do { _Pragma("unroll") for (int n = 0; n < 2; ++n) _Pragma("unroll") for (int k = 0; k < 2; ++k) dst[n][k] = *(const LAS bf16x8*)(lds + PG8_SB(b, h) + boff + n * 2048 + k * 1024); } while (0)
; #define PG8_MMA(ai, bj, At, Bt) do { __builtin_amdgcn_s_setprio(1); _Pragma("unroll") for (int m = 0; m < 4; ++m) _Pragma("unroll") for (int n = 0; n < 2; ++n) _Pragma("unroll") for (int k = 0; k < 2; ++k) \
;         acc[ai][bj][m][n] = __builtin_amdgcn_mfma_f32_16x16x32_bf16(Bt[n][k], At[m][k], acc[ai][bj][m][n], 0, 0, 0); __builtin_amdgcn_s_setprio(0); } while (0)
; #define PG8_WAIT_V(n) asm volatile("s_waitcnt vmcnt(" #n ")" ::: "memory")
; #define PG8_WAIT_L(n) asm volatile("s_waitcnt lgkmcnt(" #n ")" ::: "memory")
; #define PG8_BAR __builtin_amdgcn_s_barrier()
; #define PG8_SCHED __builtin_amdgcn_sched_barrier(0)
; template <class Epi>
; __device__ __forceinline__ void gemm_phase(LAS unsigned char* lds, const Gemm g, const Order& S, const Epi& E, const int wid) {
;     ...
;             const bool last = (t == nt - 2);
;             const char* a1 = cA + (size_t)(t + 1) * kstep;
;             const char* a2 = last ? nA : cA + (size_t)(t + 2) * kstep; const char* b2 = last ? nB : cB + (size_t)(t + 2) * kstep;
;             const char* a3 = a2 + kstep; const char* b3 = b2 + kstep;
;     ...
;             PG8_LDB(B0, 0, 0); PG8_LDB(B1, 0, 1); PG8_SCHED; PG8_LDA(At, 0, 0); PG8_STAGE(PG8_SA(1, 1), a1 + hA, voffA);
;             PG8_WAIT_V(8); PG8_WAIT_L(0); PG8_BAR; PG8_MMA(0, 0, At, B0); PG8_MMA(0, 1, At, B1); PG8_BAR; PG8_SCHED;
;             PG8_LDA(At, 0, 1); PG8_STAGE(PG8_SB(0, 0), b2, voffB); PG8_STAGE(PG8_SB(0, 1), b2 + hB, voffB); PG8_STAGE(PG8_SA(0, 0), a2, voffA);
;             PG8_WAIT_V(8); PG8_WAIT_L(0); PG8_BAR; PG8_MMA(1, 0, At, B0); PG8_MMA(1, 1, At, B1); PG8_BAR; PG8_SCHED;
.LBB0_742:
	ds_read_b128 v[138:141], v135
	ds_read_b128 v[142:145], v135 offset:1024
	ds_read_b128 v[146:149], v135 offset:2048
	ds_read_b128 v[150:153], v135 offset:3072
	ds_read_b128 v[154:157], v136
	ds_read_b128 v[158:161], v136 offset:1024
	ds_read_b128 v[170:173], v136 offset:2048
	ds_read_b128 v[174:177], v136 offset:3072
	s_add_u32 s54, s46, 0xfff00080
	s_addc_u32 s55, s47, -1
	s_cmp_eq_u32 s68, 60
	s_cselect_b32 s57, s37, s55
	s_cselect_b32 s56, s64, s54
	s_cselect_b32 s55, s39, s67
	s_cselect_b32 s54, s65, s66
	v_lshl_add_u64 v[162:163], s[46:47], 0, v[164:165]
	s_add_i32 m0, s26, 0xc000
	ds_read_b128 v[178:181], v137
	ds_read_b128 v[184:187], v137 offset:1024
	ds_read_b128 v[188:191], v137 offset:2048
	ds_read_b128 v[192:195], v137 offset:3072
	ds_read_b128 v[196:199], v137 offset:4096
	ds_read_b128 v[200:203], v137 offset:5120
	ds_read_b128 v[204:207], v137 offset:6144
	ds_read_b128 v[208:211], v137 offset:7168
	global_load_lds_dwordx4 v[162:163], off
	v_lshl_add_u64 v[162:163], s[46:47], 0, v[132:133]
	s_add_i32 m0, s26, 0xe000
	s_nop 0
	global_load_lds_dwordx4 v[162:163], off
	s_waitcnt vmcnt(8)
	s_waitcnt lgkmcnt(0)
	s_barrier
	s_waitcnt lgkmcnt(0)
	v_mfma_f32_16x16x32_bf16 v[124:127], v[138:141], v[178:181], v[124:127]
	v_mfma_f32_16x16x32_bf16 v[124:127], v[142:145], v[184:187], v[124:127]
	v_mfma_f32_16x16x32_bf16 v[120:123], v[146:149], v[178:181], v[120:123]
	v_mfma_f32_16x16x32_bf16 v[120:123], v[150:153], v[184:187], v[120:123]
	v_mfma_f32_16x16x32_bf16 v[108:111], v[138:141], v[188:191], v[108:111]
	v_mfma_f32_16x16x32_bf16 v[108:111], v[142:145], v[192:195], v[108:111]
	v_mfma_f32_16x16x32_bf16 v[104:107], v[146:149], v[188:191], v[104:107]
	v_mfma_f32_16x16x32_bf16 v[104:107], v[150:153], v[192:195], v[104:107]
	v_mfma_f32_16x16x32_bf16 v[92:95], v[138:141], v[196:199], v[92:95]
	v_mfma_f32_16x16x32_bf16 v[92:95], v[142:145], v[200:203], v[92:95]
	v_mfma_f32_16x16x32_bf16 v[88:91], v[146:149], v[196:199], v[88:91]
	v_mfma_f32_16x16x32_bf16 v[88:91], v[150:153], v[200:203], v[88:91]
	v_mfma_f32_16x16x32_bf16 v[76:79], v[138:141], v[204:207], v[76:79]
	v_mfma_f32_16x16x32_bf16 v[76:79], v[142:145], v[208:211], v[76:79]
	v_mfma_f32_16x16x32_bf16 v[72:75], v[146:149], v[204:207], v[72:75]
	v_mfma_f32_16x16x32_bf16 v[72:75], v[150:153], v[208:211], v[72:75]
	v_mfma_f32_16x16x32_bf16 v[116:119], v[154:157], v[178:181], v[116:119]
	v_mfma_f32_16x16x32_bf16 v[116:119], v[158:161], v[184:187], v[116:119]
	v_mfma_f32_16x16x32_bf16 v[112:115], v[170:173], v[178:181], v[112:115]
	v_mfma_f32_16x16x32_bf16 v[112:115], v[174:177], v[184:187], v[112:115]
	v_mfma_f32_16x16x32_bf16 v[100:103], v[154:157], v[188:191], v[100:103]
	v_mfma_f32_16x16x32_bf16 v[100:103], v[158:161], v[192:195], v[100:103]
	v_mfma_f32_16x16x32_bf16 v[96:99], v[170:173], v[188:191], v[96:99]
	v_mfma_f32_16x16x32_bf16 v[96:99], v[174:177], v[192:195], v[96:99]
	v_mfma_f32_16x16x32_bf16 v[84:87], v[154:157], v[196:199], v[84:87]
	v_mfma_f32_16x16x32_bf16 v[84:87], v[158:161], v[200:203], v[84:87]
	v_mfma_f32_16x16x32_bf16 v[80:83], v[170:173], v[196:199], v[80:83]
	v_mfma_f32_16x16x32_bf16 v[80:83], v[174:177], v[200:203], v[80:83]
	v_mfma_f32_16x16x32_bf16 v[68:71], v[154:157], v[204:207], v[68:71]
	v_mfma_f32_16x16x32_bf16 v[68:71], v[158:161], v[208:211], v[68:71]
	v_mfma_f32_16x16x32_bf16 v[64:67], v[170:173], v[204:207], v[64:67]
	v_mfma_f32_16x16x32_bf16 v[64:67], v[174:177], v[208:211], v[64:67]
	s_barrier
	s_add_i32 s69, s61, s24
	v_lshl_add_u64 v[162:163], s[54:55], 0, v[128:129]
	s_mov_b32 m0, s69
	ds_read_b128 v[178:181], v137 offset:16384
	ds_read_b128 v[184:187], v137 offset:17408
	ds_read_b128 v[188:191], v137 offset:18432
	ds_read_b128 v[192:195], v137 offset:19456
	ds_read_b128 v[196:199], v137 offset:20480
	ds_read_b128 v[200:203], v137 offset:21504
	ds_read_b128 v[204:207], v137 offset:22528
	ds_read_b128 v[208:211], v137 offset:23552
	global_load_lds_dwordx4 v[162:163], off
	s_add_i32 m0, s69, 0x2000
	s_add_u32 s70, s54, 0x100000
	v_lshl_add_u64 v[212:213], s[54:55], 0, v[130:131]
	s_addc_u32 s71, s55, 0
	s_add_i32 s69, s62, s24
	global_load_lds_dwordx4 v[212:213], off
	v_lshl_add_u64 v[214:215], s[70:71], 0, v[128:129]
	s_mov_b32 m0, s69
	v_lshl_add_u64 v[216:217], s[56:57], 0, v[132:133]
	global_load_lds_dwordx4 v[214:215], off
	v_lshl_add_u64 v[214:215], s[70:71], 0, v[130:131]
	s_add_i32 m0, s69, 0x2000
	s_nop 0
	global_load_lds_dwordx4 v[214:215], off
	v_lshl_add_u64 v[214:215], s[56:57], 0, v[164:165]
	s_mov_b32 m0, s26
	s_nop 0
	global_load_lds_dwordx4 v[214:215], off
	s_mov_b32 m0, s27
	s_nop 0
	global_load_lds_dwordx4 v[216:217], off
	s_waitcnt vmcnt(8)
	s_waitcnt lgkmcnt(0)
	s_barrier
; #define PG8_STAGE(bufoff, gbase, voff) do { _Pragma("unroll") for (int _i = 0; _i < 2; ++_i) \
;         __builtin_amdgcn_global_load_lds((const unsigned*)((const char*)(gbase) + (voff)[_i]), (LAS unsigned*)(lds + (bufoff) + ldsw + _i * 8192), 16, 0, 0); } while (0)
; #define PG8_LDA(dst, b, h) do { _Pragma("unroll") for (int m = 0; m < 4; ++m) _Pragma("unroll") for (int k = 0; k < 2; ++k) dst[m][k] = *(const LAS bf16x8*)(lds + PG8_SA(b, h) + aoff + m * 2048 + k * 1024); } while (0)
; #define PG8_LDB(dst, b, h) do { _Pragma("unroll") for (int n = 0; n < 2; ++n) _Pragma("unroll") for (int k = 0; k < 2; ++k) dst[n][k] = *(const LAS bf16x8*)(lds + PG8_SB(b, h) + boff + n * 2048 + k * 1024); } while (0)
; #define PG8_MMA(ai, bj, At, Bt) do { __builtin_amdgcn_s_setprio(1); _Pragma("unroll") for (int m = 0; m < 4; ++m) _Pragma("unroll") for (int n = 0; n < 2; ++n) _Pragma("unroll") for (int k = 0; k < 2; ++k) \
;         acc[ai][bj][m][n] = __builtin_amdgcn_mfma_f32_16x16x32_bf16(Bt[n][k], At[m][k], acc[ai][bj][m][n], 0, 0, 0); __builtin_amdgcn_s_setprio(0); } while (0)
; #define PG8_WAIT_V(n) asm volatile("s_waitcnt vmcnt(" #n ")" ::: "memory")
; #define PG8_WAIT_L(n) asm volatile("s_waitcnt lgkmcnt(" #n ")" ::: "memory")
; #define PG8_BAR __builtin_amdgcn_s_barrier()
; #define PG8_SCHED __builtin_amdgcn_sched_barrier(0)
; template <class Epi>
; __device__ __forceinline__ void gemm_phase(LAS unsigned char* lds, const Gemm g, const Order& S, const Epi& E, const int wid) {
;     ...
;             PG8_WAIT_V(8); PG8_WAIT_L(0); PG8_BAR; PG8_MMA(1, 0, At, B0); PG8_MMA(1, 1, At, B1); PG8_BAR; PG8_SCHED;
;             PG8_LDB(B0, 1, 0); PG8_LDB(B1, 1, 1); PG8_SCHED; PG8_LDA(At, 1, 0); PG8_STAGE(PG8_SA(0, 1), a2 + hA, voffA);
;             PG8_WAIT_V(8); PG8_WAIT_L(0); PG8_BAR; PG8_MMA(0, 0, At, B0); PG8_MMA(0, 1, At, B1); PG8_BAR; PG8_SCHED;
	s_waitcnt lgkmcnt(0)
	v_mfma_f32_16x16x32_bf16 v[60:63], v[138:141], v[178:181], v[60:63]
	v_mfma_f32_16x16x32_bf16 v[60:63], v[142:145], v[184:187], v[60:63]
	v_mfma_f32_16x16x32_bf16 v[56:59], v[146:149], v[178:181], v[56:59]
	v_mfma_f32_16x16x32_bf16 v[56:59], v[150:153], v[184:187], v[56:59]
	v_mfma_f32_16x16x32_bf16 v[44:47], v[138:141], v[188:191], v[44:47]
	v_mfma_f32_16x16x32_bf16 v[44:47], v[142:145], v[192:195], v[44:47]
	v_mfma_f32_16x16x32_bf16 v[40:43], v[146:149], v[188:191], v[40:43]
	v_mfma_f32_16x16x32_bf16 v[40:43], v[150:153], v[192:195], v[40:43]
	v_mfma_f32_16x16x32_bf16 v[28:31], v[138:141], v[196:199], v[28:31]
	v_mfma_f32_16x16x32_bf16 v[28:31], v[142:145], v[200:203], v[28:31]
	v_mfma_f32_16x16x32_bf16 v[24:27], v[146:149], v[196:199], v[24:27]
	v_mfma_f32_16x16x32_bf16 v[24:27], v[150:153], v[200:203], v[24:27]
	v_mfma_f32_16x16x32_bf16 v[12:15], v[138:141], v[204:207], v[12:15]
	v_mfma_f32_16x16x32_bf16 v[12:15], v[142:145], v[208:211], v[12:15]
	v_mfma_f32_16x16x32_bf16 v[8:11], v[146:149], v[204:207], v[8:11]
	v_mfma_f32_16x16x32_bf16 v[8:11], v[150:153], v[208:211], v[8:11]
	v_mfma_f32_16x16x32_bf16 v[52:55], v[154:157], v[178:181], v[52:55]
	v_mfma_f32_16x16x32_bf16 v[52:55], v[158:161], v[184:187], v[52:55]
	v_mfma_f32_16x16x32_bf16 v[48:51], v[170:173], v[178:181], v[48:51]
	v_mfma_f32_16x16x32_bf16 v[48:51], v[174:177], v[184:187], v[48:51]
	v_mfma_f32_16x16x32_bf16 v[36:39], v[154:157], v[188:191], v[36:39]
	v_mfma_f32_16x16x32_bf16 v[36:39], v[158:161], v[192:195], v[36:39]
	v_mfma_f32_16x16x32_bf16 v[32:35], v[170:173], v[188:191], v[32:35]
	v_mfma_f32_16x16x32_bf16 v[32:35], v[174:177], v[192:195], v[32:35]
	v_mfma_f32_16x16x32_bf16 v[20:23], v[154:157], v[196:199], v[20:23]
	v_mfma_f32_16x16x32_bf16 v[20:23], v[158:161], v[200:203], v[20:23]
	v_mfma_f32_16x16x32_bf16 v[16:19], v[170:173], v[196:199], v[16:19]
	v_mfma_f32_16x16x32_bf16 v[16:19], v[174:177], v[200:203], v[16:19]
	v_mfma_f32_16x16x32_bf16 v[4:7], v[154:157], v[204:207], v[4:7]
	v_mfma_f32_16x16x32_bf16 v[4:7], v[158:161], v[208:211], v[4:7]
	v_mfma_f32_16x16x32_bf16 v[0:3], v[170:173], v[204:207], v[0:3]
	v_mfma_f32_16x16x32_bf16 v[0:3], v[174:177], v[208:211], v[0:3]
	s_barrier
	s_add_i32 s69, 0, 0x18000
	s_add_i32 s70, 0, 0x1c000
	v_add_u32_e32 v150, s69, v134
	v_add_u32_e32 v174, s70, v134
	ds_read_b128 v[138:141], v150
	ds_read_b128 v[142:145], v150 offset:1024
	ds_read_b128 v[146:149], v150 offset:2048
	ds_read_b128 v[150:153], v150 offset:3072
	ds_read_b128 v[154:157], v174
	ds_read_b128 v[158:161], v174 offset:1024
	ds_read_b128 v[170:173], v174 offset:2048
	ds_read_b128 v[174:177], v174 offset:3072
	s_add_u32 s56, s56, 0x100000
	s_addc_u32 s57, s57, 0
	s_mov_b32 m0, s28
	v_lshl_add_u64 v[218:219], s[56:57], 0, v[164:165]
	ds_read_b128 v[178:181], v137 offset:32768
	ds_read_b128 v[184:187], v137 offset:33792
	ds_read_b128 v[188:191], v137 offset:34816
	ds_read_b128 v[192:195], v137 offset:35840
	ds_read_b128 v[196:199], v137 offset:36864
	ds_read_b128 v[200:203], v137 offset:37888
	ds_read_b128 v[204:207], v137 offset:38912
	ds_read_b128 v[208:211], v137 offset:39936
	global_load_lds_dwordx4 v[218:219], off
	v_lshl_add_u64 v[218:219], s[56:57], 0, v[132:133]
	s_mov_b32 m0, s29
	s_nop 0
	global_load_lds_dwordx4 v[218:219], off
	s_waitcnt vmcnt(8)
	s_waitcnt lgkmcnt(0)
	s_barrier
	s_waitcnt lgkmcnt(0)
	v_mfma_f32_16x16x32_bf16 v[124:127], v[138:141], v[178:181], v[124:127]
	v_mfma_f32_16x16x32_bf16 v[124:127], v[142:145], v[184:187], v[124:127]
	v_mfma_f32_16x16x32_bf16 v[120:123], v[146:149], v[178:181], v[120:123]
	v_mfma_f32_16x16x32_bf16 v[120:123], v[150:153], v[184:187], v[120:123]
	v_mfma_f32_16x16x32_bf16 v[108:111], v[138:141], v[188:191], v[108:111]
	v_mfma_f32_16x16x32_bf16 v[108:111], v[142:145], v[192:195], v[108:111]
	v_mfma_f32_16x16x32_bf16 v[104:107], v[146:149], v[188:191], v[104:107]
	v_mfma_f32_16x16x32_bf16 v[104:107], v[150:153], v[192:195], v[104:107]
	v_mfma_f32_16x16x32_bf16 v[92:95], v[138:141], v[196:199], v[92:95]
	v_mfma_f32_16x16x32_bf16 v[92:95], v[142:145], v[200:203], v[92:95]
	v_mfma_f32_16x16x32_bf16 v[88:91], v[146:149], v[196:199], v[88:91]
	v_mfma_f32_16x16x32_bf16 v[88:91], v[150:153], v[200:203], v[88:91]
	v_mfma_f32_16x16x32_bf16 v[76:79], v[138:141], v[204:207], v[76:79]
	v_mfma_f32_16x16x32_bf16 v[76:79], v[142:145], v[208:211], v[76:79]
	v_mfma_f32_16x16x32_bf16 v[72:75], v[146:149], v[204:207], v[72:75]
	v_mfma_f32_16x16x32_bf16 v[72:75], v[150:153], v[208:211], v[72:75]
	v_mfma_f32_16x16x32_bf16 v[116:119], v[154:157], v[178:181], v[116:119]
	v_mfma_f32_16x16x32_bf16 v[116:119], v[158:161], v[184:187], v[116:119]
	v_mfma_f32_16x16x32_bf16 v[112:115], v[170:173], v[178:181], v[112:115]
	v_mfma_f32_16x16x32_bf16 v[112:115], v[174:177], v[184:187], v[112:115]
	v_mfma_f32_16x16x32_bf16 v[100:103], v[154:157], v[188:191], v[100:103]
	v_mfma_f32_16x16x32_bf16 v[100:103], v[158:161], v[192:195], v[100:103]
	v_mfma_f32_16x16x32_bf16 v[96:99], v[170:173], v[188:191], v[96:99]
	v_mfma_f32_16x16x32_bf16 v[96:99], v[174:177], v[192:195], v[96:99]
	v_mfma_f32_16x16x32_bf16 v[84:87], v[154:157], v[196:199], v[84:87]
	v_mfma_f32_16x16x32_bf16 v[84:87], v[158:161], v[200:203], v[84:87]
	v_mfma_f32_16x16x32_bf16 v[80:83], v[170:173], v[196:199], v[80:83]
	v_mfma_f32_16x16x32_bf16 v[80:83], v[174:177], v[200:203], v[80:83]
	v_mfma_f32_16x16x32_bf16 v[68:71], v[154:157], v[204:207], v[68:71]
	v_mfma_f32_16x16x32_bf16 v[68:71], v[158:161], v[208:211], v[68:71]
	v_mfma_f32_16x16x32_bf16 v[64:67], v[170:173], v[204:207], v[64:67]
	v_mfma_f32_16x16x32_bf16 v[64:67], v[174:177], v[208:211], v[64:67]
	s_barrier
; #define PG8_STAGE(bufoff, gbase, voff) do { _Pragma("unroll") for (int _i = 0; _i < 2; ++_i) \
;         __builtin_amdgcn_global_load_lds((const unsigned*)((const char*)(gbase) + (voff)[_i]), (LAS unsigned*)(lds + (bufoff) + ldsw + _i * 8192), 16, 0, 0); } while (0)
; #define PG8_LDA(dst, b, h) do { _Pragma("unroll") for (int m = 0; m < 4; ++m) _Pragma("unroll") for (int k = 0; k < 2; ++k) dst[m][k] = *(const LAS bf16x8*)(lds + PG8_SA(b, h) + aoff + m * 2048 + k * 1024); } while (0)
; #define PG8_MMA(ai, bj, At, Bt) do { __builtin_amdgcn_s_setprio(1); _Pragma("unroll") for (int m = 0; m < 4; ++m) _Pragma("unroll") for (int n = 0; n < 2; ++n) _Pragma("unroll") for (int k = 0; k < 2; ++k) \
;         acc[ai][bj][m][n] = __builtin_amdgcn_mfma_f32_16x16x32_bf16(Bt[n][k], At[m][k], acc[ai][bj][m][n], 0, 0, 0); __builtin_amdgcn_s_setprio(0); } while (0)
; #define PG8_WAIT_V(n) asm volatile("s_waitcnt vmcnt(" #n ")" ::: "memory")
; #define PG8_WAIT_L(n) asm volatile("s_waitcnt lgkmcnt(" #n ")" ::: "memory")
; #define PG8_BAR __builtin_amdgcn_s_barrier()
; #define PG8_SCHED __builtin_amdgcn_sched_barrier(0)
; template <class Epi>
; __device__ __forceinline__ void gemm_phase(LAS unsigned char* lds, const Gemm g, const Order& S, const Epi& E, const int wid) {
;     ...
;             PG8_LDA(At, 1, 1); PG8_STAGE(PG8_SB(1, 0), b3, voffB); PG8_STAGE(PG8_SB(1, 1), b3 + hB, voffB); PG8_STAGE(PG8_SA(1, 0), a3, voffA);
;             PG8_WAIT_V(8); PG8_WAIT_L(0); PG8_BAR; PG8_MMA(1, 0, At, B0); PG8_MMA(1, 1, At, B1); PG8_BAR; PG8_SCHED;
	s_add_i32 s56, s69, s24
	v_lshl_add_u64 v[162:163], v[162:163], 0, s[18:19]
	s_mov_b32 m0, s56
	ds_read_b128 v[178:181], v137 offset:49152
	ds_read_b128 v[184:187], v137 offset:50176
	ds_read_b128 v[188:191], v137 offset:51200
	ds_read_b128 v[192:195], v137 offset:52224
	ds_read_b128 v[196:199], v137 offset:53248
	ds_read_b128 v[200:203], v137 offset:54272
	ds_read_b128 v[204:207], v137 offset:55296
	ds_read_b128 v[208:211], v137 offset:56320
	global_load_lds_dwordx4 v[162:163], off
	s_add_i32 m0, s56, 0x2000
	s_add_u32 s54, s54, 0x100080
	v_lshl_add_u64 v[162:163], v[212:213], 0, s[18:19]
	s_addc_u32 s55, s55, 0
	s_add_i32 s56, s70, s24
	global_load_lds_dwordx4 v[162:163], off
	v_lshl_add_u64 v[162:163], s[54:55], 0, v[128:129]
	s_mov_b32 m0, s56
	s_nop 0
	global_load_lds_dwordx4 v[162:163], off
	v_lshl_add_u64 v[162:163], s[54:55], 0, v[130:131]
	s_add_i32 m0, s56, 0x2000
	s_nop 0
	global_load_lds_dwordx4 v[162:163], off
	v_lshl_add_u64 v[162:163], v[214:215], 0, s[18:19]
	s_mov_b32 m0, s58
	s_nop 0
	global_load_lds_dwordx4 v[162:163], off
	v_lshl_add_u64 v[162:163], v[216:217], 0, s[18:19]
	s_mov_b32 m0, s59
	s_nop 0
	global_load_lds_dwordx4 v[162:163], off
	s_waitcnt vmcnt(8)
	s_waitcnt lgkmcnt(0)
	s_barrier
	s_waitcnt lgkmcnt(0)
	v_mfma_f32_16x16x32_bf16 v[60:63], v[138:141], v[178:181], v[60:63]
	v_mfma_f32_16x16x32_bf16 v[60:63], v[142:145], v[184:187], v[60:63]
	v_mfma_f32_16x16x32_bf16 v[56:59], v[146:149], v[178:181], v[56:59]
	v_mfma_f32_16x16x32_bf16 v[56:59], v[150:153], v[184:187], v[56:59]
	v_mfma_f32_16x16x32_bf16 v[44:47], v[138:141], v[188:191], v[44:47]
	v_mfma_f32_16x16x32_bf16 v[44:47], v[142:145], v[192:195], v[44:47]
	v_mfma_f32_16x16x32_bf16 v[40:43], v[146:149], v[188:191], v[40:43]
	v_mfma_f32_16x16x32_bf16 v[40:43], v[150:153], v[192:195], v[40:43]
	v_mfma_f32_16x16x32_bf16 v[28:31], v[138:141], v[196:199], v[28:31]
	v_mfma_f32_16x16x32_bf16 v[28:31], v[142:145], v[200:203], v[28:31]
	v_mfma_f32_16x16x32_bf16 v[24:27], v[146:149], v[196:199], v[24:27]
	v_mfma_f32_16x16x32_bf16 v[24:27], v[150:153], v[200:203], v[24:27]
	v_mfma_f32_16x16x32_bf16 v[12:15], v[138:141], v[204:207], v[12:15]
	v_mfma_f32_16x16x32_bf16 v[12:15], v[142:145], v[208:211], v[12:15]
	v_mfma_f32_16x16x32_bf16 v[8:11], v[146:149], v[204:207], v[8:11]
	v_mfma_f32_16x16x32_bf16 v[8:11], v[150:153], v[208:211], v[8:11]
	v_mfma_f32_16x16x32_bf16 v[52:55], v[154:157], v[178:181], v[52:55]
	v_mfma_f32_16x16x32_bf16 v[52:55], v[158:161], v[184:187], v[52:55]
	v_mfma_f32_16x16x32_bf16 v[48:51], v[170:173], v[178:181], v[48:51]
	v_mfma_f32_16x16x32_bf16 v[48:51], v[174:177], v[184:187], v[48:51]
	v_mfma_f32_16x16x32_bf16 v[36:39], v[154:157], v[188:191], v[36:39]
	v_mfma_f32_16x16x32_bf16 v[36:39], v[158:161], v[192:195], v[36:39]
	v_mfma_f32_16x16x32_bf16 v[32:35], v[170:173], v[188:191], v[32:35]
	v_mfma_f32_16x16x32_bf16 v[32:35], v[174:177], v[192:195], v[32:35]
	v_mfma_f32_16x16x32_bf16 v[20:23], v[154:157], v[196:199], v[20:23]
	v_mfma_f32_16x16x32_bf16 v[20:23], v[158:161], v[200:203], v[20:23]
	v_mfma_f32_16x16x32_bf16 v[16:19], v[170:173], v[196:199], v[16:19]
	v_mfma_f32_16x16x32_bf16 v[16:19], v[174:177], v[200:203], v[16:19]
	v_mfma_f32_16x16x32_bf16 v[4:7], v[154:157], v[204:207], v[4:7]
	v_mfma_f32_16x16x32_bf16 v[4:7], v[158:161], v[208:211], v[4:7]
	v_mfma_f32_16x16x32_bf16 v[0:3], v[170:173], v[204:207], v[0:3]
	v_mfma_f32_16x16x32_bf16 v[0:3], v[174:177], v[208:211], v[0:3]
	s_barrier
	s_add_i32 s68, s68, 2
	s_add_u32 s46, s46, 0x100
	s_addc_u32 s47, s47, 0
	s_add_u32 s66, s66, 0x100
	s_addc_u32 s67, s67, 0
	s_cmp_gt_u32 s68, 61
	s_cbranch_scc0 .LBB0_742
	s_and_b64 vcc, exec, s[16:17]
	s_cbranch_vccz .LBB0_745
	s_barrier

; #define PG8_STAGE(bufoff, gbase, voff) do { _Pragma("unroll") for (int _i = 0; _i < 2; ++_i) \
;         __builtin_amdgcn_global_load_lds((const unsigned*)((const char*)(gbase) + (voff)[_i]), (LAS unsigned*)(lds + (bufoff) + ldsw + _i * 8192), 16, 0, 0); } while (0)
; #define PG8_LDA(dst, b, h) do { _Pragma("unroll") for (int m = 0; m < 4; ++m) _Pragma("unroll") for (int k = 0; k < 2; ++k) dst[m][k] = *(const LAS bf16x8*)(lds + PG8_SA(b, h) + aoff + m * 2048 + k * 1024); } while (0)
; #define PG8_LDB(dst, b, h) do { _Pragma("unroll") for (int n = 0; n < 2; ++n) _Pragma("unroll") for (int k = 0; k < 2; ++k) dst[n][k] = *(const LAS bf16x8*)(lds + PG8_SB(b, h) + boff + n * 2048 + k * 1024); } while (0)
; #define PG8_MMA(ai, bj, At, Bt) do { __builtin_amdgcn_s_setprio(1); _Pragma("unroll") for (int m = 0; m < 4; ++m) _Pragma("unroll") for (int n = 0; n < 2; ++n) _Pragma("unroll") for (int k = 0; k < 2; ++k) \
;         acc[ai][bj][m][n] = __builtin_amdgcn_mfma_f32_16x16x32_bf16(Bt[n][k], At[m][k], acc[ai][bj][m][n], 0, 0, 0); __builtin_amdgcn_s_setprio(0); } while (0)
; #define PG8_WAIT_V(n) asm volatile("s_waitcnt vmcnt(" #n ")" ::: "memory")
; #define PG8_WAIT_L(n) asm volatile("s_waitcnt lgkmcnt(" #n ")" ::: "memory")
; #define PG8_BAR __builtin_amdgcn_s_barrier()
; #define PG8_SCHED __builtin_amdgcn_sched_barrier(0)
; template <class Epi>
; __device__ __forceinline__ void gemm_phase(LAS unsigned char* lds, const Gemm g, const Order& S, const Epi& E, const int wid) {
;     ...
;             const bool last = (t == nt - 2);
;             const char* a1 = cA + (size_t)(t + 1) * kstep;
;             const char* a2 = last ? nA : cA + (size_t)(t + 2) * kstep; const char* b2 = last ? nB : cB + (size_t)(t + 2) * kstep;
;             const char* a3 = a2 + kstep; const char* b3 = b2 + kstep;
;     ...
;             PG8_LDB(B0, 0, 0); PG8_LDB(B1, 0, 1); PG8_SCHED; PG8_LDA(At, 0, 0); PG8_STAGE(PG8_SA(1, 1), a1 + hA, voffA);
;             PG8_WAIT_V(8); PG8_WAIT_L(0); PG8_BAR; PG8_MMA(0, 0, At, B0); PG8_MMA(0, 1, At, B1); PG8_BAR; PG8_SCHED;
;             PG8_LDA(At, 0, 1); PG8_STAGE(PG8_SB(0, 0), b2, voffB); PG8_STAGE(PG8_SB(0, 1), b2 + hB, voffB); PG8_STAGE(PG8_SA(0, 0), a2, voffA);
;             PG8_WAIT_V(8); PG8_WAIT_L(0); PG8_BAR; PG8_MMA(1, 0, At, B0); PG8_MMA(1, 1, At, B1); PG8_BAR; PG8_SCHED;
.LBB0_821:
	ds_read_b128 v[138:141], v135
	ds_read_b128 v[150:153], v135 offset:1024
	ds_read_b128 v[154:157], v135 offset:2048
	ds_read_b128 v[162:165], v135 offset:3072
	ds_read_b128 v[166:169], v136
	ds_read_b128 v[170:173], v136 offset:1024
	ds_read_b128 v[174:177], v136 offset:2048
	ds_read_b128 v[178:181], v136 offset:3072
	s_add_u32 s54, s46, 0xfff00080
	s_addc_u32 s55, s47, -1
	s_cmp_eq_u32 s63, 60
	s_cselect_b32 s57, s5, s55
	s_cselect_b32 s56, s7, s54
	s_cselect_b32 s55, s39, s62
	s_cselect_b32 s54, s41, s61
	v_lshl_add_u64 v[142:143], s[46:47], 0, v[144:145]
	s_add_i32 m0, s25, 0xc000
	ds_read_b128 v[182:185], v137
	ds_read_b128 v[186:189], v137 offset:1024
	ds_read_b128 v[190:193], v137 offset:2048
	ds_read_b128 v[194:197], v137 offset:3072
	ds_read_b128 v[198:201], v137 offset:4096
	ds_read_b128 v[202:205], v137 offset:5120
	ds_read_b128 v[206:209], v137 offset:6144
	ds_read_b128 v[210:213], v137 offset:7168
	global_load_lds_dwordx4 v[142:143], off
	v_lshl_add_u64 v[142:143], s[46:47], 0, v[132:133]
	s_add_i32 m0, s25, 0xe000
	s_nop 0
	global_load_lds_dwordx4 v[142:143], off
	s_waitcnt vmcnt(8)
	s_waitcnt lgkmcnt(0)
	s_barrier
	s_waitcnt lgkmcnt(0)
	v_mfma_f32_16x16x32_bf16 v[124:127], v[138:141], v[182:185], v[124:127]
	v_mfma_f32_16x16x32_bf16 v[124:127], v[150:153], v[186:189], v[124:127]
	v_mfma_f32_16x16x32_bf16 v[120:123], v[154:157], v[182:185], v[120:123]
	v_mfma_f32_16x16x32_bf16 v[120:123], v[162:165], v[186:189], v[120:123]
	v_mfma_f32_16x16x32_bf16 v[108:111], v[138:141], v[190:193], v[108:111]
	v_mfma_f32_16x16x32_bf16 v[108:111], v[150:153], v[194:197], v[108:111]
	v_mfma_f32_16x16x32_bf16 v[104:107], v[154:157], v[190:193], v[104:107]
	v_mfma_f32_16x16x32_bf16 v[104:107], v[162:165], v[194:197], v[104:107]
	v_mfma_f32_16x16x32_bf16 v[92:95], v[138:141], v[198:201], v[92:95]
	v_mfma_f32_16x16x32_bf16 v[92:95], v[150:153], v[202:205], v[92:95]
	v_mfma_f32_16x16x32_bf16 v[88:91], v[154:157], v[198:201], v[88:91]
	v_mfma_f32_16x16x32_bf16 v[88:91], v[162:165], v[202:205], v[88:91]
	v_mfma_f32_16x16x32_bf16 v[76:79], v[138:141], v[206:209], v[76:79]
	v_mfma_f32_16x16x32_bf16 v[76:79], v[150:153], v[210:213], v[76:79]
	v_mfma_f32_16x16x32_bf16 v[72:75], v[154:157], v[206:209], v[72:75]
	v_mfma_f32_16x16x32_bf16 v[72:75], v[162:165], v[210:213], v[72:75]
	v_mfma_f32_16x16x32_bf16 v[116:119], v[166:169], v[182:185], v[116:119]
	v_mfma_f32_16x16x32_bf16 v[116:119], v[170:173], v[186:189], v[116:119]
	v_mfma_f32_16x16x32_bf16 v[112:115], v[174:177], v[182:185], v[112:115]
	v_mfma_f32_16x16x32_bf16 v[112:115], v[178:181], v[186:189], v[112:115]
	v_mfma_f32_16x16x32_bf16 v[100:103], v[166:169], v[190:193], v[100:103]
	v_mfma_f32_16x16x32_bf16 v[100:103], v[170:173], v[194:197], v[100:103]
	v_mfma_f32_16x16x32_bf16 v[96:99], v[174:177], v[190:193], v[96:99]
	v_mfma_f32_16x16x32_bf16 v[96:99], v[178:181], v[194:197], v[96:99]
	v_mfma_f32_16x16x32_bf16 v[84:87], v[166:169], v[198:201], v[84:87]
	v_mfma_f32_16x16x32_bf16 v[84:87], v[170:173], v[202:205], v[84:87]
	v_mfma_f32_16x16x32_bf16 v[80:83], v[174:177], v[198:201], v[80:83]
	v_mfma_f32_16x16x32_bf16 v[80:83], v[178:181], v[202:205], v[80:83]
	v_mfma_f32_16x16x32_bf16 v[68:71], v[166:169], v[206:209], v[68:71]
	v_mfma_f32_16x16x32_bf16 v[68:71], v[170:173], v[210:213], v[68:71]
	v_mfma_f32_16x16x32_bf16 v[64:67], v[174:177], v[206:209], v[64:67]
	v_mfma_f32_16x16x32_bf16 v[64:67], v[178:181], v[210:213], v[64:67]
	s_barrier
	s_add_i32 s64, s59, s24
	v_lshl_add_u64 v[142:143], s[54:55], 0, v[128:129]
	s_mov_b32 m0, s64
	ds_read_b128 v[182:185], v137 offset:16384
	ds_read_b128 v[186:189], v137 offset:17408
	ds_read_b128 v[190:193], v137 offset:18432
	ds_read_b128 v[194:197], v137 offset:19456
	ds_read_b128 v[198:201], v137 offset:20480
	ds_read_b128 v[202:205], v137 offset:21504
	ds_read_b128 v[206:209], v137 offset:22528
	ds_read_b128 v[210:213], v137 offset:23552
	global_load_lds_dwordx4 v[142:143], off
	s_add_i32 m0, s64, 0x2000
	s_add_u32 s64, s54, 0x100000
	v_lshl_add_u64 v[158:159], s[54:55], 0, v[130:131]
	s_addc_u32 s65, s55, 0
	s_add_i32 s66, s60, s24
	global_load_lds_dwordx4 v[158:159], off
	v_lshl_add_u64 v[214:215], s[64:65], 0, v[128:129]
	s_mov_b32 m0, s66
	v_lshl_add_u64 v[216:217], s[56:57], 0, v[132:133]
	global_load_lds_dwordx4 v[214:215], off
	v_lshl_add_u64 v[214:215], s[64:65], 0, v[130:131]
	s_add_i32 m0, s66, 0x2000
	s_nop 0
	global_load_lds_dwordx4 v[214:215], off
	v_lshl_add_u64 v[214:215], s[56:57], 0, v[144:145]
	s_mov_b32 m0, s25
	s_nop 0
	global_load_lds_dwordx4 v[214:215], off
	s_mov_b32 m0, s26
	s_nop 0
	global_load_lds_dwordx4 v[216:217], off
	s_waitcnt vmcnt(8)
	s_waitcnt lgkmcnt(0)
	s_barrier
; #define PG8_STAGE(bufoff, gbase, voff) do { _Pragma("unroll") for (int _i = 0; _i < 2; ++_i) \
;         __builtin_amdgcn_global_load_lds((const unsigned*)((const char*)(gbase) + (voff)[_i]), (LAS unsigned*)(lds + (bufoff) + ldsw + _i * 8192), 16, 0, 0); } while (0)
; #define PG8_LDA(dst, b, h) do { _Pragma("unroll") for (int m = 0; m < 4; ++m) _Pragma("unroll") for (int k = 0; k < 2; ++k) dst[m][k] = *(const LAS bf16x8*)(lds + PG8_SA(b, h) + aoff + m * 2048 + k * 1024); } while (0)
; #define PG8_LDB(dst, b, h) do { _Pragma("unroll") for (int n = 0; n < 2; ++n) _Pragma("unroll") for (int k = 0; k < 2; ++k) dst[n][k] = *(const LAS bf16x8*)(lds + PG8_SB(b, h) + boff + n * 2048 + k * 1024); } while (0)
; #define PG8_MMA(ai, bj, At, Bt) do { __builtin_amdgcn_s_setprio(1); _Pragma("unroll") for (int m = 0; m < 4; ++m) _Pragma("unroll") for (int n = 0; n < 2; ++n) _Pragma("unroll") for (int k = 0; k < 2; ++k) \
;         acc[ai][bj][m][n] = __builtin_amdgcn_mfma_f32_16x16x32_bf16(Bt[n][k], At[m][k], acc[ai][bj][m][n], 0, 0, 0); __builtin_amdgcn_s_setprio(0); } while (0)
; #define PG8_WAIT_V(n) asm volatile("s_waitcnt vmcnt(" #n ")" ::: "memory")
; #define PG8_WAIT_L(n) asm volatile("s_waitcnt lgkmcnt(" #n ")" ::: "memory")
; #define PG8_BAR __builtin_amdgcn_s_barrier()
; #define PG8_SCHED __builtin_amdgcn_sched_barrier(0)
; template <class Epi>
; __device__ __forceinline__ void gemm_phase(LAS unsigned char* lds, const Gemm g, const Order& S, const Epi& E, const int wid) {
;     ...
;             PG8_WAIT_V(8); PG8_WAIT_L(0); PG8_BAR; PG8_MMA(1, 0, At, B0); PG8_MMA(1, 1, At, B1); PG8_BAR; PG8_SCHED;
;             PG8_LDB(B0, 1, 0); PG8_LDB(B1, 1, 1); PG8_SCHED; PG8_LDA(At, 1, 0); PG8_STAGE(PG8_SA(0, 1), a2 + hA, voffA);
;             PG8_WAIT_V(8); PG8_WAIT_L(0); PG8_BAR; PG8_MMA(0, 0, At, B0); PG8_MMA(0, 1, At, B1); PG8_BAR; PG8_SCHED;
	s_waitcnt lgkmcnt(0)
	v_mfma_f32_16x16x32_bf16 v[60:63], v[138:141], v[182:185], v[60:63]
	v_mfma_f32_16x16x32_bf16 v[60:63], v[150:153], v[186:189], v[60:63]
	v_mfma_f32_16x16x32_bf16 v[56:59], v[154:157], v[182:185], v[56:59]
	v_mfma_f32_16x16x32_bf16 v[56:59], v[162:165], v[186:189], v[56:59]
	v_mfma_f32_16x16x32_bf16 v[44:47], v[138:141], v[190:193], v[44:47]
	v_mfma_f32_16x16x32_bf16 v[44:47], v[150:153], v[194:197], v[44:47]
	v_mfma_f32_16x16x32_bf16 v[40:43], v[154:157], v[190:193], v[40:43]
	v_mfma_f32_16x16x32_bf16 v[40:43], v[162:165], v[194:197], v[40:43]
	v_mfma_f32_16x16x32_bf16 v[28:31], v[138:141], v[198:201], v[28:31]
	v_mfma_f32_16x16x32_bf16 v[28:31], v[150:153], v[202:205], v[28:31]
	v_mfma_f32_16x16x32_bf16 v[24:27], v[154:157], v[198:201], v[24:27]
	v_mfma_f32_16x16x32_bf16 v[24:27], v[162:165], v[202:205], v[24:27]
	v_mfma_f32_16x16x32_bf16 v[12:15], v[138:141], v[206:209], v[12:15]
	v_mfma_f32_16x16x32_bf16 v[12:15], v[150:153], v[210:213], v[12:15]
	v_mfma_f32_16x16x32_bf16 v[8:11], v[154:157], v[206:209], v[8:11]
	v_mfma_f32_16x16x32_bf16 v[8:11], v[162:165], v[210:213], v[8:11]
	v_mfma_f32_16x16x32_bf16 v[52:55], v[166:169], v[182:185], v[52:55]
	v_mfma_f32_16x16x32_bf16 v[52:55], v[170:173], v[186:189], v[52:55]
	v_mfma_f32_16x16x32_bf16 v[48:51], v[174:177], v[182:185], v[48:51]
	v_mfma_f32_16x16x32_bf16 v[48:51], v[178:181], v[186:189], v[48:51]
	v_mfma_f32_16x16x32_bf16 v[36:39], v[166:169], v[190:193], v[36:39]
	v_mfma_f32_16x16x32_bf16 v[36:39], v[170:173], v[194:197], v[36:39]
	v_mfma_f32_16x16x32_bf16 v[32:35], v[174:177], v[190:193], v[32:35]
	v_mfma_f32_16x16x32_bf16 v[32:35], v[178:181], v[194:197], v[32:35]
	v_mfma_f32_16x16x32_bf16 v[20:23], v[166:169], v[198:201], v[20:23]
	v_mfma_f32_16x16x32_bf16 v[20:23], v[170:173], v[202:205], v[20:23]
	v_mfma_f32_16x16x32_bf16 v[16:19], v[174:177], v[198:201], v[16:19]
	v_mfma_f32_16x16x32_bf16 v[16:19], v[178:181], v[202:205], v[16:19]
	v_mfma_f32_16x16x32_bf16 v[4:7], v[166:169], v[206:209], v[4:7]
	v_mfma_f32_16x16x32_bf16 v[4:7], v[170:173], v[210:213], v[4:7]
	v_mfma_f32_16x16x32_bf16 v[0:3], v[174:177], v[206:209], v[0:3]
	v_mfma_f32_16x16x32_bf16 v[0:3], v[178:181], v[210:213], v[0:3]
	s_barrier
	s_add_i32 s64, 0, 0x18000
	s_add_i32 s65, 0, 0x1c000
	v_add_u32_e32 v162, s64, v134
	v_add_u32_e32 v178, s65, v134
	ds_read_b128 v[138:141], v162
	ds_read_b128 v[150:153], v162 offset:1024
	ds_read_b128 v[154:157], v162 offset:2048
	ds_read_b128 v[162:165], v162 offset:3072
	ds_read_b128 v[166:169], v178
	ds_read_b128 v[170:173], v178 offset:1024
	ds_read_b128 v[174:177], v178 offset:2048
	ds_read_b128 v[178:181], v178 offset:3072
	s_add_u32 s56, s56, 0x100000
	s_addc_u32 s57, s57, 0
	s_mov_b32 m0, s27
	v_lshl_add_u64 v[218:219], s[56:57], 0, v[144:145]
	ds_read_b128 v[182:185], v137 offset:32768
	ds_read_b128 v[186:189], v137 offset:33792
	ds_read_b128 v[190:193], v137 offset:34816
	ds_read_b128 v[194:197], v137 offset:35840
	ds_read_b128 v[198:201], v137 offset:36864
	ds_read_b128 v[202:205], v137 offset:37888
	ds_read_b128 v[206:209], v137 offset:38912
	ds_read_b128 v[210:213], v137 offset:39936
	global_load_lds_dwordx4 v[218:219], off
	v_lshl_add_u64 v[218:219], s[56:57], 0, v[132:133]
	s_mov_b32 m0, s28
	s_nop 0
	global_load_lds_dwordx4 v[218:219], off
	s_waitcnt vmcnt(8)
	s_waitcnt lgkmcnt(0)
	s_barrier
	s_waitcnt lgkmcnt(0)
	v_mfma_f32_16x16x32_bf16 v[124:127], v[138:141], v[182:185], v[124:127]
	v_mfma_f32_16x16x32_bf16 v[124:127], v[150:153], v[186:189], v[124:127]
	v_mfma_f32_16x16x32_bf16 v[120:123], v[154:157], v[182:185], v[120:123]
	v_mfma_f32_16x16x32_bf16 v[120:123], v[162:165], v[186:189], v[120:123]
	v_mfma_f32_16x16x32_bf16 v[108:111], v[138:141], v[190:193], v[108:111]
	v_mfma_f32_16x16x32_bf16 v[108:111], v[150:153], v[194:197], v[108:111]
	v_mfma_f32_16x16x32_bf16 v[104:107], v[154:157], v[190:193], v[104:107]
	v_mfma_f32_16x16x32_bf16 v[104:107], v[162:165], v[194:197], v[104:107]
	v_mfma_f32_16x16x32_bf16 v[92:95], v[138:141], v[198:201], v[92:95]
	v_mfma_f32_16x16x32_bf16 v[92:95], v[150:153], v[202:205], v[92:95]
	v_mfma_f32_16x16x32_bf16 v[88:91], v[154:157], v[198:201], v[88:91]
	v_mfma_f32_16x16x32_bf16 v[88:91], v[162:165], v[202:205], v[88:91]
	v_mfma_f32_16x16x32_bf16 v[76:79], v[138:141], v[206:209], v[76:79]
	v_mfma_f32_16x16x32_bf16 v[76:79], v[150:153], v[210:213], v[76:79]
	v_mfma_f32_16x16x32_bf16 v[72:75], v[154:157], v[206:209], v[72:75]
	v_mfma_f32_16x16x32_bf16 v[72:75], v[162:165], v[210:213], v[72:75]
	v_mfma_f32_16x16x32_bf16 v[116:119], v[166:169], v[182:185], v[116:119]
	v_mfma_f32_16x16x32_bf16 v[116:119], v[170:173], v[186:189], v[116:119]
	v_mfma_f32_16x16x32_bf16 v[112:115], v[174:177], v[182:185], v[112:115]
	v_mfma_f32_16x16x32_bf16 v[112:115], v[178:181], v[186:189], v[112:115]
	v_mfma_f32_16x16x32_bf16 v[100:103], v[166:169], v[190:193], v[100:103]
	v_mfma_f32_16x16x32_bf16 v[100:103], v[170:173], v[194:197], v[100:103]
	v_mfma_f32_16x16x32_bf16 v[96:99], v[174:177], v[190:193], v[96:99]
	v_mfma_f32_16x16x32_bf16 v[96:99], v[178:181], v[194:197], v[96:99]
	v_mfma_f32_16x16x32_bf16 v[84:87], v[166:169], v[198:201], v[84:87]
	v_mfma_f32_16x16x32_bf16 v[84:87], v[170:173], v[202:205], v[84:87]
	v_mfma_f32_16x16x32_bf16 v[80:83], v[174:177], v[198:201], v[80:83]
	v_mfma_f32_16x16x32_bf16 v[80:83], v[178:181], v[202:205], v[80:83]
	v_mfma_f32_16x16x32_bf16 v[68:71], v[166:169], v[206:209], v[68:71]
	v_mfma_f32_16x16x32_bf16 v[68:71], v[170:173], v[210:213], v[68:71]
	v_mfma_f32_16x16x32_bf16 v[64:67], v[174:177], v[206:209], v[64:67]
	v_mfma_f32_16x16x32_bf16 v[64:67], v[178:181], v[210:213], v[64:67]
	s_barrier
; #define PG8_STAGE(bufoff, gbase, voff) do { _Pragma("unroll") for (int _i = 0; _i < 2; ++_i) \
;         __builtin_amdgcn_global_load_lds((const unsigned*)((const char*)(gbase) + (voff)[_i]), (LAS unsigned*)(lds + (bufoff) + ldsw + _i * 8192), 16, 0, 0); } while (0)
; #define PG8_LDA(dst, b, h) do { _Pragma("unroll") for (int m = 0; m < 4; ++m) _Pragma("unroll") for (int k = 0; k < 2; ++k) dst[m][k] = *(const LAS bf16x8*)(lds + PG8_SA(b, h) + aoff + m * 2048 + k * 1024); } while (0)
; #define PG8_MMA(ai, bj, At, Bt) do { __builtin_amdgcn_s_setprio(1); _Pragma("unroll") for (int m = 0; m < 4; ++m) _Pragma("unroll") for (int n = 0; n < 2; ++n) _Pragma("unroll") for (int k = 0; k < 2; ++k) \
;         acc[ai][bj][m][n] = __builtin_amdgcn_mfma_f32_16x16x32_bf16(Bt[n][k], At[m][k], acc[ai][bj][m][n], 0, 0, 0); __builtin_amdgcn_s_setprio(0); } while (0)
; #define PG8_WAIT_V(n) asm volatile("s_waitcnt vmcnt(" #n ")" ::: "memory")
; #define PG8_WAIT_L(n) asm volatile("s_waitcnt lgkmcnt(" #n ")" ::: "memory")
; #define PG8_BAR __builtin_amdgcn_s_barrier()
; #define PG8_SCHED __builtin_amdgcn_sched_barrier(0)
; template <class Epi>
; __device__ __forceinline__ void gemm_phase(LAS unsigned char* lds, const Gemm g, const Order& S, const Epi& E, const int wid) {
;     ...
;             PG8_LDA(At, 1, 1); PG8_STAGE(PG8_SB(1, 0), b3, voffB); PG8_STAGE(PG8_SB(1, 1), b3 + hB, voffB); PG8_STAGE(PG8_SA(1, 0), a3, voffA);
;             PG8_WAIT_V(8); PG8_WAIT_L(0); PG8_BAR; PG8_MMA(1, 0, At, B0); PG8_MMA(1, 1, At, B1); PG8_BAR; PG8_SCHED;
	s_add_i32 s56, s64, s24
	v_lshl_add_u64 v[142:143], v[142:143], 0, s[20:21]
	s_mov_b32 m0, s56
	ds_read_b128 v[182:185], v137 offset:49152
	ds_read_b128 v[186:189], v137 offset:50176
	ds_read_b128 v[190:193], v137 offset:51200
	ds_read_b128 v[194:197], v137 offset:52224
	ds_read_b128 v[198:201], v137 offset:53248
	ds_read_b128 v[202:205], v137 offset:54272
	ds_read_b128 v[206:209], v137 offset:55296
	ds_read_b128 v[210:213], v137 offset:56320
	global_load_lds_dwordx4 v[142:143], off
	s_add_i32 m0, s56, 0x2000
	s_add_u32 s54, s54, 0x100080
	v_lshl_add_u64 v[142:143], v[158:159], 0, s[20:21]
	s_addc_u32 s55, s55, 0
	s_add_i32 s56, s65, s24
	global_load_lds_dwordx4 v[142:143], off
	v_lshl_add_u64 v[142:143], s[54:55], 0, v[128:129]
	s_mov_b32 m0, s56
	s_nop 0
	global_load_lds_dwordx4 v[142:143], off
	v_lshl_add_u64 v[142:143], s[54:55], 0, v[130:131]
	s_add_i32 m0, s56, 0x2000
	s_nop 0
	global_load_lds_dwordx4 v[142:143], off
	v_lshl_add_u64 v[142:143], v[214:215], 0, s[20:21]
	s_mov_b32 m0, s50
	s_nop 0
	global_load_lds_dwordx4 v[142:143], off
	v_lshl_add_u64 v[142:143], v[216:217], 0, s[20:21]
	s_mov_b32 m0, s51
	s_nop 0
	global_load_lds_dwordx4 v[142:143], off
	s_waitcnt vmcnt(8)
	s_waitcnt lgkmcnt(0)
	s_barrier
	s_waitcnt lgkmcnt(0)
	v_mfma_f32_16x16x32_bf16 v[60:63], v[138:141], v[182:185], v[60:63]
	v_mfma_f32_16x16x32_bf16 v[60:63], v[150:153], v[186:189], v[60:63]
	v_mfma_f32_16x16x32_bf16 v[56:59], v[154:157], v[182:185], v[56:59]
	v_mfma_f32_16x16x32_bf16 v[56:59], v[162:165], v[186:189], v[56:59]
	v_mfma_f32_16x16x32_bf16 v[44:47], v[138:141], v[190:193], v[44:47]
	v_mfma_f32_16x16x32_bf16 v[44:47], v[150:153], v[194:197], v[44:47]
	v_mfma_f32_16x16x32_bf16 v[40:43], v[154:157], v[190:193], v[40:43]
	v_mfma_f32_16x16x32_bf16 v[40:43], v[162:165], v[194:197], v[40:43]
	v_mfma_f32_16x16x32_bf16 v[28:31], v[138:141], v[198:201], v[28:31]
	v_mfma_f32_16x16x32_bf16 v[28:31], v[150:153], v[202:205], v[28:31]
	v_mfma_f32_16x16x32_bf16 v[24:27], v[154:157], v[198:201], v[24:27]
	v_mfma_f32_16x16x32_bf16 v[24:27], v[162:165], v[202:205], v[24:27]
	v_mfma_f32_16x16x32_bf16 v[12:15], v[138:141], v[206:209], v[12:15]
	v_mfma_f32_16x16x32_bf16 v[12:15], v[150:153], v[210:213], v[12:15]
	v_mfma_f32_16x16x32_bf16 v[8:11], v[154:157], v[206:209], v[8:11]
	v_mfma_f32_16x16x32_bf16 v[8:11], v[162:165], v[210:213], v[8:11]
	v_mfma_f32_16x16x32_bf16 v[52:55], v[166:169], v[182:185], v[52:55]
	v_mfma_f32_16x16x32_bf16 v[52:55], v[170:173], v[186:189], v[52:55]
	v_mfma_f32_16x16x32_bf16 v[48:51], v[174:177], v[182:185], v[48:51]
	v_mfma_f32_16x16x32_bf16 v[48:51], v[178:181], v[186:189], v[48:51]
	v_mfma_f32_16x16x32_bf16 v[36:39], v[166:169], v[190:193], v[36:39]
	v_mfma_f32_16x16x32_bf16 v[36:39], v[170:173], v[194:197], v[36:39]
	v_mfma_f32_16x16x32_bf16 v[32:35], v[174:177], v[190:193], v[32:35]
	v_mfma_f32_16x16x32_bf16 v[32:35], v[178:181], v[194:197], v[32:35]
	v_mfma_f32_16x16x32_bf16 v[20:23], v[166:169], v[198:201], v[20:23]
	v_mfma_f32_16x16x32_bf16 v[20:23], v[170:173], v[202:205], v[20:23]
	v_mfma_f32_16x16x32_bf16 v[16:19], v[174:177], v[198:201], v[16:19]
	v_mfma_f32_16x16x32_bf16 v[16:19], v[178:181], v[202:205], v[16:19]
	v_mfma_f32_16x16x32_bf16 v[4:7], v[166:169], v[206:209], v[4:7]
	v_mfma_f32_16x16x32_bf16 v[4:7], v[170:173], v[210:213], v[4:7]
	v_mfma_f32_16x16x32_bf16 v[0:3], v[174:177], v[206:209], v[0:3]
	v_mfma_f32_16x16x32_bf16 v[0:3], v[178:181], v[210:213], v[0:3]
	s_barrier
	s_add_i32 s63, s63, 2
	s_add_u32 s46, s46, 0x100
	s_addc_u32 s47, s47, 0
	s_add_u32 s61, s61, 0x100
	s_addc_u32 s62, s62, 0
	s_cmp_gt_u32 s63, 61
	s_cbranch_scc0 .LBB0_821
	s_and_b64 vcc, exec, s[12:13]
	s_cbranch_vccz .LBB0_824
	s_barrier

; #define PG8_STAGE(bufoff, gbase, voff) do { _Pragma("unroll") for (int _i = 0; _i < 2; ++_i) \
;         __builtin_amdgcn_global_load_lds((const unsigned*)((const char*)(gbase) + (voff)[_i]), (LAS unsigned*)(lds + (bufoff) + ldsw + _i * 8192), 16, 0, 0); } while (0)
; #define PG8_LDA(dst, b, h) do { _Pragma("unroll") for (int m = 0; m < 4; ++m) _Pragma("unroll") for (int k = 0; k < 2; ++k) dst[m][k] = *(const LAS bf16x8*)(lds + PG8_SA(b, h) + aoff + m * 2048 + k * 1024); } while (0)
; #define PG8_LDB(dst, b, h) do { _Pragma("unroll") for (int n = 0; n < 2; ++n) _Pragma("unroll") for (int k = 0; k < 2; ++k) dst[n][k] = *(const LAS bf16x8*)(lds + PG8_SB(b, h) + boff + n * 2048 + k * 1024); } while (0)
; #define PG8_MMA(ai, bj, At, Bt) do { __builtin_amdgcn_s_setprio(1); _Pragma("unroll") for (int m = 0; m < 4; ++m) _Pragma("unroll") for (int n = 0; n < 2; ++n) _Pragma("unroll") for (int k = 0; k < 2; ++k) \
;         acc[ai][bj][m][n] = __builtin_amdgcn_mfma_f32_16x16x32_bf16(Bt[n][k], At[m][k], acc[ai][bj][m][n], 0, 0, 0); __builtin_amdgcn_s_setprio(0); } while (0)
; #define PG8_WAIT_V(n) asm volatile("s_waitcnt vmcnt(" #n ")" ::: "memory")
; #define PG8_WAIT_L(n) asm volatile("s_waitcnt lgkmcnt(" #n ")" ::: "memory")
; #define PG8_BAR __builtin_amdgcn_s_barrier()
; #define PG8_SCHED __builtin_amdgcn_sched_barrier(0)
; template <class Epi>
; __device__ __forceinline__ void gemm_phase(LAS unsigned char* lds, const Gemm g, const Order& S, const Epi& E, const int wid) {
;     ...
;             const bool last = (t == nt - 2);
;             const char* a1 = cA + (size_t)(t + 1) * kstep;
;             const char* a2 = last ? nA : cA + (size_t)(t + 2) * kstep; const char* b2 = last ? nB : cB + (size_t)(t + 2) * kstep;
;             const char* a3 = a2 + kstep; const char* b3 = b2 + kstep;
;     ...
;             PG8_LDB(B0, 0, 0); PG8_LDB(B1, 0, 1); PG8_SCHED; PG8_LDA(At, 0, 0); PG8_STAGE(PG8_SA(1, 1), a1 + hA, voffA);
;             PG8_WAIT_V(8); PG8_WAIT_L(0); PG8_BAR; PG8_MMA(0, 0, At, B0); PG8_MMA(0, 1, At, B1); PG8_BAR; PG8_SCHED;
;             PG8_LDA(At, 0, 1); PG8_STAGE(PG8_SB(0, 0), b2, voffB); PG8_STAGE(PG8_SB(0, 1), b2 + hB, voffB); PG8_STAGE(PG8_SA(0, 0), a2, voffA);
;             PG8_WAIT_V(8); PG8_WAIT_L(0); PG8_BAR; PG8_MMA(1, 0, At, B0); PG8_MMA(1, 1, At, B1); PG8_BAR; PG8_SCHED;
.LBB0_915:
	ds_read_b128 v[142:145], v139
	ds_read_b128 v[146:149], v139 offset:1024
	ds_read_b128 v[150:153], v139 offset:2048
	ds_read_b128 v[154:157], v139 offset:3072
	ds_read_b128 v[158:161], v140
	ds_read_b128 v[162:165], v140 offset:1024
	ds_read_b128 v[166:169], v140 offset:2048
	ds_read_b128 v[170:173], v140 offset:3072
	s_add_u32 s44, s42, 0xfff00080
	s_addc_u32 s45, s43, -1
	s_cmp_eq_u32 s62, 60
	s_cselect_b32 s47, s11, s45
	s_cselect_b32 s46, s58, s44
	s_cselect_b32 s45, s21, s61
	s_cselect_b32 s44, s59, s60
	v_lshl_add_u64 v[206:207], s[42:43], 0, v[128:129]
	s_add_i32 m0, s33, 0xc000
	ds_read_b128 v[174:177], v141
	ds_read_b128 v[178:181], v141 offset:1024
	ds_read_b128 v[182:185], v141 offset:2048
	ds_read_b128 v[186:189], v141 offset:3072
	ds_read_b128 v[190:193], v141 offset:4096
	ds_read_b128 v[194:197], v141 offset:5120
	ds_read_b128 v[198:201], v141 offset:6144
	ds_read_b128 v[202:205], v141 offset:7168
	global_load_lds_dwordx4 v[206:207], off
	v_lshl_add_u64 v[206:207], s[42:43], 0, v[134:135]
	s_add_i32 m0, s33, 0xe000
	s_nop 0
	global_load_lds_dwordx4 v[206:207], off
	s_waitcnt vmcnt(8)
	s_waitcnt lgkmcnt(0)
	s_barrier
	s_waitcnt lgkmcnt(0)
	v_mfma_f32_16x16x32_bf16 v[124:127], v[142:145], v[174:177], v[124:127]
	v_mfma_f32_16x16x32_bf16 v[124:127], v[146:149], v[178:181], v[124:127]
	v_mfma_f32_16x16x32_bf16 v[120:123], v[150:153], v[174:177], v[120:123]
	v_mfma_f32_16x16x32_bf16 v[120:123], v[154:157], v[178:181], v[120:123]
	v_mfma_f32_16x16x32_bf16 v[116:119], v[142:145], v[182:185], v[116:119]
	v_mfma_f32_16x16x32_bf16 v[116:119], v[146:149], v[186:189], v[116:119]
	v_mfma_f32_16x16x32_bf16 v[112:115], v[150:153], v[182:185], v[112:115]
	v_mfma_f32_16x16x32_bf16 v[112:115], v[154:157], v[186:189], v[112:115]
	v_mfma_f32_16x16x32_bf16 v[100:103], v[142:145], v[190:193], v[100:103]
	v_mfma_f32_16x16x32_bf16 v[100:103], v[146:149], v[194:197], v[100:103]
	v_mfma_f32_16x16x32_bf16 v[96:99], v[150:153], v[190:193], v[96:99]
	v_mfma_f32_16x16x32_bf16 v[96:99], v[154:157], v[194:197], v[96:99]
	v_mfma_f32_16x16x32_bf16 v[84:87], v[142:145], v[198:201], v[84:87]
	v_mfma_f32_16x16x32_bf16 v[84:87], v[146:149], v[202:205], v[84:87]
	v_mfma_f32_16x16x32_bf16 v[80:83], v[150:153], v[198:201], v[80:83]
	v_mfma_f32_16x16x32_bf16 v[80:83], v[154:157], v[202:205], v[80:83]
	v_mfma_f32_16x16x32_bf16 v[108:111], v[158:161], v[174:177], v[108:111]
	v_mfma_f32_16x16x32_bf16 v[108:111], v[162:165], v[178:181], v[108:111]
	v_mfma_f32_16x16x32_bf16 v[104:107], v[166:169], v[174:177], v[104:107]
	v_mfma_f32_16x16x32_bf16 v[104:107], v[170:173], v[178:181], v[104:107]
	v_mfma_f32_16x16x32_bf16 v[92:95], v[158:161], v[182:185], v[92:95]
	v_mfma_f32_16x16x32_bf16 v[92:95], v[162:165], v[186:189], v[92:95]
	v_mfma_f32_16x16x32_bf16 v[88:91], v[166:169], v[182:185], v[88:91]
	v_mfma_f32_16x16x32_bf16 v[88:91], v[170:173], v[186:189], v[88:91]
	v_mfma_f32_16x16x32_bf16 v[76:79], v[158:161], v[190:193], v[76:79]
	v_mfma_f32_16x16x32_bf16 v[76:79], v[162:165], v[194:197], v[76:79]
	v_mfma_f32_16x16x32_bf16 v[72:75], v[166:169], v[190:193], v[72:75]
	v_mfma_f32_16x16x32_bf16 v[72:75], v[170:173], v[194:197], v[72:75]
	v_mfma_f32_16x16x32_bf16 v[68:71], v[158:161], v[198:201], v[68:71]
	v_mfma_f32_16x16x32_bf16 v[68:71], v[162:165], v[202:205], v[68:71]
	v_mfma_f32_16x16x32_bf16 v[64:67], v[166:169], v[198:201], v[64:67]
	v_mfma_f32_16x16x32_bf16 v[64:67], v[170:173], v[202:205], v[64:67]
	s_barrier
	s_add_i32 s63, s54, s24
	v_lshl_add_u64 v[206:207], s[44:45], 0, v[130:131]
	s_mov_b32 m0, s63
	ds_read_b128 v[174:177], v141 offset:16384
	ds_read_b128 v[178:181], v141 offset:17408
	ds_read_b128 v[182:185], v141 offset:18432
	ds_read_b128 v[186:189], v141 offset:19456
	ds_read_b128 v[190:193], v141 offset:20480
	ds_read_b128 v[194:197], v141 offset:21504
	ds_read_b128 v[198:201], v141 offset:22528
	ds_read_b128 v[202:205], v141 offset:23552
	global_load_lds_dwordx4 v[206:207], off
	s_add_i32 m0, s63, 0x2000
	s_add_u32 s64, s44, 0x100000
	v_lshl_add_u64 v[208:209], s[44:45], 0, v[132:133]
	s_addc_u32 s65, s45, 0
	s_add_i32 s63, s55, s24
	global_load_lds_dwordx4 v[208:209], off
	v_lshl_add_u64 v[210:211], s[64:65], 0, v[130:131]
	s_mov_b32 m0, s63
	v_lshl_add_u64 v[212:213], s[46:47], 0, v[134:135]
	global_load_lds_dwordx4 v[210:211], off
	v_lshl_add_u64 v[210:211], s[64:65], 0, v[132:133]
	s_add_i32 m0, s63, 0x2000
	s_nop 0
	global_load_lds_dwordx4 v[210:211], off
	v_lshl_add_u64 v[210:211], s[46:47], 0, v[128:129]
	s_mov_b32 m0, s33
	s_nop 0
	global_load_lds_dwordx4 v[210:211], off
	s_mov_b32 m0, s35
	s_nop 0
	global_load_lds_dwordx4 v[212:213], off
	s_waitcnt vmcnt(8)
	s_waitcnt lgkmcnt(0)
	s_barrier
; #define PG8_STAGE(bufoff, gbase, voff) do { _Pragma("unroll") for (int _i = 0; _i < 2; ++_i) \
;         __builtin_amdgcn_global_load_lds((const unsigned*)((const char*)(gbase) + (voff)[_i]), (LAS unsigned*)(lds + (bufoff) + ldsw + _i * 8192), 16, 0, 0); } while (0)
; #define PG8_LDA(dst, b, h) do { _Pragma("unroll") for (int m = 0; m < 4; ++m) _Pragma("unroll") for (int k = 0; k < 2; ++k) dst[m][k] = *(const LAS bf16x8*)(lds + PG8_SA(b, h) + aoff + m * 2048 + k * 1024); } while (0)
; #define PG8_LDB(dst, b, h) do { _Pragma("unroll") for (int n = 0; n < 2; ++n) _Pragma("unroll") for (int k = 0; k < 2; ++k) dst[n][k] = *(const LAS bf16x8*)(lds + PG8_SB(b, h) + boff + n * 2048 + k * 1024); } while (0)
; #define PG8_MMA(ai, bj, At, Bt) do { __builtin_amdgcn_s_setprio(1); _Pragma("unroll") for (int m = 0; m < 4; ++m) _Pragma("unroll") for (int n = 0; n < 2; ++n) _Pragma("unroll") for (int k = 0; k < 2; ++k) \
;         acc[ai][bj][m][n] = __builtin_amdgcn_mfma_f32_16x16x32_bf16(Bt[n][k], At[m][k], acc[ai][bj][m][n], 0, 0, 0); __builtin_amdgcn_s_setprio(0); } while (0)
; #define PG8_WAIT_V(n) asm volatile("s_waitcnt vmcnt(" #n ")" ::: "memory")
; #define PG8_WAIT_L(n) asm volatile("s_waitcnt lgkmcnt(" #n ")" ::: "memory")
; #define PG8_BAR __builtin_amdgcn_s_barrier()
; #define PG8_SCHED __builtin_amdgcn_sched_barrier(0)
; template <class Epi>
; __device__ __forceinline__ void gemm_phase(LAS unsigned char* lds, const Gemm g, const Order& S, const Epi& E, const int wid) {
;     ...
;             PG8_WAIT_V(8); PG8_WAIT_L(0); PG8_BAR; PG8_MMA(1, 0, At, B0); PG8_MMA(1, 1, At, B1); PG8_BAR; PG8_SCHED;
;             PG8_LDB(B0, 1, 0); PG8_LDB(B1, 1, 1); PG8_SCHED; PG8_LDA(At, 1, 0); PG8_STAGE(PG8_SA(0, 1), a2 + hA, voffA);
;             PG8_WAIT_V(8); PG8_WAIT_L(0); PG8_BAR; PG8_MMA(0, 0, At, B0); PG8_MMA(0, 1, At, B1); PG8_BAR; PG8_SCHED;
	s_waitcnt lgkmcnt(0)
	v_mfma_f32_16x16x32_bf16 v[60:63], v[142:145], v[174:177], v[60:63]
	v_mfma_f32_16x16x32_bf16 v[60:63], v[146:149], v[178:181], v[60:63]
	v_mfma_f32_16x16x32_bf16 v[56:59], v[150:153], v[174:177], v[56:59]
	v_mfma_f32_16x16x32_bf16 v[56:59], v[154:157], v[178:181], v[56:59]
	v_mfma_f32_16x16x32_bf16 v[52:55], v[142:145], v[182:185], v[52:55]
	v_mfma_f32_16x16x32_bf16 v[52:55], v[146:149], v[186:189], v[52:55]
	v_mfma_f32_16x16x32_bf16 v[48:51], v[150:153], v[182:185], v[48:51]
	v_mfma_f32_16x16x32_bf16 v[48:51], v[154:157], v[186:189], v[48:51]
	v_mfma_f32_16x16x32_bf16 v[36:39], v[142:145], v[190:193], v[36:39]
	v_mfma_f32_16x16x32_bf16 v[36:39], v[146:149], v[194:197], v[36:39]
	v_mfma_f32_16x16x32_bf16 v[32:35], v[150:153], v[190:193], v[32:35]
	v_mfma_f32_16x16x32_bf16 v[32:35], v[154:157], v[194:197], v[32:35]
	v_mfma_f32_16x16x32_bf16 v[20:23], v[142:145], v[198:201], v[20:23]
	v_mfma_f32_16x16x32_bf16 v[20:23], v[146:149], v[202:205], v[20:23]
	v_mfma_f32_16x16x32_bf16 v[16:19], v[150:153], v[198:201], v[16:19]
	v_mfma_f32_16x16x32_bf16 v[16:19], v[154:157], v[202:205], v[16:19]
	v_mfma_f32_16x16x32_bf16 v[44:47], v[158:161], v[174:177], v[44:47]
	v_mfma_f32_16x16x32_bf16 v[44:47], v[162:165], v[178:181], v[44:47]
	v_mfma_f32_16x16x32_bf16 v[40:43], v[166:169], v[174:177], v[40:43]
	v_mfma_f32_16x16x32_bf16 v[40:43], v[170:173], v[178:181], v[40:43]
	v_mfma_f32_16x16x32_bf16 v[28:31], v[158:161], v[182:185], v[28:31]
	v_mfma_f32_16x16x32_bf16 v[28:31], v[162:165], v[186:189], v[28:31]
	v_mfma_f32_16x16x32_bf16 v[24:27], v[166:169], v[182:185], v[24:27]
	v_mfma_f32_16x16x32_bf16 v[24:27], v[170:173], v[186:189], v[24:27]
	v_mfma_f32_16x16x32_bf16 v[12:15], v[158:161], v[190:193], v[12:15]
	v_mfma_f32_16x16x32_bf16 v[12:15], v[162:165], v[194:197], v[12:15]
	v_mfma_f32_16x16x32_bf16 v[8:11], v[166:169], v[190:193], v[8:11]
	v_mfma_f32_16x16x32_bf16 v[8:11], v[170:173], v[194:197], v[8:11]
	v_mfma_f32_16x16x32_bf16 v[4:7], v[158:161], v[198:201], v[4:7]
	v_mfma_f32_16x16x32_bf16 v[4:7], v[162:165], v[202:205], v[4:7]
	v_mfma_f32_16x16x32_bf16 v[0:3], v[166:169], v[198:201], v[0:3]
	v_mfma_f32_16x16x32_bf16 v[0:3], v[170:173], v[202:205], v[0:3]
	s_barrier
	s_add_i32 s63, 0, 0x18000
	s_add_i32 s64, 0, 0x1c000
	v_add_u32_e32 v154, s63, v138
	v_add_u32_e32 v170, s64, v138
	ds_read_b128 v[142:145], v154
	ds_read_b128 v[146:149], v154 offset:1024
	ds_read_b128 v[150:153], v154 offset:2048
	ds_read_b128 v[154:157], v154 offset:3072
	ds_read_b128 v[158:161], v170
	ds_read_b128 v[162:165], v170 offset:1024
	ds_read_b128 v[166:169], v170 offset:2048
	ds_read_b128 v[170:173], v170 offset:3072
	s_add_u32 s46, s46, 0x100000
	s_addc_u32 s47, s47, 0
	s_mov_b32 m0, s48
	v_lshl_add_u64 v[214:215], s[46:47], 0, v[128:129]
	ds_read_b128 v[174:177], v141 offset:32768
	ds_read_b128 v[178:181], v141 offset:33792
	ds_read_b128 v[182:185], v141 offset:34816
	ds_read_b128 v[186:189], v141 offset:35840
	ds_read_b128 v[190:193], v141 offset:36864
	ds_read_b128 v[194:197], v141 offset:37888
	ds_read_b128 v[198:201], v141 offset:38912
	ds_read_b128 v[202:205], v141 offset:39936
	global_load_lds_dwordx4 v[214:215], off
	v_lshl_add_u64 v[214:215], s[46:47], 0, v[134:135]
	s_mov_b32 m0, s49
	s_nop 0
	global_load_lds_dwordx4 v[214:215], off
	s_waitcnt vmcnt(8)
	s_waitcnt lgkmcnt(0)
	s_barrier
	s_waitcnt lgkmcnt(0)
	v_mfma_f32_16x16x32_bf16 v[124:127], v[142:145], v[174:177], v[124:127]
	v_mfma_f32_16x16x32_bf16 v[124:127], v[146:149], v[178:181], v[124:127]
	v_mfma_f32_16x16x32_bf16 v[120:123], v[150:153], v[174:177], v[120:123]
	v_mfma_f32_16x16x32_bf16 v[120:123], v[154:157], v[178:181], v[120:123]
	v_mfma_f32_16x16x32_bf16 v[116:119], v[142:145], v[182:185], v[116:119]
	v_mfma_f32_16x16x32_bf16 v[116:119], v[146:149], v[186:189], v[116:119]
	v_mfma_f32_16x16x32_bf16 v[112:115], v[150:153], v[182:185], v[112:115]
	v_mfma_f32_16x16x32_bf16 v[112:115], v[154:157], v[186:189], v[112:115]
	v_mfma_f32_16x16x32_bf16 v[100:103], v[142:145], v[190:193], v[100:103]
	v_mfma_f32_16x16x32_bf16 v[100:103], v[146:149], v[194:197], v[100:103]
	v_mfma_f32_16x16x32_bf16 v[96:99], v[150:153], v[190:193], v[96:99]
	v_mfma_f32_16x16x32_bf16 v[96:99], v[154:157], v[194:197], v[96:99]
	v_mfma_f32_16x16x32_bf16 v[84:87], v[142:145], v[198:201], v[84:87]
	v_mfma_f32_16x16x32_bf16 v[84:87], v[146:149], v[202:205], v[84:87]
	v_mfma_f32_16x16x32_bf16 v[80:83], v[150:153], v[198:201], v[80:83]
	v_mfma_f32_16x16x32_bf16 v[80:83], v[154:157], v[202:205], v[80:83]
	v_mfma_f32_16x16x32_bf16 v[108:111], v[158:161], v[174:177], v[108:111]
	v_mfma_f32_16x16x32_bf16 v[108:111], v[162:165], v[178:181], v[108:111]
	v_mfma_f32_16x16x32_bf16 v[104:107], v[166:169], v[174:177], v[104:107]
	v_mfma_f32_16x16x32_bf16 v[104:107], v[170:173], v[178:181], v[104:107]
	v_mfma_f32_16x16x32_bf16 v[92:95], v[158:161], v[182:185], v[92:95]
	v_mfma_f32_16x16x32_bf16 v[92:95], v[162:165], v[186:189], v[92:95]
	v_mfma_f32_16x16x32_bf16 v[88:91], v[166:169], v[182:185], v[88:91]
	v_mfma_f32_16x16x32_bf16 v[88:91], v[170:173], v[186:189], v[88:91]
	v_mfma_f32_16x16x32_bf16 v[76:79], v[158:161], v[190:193], v[76:79]
	v_mfma_f32_16x16x32_bf16 v[76:79], v[162:165], v[194:197], v[76:79]
	v_mfma_f32_16x16x32_bf16 v[72:75], v[166:169], v[190:193], v[72:75]
	v_mfma_f32_16x16x32_bf16 v[72:75], v[170:173], v[194:197], v[72:75]
	v_mfma_f32_16x16x32_bf16 v[68:71], v[158:161], v[198:201], v[68:71]
	v_mfma_f32_16x16x32_bf16 v[68:71], v[162:165], v[202:205], v[68:71]
	v_mfma_f32_16x16x32_bf16 v[64:67], v[166:169], v[198:201], v[64:67]
	v_mfma_f32_16x16x32_bf16 v[64:67], v[170:173], v[202:205], v[64:67]
	s_barrier
; #define PG8_STAGE(bufoff, gbase, voff) do { _Pragma("unroll") for (int _i = 0; _i < 2; ++_i) \
;         __builtin_amdgcn_global_load_lds((const unsigned*)((const char*)(gbase) + (voff)[_i]), (LAS unsigned*)(lds + (bufoff) + ldsw + _i * 8192), 16, 0, 0); } while (0)
; #define PG8_LDA(dst, b, h) do { _Pragma("unroll") for (int m = 0; m < 4; ++m) _Pragma("unroll") for (int k = 0; k < 2; ++k) dst[m][k] = *(const LAS bf16x8*)(lds + PG8_SA(b, h) + aoff + m * 2048 + k * 1024); } while (0)
; #define PG8_MMA(ai, bj, At, Bt) do { __builtin_amdgcn_s_setprio(1); _Pragma("unroll") for (int m = 0; m < 4; ++m) _Pragma("unroll") for (int n = 0; n < 2; ++n) _Pragma("unroll") for (int k = 0; k < 2; ++k) \
;         acc[ai][bj][m][n] = __builtin_amdgcn_mfma_f32_16x16x32_bf16(Bt[n][k], At[m][k], acc[ai][bj][m][n], 0, 0, 0); __builtin_amdgcn_s_setprio(0); } while (0)
; #define PG8_WAIT_V(n) asm volatile("s_waitcnt vmcnt(" #n ")" ::: "memory")
; #define PG8_WAIT_L(n) asm volatile("s_waitcnt lgkmcnt(" #n ")" ::: "memory")
; #define PG8_BAR __builtin_amdgcn_s_barrier()
; #define PG8_SCHED __builtin_amdgcn_sched_barrier(0)
; template <class Epi>
; __device__ __forceinline__ void gemm_phase(LAS unsigned char* lds, const Gemm g, const Order& S, const Epi& E, const int wid) {
;     ...
;             PG8_LDA(At, 1, 1); PG8_STAGE(PG8_SB(1, 0), b3, voffB); PG8_STAGE(PG8_SB(1, 1), b3 + hB, voffB); PG8_STAGE(PG8_SA(1, 0), a3, voffA);
;             PG8_WAIT_V(8); PG8_WAIT_L(0); PG8_BAR; PG8_MMA(1, 0, At, B0); PG8_MMA(1, 1, At, B1); PG8_BAR; PG8_SCHED;
	s_add_i32 s46, s63, s24
	v_lshl_add_u64 v[206:207], v[206:207], 0, s[8:9]
	s_mov_b32 m0, s46
	ds_read_b128 v[174:177], v141 offset:49152
	ds_read_b128 v[178:181], v141 offset:50176
	ds_read_b128 v[182:185], v141 offset:51200
	ds_read_b128 v[186:189], v141 offset:52224
	ds_read_b128 v[190:193], v141 offset:53248
	ds_read_b128 v[194:197], v141 offset:54272
	ds_read_b128 v[198:201], v141 offset:55296
	ds_read_b128 v[202:205], v141 offset:56320
	global_load_lds_dwordx4 v[206:207], off
	s_add_i32 m0, s46, 0x2000
	s_add_u32 s44, s44, 0x100080
	v_lshl_add_u64 v[206:207], v[208:209], 0, s[8:9]
	s_addc_u32 s45, s45, 0
	s_add_i32 s46, s64, s24
	global_load_lds_dwordx4 v[206:207], off
	v_lshl_add_u64 v[206:207], s[44:45], 0, v[130:131]
	s_mov_b32 m0, s46
	s_nop 0
	global_load_lds_dwordx4 v[206:207], off
	v_lshl_add_u64 v[206:207], s[44:45], 0, v[132:133]
	s_add_i32 m0, s46, 0x2000
	s_nop 0
	global_load_lds_dwordx4 v[206:207], off
	v_lshl_add_u64 v[206:207], v[210:211], 0, s[8:9]
	s_mov_b32 m0, s50
	s_nop 0
	global_load_lds_dwordx4 v[206:207], off
	v_lshl_add_u64 v[206:207], v[212:213], 0, s[8:9]
	s_mov_b32 m0, s51
	s_nop 0
	global_load_lds_dwordx4 v[206:207], off
	s_waitcnt vmcnt(8)
	s_waitcnt lgkmcnt(0)
	s_barrier
	s_waitcnt lgkmcnt(0)
	v_mfma_f32_16x16x32_bf16 v[60:63], v[142:145], v[174:177], v[60:63]
	v_mfma_f32_16x16x32_bf16 v[60:63], v[146:149], v[178:181], v[60:63]
	v_mfma_f32_16x16x32_bf16 v[56:59], v[150:153], v[174:177], v[56:59]
	v_mfma_f32_16x16x32_bf16 v[56:59], v[154:157], v[178:181], v[56:59]
	v_mfma_f32_16x16x32_bf16 v[52:55], v[142:145], v[182:185], v[52:55]
	v_mfma_f32_16x16x32_bf16 v[52:55], v[146:149], v[186:189], v[52:55]
	v_mfma_f32_16x16x32_bf16 v[48:51], v[150:153], v[182:185], v[48:51]
	v_mfma_f32_16x16x32_bf16 v[48:51], v[154:157], v[186:189], v[48:51]
	v_mfma_f32_16x16x32_bf16 v[36:39], v[142:145], v[190:193], v[36:39]
	v_mfma_f32_16x16x32_bf16 v[36:39], v[146:149], v[194:197], v[36:39]
	v_mfma_f32_16x16x32_bf16 v[32:35], v[150:153], v[190:193], v[32:35]
	v_mfma_f32_16x16x32_bf16 v[32:35], v[154:157], v[194:197], v[32:35]
	v_mfma_f32_16x16x32_bf16 v[20:23], v[142:145], v[198:201], v[20:23]
	v_mfma_f32_16x16x32_bf16 v[20:23], v[146:149], v[202:205], v[20:23]
	v_mfma_f32_16x16x32_bf16 v[16:19], v[150:153], v[198:201], v[16:19]
	v_mfma_f32_16x16x32_bf16 v[16:19], v[154:157], v[202:205], v[16:19]
	v_mfma_f32_16x16x32_bf16 v[44:47], v[158:161], v[174:177], v[44:47]
	v_mfma_f32_16x16x32_bf16 v[44:47], v[162:165], v[178:181], v[44:47]
	v_mfma_f32_16x16x32_bf16 v[40:43], v[166:169], v[174:177], v[40:43]
	v_mfma_f32_16x16x32_bf16 v[40:43], v[170:173], v[178:181], v[40:43]
	v_mfma_f32_16x16x32_bf16 v[28:31], v[158:161], v[182:185], v[28:31]
	v_mfma_f32_16x16x32_bf16 v[28:31], v[162:165], v[186:189], v[28:31]
	v_mfma_f32_16x16x32_bf16 v[24:27], v[166:169], v[182:185], v[24:27]
	v_mfma_f32_16x16x32_bf16 v[24:27], v[170:173], v[186:189], v[24:27]
	v_mfma_f32_16x16x32_bf16 v[12:15], v[158:161], v[190:193], v[12:15]
	v_mfma_f32_16x16x32_bf16 v[12:15], v[162:165], v[194:197], v[12:15]
	v_mfma_f32_16x16x32_bf16 v[8:11], v[166:169], v[190:193], v[8:11]
	v_mfma_f32_16x16x32_bf16 v[8:11], v[170:173], v[194:197], v[8:11]
	v_mfma_f32_16x16x32_bf16 v[4:7], v[158:161], v[198:201], v[4:7]
	v_mfma_f32_16x16x32_bf16 v[4:7], v[162:165], v[202:205], v[4:7]
	v_mfma_f32_16x16x32_bf16 v[0:3], v[166:169], v[198:201], v[0:3]
	v_mfma_f32_16x16x32_bf16 v[0:3], v[170:173], v[202:205], v[0:3]
	s_barrier
	s_add_i32 s62, s62, 2
	s_add_u32 s42, s42, 0x100
	s_addc_u32 s43, s43, 0
	s_add_u32 s60, s60, 0x100
	s_addc_u32 s61, s61, 0
	s_cmp_gt_u32 s62, 61
	s_cbranch_scc0 .LBB0_915
	s_and_b64 vcc, exec, s[16:17]
	s_cbranch_vccz .LBB0_918
	s_barrier

; #define PG8_STAGE(bufoff, gbase, voff) do { _Pragma("unroll") for (int _i = 0; _i < 2; ++_i) \
;         __builtin_amdgcn_global_load_lds((const unsigned*)((const char*)(gbase) + (voff)[_i]), (LAS unsigned*)(lds + (bufoff) + ldsw + _i * 8192), 16, 0, 0); } while (0)
; #define PG8_LDA(dst, b, h) do { _Pragma("unroll") for (int m = 0; m < 4; ++m) _Pragma("unroll") for (int k = 0; k < 2; ++k) dst[m][k] = *(const LAS bf16x8*)(lds + PG8_SA(b, h) + aoff + m * 2048 + k * 1024); } while (0)
; #define PG8_LDB(dst, b, h) do { _Pragma("unroll") for (int n = 0; n < 2; ++n) _Pragma("unroll") for (int k = 0; k < 2; ++k) dst[n][k] = *(const LAS bf16x8*)(lds + PG8_SB(b, h) + boff + n * 2048 + k * 1024); } while (0)
; #define PG8_MMA(ai, bj, At, Bt) do { __builtin_amdgcn_s_setprio(1); _Pragma("unroll") for (int m = 0; m < 4; ++m) _Pragma("unroll") for (int n = 0; n < 2; ++n) _Pragma("unroll") for (int k = 0; k < 2; ++k) \
;         acc[ai][bj][m][n] = __builtin_amdgcn_mfma_f32_16x16x32_bf16(Bt[n][k], At[m][k], acc[ai][bj][m][n], 0, 0, 0); __builtin_amdgcn_s_setprio(0); } while (0)
; #define PG8_WAIT_V(n) asm volatile("s_waitcnt vmcnt(" #n ")" ::: "memory")
; #define PG8_WAIT_L(n) asm volatile("s_waitcnt lgkmcnt(" #n ")" ::: "memory")
; #define PG8_BAR __builtin_amdgcn_s_barrier()
; #define PG8_SCHED __builtin_amdgcn_sched_barrier(0)
; template <class Epi>
; __device__ __forceinline__ void gemm_phase(LAS unsigned char* lds, const Gemm g, const Order& S, const Epi& E, const int wid) {
;     ...
;             const bool last = (t == nt - 2);
;             const char* a1 = cA + (size_t)(t + 1) * kstep;
;             const char* a2 = last ? nA : cA + (size_t)(t + 2) * kstep; const char* b2 = last ? nB : cB + (size_t)(t + 2) * kstep;
;             const char* a3 = a2 + kstep; const char* b3 = b2 + kstep;
;     ...
;             PG8_LDB(B0, 0, 0); PG8_LDB(B1, 0, 1); PG8_SCHED; PG8_LDA(At, 0, 0); PG8_STAGE(PG8_SA(1, 1), a1 + hA, voffA);
;             PG8_WAIT_V(8); PG8_WAIT_L(0); PG8_BAR; PG8_MMA(0, 0, At, B0); PG8_MMA(0, 1, At, B1); PG8_BAR; PG8_SCHED;
;             PG8_LDA(At, 0, 1); PG8_STAGE(PG8_SB(0, 0), b2, voffB); PG8_STAGE(PG8_SB(0, 1), b2 + hB, voffB); PG8_STAGE(PG8_SA(0, 0), a2, voffA);
;             PG8_WAIT_V(8); PG8_WAIT_L(0); PG8_BAR; PG8_MMA(1, 0, At, B0); PG8_MMA(1, 1, At, B1); PG8_BAR; PG8_SCHED;
.LBB0_954:
	ds_read_b128 v[142:145], v138
	ds_read_b128 v[146:149], v138 offset:1024
	ds_read_b128 v[150:153], v138 offset:2048
	ds_read_b128 v[154:157], v138 offset:3072
	ds_read_b128 v[158:161], v139
	ds_read_b128 v[162:165], v139 offset:1024
	ds_read_b128 v[166:169], v139 offset:2048
	ds_read_b128 v[170:173], v139 offset:3072
	s_add_u32 s38, s36, 0xfff00080
	s_addc_u32 s39, s37, -1
	s_cmp_eq_u32 s59, 60
	s_cselect_b32 s41, s11, s39
	s_cselect_b32 s40, s55, s38
	s_cselect_b32 s39, s19, s58
	s_cselect_b32 s38, s56, s57
	v_lshl_add_u64 v[206:207], s[36:37], 0, v[128:129]
	s_add_i32 m0, s43, 0xc000
	ds_read_b128 v[174:177], v140
	ds_read_b128 v[178:181], v140 offset:1024
	ds_read_b128 v[182:185], v140 offset:2048
	ds_read_b128 v[186:189], v140 offset:3072
	ds_read_b128 v[190:193], v140 offset:4096
	ds_read_b128 v[194:197], v140 offset:5120
	ds_read_b128 v[198:201], v140 offset:6144
	ds_read_b128 v[202:205], v140 offset:7168
	global_load_lds_dwordx4 v[206:207], off
	v_lshl_add_u64 v[206:207], s[36:37], 0, v[134:135]
	s_add_i32 m0, s43, 0xe000
	s_nop 0
	global_load_lds_dwordx4 v[206:207], off
	s_waitcnt vmcnt(8)
	s_waitcnt lgkmcnt(0)
	s_barrier
	s_waitcnt lgkmcnt(0)
	v_mfma_f32_16x16x32_bf16 v[124:127], v[142:145], v[174:177], v[124:127]
	v_mfma_f32_16x16x32_bf16 v[124:127], v[146:149], v[178:181], v[124:127]
	v_mfma_f32_16x16x32_bf16 v[120:123], v[150:153], v[174:177], v[120:123]
	v_mfma_f32_16x16x32_bf16 v[120:123], v[154:157], v[178:181], v[120:123]
	v_mfma_f32_16x16x32_bf16 v[116:119], v[142:145], v[182:185], v[116:119]
	v_mfma_f32_16x16x32_bf16 v[116:119], v[146:149], v[186:189], v[116:119]
	v_mfma_f32_16x16x32_bf16 v[112:115], v[150:153], v[182:185], v[112:115]
	v_mfma_f32_16x16x32_bf16 v[112:115], v[154:157], v[186:189], v[112:115]
	v_mfma_f32_16x16x32_bf16 v[100:103], v[142:145], v[190:193], v[100:103]
	v_mfma_f32_16x16x32_bf16 v[100:103], v[146:149], v[194:197], v[100:103]
	v_mfma_f32_16x16x32_bf16 v[96:99], v[150:153], v[190:193], v[96:99]
	v_mfma_f32_16x16x32_bf16 v[96:99], v[154:157], v[194:197], v[96:99]
	v_mfma_f32_16x16x32_bf16 v[84:87], v[142:145], v[198:201], v[84:87]
	v_mfma_f32_16x16x32_bf16 v[84:87], v[146:149], v[202:205], v[84:87]
	v_mfma_f32_16x16x32_bf16 v[80:83], v[150:153], v[198:201], v[80:83]
	v_mfma_f32_16x16x32_bf16 v[80:83], v[154:157], v[202:205], v[80:83]
	v_mfma_f32_16x16x32_bf16 v[108:111], v[158:161], v[174:177], v[108:111]
	v_mfma_f32_16x16x32_bf16 v[108:111], v[162:165], v[178:181], v[108:111]
	v_mfma_f32_16x16x32_bf16 v[104:107], v[166:169], v[174:177], v[104:107]
	v_mfma_f32_16x16x32_bf16 v[104:107], v[170:173], v[178:181], v[104:107]
	v_mfma_f32_16x16x32_bf16 v[92:95], v[158:161], v[182:185], v[92:95]
	v_mfma_f32_16x16x32_bf16 v[92:95], v[162:165], v[186:189], v[92:95]
	v_mfma_f32_16x16x32_bf16 v[88:91], v[166:169], v[182:185], v[88:91]
	v_mfma_f32_16x16x32_bf16 v[88:91], v[170:173], v[186:189], v[88:91]
	v_mfma_f32_16x16x32_bf16 v[76:79], v[158:161], v[190:193], v[76:79]
	v_mfma_f32_16x16x32_bf16 v[76:79], v[162:165], v[194:197], v[76:79]
	v_mfma_f32_16x16x32_bf16 v[72:75], v[166:169], v[190:193], v[72:75]
	v_mfma_f32_16x16x32_bf16 v[72:75], v[170:173], v[194:197], v[72:75]
	v_mfma_f32_16x16x32_bf16 v[68:71], v[158:161], v[198:201], v[68:71]
	v_mfma_f32_16x16x32_bf16 v[68:71], v[162:165], v[202:205], v[68:71]
	v_mfma_f32_16x16x32_bf16 v[64:67], v[166:169], v[198:201], v[64:67]
	v_mfma_f32_16x16x32_bf16 v[64:67], v[170:173], v[202:205], v[64:67]
	s_barrier
	s_add_i32 s60, s50, s24
	v_lshl_add_u64 v[206:207], s[38:39], 0, v[130:131]
	s_mov_b32 m0, s60
	ds_read_b128 v[174:177], v140 offset:16384
	ds_read_b128 v[178:181], v140 offset:17408
	ds_read_b128 v[182:185], v140 offset:18432
	ds_read_b128 v[186:189], v140 offset:19456
	ds_read_b128 v[190:193], v140 offset:20480
	ds_read_b128 v[194:197], v140 offset:21504
	ds_read_b128 v[198:201], v140 offset:22528
	ds_read_b128 v[202:205], v140 offset:23552
	global_load_lds_dwordx4 v[206:207], off
	s_add_i32 m0, s60, 0x2000
	s_add_u32 s60, s38, 0x100000
	v_lshl_add_u64 v[208:209], s[38:39], 0, v[132:133]
	s_addc_u32 s61, s39, 0
	s_add_i32 s62, s51, s24
	global_load_lds_dwordx4 v[208:209], off
	v_lshl_add_u64 v[210:211], s[60:61], 0, v[130:131]
	s_mov_b32 m0, s62
	v_lshl_add_u64 v[212:213], s[40:41], 0, v[134:135]
	global_load_lds_dwordx4 v[210:211], off
	v_lshl_add_u64 v[210:211], s[60:61], 0, v[132:133]
	s_add_i32 m0, s62, 0x2000
	s_nop 0
	global_load_lds_dwordx4 v[210:211], off
	v_lshl_add_u64 v[210:211], s[40:41], 0, v[128:129]
	s_mov_b32 m0, s43
	s_nop 0
	global_load_lds_dwordx4 v[210:211], off
	s_mov_b32 m0, s44
	s_nop 0
	global_load_lds_dwordx4 v[212:213], off
	s_waitcnt vmcnt(8)
	s_waitcnt lgkmcnt(0)
	s_barrier
; #define PG8_STAGE(bufoff, gbase, voff) do { _Pragma("unroll") for (int _i = 0; _i < 2; ++_i) \
;         __builtin_amdgcn_global_load_lds((const unsigned*)((const char*)(gbase) + (voff)[_i]), (LAS unsigned*)(lds + (bufoff) + ldsw + _i * 8192), 16, 0, 0); } while (0)
; #define PG8_LDA(dst, b, h) do { _Pragma("unroll") for (int m = 0; m < 4; ++m) _Pragma("unroll") for (int k = 0; k < 2; ++k) dst[m][k] = *(const LAS bf16x8*)(lds + PG8_SA(b, h) + aoff + m * 2048 + k * 1024); } while (0)
; #define PG8_LDB(dst, b, h) do { _Pragma("unroll") for (int n = 0; n < 2; ++n) _Pragma("unroll") for (int k = 0; k < 2; ++k) dst[n][k] = *(const LAS bf16x8*)(lds + PG8_SB(b, h) + boff + n * 2048 + k * 1024); } while (0)
; #define PG8_MMA(ai, bj, At, Bt) do { __builtin_amdgcn_s_setprio(1); _Pragma("unroll") for (int m = 0; m < 4; ++m) _Pragma("unroll") for (int n = 0; n < 2; ++n) _Pragma("unroll") for (int k = 0; k < 2; ++k) \
;         acc[ai][bj][m][n] = __builtin_amdgcn_mfma_f32_16x16x32_bf16(Bt[n][k], At[m][k], acc[ai][bj][m][n], 0, 0, 0); __builtin_amdgcn_s_setprio(0); } while (0)
; #define PG8_WAIT_V(n) asm volatile("s_waitcnt vmcnt(" #n ")" ::: "memory")
; #define PG8_WAIT_L(n) asm volatile("s_waitcnt lgkmcnt(" #n ")" ::: "memory")
; #define PG8_BAR __builtin_amdgcn_s_barrier()
; #define PG8_SCHED __builtin_amdgcn_sched_barrier(0)
; template <class Epi>
; __device__ __forceinline__ void gemm_phase(LAS unsigned char* lds, const Gemm g, const Order& S, const Epi& E, const int wid) {
;     ...
;             PG8_WAIT_V(8); PG8_WAIT_L(0); PG8_BAR; PG8_MMA(1, 0, At, B0); PG8_MMA(1, 1, At, B1); PG8_BAR; PG8_SCHED;
;             PG8_LDB(B0, 1, 0); PG8_LDB(B1, 1, 1); PG8_SCHED; PG8_LDA(At, 1, 0); PG8_STAGE(PG8_SA(0, 1), a2 + hA, voffA);
;             PG8_WAIT_V(8); PG8_WAIT_L(0); PG8_BAR; PG8_MMA(0, 0, At, B0); PG8_MMA(0, 1, At, B1); PG8_BAR; PG8_SCHED;
	s_waitcnt lgkmcnt(0)
	v_mfma_f32_16x16x32_bf16 v[60:63], v[142:145], v[174:177], v[60:63]
	v_mfma_f32_16x16x32_bf16 v[60:63], v[146:149], v[178:181], v[60:63]
	v_mfma_f32_16x16x32_bf16 v[56:59], v[150:153], v[174:177], v[56:59]
	v_mfma_f32_16x16x32_bf16 v[56:59], v[154:157], v[178:181], v[56:59]
	v_mfma_f32_16x16x32_bf16 v[52:55], v[142:145], v[182:185], v[52:55]
	v_mfma_f32_16x16x32_bf16 v[52:55], v[146:149], v[186:189], v[52:55]
	v_mfma_f32_16x16x32_bf16 v[48:51], v[150:153], v[182:185], v[48:51]
	v_mfma_f32_16x16x32_bf16 v[48:51], v[154:157], v[186:189], v[48:51]
	v_mfma_f32_16x16x32_bf16 v[36:39], v[142:145], v[190:193], v[36:39]
	v_mfma_f32_16x16x32_bf16 v[36:39], v[146:149], v[194:197], v[36:39]
	v_mfma_f32_16x16x32_bf16 v[32:35], v[150:153], v[190:193], v[32:35]
	v_mfma_f32_16x16x32_bf16 v[32:35], v[154:157], v[194:197], v[32:35]
	v_mfma_f32_16x16x32_bf16 v[20:23], v[142:145], v[198:201], v[20:23]
	v_mfma_f32_16x16x32_bf16 v[20:23], v[146:149], v[202:205], v[20:23]
	v_mfma_f32_16x16x32_bf16 v[16:19], v[150:153], v[198:201], v[16:19]
	v_mfma_f32_16x16x32_bf16 v[16:19], v[154:157], v[202:205], v[16:19]
	v_mfma_f32_16x16x32_bf16 v[44:47], v[158:161], v[174:177], v[44:47]
	v_mfma_f32_16x16x32_bf16 v[44:47], v[162:165], v[178:181], v[44:47]
	v_mfma_f32_16x16x32_bf16 v[40:43], v[166:169], v[174:177], v[40:43]
	v_mfma_f32_16x16x32_bf16 v[40:43], v[170:173], v[178:181], v[40:43]
	v_mfma_f32_16x16x32_bf16 v[28:31], v[158:161], v[182:185], v[28:31]
	v_mfma_f32_16x16x32_bf16 v[28:31], v[162:165], v[186:189], v[28:31]
	v_mfma_f32_16x16x32_bf16 v[24:27], v[166:169], v[182:185], v[24:27]
	v_mfma_f32_16x16x32_bf16 v[24:27], v[170:173], v[186:189], v[24:27]
	v_mfma_f32_16x16x32_bf16 v[12:15], v[158:161], v[190:193], v[12:15]
	v_mfma_f32_16x16x32_bf16 v[12:15], v[162:165], v[194:197], v[12:15]
	v_mfma_f32_16x16x32_bf16 v[8:11], v[166:169], v[190:193], v[8:11]
	v_mfma_f32_16x16x32_bf16 v[8:11], v[170:173], v[194:197], v[8:11]
	v_mfma_f32_16x16x32_bf16 v[4:7], v[158:161], v[198:201], v[4:7]
	v_mfma_f32_16x16x32_bf16 v[4:7], v[162:165], v[202:205], v[4:7]
	v_mfma_f32_16x16x32_bf16 v[0:3], v[166:169], v[198:201], v[0:3]
	v_mfma_f32_16x16x32_bf16 v[0:3], v[170:173], v[202:205], v[0:3]
	s_barrier
	s_add_i32 s60, 0, 0x18000
	v_add_u32_e32 v141, s60, v137
	s_add_i32 s61, 0, 0x1c000
	ds_read_b128 v[142:145], v141
	ds_read_b128 v[146:149], v141 offset:1024
	ds_read_b128 v[150:153], v141 offset:2048
	ds_read_b128 v[154:157], v141 offset:3072
	v_add_u32_e32 v141, s61, v137
	ds_read_b128 v[158:161], v141
	ds_read_b128 v[162:165], v141 offset:1024
	ds_read_b128 v[166:169], v141 offset:2048
	ds_read_b128 v[170:173], v141 offset:3072
	s_add_u32 s40, s40, 0x100000
	s_addc_u32 s41, s41, 0
	s_mov_b32 m0, s45
	v_lshl_add_u64 v[214:215], s[40:41], 0, v[128:129]
	ds_read_b128 v[174:177], v140 offset:32768
	ds_read_b128 v[178:181], v140 offset:33792
	ds_read_b128 v[182:185], v140 offset:34816
	ds_read_b128 v[186:189], v140 offset:35840
	ds_read_b128 v[190:193], v140 offset:36864
	ds_read_b128 v[194:197], v140 offset:37888
	ds_read_b128 v[198:201], v140 offset:38912
	ds_read_b128 v[202:205], v140 offset:39936
	global_load_lds_dwordx4 v[214:215], off
	v_lshl_add_u64 v[214:215], s[40:41], 0, v[134:135]
	s_mov_b32 m0, s46
	s_nop 0
	global_load_lds_dwordx4 v[214:215], off
	s_waitcnt vmcnt(8)
	s_waitcnt lgkmcnt(0)
	s_barrier
	s_waitcnt lgkmcnt(0)
	v_mfma_f32_16x16x32_bf16 v[124:127], v[142:145], v[174:177], v[124:127]
	v_mfma_f32_16x16x32_bf16 v[124:127], v[146:149], v[178:181], v[124:127]
	v_mfma_f32_16x16x32_bf16 v[120:123], v[150:153], v[174:177], v[120:123]
	v_mfma_f32_16x16x32_bf16 v[120:123], v[154:157], v[178:181], v[120:123]
	v_mfma_f32_16x16x32_bf16 v[116:119], v[142:145], v[182:185], v[116:119]
	v_mfma_f32_16x16x32_bf16 v[116:119], v[146:149], v[186:189], v[116:119]
	v_mfma_f32_16x16x32_bf16 v[112:115], v[150:153], v[182:185], v[112:115]
	v_mfma_f32_16x16x32_bf16 v[112:115], v[154:157], v[186:189], v[112:115]
	v_mfma_f32_16x16x32_bf16 v[100:103], v[142:145], v[190:193], v[100:103]
	v_mfma_f32_16x16x32_bf16 v[100:103], v[146:149], v[194:197], v[100:103]
	v_mfma_f32_16x16x32_bf16 v[96:99], v[150:153], v[190:193], v[96:99]
	v_mfma_f32_16x16x32_bf16 v[96:99], v[154:157], v[194:197], v[96:99]
	v_mfma_f32_16x16x32_bf16 v[84:87], v[142:145], v[198:201], v[84:87]
	v_mfma_f32_16x16x32_bf16 v[84:87], v[146:149], v[202:205], v[84:87]
	v_mfma_f32_16x16x32_bf16 v[80:83], v[150:153], v[198:201], v[80:83]
	v_mfma_f32_16x16x32_bf16 v[80:83], v[154:157], v[202:205], v[80:83]
	v_mfma_f32_16x16x32_bf16 v[108:111], v[158:161], v[174:177], v[108:111]
	v_mfma_f32_16x16x32_bf16 v[108:111], v[162:165], v[178:181], v[108:111]
	v_mfma_f32_16x16x32_bf16 v[104:107], v[166:169], v[174:177], v[104:107]
	v_mfma_f32_16x16x32_bf16 v[104:107], v[170:173], v[178:181], v[104:107]
	v_mfma_f32_16x16x32_bf16 v[92:95], v[158:161], v[182:185], v[92:95]
	v_mfma_f32_16x16x32_bf16 v[92:95], v[162:165], v[186:189], v[92:95]
	v_mfma_f32_16x16x32_bf16 v[88:91], v[166:169], v[182:185], v[88:91]
	v_mfma_f32_16x16x32_bf16 v[88:91], v[170:173], v[186:189], v[88:91]
	v_mfma_f32_16x16x32_bf16 v[76:79], v[158:161], v[190:193], v[76:79]
	v_mfma_f32_16x16x32_bf16 v[76:79], v[162:165], v[194:197], v[76:79]
	v_mfma_f32_16x16x32_bf16 v[72:75], v[166:169], v[190:193], v[72:75]
	v_mfma_f32_16x16x32_bf16 v[72:75], v[170:173], v[194:197], v[72:75]
	v_mfma_f32_16x16x32_bf16 v[68:71], v[158:161], v[198:201], v[68:71]
	v_mfma_f32_16x16x32_bf16 v[68:71], v[162:165], v[202:205], v[68:71]
	v_mfma_f32_16x16x32_bf16 v[64:67], v[166:169], v[198:201], v[64:67]
	v_mfma_f32_16x16x32_bf16 v[64:67], v[170:173], v[202:205], v[64:67]
	s_barrier
; #define PG8_STAGE(bufoff, gbase, voff) do { _Pragma("unroll") for (int _i = 0; _i < 2; ++_i) \
;         __builtin_amdgcn_global_load_lds((const unsigned*)((const char*)(gbase) + (voff)[_i]), (LAS unsigned*)(lds + (bufoff) + ldsw + _i * 8192), 16, 0, 0); } while (0)
; #define PG8_LDA(dst, b, h) do { _Pragma("unroll") for (int m = 0; m < 4; ++m) _Pragma("unroll") for (int k = 0; k < 2; ++k) dst[m][k] = *(const LAS bf16x8*)(lds + PG8_SA(b, h) + aoff + m * 2048 + k * 1024); } while (0)
; #define PG8_MMA(ai, bj, At, Bt) do { __builtin_amdgcn_s_setprio(1); _Pragma("unroll") for (int m = 0; m < 4; ++m) _Pragma("unroll") for (int n = 0; n < 2; ++n) _Pragma("unroll") for (int k = 0; k < 2; ++k) \
;         acc[ai][bj][m][n] = __builtin_amdgcn_mfma_f32_16x16x32_bf16(Bt[n][k], At[m][k], acc[ai][bj][m][n], 0, 0, 0); __builtin_amdgcn_s_setprio(0); } while (0)
; #define PG8_WAIT_V(n) asm volatile("s_waitcnt vmcnt(" #n ")" ::: "memory")
; #define PG8_WAIT_L(n) asm volatile("s_waitcnt lgkmcnt(" #n ")" ::: "memory")
; #define PG8_BAR __builtin_amdgcn_s_barrier()
; #define PG8_SCHED __builtin_amdgcn_sched_barrier(0)
; template <class Epi>
; __device__ __forceinline__ void gemm_phase(LAS unsigned char* lds, const Gemm g, const Order& S, const Epi& E, const int wid) {
;     ...
;             PG8_LDA(At, 1, 1); PG8_STAGE(PG8_SB(1, 0), b3, voffB); PG8_STAGE(PG8_SB(1, 1), b3 + hB, voffB); PG8_STAGE(PG8_SA(1, 0), a3, voffA);
;             PG8_WAIT_V(8); PG8_WAIT_L(0); PG8_BAR; PG8_MMA(1, 0, At, B0); PG8_MMA(1, 1, At, B1); PG8_BAR; PG8_SCHED;
	s_add_i32 s40, s60, s24
	v_lshl_add_u64 v[206:207], v[206:207], 0, s[8:9]
	s_mov_b32 m0, s40
	ds_read_b128 v[174:177], v140 offset:49152
	ds_read_b128 v[178:181], v140 offset:50176
	ds_read_b128 v[182:185], v140 offset:51200
	ds_read_b128 v[186:189], v140 offset:52224
	ds_read_b128 v[190:193], v140 offset:53248
	ds_read_b128 v[194:197], v140 offset:54272
	ds_read_b128 v[198:201], v140 offset:55296
	ds_read_b128 v[202:205], v140 offset:56320
	global_load_lds_dwordx4 v[206:207], off
	s_add_i32 m0, s40, 0x2000
	s_add_u32 s38, s38, 0x100080
	v_lshl_add_u64 v[206:207], v[208:209], 0, s[8:9]
	s_addc_u32 s39, s39, 0
	s_add_i32 s40, s61, s24
	global_load_lds_dwordx4 v[206:207], off
	v_lshl_add_u64 v[206:207], s[38:39], 0, v[130:131]
	s_mov_b32 m0, s40
	s_nop 0
	global_load_lds_dwordx4 v[206:207], off
	v_lshl_add_u64 v[206:207], s[38:39], 0, v[132:133]
	s_add_i32 m0, s40, 0x2000
	s_nop 0
	global_load_lds_dwordx4 v[206:207], off
	v_lshl_add_u64 v[206:207], v[210:211], 0, s[8:9]
	s_mov_b32 m0, s47
	s_nop 0
	global_load_lds_dwordx4 v[206:207], off
	v_lshl_add_u64 v[206:207], v[212:213], 0, s[8:9]
	s_mov_b32 m0, s48
	s_nop 0
	global_load_lds_dwordx4 v[206:207], off
	s_waitcnt vmcnt(8)
	s_waitcnt lgkmcnt(0)
	s_barrier
	s_waitcnt lgkmcnt(0)
	v_mfma_f32_16x16x32_bf16 v[60:63], v[142:145], v[174:177], v[60:63]
	v_mfma_f32_16x16x32_bf16 v[60:63], v[146:149], v[178:181], v[60:63]
	v_mfma_f32_16x16x32_bf16 v[56:59], v[150:153], v[174:177], v[56:59]
	v_mfma_f32_16x16x32_bf16 v[56:59], v[154:157], v[178:181], v[56:59]
	v_mfma_f32_16x16x32_bf16 v[52:55], v[142:145], v[182:185], v[52:55]
	v_mfma_f32_16x16x32_bf16 v[52:55], v[146:149], v[186:189], v[52:55]
	v_mfma_f32_16x16x32_bf16 v[48:51], v[150:153], v[182:185], v[48:51]
	v_mfma_f32_16x16x32_bf16 v[48:51], v[154:157], v[186:189], v[48:51]
	v_mfma_f32_16x16x32_bf16 v[36:39], v[142:145], v[190:193], v[36:39]
	v_mfma_f32_16x16x32_bf16 v[36:39], v[146:149], v[194:197], v[36:39]
	v_mfma_f32_16x16x32_bf16 v[32:35], v[150:153], v[190:193], v[32:35]
	v_mfma_f32_16x16x32_bf16 v[32:35], v[154:157], v[194:197], v[32:35]
	v_mfma_f32_16x16x32_bf16 v[20:23], v[142:145], v[198:201], v[20:23]
	v_mfma_f32_16x16x32_bf16 v[20:23], v[146:149], v[202:205], v[20:23]
	v_mfma_f32_16x16x32_bf16 v[16:19], v[150:153], v[198:201], v[16:19]
	v_mfma_f32_16x16x32_bf16 v[16:19], v[154:157], v[202:205], v[16:19]
	v_mfma_f32_16x16x32_bf16 v[44:47], v[158:161], v[174:177], v[44:47]
	v_mfma_f32_16x16x32_bf16 v[44:47], v[162:165], v[178:181], v[44:47]
	v_mfma_f32_16x16x32_bf16 v[40:43], v[166:169], v[174:177], v[40:43]
	v_mfma_f32_16x16x32_bf16 v[40:43], v[170:173], v[178:181], v[40:43]
	v_mfma_f32_16x16x32_bf16 v[28:31], v[158:161], v[182:185], v[28:31]
	v_mfma_f32_16x16x32_bf16 v[28:31], v[162:165], v[186:189], v[28:31]
	v_mfma_f32_16x16x32_bf16 v[24:27], v[166:169], v[182:185], v[24:27]
	v_mfma_f32_16x16x32_bf16 v[24:27], v[170:173], v[186:189], v[24:27]
	v_mfma_f32_16x16x32_bf16 v[12:15], v[158:161], v[190:193], v[12:15]
	v_mfma_f32_16x16x32_bf16 v[12:15], v[162:165], v[194:197], v[12:15]
	v_mfma_f32_16x16x32_bf16 v[8:11], v[166:169], v[190:193], v[8:11]
	v_mfma_f32_16x16x32_bf16 v[8:11], v[170:173], v[194:197], v[8:11]
	v_mfma_f32_16x16x32_bf16 v[4:7], v[158:161], v[198:201], v[4:7]
	v_mfma_f32_16x16x32_bf16 v[4:7], v[162:165], v[202:205], v[4:7]
	v_mfma_f32_16x16x32_bf16 v[0:3], v[166:169], v[198:201], v[0:3]
	v_mfma_f32_16x16x32_bf16 v[0:3], v[170:173], v[202:205], v[0:3]
	s_barrier
	s_add_i32 s59, s59, 2
	s_add_u32 s36, s36, 0x100
	s_addc_u32 s37, s37, 0
	s_add_u32 s57, s57, 0x100
	s_addc_u32 s58, s58, 0
	s_cmp_gt_u32 s59, 61
	s_cbranch_scc0 .LBB0_954
	s_and_b64 vcc, exec, s[16:17]
	s_cbranch_vccz .LBB0_957
	s_barrier

; #define PG8_STAGE(bufoff, gbase, voff) do { _Pragma("unroll") for (int _i = 0; _i < 2; ++_i) \
;         __builtin_amdgcn_global_load_lds((const unsigned*)((const char*)(gbase) + (voff)[_i]), (LAS unsigned*)(lds + (bufoff) + ldsw + _i * 8192), 16, 0, 0); } while (0)
; #define PG8_LDA(dst, b, h) do { _Pragma("unroll") for (int m = 0; m < 4; ++m) _Pragma("unroll") for (int k = 0; k < 2; ++k) dst[m][k] = *(const LAS bf16x8*)(lds + PG8_SA(b, h) + aoff + m * 2048 + k * 1024); } while (0)
; #define PG8_LDB(dst, b, h) do { _Pragma("unroll") for (int n = 0; n < 2; ++n) _Pragma("unroll") for (int k = 0; k < 2; ++k) dst[n][k] = *(const LAS bf16x8*)(lds + PG8_SB(b, h) + boff + n * 2048 + k * 1024); } while (0)
; #define PG8_MMA(ai, bj, At, Bt) do { __builtin_amdgcn_s_setprio(1); _Pragma("unroll") for (int m = 0; m < 4; ++m) _Pragma("unroll") for (int n = 0; n < 2; ++n) _Pragma("unroll") for (int k = 0; k < 2; ++k) \
;         acc[ai][bj][m][n] = __builtin_amdgcn_mfma_f32_16x16x32_bf16(Bt[n][k], At[m][k], acc[ai][bj][m][n], 0, 0, 0); __builtin_amdgcn_s_setprio(0); } while (0)
; #define PG8_WAIT_V(n) asm volatile("s_waitcnt vmcnt(" #n ")" ::: "memory")
; #define PG8_WAIT_L(n) asm volatile("s_waitcnt lgkmcnt(" #n ")" ::: "memory")
; #define PG8_BAR __builtin_amdgcn_s_barrier()
; #define PG8_SCHED __builtin_amdgcn_sched_barrier(0)
; template <class Epi>
; __device__ __forceinline__ void gemm_phase(LAS unsigned char* lds, const Gemm g, const Order& S, const Epi& E, const int wid) {
;     ...
;             const bool last = (t == nt - 2);
;             const char* a1 = cA + (size_t)(t + 1) * kstep;
;             const char* a2 = last ? nA : cA + (size_t)(t + 2) * kstep; const char* b2 = last ? nB : cB + (size_t)(t + 2) * kstep;
;             const char* a3 = a2 + kstep; const char* b3 = b2 + kstep;
;     ...
;             PG8_LDB(B0, 0, 0); PG8_LDB(B1, 0, 1); PG8_SCHED; PG8_LDA(At, 0, 0); PG8_STAGE(PG8_SA(1, 1), a1 + hA, voffA);
;             PG8_WAIT_V(8); PG8_WAIT_L(0); PG8_BAR; PG8_MMA(0, 0, At, B0); PG8_MMA(0, 1, At, B1); PG8_BAR; PG8_SCHED;
;             PG8_LDA(At, 0, 1); PG8_STAGE(PG8_SB(0, 0), b2, voffB); PG8_STAGE(PG8_SB(0, 1), b2 + hB, voffB); PG8_STAGE(PG8_SA(0, 0), a2, voffA);
;             PG8_WAIT_V(8); PG8_WAIT_L(0); PG8_BAR; PG8_MMA(1, 0, At, B0); PG8_MMA(1, 1, At, B1); PG8_BAR; PG8_SCHED;
.LBB0_1035:
	ds_read_b128 v[146:149], v142
	ds_read_b128 v[150:153], v142 offset:1024
	ds_read_b128 v[154:157], v142 offset:2048
	ds_read_b128 v[158:161], v142 offset:3072
	ds_read_b128 v[162:165], v143
	ds_read_b128 v[166:169], v143 offset:1024
	ds_read_b128 v[170:173], v143 offset:2048
	ds_read_b128 v[174:177], v143 offset:3072
	s_add_u32 s38, s36, 0xfff00080
	s_addc_u32 s39, s37, -1
	s_cmp_eq_u32 s61, 12
	s_cselect_b32 s41, s7, s39
	s_cselect_b32 s40, s6, s38
	s_cselect_b32 s39, s23, s60
	s_cselect_b32 s38, s22, s21
	v_lshl_add_u64 v[210:211], s[36:37], 0, v[128:129]
	s_add_i32 m0, s29, 0xc000
	ds_read_b128 v[178:181], v144
	ds_read_b128 v[182:185], v144 offset:1024
	ds_read_b128 v[186:189], v144 offset:2048
	ds_read_b128 v[190:193], v144 offset:3072
	ds_read_b128 v[194:197], v144 offset:4096
	ds_read_b128 v[198:201], v144 offset:5120
	ds_read_b128 v[202:205], v144 offset:6144
	ds_read_b128 v[206:209], v144 offset:7168
	global_load_lds_dwordx4 v[210:211], off
	v_lshl_add_u64 v[210:211], s[36:37], 0, v[138:139]
	s_add_i32 m0, s29, 0xe000
	s_nop 0
	global_load_lds_dwordx4 v[210:211], off
	s_waitcnt vmcnt(8)
	s_waitcnt lgkmcnt(0)
	s_barrier
	s_waitcnt lgkmcnt(0)
	v_mfma_f32_16x16x32_bf16 v[124:127], v[146:149], v[178:181], v[124:127]
	v_mfma_f32_16x16x32_bf16 v[124:127], v[150:153], v[182:185], v[124:127]
	v_mfma_f32_16x16x32_bf16 v[120:123], v[154:157], v[178:181], v[120:123]
	v_mfma_f32_16x16x32_bf16 v[120:123], v[158:161], v[182:185], v[120:123]
	v_mfma_f32_16x16x32_bf16 v[116:119], v[146:149], v[186:189], v[116:119]
	v_mfma_f32_16x16x32_bf16 v[116:119], v[150:153], v[190:193], v[116:119]
	v_mfma_f32_16x16x32_bf16 v[112:115], v[154:157], v[186:189], v[112:115]
	v_mfma_f32_16x16x32_bf16 v[112:115], v[158:161], v[190:193], v[112:115]
	v_mfma_f32_16x16x32_bf16 v[100:103], v[146:149], v[194:197], v[100:103]
	v_mfma_f32_16x16x32_bf16 v[100:103], v[150:153], v[198:201], v[100:103]
	v_mfma_f32_16x16x32_bf16 v[96:99], v[154:157], v[194:197], v[96:99]
	v_mfma_f32_16x16x32_bf16 v[96:99], v[158:161], v[198:201], v[96:99]
	v_mfma_f32_16x16x32_bf16 v[84:87], v[146:149], v[202:205], v[84:87]
	v_mfma_f32_16x16x32_bf16 v[84:87], v[150:153], v[206:209], v[84:87]
	v_mfma_f32_16x16x32_bf16 v[80:83], v[154:157], v[202:205], v[80:83]
	v_mfma_f32_16x16x32_bf16 v[80:83], v[158:161], v[206:209], v[80:83]
	v_mfma_f32_16x16x32_bf16 v[108:111], v[162:165], v[178:181], v[108:111]
	v_mfma_f32_16x16x32_bf16 v[108:111], v[166:169], v[182:185], v[108:111]
	v_mfma_f32_16x16x32_bf16 v[104:107], v[170:173], v[178:181], v[104:107]
	v_mfma_f32_16x16x32_bf16 v[104:107], v[174:177], v[182:185], v[104:107]
	v_mfma_f32_16x16x32_bf16 v[92:95], v[162:165], v[186:189], v[92:95]
	v_mfma_f32_16x16x32_bf16 v[92:95], v[166:169], v[190:193], v[92:95]
	v_mfma_f32_16x16x32_bf16 v[88:91], v[170:173], v[186:189], v[88:91]
	v_mfma_f32_16x16x32_bf16 v[88:91], v[174:177], v[190:193], v[88:91]
	v_mfma_f32_16x16x32_bf16 v[76:79], v[162:165], v[194:197], v[76:79]
	v_mfma_f32_16x16x32_bf16 v[76:79], v[166:169], v[198:201], v[76:79]
	v_mfma_f32_16x16x32_bf16 v[72:75], v[170:173], v[194:197], v[72:75]
	v_mfma_f32_16x16x32_bf16 v[72:75], v[174:177], v[198:201], v[72:75]
	v_mfma_f32_16x16x32_bf16 v[68:71], v[162:165], v[202:205], v[68:71]
	v_mfma_f32_16x16x32_bf16 v[68:71], v[166:169], v[206:209], v[68:71]
	v_mfma_f32_16x16x32_bf16 v[64:67], v[170:173], v[202:205], v[64:67]
	v_mfma_f32_16x16x32_bf16 v[64:67], v[174:177], v[206:209], v[64:67]
	s_barrier
	s_add_i32 s62, s56, s24
	v_lshl_add_u64 v[210:211], s[38:39], 0, v[134:135]
	s_mov_b32 m0, s62
	ds_read_b128 v[178:181], v144 offset:16384
	ds_read_b128 v[182:185], v144 offset:17408
	ds_read_b128 v[186:189], v144 offset:18432
	ds_read_b128 v[190:193], v144 offset:19456
	ds_read_b128 v[194:197], v144 offset:20480
	ds_read_b128 v[198:201], v144 offset:21504
	ds_read_b128 v[202:205], v144 offset:22528
	ds_read_b128 v[206:209], v144 offset:23552
	global_load_lds_dwordx4 v[210:211], off
	s_add_i32 m0, s62, 0x2000
	s_add_u32 s62, s38, 0x100000
	v_lshl_add_u64 v[212:213], s[38:39], 0, v[136:137]
	s_addc_u32 s63, s39, 0
	s_add_i32 s64, s57, s24
	global_load_lds_dwordx4 v[212:213], off
	v_lshl_add_u64 v[214:215], s[62:63], 0, v[134:135]
	s_mov_b32 m0, s64
	v_lshl_add_u64 v[216:217], s[40:41], 0, v[138:139]
	global_load_lds_dwordx4 v[214:215], off
	v_lshl_add_u64 v[214:215], s[62:63], 0, v[136:137]
	s_add_i32 m0, s64, 0x2000
	s_nop 0
	global_load_lds_dwordx4 v[214:215], off
	v_lshl_add_u64 v[214:215], s[40:41], 0, v[128:129]
	s_mov_b32 m0, s29
	s_nop 0
	global_load_lds_dwordx4 v[214:215], off
	s_mov_b32 m0, s47
	s_nop 0
	global_load_lds_dwordx4 v[216:217], off
	s_waitcnt vmcnt(8)
	s_waitcnt lgkmcnt(0)
	s_barrier
; #define PG8_STAGE(bufoff, gbase, voff) do { _Pragma("unroll") for (int _i = 0; _i < 2; ++_i) \
;         __builtin_amdgcn_global_load_lds((const unsigned*)((const char*)(gbase) + (voff)[_i]), (LAS unsigned*)(lds + (bufoff) + ldsw + _i * 8192), 16, 0, 0); } while (0)
; #define PG8_LDA(dst, b, h) do { _Pragma("unroll") for (int m = 0; m < 4; ++m) _Pragma("unroll") for (int k = 0; k < 2; ++k) dst[m][k] = *(const LAS bf16x8*)(lds + PG8_SA(b, h) + aoff + m * 2048 + k * 1024); } while (0)
; #define PG8_LDB(dst, b, h) do { _Pragma("unroll") for (int n = 0; n < 2; ++n) _Pragma("unroll") for (int k = 0; k < 2; ++k) dst[n][k] = *(const LAS bf16x8*)(lds + PG8_SB(b, h) + boff + n * 2048 + k * 1024); } while (0)
; #define PG8_MMA(ai, bj, At, Bt) do { __builtin_amdgcn_s_setprio(1); _Pragma("unroll") for (int m = 0; m < 4; ++m) _Pragma("unroll") for (int n = 0; n < 2; ++n) _Pragma("unroll") for (int k = 0; k < 2; ++k) \
;         acc[ai][bj][m][n] = __builtin_amdgcn_mfma_f32_16x16x32_bf16(Bt[n][k], At[m][k], acc[ai][bj][m][n], 0, 0, 0); __builtin_amdgcn_s_setprio(0); } while (0)
; #define PG8_WAIT_V(n) asm volatile("s_waitcnt vmcnt(" #n ")" ::: "memory")
; #define PG8_WAIT_L(n) asm volatile("s_waitcnt lgkmcnt(" #n ")" ::: "memory")
; #define PG8_BAR __builtin_amdgcn_s_barrier()
; #define PG8_SCHED __builtin_amdgcn_sched_barrier(0)
; template <class Epi>
; __device__ __forceinline__ void gemm_phase(LAS unsigned char* lds, const Gemm g, const Order& S, const Epi& E, const int wid) {
;     ...
;             PG8_WAIT_V(8); PG8_WAIT_L(0); PG8_BAR; PG8_MMA(1, 0, At, B0); PG8_MMA(1, 1, At, B1); PG8_BAR; PG8_SCHED;
;             PG8_LDB(B0, 1, 0); PG8_LDB(B1, 1, 1); PG8_SCHED; PG8_LDA(At, 1, 0); PG8_STAGE(PG8_SA(0, 1), a2 + hA, voffA);
;             PG8_WAIT_V(8); PG8_WAIT_L(0); PG8_BAR; PG8_MMA(0, 0, At, B0); PG8_MMA(0, 1, At, B1); PG8_BAR; PG8_SCHED;
	s_waitcnt lgkmcnt(0)
	v_mfma_f32_16x16x32_bf16 v[60:63], v[146:149], v[178:181], v[60:63]
	v_mfma_f32_16x16x32_bf16 v[60:63], v[150:153], v[182:185], v[60:63]
	v_mfma_f32_16x16x32_bf16 v[56:59], v[154:157], v[178:181], v[56:59]
	v_mfma_f32_16x16x32_bf16 v[56:59], v[158:161], v[182:185], v[56:59]
	v_mfma_f32_16x16x32_bf16 v[52:55], v[146:149], v[186:189], v[52:55]
	v_mfma_f32_16x16x32_bf16 v[52:55], v[150:153], v[190:193], v[52:55]
	v_mfma_f32_16x16x32_bf16 v[48:51], v[154:157], v[186:189], v[48:51]
	v_mfma_f32_16x16x32_bf16 v[48:51], v[158:161], v[190:193], v[48:51]
	v_mfma_f32_16x16x32_bf16 v[36:39], v[146:149], v[194:197], v[36:39]
	v_mfma_f32_16x16x32_bf16 v[36:39], v[150:153], v[198:201], v[36:39]
	v_mfma_f32_16x16x32_bf16 v[32:35], v[154:157], v[194:197], v[32:35]
	v_mfma_f32_16x16x32_bf16 v[32:35], v[158:161], v[198:201], v[32:35]
	v_mfma_f32_16x16x32_bf16 v[20:23], v[146:149], v[202:205], v[20:23]
	v_mfma_f32_16x16x32_bf16 v[20:23], v[150:153], v[206:209], v[20:23]
	v_mfma_f32_16x16x32_bf16 v[16:19], v[154:157], v[202:205], v[16:19]
	v_mfma_f32_16x16x32_bf16 v[16:19], v[158:161], v[206:209], v[16:19]
	v_mfma_f32_16x16x32_bf16 v[44:47], v[162:165], v[178:181], v[44:47]
	v_mfma_f32_16x16x32_bf16 v[44:47], v[166:169], v[182:185], v[44:47]
	v_mfma_f32_16x16x32_bf16 v[40:43], v[170:173], v[178:181], v[40:43]
	v_mfma_f32_16x16x32_bf16 v[40:43], v[174:177], v[182:185], v[40:43]
	v_mfma_f32_16x16x32_bf16 v[28:31], v[162:165], v[186:189], v[28:31]
	v_mfma_f32_16x16x32_bf16 v[28:31], v[166:169], v[190:193], v[28:31]
	v_mfma_f32_16x16x32_bf16 v[24:27], v[170:173], v[186:189], v[24:27]
	v_mfma_f32_16x16x32_bf16 v[24:27], v[174:177], v[190:193], v[24:27]
	v_mfma_f32_16x16x32_bf16 v[12:15], v[162:165], v[194:197], v[12:15]
	v_mfma_f32_16x16x32_bf16 v[12:15], v[166:169], v[198:201], v[12:15]
	v_mfma_f32_16x16x32_bf16 v[8:11], v[170:173], v[194:197], v[8:11]
	v_mfma_f32_16x16x32_bf16 v[8:11], v[174:177], v[198:201], v[8:11]
	v_mfma_f32_16x16x32_bf16 v[4:7], v[162:165], v[202:205], v[4:7]
	v_mfma_f32_16x16x32_bf16 v[4:7], v[166:169], v[206:209], v[4:7]
	v_mfma_f32_16x16x32_bf16 v[0:3], v[170:173], v[202:205], v[0:3]
	v_mfma_f32_16x16x32_bf16 v[0:3], v[174:177], v[206:209], v[0:3]
	s_barrier
	s_add_i32 s62, 0, 0x18000
	v_add_u32_e32 v145, s62, v141
	s_add_i32 s63, 0, 0x1c000
	ds_read_b128 v[146:149], v145
	ds_read_b128 v[150:153], v145 offset:1024
	ds_read_b128 v[154:157], v145 offset:2048
	ds_read_b128 v[158:161], v145 offset:3072
	v_add_u32_e32 v145, s63, v141
	ds_read_b128 v[162:165], v145
	ds_read_b128 v[166:169], v145 offset:1024
	ds_read_b128 v[170:173], v145 offset:2048
	ds_read_b128 v[174:177], v145 offset:3072
	s_add_u32 s40, s40, 0x100000
	s_addc_u32 s41, s41, 0
	s_mov_b32 m0, s48
	v_lshl_add_u64 v[218:219], s[40:41], 0, v[128:129]
	ds_read_b128 v[178:181], v144 offset:32768
	ds_read_b128 v[182:185], v144 offset:33792
	ds_read_b128 v[186:189], v144 offset:34816
	ds_read_b128 v[190:193], v144 offset:35840
	ds_read_b128 v[194:197], v144 offset:36864
	ds_read_b128 v[198:201], v144 offset:37888
	ds_read_b128 v[202:205], v144 offset:38912
	ds_read_b128 v[206:209], v144 offset:39936
	global_load_lds_dwordx4 v[218:219], off
	v_lshl_add_u64 v[218:219], s[40:41], 0, v[138:139]
	s_mov_b32 m0, s49
	s_nop 0
	global_load_lds_dwordx4 v[218:219], off
	s_waitcnt vmcnt(8)
	s_waitcnt lgkmcnt(0)
	s_barrier
	s_waitcnt lgkmcnt(0)
	v_mfma_f32_16x16x32_bf16 v[124:127], v[146:149], v[178:181], v[124:127]
	v_mfma_f32_16x16x32_bf16 v[124:127], v[150:153], v[182:185], v[124:127]
	v_mfma_f32_16x16x32_bf16 v[120:123], v[154:157], v[178:181], v[120:123]
	v_mfma_f32_16x16x32_bf16 v[120:123], v[158:161], v[182:185], v[120:123]
	v_mfma_f32_16x16x32_bf16 v[116:119], v[146:149], v[186:189], v[116:119]
	v_mfma_f32_16x16x32_bf16 v[116:119], v[150:153], v[190:193], v[116:119]
	v_mfma_f32_16x16x32_bf16 v[112:115], v[154:157], v[186:189], v[112:115]
	v_mfma_f32_16x16x32_bf16 v[112:115], v[158:161], v[190:193], v[112:115]
	v_mfma_f32_16x16x32_bf16 v[100:103], v[146:149], v[194:197], v[100:103]
	v_mfma_f32_16x16x32_bf16 v[100:103], v[150:153], v[198:201], v[100:103]
	v_mfma_f32_16x16x32_bf16 v[96:99], v[154:157], v[194:197], v[96:99]
	v_mfma_f32_16x16x32_bf16 v[96:99], v[158:161], v[198:201], v[96:99]
	v_mfma_f32_16x16x32_bf16 v[84:87], v[146:149], v[202:205], v[84:87]
	v_mfma_f32_16x16x32_bf16 v[84:87], v[150:153], v[206:209], v[84:87]
	v_mfma_f32_16x16x32_bf16 v[80:83], v[154:157], v[202:205], v[80:83]
	v_mfma_f32_16x16x32_bf16 v[80:83], v[158:161], v[206:209], v[80:83]
	v_mfma_f32_16x16x32_bf16 v[108:111], v[162:165], v[178:181], v[108:111]
	v_mfma_f32_16x16x32_bf16 v[108:111], v[166:169], v[182:185], v[108:111]
	v_mfma_f32_16x16x32_bf16 v[104:107], v[170:173], v[178:181], v[104:107]
	v_mfma_f32_16x16x32_bf16 v[104:107], v[174:177], v[182:185], v[104:107]
	v_mfma_f32_16x16x32_bf16 v[92:95], v[162:165], v[186:189], v[92:95]
	v_mfma_f32_16x16x32_bf16 v[92:95], v[166:169], v[190:193], v[92:95]
	v_mfma_f32_16x16x32_bf16 v[88:91], v[170:173], v[186:189], v[88:91]
	v_mfma_f32_16x16x32_bf16 v[88:91], v[174:177], v[190:193], v[88:91]
	v_mfma_f32_16x16x32_bf16 v[76:79], v[162:165], v[194:197], v[76:79]
	v_mfma_f32_16x16x32_bf16 v[76:79], v[166:169], v[198:201], v[76:79]
	v_mfma_f32_16x16x32_bf16 v[72:75], v[170:173], v[194:197], v[72:75]
	v_mfma_f32_16x16x32_bf16 v[72:75], v[174:177], v[198:201], v[72:75]
	v_mfma_f32_16x16x32_bf16 v[68:71], v[162:165], v[202:205], v[68:71]
	v_mfma_f32_16x16x32_bf16 v[68:71], v[166:169], v[206:209], v[68:71]
	v_mfma_f32_16x16x32_bf16 v[64:67], v[170:173], v[202:205], v[64:67]
	v_mfma_f32_16x16x32_bf16 v[64:67], v[174:177], v[206:209], v[64:67]
	s_barrier
; #define PG8_STAGE(bufoff, gbase, voff) do { _Pragma("unroll") for (int _i = 0; _i < 2; ++_i) \
;         __builtin_amdgcn_global_load_lds((const unsigned*)((const char*)(gbase) + (voff)[_i]), (LAS unsigned*)(lds + (bufoff) + ldsw + _i * 8192), 16, 0, 0); } while (0)
; #define PG8_LDA(dst, b, h) do { _Pragma("unroll") for (int m = 0; m < 4; ++m) _Pragma("unroll") for (int k = 0; k < 2; ++k) dst[m][k] = *(const LAS bf16x8*)(lds + PG8_SA(b, h) + aoff + m * 2048 + k * 1024); } while (0)
; #define PG8_MMA(ai, bj, At, Bt) do { __builtin_amdgcn_s_setprio(1); _Pragma("unroll") for (int m = 0; m < 4; ++m) _Pragma("unroll") for (int n = 0; n < 2; ++n) _Pragma("unroll") for (int k = 0; k < 2; ++k) \
;         acc[ai][bj][m][n] = __builtin_amdgcn_mfma_f32_16x16x32_bf16(Bt[n][k], At[m][k], acc[ai][bj][m][n], 0, 0, 0); __builtin_amdgcn_s_setprio(0); } while (0)
; #define PG8_WAIT_V(n) asm volatile("s_waitcnt vmcnt(" #n ")" ::: "memory")
; #define PG8_WAIT_L(n) asm volatile("s_waitcnt lgkmcnt(" #n ")" ::: "memory")
; #define PG8_BAR __builtin_amdgcn_s_barrier()
; #define PG8_SCHED __builtin_amdgcn_sched_barrier(0)
; template <class Epi>
; __device__ __forceinline__ void gemm_phase(LAS unsigned char* lds, const Gemm g, const Order& S, const Epi& E, const int wid) {
;     ...
;             PG8_LDA(At, 1, 1); PG8_STAGE(PG8_SB(1, 0), b3, voffB); PG8_STAGE(PG8_SB(1, 1), b3 + hB, voffB); PG8_STAGE(PG8_SA(1, 0), a3, voffA);
;             PG8_WAIT_V(8); PG8_WAIT_L(0); PG8_BAR; PG8_MMA(1, 0, At, B0); PG8_MMA(1, 1, At, B1); PG8_BAR; PG8_SCHED;
	s_add_i32 s40, s62, s24
	v_lshl_add_u64 v[210:211], v[210:211], 0, s[18:19]
	s_mov_b32 m0, s40
	ds_read_b128 v[178:181], v144 offset:49152
	ds_read_b128 v[182:185], v144 offset:50176
	ds_read_b128 v[186:189], v144 offset:51200
	ds_read_b128 v[190:193], v144 offset:52224
	ds_read_b128 v[194:197], v144 offset:53248
	ds_read_b128 v[198:201], v144 offset:54272
	ds_read_b128 v[202:205], v144 offset:55296
	ds_read_b128 v[206:209], v144 offset:56320
	global_load_lds_dwordx4 v[210:211], off
	s_add_i32 m0, s40, 0x2000
	s_add_u32 s38, s38, 0x100080
	v_lshl_add_u64 v[210:211], v[212:213], 0, s[18:19]
	s_addc_u32 s39, s39, 0
	s_add_i32 s40, s63, s24
	global_load_lds_dwordx4 v[210:211], off
	v_lshl_add_u64 v[210:211], s[38:39], 0, v[134:135]
	s_mov_b32 m0, s40
	s_nop 0
	global_load_lds_dwordx4 v[210:211], off
	v_lshl_add_u64 v[210:211], s[38:39], 0, v[136:137]
	s_add_i32 m0, s40, 0x2000
	s_nop 0
	global_load_lds_dwordx4 v[210:211], off
	v_lshl_add_u64 v[210:211], v[214:215], 0, s[18:19]
	s_mov_b32 m0, s52
	s_nop 0
	global_load_lds_dwordx4 v[210:211], off
	v_lshl_add_u64 v[210:211], v[216:217], 0, s[18:19]
	s_mov_b32 m0, s53
	s_nop 0
	global_load_lds_dwordx4 v[210:211], off
	s_waitcnt vmcnt(8)
	s_waitcnt lgkmcnt(0)
	s_barrier
	s_waitcnt lgkmcnt(0)
	v_mfma_f32_16x16x32_bf16 v[60:63], v[146:149], v[178:181], v[60:63]
	v_mfma_f32_16x16x32_bf16 v[60:63], v[150:153], v[182:185], v[60:63]
	v_mfma_f32_16x16x32_bf16 v[56:59], v[154:157], v[178:181], v[56:59]
	v_mfma_f32_16x16x32_bf16 v[56:59], v[158:161], v[182:185], v[56:59]
	v_mfma_f32_16x16x32_bf16 v[52:55], v[146:149], v[186:189], v[52:55]
	v_mfma_f32_16x16x32_bf16 v[52:55], v[150:153], v[190:193], v[52:55]
	v_mfma_f32_16x16x32_bf16 v[48:51], v[154:157], v[186:189], v[48:51]
	v_mfma_f32_16x16x32_bf16 v[48:51], v[158:161], v[190:193], v[48:51]
	v_mfma_f32_16x16x32_bf16 v[36:39], v[146:149], v[194:197], v[36:39]
	v_mfma_f32_16x16x32_bf16 v[36:39], v[150:153], v[198:201], v[36:39]
	v_mfma_f32_16x16x32_bf16 v[32:35], v[154:157], v[194:197], v[32:35]
	v_mfma_f32_16x16x32_bf16 v[32:35], v[158:161], v[198:201], v[32:35]
	v_mfma_f32_16x16x32_bf16 v[20:23], v[146:149], v[202:205], v[20:23]
	v_mfma_f32_16x16x32_bf16 v[20:23], v[150:153], v[206:209], v[20:23]
	v_mfma_f32_16x16x32_bf16 v[16:19], v[154:157], v[202:205], v[16:19]
	v_mfma_f32_16x16x32_bf16 v[16:19], v[158:161], v[206:209], v[16:19]
	v_mfma_f32_16x16x32_bf16 v[44:47], v[162:165], v[178:181], v[44:47]
	v_mfma_f32_16x16x32_bf16 v[44:47], v[166:169], v[182:185], v[44:47]
	v_mfma_f32_16x16x32_bf16 v[40:43], v[170:173], v[178:181], v[40:43]
	v_mfma_f32_16x16x32_bf16 v[40:43], v[174:177], v[182:185], v[40:43]
	v_mfma_f32_16x16x32_bf16 v[28:31], v[162:165], v[186:189], v[28:31]
	v_mfma_f32_16x16x32_bf16 v[28:31], v[166:169], v[190:193], v[28:31]
	v_mfma_f32_16x16x32_bf16 v[24:27], v[170:173], v[186:189], v[24:27]
	v_mfma_f32_16x16x32_bf16 v[24:27], v[174:177], v[190:193], v[24:27]
	v_mfma_f32_16x16x32_bf16 v[12:15], v[162:165], v[194:197], v[12:15]
	v_mfma_f32_16x16x32_bf16 v[12:15], v[166:169], v[198:201], v[12:15]
	v_mfma_f32_16x16x32_bf16 v[8:11], v[170:173], v[194:197], v[8:11]
	v_mfma_f32_16x16x32_bf16 v[8:11], v[174:177], v[198:201], v[8:11]
	v_mfma_f32_16x16x32_bf16 v[4:7], v[162:165], v[202:205], v[4:7]
	v_mfma_f32_16x16x32_bf16 v[4:7], v[166:169], v[206:209], v[4:7]
	v_mfma_f32_16x16x32_bf16 v[0:3], v[170:173], v[202:205], v[0:3]
	v_mfma_f32_16x16x32_bf16 v[0:3], v[174:177], v[206:209], v[0:3]
	s_barrier
	s_add_i32 s61, s61, 2
	s_add_u32 s36, s36, 0x100
	s_addc_u32 s37, s37, 0
	s_add_u32 s21, s21, 0x100
	s_addc_u32 s60, s60, 0
	s_cmp_gt_u32 s61, 13
	s_cbranch_scc0 .LBB0_1035
	s_and_b64 vcc, exec, s[10:11]
	s_cbranch_vccz .LBB0_1038
	s_barrier

; #define PG8_STAGE(bufoff, gbase, voff) do { _Pragma("unroll") for (int _i = 0; _i < 2; ++_i) \
;         __builtin_amdgcn_global_load_lds((const unsigned*)((const char*)(gbase) + (voff)[_i]), (LAS unsigned*)(lds + (bufoff) + ldsw + _i * 8192), 16, 0, 0); } while (0)
; #define PG8_LDA(dst, b, h) do { _Pragma("unroll") for (int m = 0; m < 4; ++m) _Pragma("unroll") for (int k = 0; k < 2; ++k) dst[m][k] = *(const LAS bf16x8*)(lds + PG8_SA(b, h) + aoff + m * 2048 + k * 1024); } while (0)
; #define PG8_LDB(dst, b, h) do { _Pragma("unroll") for (int n = 0; n < 2; ++n) _Pragma("unroll") for (int k = 0; k < 2; ++k) dst[n][k] = *(const LAS bf16x8*)(lds + PG8_SB(b, h) + boff + n * 2048 + k * 1024); } while (0)
; #define PG8_MMA(ai, bj, At, Bt) do { __builtin_amdgcn_s_setprio(1); _Pragma("unroll") for (int m = 0; m < 4; ++m) _Pragma("unroll") for (int n = 0; n < 2; ++n) _Pragma("unroll") for (int k = 0; k < 2; ++k) \
;         acc[ai][bj][m][n] = __builtin_amdgcn_mfma_f32_16x16x32_bf16(Bt[n][k], At[m][k], acc[ai][bj][m][n], 0, 0, 0); __builtin_amdgcn_s_setprio(0); } while (0)
; #define PG8_WAIT_V(n) asm volatile("s_waitcnt vmcnt(" #n ")" ::: "memory")
; #define PG8_WAIT_L(n) asm volatile("s_waitcnt lgkmcnt(" #n ")" ::: "memory")
; #define PG8_BAR __builtin_amdgcn_s_barrier()
; #define PG8_SCHED __builtin_amdgcn_sched_barrier(0)
; template <class Epi>
; __device__ __forceinline__ void gemm_phase(LAS unsigned char* lds, const Gemm g, const Order& S, const Epi& E, const int wid) {
;     ...
;             const bool last = (t == nt - 2);
;             const char* a1 = cA + (size_t)(t + 1) * kstep;
;             const char* a2 = last ? nA : cA + (size_t)(t + 2) * kstep; const char* b2 = last ? nB : cB + (size_t)(t + 2) * kstep;
;             const char* a3 = a2 + kstep; const char* b3 = b2 + kstep;
;     ...
;             PG8_LDB(B0, 0, 0); PG8_LDB(B1, 0, 1); PG8_SCHED; PG8_LDA(At, 0, 0); PG8_STAGE(PG8_SA(1, 1), a1 + hA, voffA);
;             PG8_WAIT_V(8); PG8_WAIT_L(0); PG8_BAR; PG8_MMA(0, 0, At, B0); PG8_MMA(0, 1, At, B1); PG8_BAR; PG8_SCHED;
;             PG8_LDA(At, 0, 1); PG8_STAGE(PG8_SB(0, 0), b2, voffB); PG8_STAGE(PG8_SB(0, 1), b2 + hB, voffB); PG8_STAGE(PG8_SA(0, 0), a2, voffA);
;             PG8_WAIT_V(8); PG8_WAIT_L(0); PG8_BAR; PG8_MMA(1, 0, At, B0); PG8_MMA(1, 1, At, B1); PG8_BAR; PG8_SCHED;
.LBB0_1059:
	ds_read_b128 v[146:149], v142
	ds_read_b128 v[150:153], v142 offset:1024
	ds_read_b128 v[154:157], v142 offset:2048
	ds_read_b128 v[158:161], v142 offset:3072
	ds_read_b128 v[162:165], v143
	ds_read_b128 v[166:169], v143 offset:1024
	ds_read_b128 v[170:173], v143 offset:2048
	ds_read_b128 v[174:177], v143 offset:3072
	s_add_u32 s36, s28, 0xfff00080
	s_addc_u32 s37, s29, -1
	s_cmp_eq_u32 s60, 12
	s_cselect_b32 s39, s7, s37
	s_cselect_b32 s38, s6, s36
	s_cselect_b32 s37, s23, s59
	s_cselect_b32 s36, s22, s19
	v_lshl_add_u64 v[210:211], s[28:29], 0, v[128:129]
	s_add_i32 m0, s21, 0xc000
	ds_read_b128 v[178:181], v144
	ds_read_b128 v[182:185], v144 offset:1024
	ds_read_b128 v[186:189], v144 offset:2048
	ds_read_b128 v[190:193], v144 offset:3072
	ds_read_b128 v[194:197], v144 offset:4096
	ds_read_b128 v[198:201], v144 offset:5120
	ds_read_b128 v[202:205], v144 offset:6144
	ds_read_b128 v[206:209], v144 offset:7168
	global_load_lds_dwordx4 v[210:211], off
	v_lshl_add_u64 v[210:211], s[28:29], 0, v[138:139]
	s_add_i32 m0, s21, 0xe000
	s_nop 0
	global_load_lds_dwordx4 v[210:211], off
	s_waitcnt vmcnt(8)
	s_waitcnt lgkmcnt(0)
	s_barrier
	s_waitcnt lgkmcnt(0)
	v_mfma_f32_16x16x32_bf16 v[124:127], v[146:149], v[178:181], v[124:127]
	v_mfma_f32_16x16x32_bf16 v[124:127], v[150:153], v[182:185], v[124:127]
	v_mfma_f32_16x16x32_bf16 v[120:123], v[154:157], v[178:181], v[120:123]
	v_mfma_f32_16x16x32_bf16 v[120:123], v[158:161], v[182:185], v[120:123]
	v_mfma_f32_16x16x32_bf16 v[116:119], v[146:149], v[186:189], v[116:119]
	v_mfma_f32_16x16x32_bf16 v[116:119], v[150:153], v[190:193], v[116:119]
	v_mfma_f32_16x16x32_bf16 v[112:115], v[154:157], v[186:189], v[112:115]
	v_mfma_f32_16x16x32_bf16 v[112:115], v[158:161], v[190:193], v[112:115]
	v_mfma_f32_16x16x32_bf16 v[100:103], v[146:149], v[194:197], v[100:103]
	v_mfma_f32_16x16x32_bf16 v[100:103], v[150:153], v[198:201], v[100:103]
	v_mfma_f32_16x16x32_bf16 v[96:99], v[154:157], v[194:197], v[96:99]
	v_mfma_f32_16x16x32_bf16 v[96:99], v[158:161], v[198:201], v[96:99]
	v_mfma_f32_16x16x32_bf16 v[84:87], v[146:149], v[202:205], v[84:87]
	v_mfma_f32_16x16x32_bf16 v[84:87], v[150:153], v[206:209], v[84:87]
	v_mfma_f32_16x16x32_bf16 v[80:83], v[154:157], v[202:205], v[80:83]
	v_mfma_f32_16x16x32_bf16 v[80:83], v[158:161], v[206:209], v[80:83]
	v_mfma_f32_16x16x32_bf16 v[108:111], v[162:165], v[178:181], v[108:111]
	v_mfma_f32_16x16x32_bf16 v[108:111], v[166:169], v[182:185], v[108:111]
	v_mfma_f32_16x16x32_bf16 v[104:107], v[170:173], v[178:181], v[104:107]
	v_mfma_f32_16x16x32_bf16 v[104:107], v[174:177], v[182:185], v[104:107]
	v_mfma_f32_16x16x32_bf16 v[92:95], v[162:165], v[186:189], v[92:95]
	v_mfma_f32_16x16x32_bf16 v[92:95], v[166:169], v[190:193], v[92:95]
	v_mfma_f32_16x16x32_bf16 v[88:91], v[170:173], v[186:189], v[88:91]
	v_mfma_f32_16x16x32_bf16 v[88:91], v[174:177], v[190:193], v[88:91]
	v_mfma_f32_16x16x32_bf16 v[76:79], v[162:165], v[194:197], v[76:79]
	v_mfma_f32_16x16x32_bf16 v[76:79], v[166:169], v[198:201], v[76:79]
	v_mfma_f32_16x16x32_bf16 v[72:75], v[170:173], v[194:197], v[72:75]
	v_mfma_f32_16x16x32_bf16 v[72:75], v[174:177], v[198:201], v[72:75]
	v_mfma_f32_16x16x32_bf16 v[68:71], v[162:165], v[202:205], v[68:71]
	v_mfma_f32_16x16x32_bf16 v[68:71], v[166:169], v[206:209], v[68:71]
	v_mfma_f32_16x16x32_bf16 v[64:67], v[170:173], v[202:205], v[64:67]
	v_mfma_f32_16x16x32_bf16 v[64:67], v[174:177], v[206:209], v[64:67]
	s_barrier
	s_add_i32 s61, s53, s24
	v_lshl_add_u64 v[210:211], s[36:37], 0, v[134:135]
	s_mov_b32 m0, s61
	ds_read_b128 v[178:181], v144 offset:16384
	ds_read_b128 v[182:185], v144 offset:17408
	ds_read_b128 v[186:189], v144 offset:18432
	ds_read_b128 v[190:193], v144 offset:19456
	ds_read_b128 v[194:197], v144 offset:20480
	ds_read_b128 v[198:201], v144 offset:21504
	ds_read_b128 v[202:205], v144 offset:22528
	ds_read_b128 v[206:209], v144 offset:23552
	global_load_lds_dwordx4 v[210:211], off
	s_add_i32 m0, s61, 0x2000
	s_add_u32 s62, s36, 0x100000
	v_lshl_add_u64 v[212:213], s[36:37], 0, v[136:137]
	s_addc_u32 s63, s37, 0
	s_add_i32 s61, s54, s24
	global_load_lds_dwordx4 v[212:213], off
	v_lshl_add_u64 v[214:215], s[62:63], 0, v[134:135]
	s_mov_b32 m0, s61
	v_lshl_add_u64 v[216:217], s[38:39], 0, v[138:139]
	global_load_lds_dwordx4 v[214:215], off
	v_lshl_add_u64 v[214:215], s[62:63], 0, v[136:137]
	s_add_i32 m0, s61, 0x2000
	s_nop 0
	global_load_lds_dwordx4 v[214:215], off
	v_lshl_add_u64 v[214:215], s[38:39], 0, v[128:129]
	s_mov_b32 m0, s21
	s_nop 0
	global_load_lds_dwordx4 v[214:215], off
	s_mov_b32 m0, s35
	s_nop 0
	global_load_lds_dwordx4 v[216:217], off
	s_waitcnt vmcnt(8)
	s_waitcnt lgkmcnt(0)
	s_barrier
; #define PG8_STAGE(bufoff, gbase, voff) do { _Pragma("unroll") for (int _i = 0; _i < 2; ++_i) \
;         __builtin_amdgcn_global_load_lds((const unsigned*)((const char*)(gbase) + (voff)[_i]), (LAS unsigned*)(lds + (bufoff) + ldsw + _i * 8192), 16, 0, 0); } while (0)
; #define PG8_LDA(dst, b, h) do { _Pragma("unroll") for (int m = 0; m < 4; ++m) _Pragma("unroll") for (int k = 0; k < 2; ++k) dst[m][k] = *(const LAS bf16x8*)(lds + PG8_SA(b, h) + aoff + m * 2048 + k * 1024); } while (0)
; #define PG8_LDB(dst, b, h) do { _Pragma("unroll") for (int n = 0; n < 2; ++n) _Pragma("unroll") for (int k = 0; k < 2; ++k) dst[n][k] = *(const LAS bf16x8*)(lds + PG8_SB(b, h) + boff + n * 2048 + k * 1024); } while (0)
; #define PG8_MMA(ai, bj, At, Bt) do { __builtin_amdgcn_s_setprio(1); _Pragma("unroll") for (int m = 0; m < 4; ++m) _Pragma("unroll") for (int n = 0; n < 2; ++n) _Pragma("unroll") for (int k = 0; k < 2; ++k) \
;         acc[ai][bj][m][n] = __builtin_amdgcn_mfma_f32_16x16x32_bf16(Bt[n][k], At[m][k], acc[ai][bj][m][n], 0, 0, 0); __builtin_amdgcn_s_setprio(0); } while (0)
; #define PG8_WAIT_V(n) asm volatile("s_waitcnt vmcnt(" #n ")" ::: "memory")
; #define PG8_WAIT_L(n) asm volatile("s_waitcnt lgkmcnt(" #n ")" ::: "memory")
; #define PG8_BAR __builtin_amdgcn_s_barrier()
; #define PG8_SCHED __builtin_amdgcn_sched_barrier(0)
; template <class Epi>
; __device__ __forceinline__ void gemm_phase(LAS unsigned char* lds, const Gemm g, const Order& S, const Epi& E, const int wid) {
;     ...
;             PG8_WAIT_V(8); PG8_WAIT_L(0); PG8_BAR; PG8_MMA(1, 0, At, B0); PG8_MMA(1, 1, At, B1); PG8_BAR; PG8_SCHED;
;             PG8_LDB(B0, 1, 0); PG8_LDB(B1, 1, 1); PG8_SCHED; PG8_LDA(At, 1, 0); PG8_STAGE(PG8_SA(0, 1), a2 + hA, voffA);
;             PG8_WAIT_V(8); PG8_WAIT_L(0); PG8_BAR; PG8_MMA(0, 0, At, B0); PG8_MMA(0, 1, At, B1); PG8_BAR; PG8_SCHED;
	s_waitcnt lgkmcnt(0)
	v_mfma_f32_16x16x32_bf16 v[60:63], v[146:149], v[178:181], v[60:63]
	v_mfma_f32_16x16x32_bf16 v[60:63], v[150:153], v[182:185], v[60:63]
	v_mfma_f32_16x16x32_bf16 v[56:59], v[154:157], v[178:181], v[56:59]
	v_mfma_f32_16x16x32_bf16 v[56:59], v[158:161], v[182:185], v[56:59]
	v_mfma_f32_16x16x32_bf16 v[52:55], v[146:149], v[186:189], v[52:55]
	v_mfma_f32_16x16x32_bf16 v[52:55], v[150:153], v[190:193], v[52:55]
	v_mfma_f32_16x16x32_bf16 v[48:51], v[154:157], v[186:189], v[48:51]
	v_mfma_f32_16x16x32_bf16 v[48:51], v[158:161], v[190:193], v[48:51]
	v_mfma_f32_16x16x32_bf16 v[36:39], v[146:149], v[194:197], v[36:39]
	v_mfma_f32_16x16x32_bf16 v[36:39], v[150:153], v[198:201], v[36:39]
	v_mfma_f32_16x16x32_bf16 v[32:35], v[154:157], v[194:197], v[32:35]
	v_mfma_f32_16x16x32_bf16 v[32:35], v[158:161], v[198:201], v[32:35]
	v_mfma_f32_16x16x32_bf16 v[20:23], v[146:149], v[202:205], v[20:23]
	v_mfma_f32_16x16x32_bf16 v[20:23], v[150:153], v[206:209], v[20:23]
	v_mfma_f32_16x16x32_bf16 v[16:19], v[154:157], v[202:205], v[16:19]
	v_mfma_f32_16x16x32_bf16 v[16:19], v[158:161], v[206:209], v[16:19]
	v_mfma_f32_16x16x32_bf16 v[44:47], v[162:165], v[178:181], v[44:47]
	v_mfma_f32_16x16x32_bf16 v[44:47], v[166:169], v[182:185], v[44:47]
	v_mfma_f32_16x16x32_bf16 v[40:43], v[170:173], v[178:181], v[40:43]
	v_mfma_f32_16x16x32_bf16 v[40:43], v[174:177], v[182:185], v[40:43]
	v_mfma_f32_16x16x32_bf16 v[28:31], v[162:165], v[186:189], v[28:31]
	v_mfma_f32_16x16x32_bf16 v[28:31], v[166:169], v[190:193], v[28:31]
	v_mfma_f32_16x16x32_bf16 v[24:27], v[170:173], v[186:189], v[24:27]
	v_mfma_f32_16x16x32_bf16 v[24:27], v[174:177], v[190:193], v[24:27]
	v_mfma_f32_16x16x32_bf16 v[12:15], v[162:165], v[194:197], v[12:15]
	v_mfma_f32_16x16x32_bf16 v[12:15], v[166:169], v[198:201], v[12:15]
	v_mfma_f32_16x16x32_bf16 v[8:11], v[170:173], v[194:197], v[8:11]
	v_mfma_f32_16x16x32_bf16 v[8:11], v[174:177], v[198:201], v[8:11]
	v_mfma_f32_16x16x32_bf16 v[4:7], v[162:165], v[202:205], v[4:7]
	v_mfma_f32_16x16x32_bf16 v[4:7], v[166:169], v[206:209], v[4:7]
	v_mfma_f32_16x16x32_bf16 v[0:3], v[170:173], v[202:205], v[0:3]
	v_mfma_f32_16x16x32_bf16 v[0:3], v[174:177], v[206:209], v[0:3]
	s_barrier
	s_add_i32 s61, 0, 0x18000
	v_add_u32_e32 v145, s61, v141
	s_add_i32 s62, 0, 0x1c000
	ds_read_b128 v[146:149], v145
	ds_read_b128 v[150:153], v145 offset:1024
	ds_read_b128 v[154:157], v145 offset:2048
	ds_read_b128 v[158:161], v145 offset:3072
	v_add_u32_e32 v145, s62, v141
	ds_read_b128 v[162:165], v145
	ds_read_b128 v[166:169], v145 offset:1024
	ds_read_b128 v[170:173], v145 offset:2048
	ds_read_b128 v[174:177], v145 offset:3072
	s_add_u32 s38, s38, 0x100000
	s_addc_u32 s39, s39, 0
	s_mov_b32 m0, s42
	v_lshl_add_u64 v[218:219], s[38:39], 0, v[128:129]
	ds_read_b128 v[178:181], v144 offset:32768
	ds_read_b128 v[182:185], v144 offset:33792
	ds_read_b128 v[186:189], v144 offset:34816
	ds_read_b128 v[190:193], v144 offset:35840
	ds_read_b128 v[194:197], v144 offset:36864
	ds_read_b128 v[198:201], v144 offset:37888
	ds_read_b128 v[202:205], v144 offset:38912
	ds_read_b128 v[206:209], v144 offset:39936
	global_load_lds_dwordx4 v[218:219], off
	v_lshl_add_u64 v[218:219], s[38:39], 0, v[138:139]
	s_mov_b32 m0, s43
	s_nop 0
	global_load_lds_dwordx4 v[218:219], off
	s_waitcnt vmcnt(8)
	s_waitcnt lgkmcnt(0)
	s_barrier
	s_waitcnt lgkmcnt(0)
	v_mfma_f32_16x16x32_bf16 v[124:127], v[146:149], v[178:181], v[124:127]
	v_mfma_f32_16x16x32_bf16 v[124:127], v[150:153], v[182:185], v[124:127]
	v_mfma_f32_16x16x32_bf16 v[120:123], v[154:157], v[178:181], v[120:123]
	v_mfma_f32_16x16x32_bf16 v[120:123], v[158:161], v[182:185], v[120:123]
	v_mfma_f32_16x16x32_bf16 v[116:119], v[146:149], v[186:189], v[116:119]
	v_mfma_f32_16x16x32_bf16 v[116:119], v[150:153], v[190:193], v[116:119]
	v_mfma_f32_16x16x32_bf16 v[112:115], v[154:157], v[186:189], v[112:115]
	v_mfma_f32_16x16x32_bf16 v[112:115], v[158:161], v[190:193], v[112:115]
	v_mfma_f32_16x16x32_bf16 v[100:103], v[146:149], v[194:197], v[100:103]
	v_mfma_f32_16x16x32_bf16 v[100:103], v[150:153], v[198:201], v[100:103]
	v_mfma_f32_16x16x32_bf16 v[96:99], v[154:157], v[194:197], v[96:99]
	v_mfma_f32_16x16x32_bf16 v[96:99], v[158:161], v[198:201], v[96:99]
	v_mfma_f32_16x16x32_bf16 v[84:87], v[146:149], v[202:205], v[84:87]
	v_mfma_f32_16x16x32_bf16 v[84:87], v[150:153], v[206:209], v[84:87]
	v_mfma_f32_16x16x32_bf16 v[80:83], v[154:157], v[202:205], v[80:83]
	v_mfma_f32_16x16x32_bf16 v[80:83], v[158:161], v[206:209], v[80:83]
	v_mfma_f32_16x16x32_bf16 v[108:111], v[162:165], v[178:181], v[108:111]
	v_mfma_f32_16x16x32_bf16 v[108:111], v[166:169], v[182:185], v[108:111]
	v_mfma_f32_16x16x32_bf16 v[104:107], v[170:173], v[178:181], v[104:107]
	v_mfma_f32_16x16x32_bf16 v[104:107], v[174:177], v[182:185], v[104:107]
	v_mfma_f32_16x16x32_bf16 v[92:95], v[162:165], v[186:189], v[92:95]
	v_mfma_f32_16x16x32_bf16 v[92:95], v[166:169], v[190:193], v[92:95]
	v_mfma_f32_16x16x32_bf16 v[88:91], v[170:173], v[186:189], v[88:91]
	v_mfma_f32_16x16x32_bf16 v[88:91], v[174:177], v[190:193], v[88:91]
	v_mfma_f32_16x16x32_bf16 v[76:79], v[162:165], v[194:197], v[76:79]
	v_mfma_f32_16x16x32_bf16 v[76:79], v[166:169], v[198:201], v[76:79]
	v_mfma_f32_16x16x32_bf16 v[72:75], v[170:173], v[194:197], v[72:75]
	v_mfma_f32_16x16x32_bf16 v[72:75], v[174:177], v[198:201], v[72:75]
	v_mfma_f32_16x16x32_bf16 v[68:71], v[162:165], v[202:205], v[68:71]
	v_mfma_f32_16x16x32_bf16 v[68:71], v[166:169], v[206:209], v[68:71]
	v_mfma_f32_16x16x32_bf16 v[64:67], v[170:173], v[202:205], v[64:67]
	v_mfma_f32_16x16x32_bf16 v[64:67], v[174:177], v[206:209], v[64:67]
	s_barrier
; #define PG8_STAGE(bufoff, gbase, voff) do { _Pragma("unroll") for (int _i = 0; _i < 2; ++_i) \
;         __builtin_amdgcn_global_load_lds((const unsigned*)((const char*)(gbase) + (voff)[_i]), (LAS unsigned*)(lds + (bufoff) + ldsw + _i * 8192), 16, 0, 0); } while (0)
; #define PG8_LDA(dst, b, h) do { _Pragma("unroll") for (int m = 0; m < 4; ++m) _Pragma("unroll") for (int k = 0; k < 2; ++k) dst[m][k] = *(const LAS bf16x8*)(lds + PG8_SA(b, h) + aoff + m * 2048 + k * 1024); } while (0)
; #define PG8_MMA(ai, bj, At, Bt) do { __builtin_amdgcn_s_setprio(1); _Pragma("unroll") for (int m = 0; m < 4; ++m) _Pragma("unroll") for (int n = 0; n < 2; ++n) _Pragma("unroll") for (int k = 0; k < 2; ++k) \
;         acc[ai][bj][m][n] = __builtin_amdgcn_mfma_f32_16x16x32_bf16(Bt[n][k], At[m][k], acc[ai][bj][m][n], 0, 0, 0); __builtin_amdgcn_s_setprio(0); } while (0)
; #define PG8_WAIT_V(n) asm volatile("s_waitcnt vmcnt(" #n ")" ::: "memory")
; #define PG8_WAIT_L(n) asm volatile("s_waitcnt lgkmcnt(" #n ")" ::: "memory")
; #define PG8_BAR __builtin_amdgcn_s_barrier()
; #define PG8_SCHED __builtin_amdgcn_sched_barrier(0)
; template <class Epi>
; __device__ __forceinline__ void gemm_phase(LAS unsigned char* lds, const Gemm g, const Order& S, const Epi& E, const int wid) {
;     ...
;             PG8_LDA(At, 1, 1); PG8_STAGE(PG8_SB(1, 0), b3, voffB); PG8_STAGE(PG8_SB(1, 1), b3 + hB, voffB); PG8_STAGE(PG8_SA(1, 0), a3, voffA);
;             PG8_WAIT_V(8); PG8_WAIT_L(0); PG8_BAR; PG8_MMA(1, 0, At, B0); PG8_MMA(1, 1, At, B1); PG8_BAR; PG8_SCHED;
	s_add_i32 s38, s61, s24
	v_lshl_add_u64 v[210:211], v[210:211], 0, s[12:13]
	s_mov_b32 m0, s38
	ds_read_b128 v[178:181], v144 offset:49152
	ds_read_b128 v[182:185], v144 offset:50176
	ds_read_b128 v[186:189], v144 offset:51200
	ds_read_b128 v[190:193], v144 offset:52224
	ds_read_b128 v[194:197], v144 offset:53248
	ds_read_b128 v[198:201], v144 offset:54272
	ds_read_b128 v[202:205], v144 offset:55296
	ds_read_b128 v[206:209], v144 offset:56320
	global_load_lds_dwordx4 v[210:211], off
	s_add_i32 m0, s38, 0x2000
	s_add_u32 s36, s36, 0x100080
	v_lshl_add_u64 v[210:211], v[212:213], 0, s[12:13]
	s_addc_u32 s37, s37, 0
	s_add_i32 s38, s62, s24
	global_load_lds_dwordx4 v[210:211], off
	v_lshl_add_u64 v[210:211], s[36:37], 0, v[134:135]
	s_mov_b32 m0, s38
	s_nop 0
	global_load_lds_dwordx4 v[210:211], off
	v_lshl_add_u64 v[210:211], s[36:37], 0, v[136:137]
	s_add_i32 m0, s38, 0x2000
	s_nop 0
	global_load_lds_dwordx4 v[210:211], off
	v_lshl_add_u64 v[210:211], v[214:215], 0, s[12:13]
	s_mov_b32 m0, s50
	s_nop 0
	global_load_lds_dwordx4 v[210:211], off
	v_lshl_add_u64 v[210:211], v[216:217], 0, s[12:13]
	s_mov_b32 m0, s51
	s_nop 0
	global_load_lds_dwordx4 v[210:211], off
	s_waitcnt vmcnt(8)
	s_waitcnt lgkmcnt(0)
	s_barrier
	s_waitcnt lgkmcnt(0)
	v_mfma_f32_16x16x32_bf16 v[60:63], v[146:149], v[178:181], v[60:63]
	v_mfma_f32_16x16x32_bf16 v[60:63], v[150:153], v[182:185], v[60:63]
	v_mfma_f32_16x16x32_bf16 v[56:59], v[154:157], v[178:181], v[56:59]
	v_mfma_f32_16x16x32_bf16 v[56:59], v[158:161], v[182:185], v[56:59]
	v_mfma_f32_16x16x32_bf16 v[52:55], v[146:149], v[186:189], v[52:55]
	v_mfma_f32_16x16x32_bf16 v[52:55], v[150:153], v[190:193], v[52:55]
	v_mfma_f32_16x16x32_bf16 v[48:51], v[154:157], v[186:189], v[48:51]
	v_mfma_f32_16x16x32_bf16 v[48:51], v[158:161], v[190:193], v[48:51]
	v_mfma_f32_16x16x32_bf16 v[36:39], v[146:149], v[194:197], v[36:39]
	v_mfma_f32_16x16x32_bf16 v[36:39], v[150:153], v[198:201], v[36:39]
	v_mfma_f32_16x16x32_bf16 v[32:35], v[154:157], v[194:197], v[32:35]
	v_mfma_f32_16x16x32_bf16 v[32:35], v[158:161], v[198:201], v[32:35]
	v_mfma_f32_16x16x32_bf16 v[20:23], v[146:149], v[202:205], v[20:23]
	v_mfma_f32_16x16x32_bf16 v[20:23], v[150:153], v[206:209], v[20:23]
	v_mfma_f32_16x16x32_bf16 v[16:19], v[154:157], v[202:205], v[16:19]
	v_mfma_f32_16x16x32_bf16 v[16:19], v[158:161], v[206:209], v[16:19]
	v_mfma_f32_16x16x32_bf16 v[44:47], v[162:165], v[178:181], v[44:47]
	v_mfma_f32_16x16x32_bf16 v[44:47], v[166:169], v[182:185], v[44:47]
	v_mfma_f32_16x16x32_bf16 v[40:43], v[170:173], v[178:181], v[40:43]
	v_mfma_f32_16x16x32_bf16 v[40:43], v[174:177], v[182:185], v[40:43]
	v_mfma_f32_16x16x32_bf16 v[28:31], v[162:165], v[186:189], v[28:31]
	v_mfma_f32_16x16x32_bf16 v[28:31], v[166:169], v[190:193], v[28:31]
	v_mfma_f32_16x16x32_bf16 v[24:27], v[170:173], v[186:189], v[24:27]
	v_mfma_f32_16x16x32_bf16 v[24:27], v[174:177], v[190:193], v[24:27]
	v_mfma_f32_16x16x32_bf16 v[12:15], v[162:165], v[194:197], v[12:15]
	v_mfma_f32_16x16x32_bf16 v[12:15], v[166:169], v[198:201], v[12:15]
	v_mfma_f32_16x16x32_bf16 v[8:11], v[170:173], v[194:197], v[8:11]
	v_mfma_f32_16x16x32_bf16 v[8:11], v[174:177], v[198:201], v[8:11]
	v_mfma_f32_16x16x32_bf16 v[4:7], v[162:165], v[202:205], v[4:7]
	v_mfma_f32_16x16x32_bf16 v[4:7], v[166:169], v[206:209], v[4:7]
	v_mfma_f32_16x16x32_bf16 v[0:3], v[170:173], v[202:205], v[0:3]
	v_mfma_f32_16x16x32_bf16 v[0:3], v[174:177], v[206:209], v[0:3]
	s_barrier
	s_add_i32 s60, s60, 2
	s_add_u32 s28, s28, 0x100
	s_addc_u32 s29, s29, 0
	s_add_u32 s19, s19, 0x100
	s_addc_u32 s59, s59, 0
	s_cmp_gt_u32 s60, 13
	s_cbranch_scc0 .LBB0_1059
	s_and_b64 vcc, exec, s[10:11]
	s_cbranch_vccz .LBB0_1062
	s_barrier

; #define PG8_STAGE(bufoff, gbase, voff) do { _Pragma("unroll") for (int _i = 0; _i < 2; ++_i) \
;         __builtin_amdgcn_global_load_lds((const unsigned*)((const char*)(gbase) + (voff)[_i]), (LAS unsigned*)(lds + (bufoff) + ldsw + _i * 8192), 16, 0, 0); } while (0)
; #define PG8_LDA(dst, b, h) do { _Pragma("unroll") for (int m = 0; m < 4; ++m) _Pragma("unroll") for (int k = 0; k < 2; ++k) dst[m][k] = *(const LAS bf16x8*)(lds + PG8_SA(b, h) + aoff + m * 2048 + k * 1024); } while (0)
; #define PG8_LDB(dst, b, h) do { _Pragma("unroll") for (int n = 0; n < 2; ++n) _Pragma("unroll") for (int k = 0; k < 2; ++k) dst[n][k] = *(const LAS bf16x8*)(lds + PG8_SB(b, h) + boff + n * 2048 + k * 1024); } while (0)
; #define PG8_MMA(ai, bj, At, Bt) do { __builtin_amdgcn_s_setprio(1); _Pragma("unroll") for (int m = 0; m < 4; ++m) _Pragma("unroll") for (int n = 0; n < 2; ++n) _Pragma("unroll") for (int k = 0; k < 2; ++k) \
;         acc[ai][bj][m][n] = __builtin_amdgcn_mfma_f32_16x16x32_bf16(Bt[n][k], At[m][k], acc[ai][bj][m][n], 0, 0, 0); __builtin_amdgcn_s_setprio(0); } while (0)
; #define PG8_WAIT_V(n) asm volatile("s_waitcnt vmcnt(" #n ")" ::: "memory")
; #define PG8_WAIT_L(n) asm volatile("s_waitcnt lgkmcnt(" #n ")" ::: "memory")
; #define PG8_BAR __builtin_amdgcn_s_barrier()
; #define PG8_SCHED __builtin_amdgcn_sched_barrier(0)
; template <class Epi>
; __device__ __forceinline__ void gemm_phase(LAS unsigned char* lds, const Gemm g, const Order& S, const Epi& E, const int wid) {
;     ...
;             const bool last = (t == nt - 2);
;             const char* a1 = cA + (size_t)(t + 1) * kstep;
;             const char* a2 = last ? nA : cA + (size_t)(t + 2) * kstep; const char* b2 = last ? nB : cB + (size_t)(t + 2) * kstep;
;             const char* a3 = a2 + kstep; const char* b3 = b2 + kstep;
;     ...
;             PG8_LDB(B0, 0, 0); PG8_LDB(B1, 0, 1); PG8_SCHED; PG8_LDA(At, 0, 0); PG8_STAGE(PG8_SA(1, 1), a1 + hA, voffA);
;             PG8_WAIT_V(8); PG8_WAIT_L(0); PG8_BAR; PG8_MMA(0, 0, At, B0); PG8_MMA(0, 1, At, B1); PG8_BAR; PG8_SCHED;
;             PG8_LDA(At, 0, 1); PG8_STAGE(PG8_SB(0, 0), b2, voffB); PG8_STAGE(PG8_SB(0, 1), b2 + hB, voffB); PG8_STAGE(PG8_SA(0, 0), a2, voffA);
;             PG8_WAIT_V(8); PG8_WAIT_L(0); PG8_BAR; PG8_MMA(1, 0, At, B0); PG8_MMA(1, 1, At, B1); PG8_BAR; PG8_SCHED;
.LBB0_1145:
	ds_read_b128 v[142:145], v138
	ds_read_b128 v[146:149], v138 offset:1024
	ds_read_b128 v[150:153], v138 offset:2048
	ds_read_b128 v[154:157], v138 offset:3072
	ds_read_b128 v[158:161], v139
	ds_read_b128 v[162:165], v139 offset:1024
	ds_read_b128 v[166:169], v139 offset:2048
	ds_read_b128 v[170:173], v139 offset:3072
	s_add_u32 s38, s36, 0xfff00080
	s_addc_u32 s39, s37, -1
	s_cmp_eq_u32 s60, 28
	s_cselect_b32 s41, s5, s39
	s_cselect_b32 s40, s4, s38
	s_cselect_b32 s39, s29, s23
	s_cselect_b32 s38, s28, s21
	v_lshl_add_u64 v[206:207], s[36:37], 0, v[128:129]
	s_add_i32 m0, s30, 0xc000
	ds_read_b128 v[174:177], v140
	ds_read_b128 v[178:181], v140 offset:1024
	ds_read_b128 v[182:185], v140 offset:2048
	ds_read_b128 v[186:189], v140 offset:3072
	ds_read_b128 v[190:193], v140 offset:4096
	ds_read_b128 v[194:197], v140 offset:5120
	ds_read_b128 v[198:201], v140 offset:6144
	ds_read_b128 v[202:205], v140 offset:7168
	global_load_lds_dwordx4 v[206:207], off
	v_lshl_add_u64 v[206:207], s[36:37], 0, v[134:135]
	s_add_i32 m0, s30, 0xe000
	s_nop 0
	global_load_lds_dwordx4 v[206:207], off
	s_waitcnt vmcnt(8)
	s_waitcnt lgkmcnt(0)
	s_barrier
	s_waitcnt lgkmcnt(0)
	v_mfma_f32_16x16x32_bf16 v[124:127], v[142:145], v[174:177], v[124:127]
	v_mfma_f32_16x16x32_bf16 v[124:127], v[146:149], v[178:181], v[124:127]
	v_mfma_f32_16x16x32_bf16 v[120:123], v[150:153], v[174:177], v[120:123]
	v_mfma_f32_16x16x32_bf16 v[120:123], v[154:157], v[178:181], v[120:123]
	v_mfma_f32_16x16x32_bf16 v[116:119], v[142:145], v[182:185], v[116:119]
	v_mfma_f32_16x16x32_bf16 v[116:119], v[146:149], v[186:189], v[116:119]
	v_mfma_f32_16x16x32_bf16 v[112:115], v[150:153], v[182:185], v[112:115]
	v_mfma_f32_16x16x32_bf16 v[112:115], v[154:157], v[186:189], v[112:115]
	v_mfma_f32_16x16x32_bf16 v[104:107], v[142:145], v[190:193], v[104:107]
	v_mfma_f32_16x16x32_bf16 v[104:107], v[146:149], v[194:197], v[104:107]
	v_mfma_f32_16x16x32_bf16 v[96:99], v[150:153], v[190:193], v[96:99]
	v_mfma_f32_16x16x32_bf16 v[96:99], v[154:157], v[194:197], v[96:99]
	v_mfma_f32_16x16x32_bf16 v[88:91], v[142:145], v[198:201], v[88:91]
	v_mfma_f32_16x16x32_bf16 v[88:91], v[146:149], v[202:205], v[88:91]
	v_mfma_f32_16x16x32_bf16 v[80:83], v[150:153], v[198:201], v[80:83]
	v_mfma_f32_16x16x32_bf16 v[80:83], v[154:157], v[202:205], v[80:83]
	v_mfma_f32_16x16x32_bf16 v[108:111], v[158:161], v[174:177], v[108:111]
	v_mfma_f32_16x16x32_bf16 v[108:111], v[162:165], v[178:181], v[108:111]
	v_mfma_f32_16x16x32_bf16 v[100:103], v[166:169], v[174:177], v[100:103]
	v_mfma_f32_16x16x32_bf16 v[100:103], v[170:173], v[178:181], v[100:103]
	v_mfma_f32_16x16x32_bf16 v[92:95], v[158:161], v[182:185], v[92:95]
	v_mfma_f32_16x16x32_bf16 v[92:95], v[162:165], v[186:189], v[92:95]
	v_mfma_f32_16x16x32_bf16 v[84:87], v[166:169], v[182:185], v[84:87]
	v_mfma_f32_16x16x32_bf16 v[84:87], v[170:173], v[186:189], v[84:87]
	v_mfma_f32_16x16x32_bf16 v[76:79], v[158:161], v[190:193], v[76:79]
	v_mfma_f32_16x16x32_bf16 v[76:79], v[162:165], v[194:197], v[76:79]
	v_mfma_f32_16x16x32_bf16 v[72:75], v[166:169], v[190:193], v[72:75]
	v_mfma_f32_16x16x32_bf16 v[72:75], v[170:173], v[194:197], v[72:75]
	v_mfma_f32_16x16x32_bf16 v[68:71], v[158:161], v[198:201], v[68:71]
	v_mfma_f32_16x16x32_bf16 v[68:71], v[162:165], v[202:205], v[68:71]
	v_mfma_f32_16x16x32_bf16 v[64:67], v[166:169], v[198:201], v[64:67]
	v_mfma_f32_16x16x32_bf16 v[64:67], v[170:173], v[202:205], v[64:67]
	s_barrier
	s_add_i32 s61, s54, s26
	v_lshl_add_u64 v[206:207], s[38:39], 0, v[128:129]
	s_mov_b32 m0, s61
	ds_read_b128 v[174:177], v140 offset:16384
	ds_read_b128 v[178:181], v140 offset:17408
	ds_read_b128 v[182:185], v140 offset:18432
	ds_read_b128 v[186:189], v140 offset:19456
	ds_read_b128 v[190:193], v140 offset:20480
	ds_read_b128 v[194:197], v140 offset:21504
	ds_read_b128 v[198:201], v140 offset:22528
	ds_read_b128 v[202:205], v140 offset:23552
	global_load_lds_dwordx4 v[206:207], off
	s_add_i32 m0, s61, 0x2000
	s_add_u32 s62, s38, 0x100000
	v_lshl_add_u64 v[208:209], s[38:39], 0, v[134:135]
	s_addc_u32 s63, s39, 0
	s_add_i32 s61, s55, s26
	global_load_lds_dwordx4 v[208:209], off
	v_lshl_add_u64 v[210:211], s[62:63], 0, v[128:129]
	s_mov_b32 m0, s61
	v_lshl_add_u64 v[212:213], s[40:41], 0, v[134:135]
	global_load_lds_dwordx4 v[210:211], off
	v_lshl_add_u64 v[210:211], s[62:63], 0, v[134:135]
	s_add_i32 m0, s61, 0x2000
	s_nop 0
	global_load_lds_dwordx4 v[210:211], off
	v_lshl_add_u64 v[210:211], s[40:41], 0, v[128:129]
	s_mov_b32 m0, s30
	s_nop 0
	global_load_lds_dwordx4 v[210:211], off
	s_mov_b32 m0, s31
	s_nop 0
	global_load_lds_dwordx4 v[212:213], off
	s_waitcnt vmcnt(8)
	s_waitcnt lgkmcnt(0)
	s_barrier
; #define PG8_STAGE(bufoff, gbase, voff) do { _Pragma("unroll") for (int _i = 0; _i < 2; ++_i) \
;         __builtin_amdgcn_global_load_lds((const unsigned*)((const char*)(gbase) + (voff)[_i]), (LAS unsigned*)(lds + (bufoff) + ldsw + _i * 8192), 16, 0, 0); } while (0)
; #define PG8_LDA(dst, b, h) do { _Pragma("unroll") for (int m = 0; m < 4; ++m) _Pragma("unroll") for (int k = 0; k < 2; ++k) dst[m][k] = *(const LAS bf16x8*)(lds + PG8_SA(b, h) + aoff + m * 2048 + k * 1024); } while (0)
; #define PG8_LDB(dst, b, h) do { _Pragma("unroll") for (int n = 0; n < 2; ++n) _Pragma("unroll") for (int k = 0; k < 2; ++k) dst[n][k] = *(const LAS bf16x8*)(lds + PG8_SB(b, h) + boff + n * 2048 + k * 1024); } while (0)
; #define PG8_MMA(ai, bj, At, Bt) do { __builtin_amdgcn_s_setprio(1); _Pragma("unroll") for (int m = 0; m < 4; ++m) _Pragma("unroll") for (int n = 0; n < 2; ++n) _Pragma("unroll") for (int k = 0; k < 2; ++k) \
;         acc[ai][bj][m][n] = __builtin_amdgcn_mfma_f32_16x16x32_bf16(Bt[n][k], At[m][k], acc[ai][bj][m][n], 0, 0, 0); __builtin_amdgcn_s_setprio(0); } while (0)
; #define PG8_WAIT_V(n) asm volatile("s_waitcnt vmcnt(" #n ")" ::: "memory")
; #define PG8_WAIT_L(n) asm volatile("s_waitcnt lgkmcnt(" #n ")" ::: "memory")
; #define PG8_BAR __builtin_amdgcn_s_barrier()
; #define PG8_SCHED __builtin_amdgcn_sched_barrier(0)
; template <class Epi>
; __device__ __forceinline__ void gemm_phase(LAS unsigned char* lds, const Gemm g, const Order& S, const Epi& E, const int wid) {
;     ...
;             PG8_WAIT_V(8); PG8_WAIT_L(0); PG8_BAR; PG8_MMA(1, 0, At, B0); PG8_MMA(1, 1, At, B1); PG8_BAR; PG8_SCHED;
;             PG8_LDB(B0, 1, 0); PG8_LDB(B1, 1, 1); PG8_SCHED; PG8_LDA(At, 1, 0); PG8_STAGE(PG8_SA(0, 1), a2 + hA, voffA);
;             PG8_WAIT_V(8); PG8_WAIT_L(0); PG8_BAR; PG8_MMA(0, 0, At, B0); PG8_MMA(0, 1, At, B1); PG8_BAR; PG8_SCHED;
	s_waitcnt lgkmcnt(0)
	v_mfma_f32_16x16x32_bf16 v[60:63], v[142:145], v[174:177], v[60:63]
	v_mfma_f32_16x16x32_bf16 v[60:63], v[146:149], v[178:181], v[60:63]
	v_mfma_f32_16x16x32_bf16 v[56:59], v[150:153], v[174:177], v[56:59]
	v_mfma_f32_16x16x32_bf16 v[56:59], v[154:157], v[178:181], v[56:59]
	v_mfma_f32_16x16x32_bf16 v[52:55], v[142:145], v[182:185], v[52:55]
	v_mfma_f32_16x16x32_bf16 v[52:55], v[146:149], v[186:189], v[52:55]
	v_mfma_f32_16x16x32_bf16 v[48:51], v[150:153], v[182:185], v[48:51]
	v_mfma_f32_16x16x32_bf16 v[48:51], v[154:157], v[186:189], v[48:51]
	v_mfma_f32_16x16x32_bf16 v[40:43], v[142:145], v[190:193], v[40:43]
	v_mfma_f32_16x16x32_bf16 v[40:43], v[146:149], v[194:197], v[40:43]
	v_mfma_f32_16x16x32_bf16 v[32:35], v[150:153], v[190:193], v[32:35]
	v_mfma_f32_16x16x32_bf16 v[32:35], v[154:157], v[194:197], v[32:35]
	v_mfma_f32_16x16x32_bf16 v[24:27], v[142:145], v[198:201], v[24:27]
	v_mfma_f32_16x16x32_bf16 v[24:27], v[146:149], v[202:205], v[24:27]
	v_mfma_f32_16x16x32_bf16 v[16:19], v[150:153], v[198:201], v[16:19]
	v_mfma_f32_16x16x32_bf16 v[16:19], v[154:157], v[202:205], v[16:19]
	v_mfma_f32_16x16x32_bf16 v[44:47], v[158:161], v[174:177], v[44:47]
	v_mfma_f32_16x16x32_bf16 v[44:47], v[162:165], v[178:181], v[44:47]
	v_mfma_f32_16x16x32_bf16 v[36:39], v[166:169], v[174:177], v[36:39]
	v_mfma_f32_16x16x32_bf16 v[36:39], v[170:173], v[178:181], v[36:39]
	v_mfma_f32_16x16x32_bf16 v[28:31], v[158:161], v[182:185], v[28:31]
	v_mfma_f32_16x16x32_bf16 v[28:31], v[162:165], v[186:189], v[28:31]
	v_mfma_f32_16x16x32_bf16 v[20:23], v[166:169], v[182:185], v[20:23]
	v_mfma_f32_16x16x32_bf16 v[20:23], v[170:173], v[186:189], v[20:23]
	v_mfma_f32_16x16x32_bf16 v[12:15], v[158:161], v[190:193], v[12:15]
	v_mfma_f32_16x16x32_bf16 v[12:15], v[162:165], v[194:197], v[12:15]
	v_mfma_f32_16x16x32_bf16 v[8:11], v[166:169], v[190:193], v[8:11]
	v_mfma_f32_16x16x32_bf16 v[8:11], v[170:173], v[194:197], v[8:11]
	v_mfma_f32_16x16x32_bf16 v[4:7], v[158:161], v[198:201], v[4:7]
	v_mfma_f32_16x16x32_bf16 v[4:7], v[162:165], v[202:205], v[4:7]
	v_mfma_f32_16x16x32_bf16 v[0:3], v[166:169], v[198:201], v[0:3]
	v_mfma_f32_16x16x32_bf16 v[0:3], v[170:173], v[202:205], v[0:3]
	s_barrier
	s_add_i32 s61, 0, 0x18000
	v_add_u32_e32 v141, s61, v137
	s_add_i32 s62, 0, 0x1c000
	ds_read_b128 v[142:145], v141
	ds_read_b128 v[146:149], v141 offset:1024
	ds_read_b128 v[150:153], v141 offset:2048
	ds_read_b128 v[154:157], v141 offset:3072
	v_add_u32_e32 v141, s62, v137
	ds_read_b128 v[158:161], v141
	ds_read_b128 v[162:165], v141 offset:1024
	ds_read_b128 v[166:169], v141 offset:2048
	ds_read_b128 v[170:173], v141 offset:3072
	s_add_u32 s40, s40, 0x100000
	s_addc_u32 s41, s41, 0
	s_mov_b32 m0, s33
	v_lshl_add_u64 v[214:215], s[40:41], 0, v[128:129]
	ds_read_b128 v[174:177], v140 offset:32768
	ds_read_b128 v[178:181], v140 offset:33792
	ds_read_b128 v[182:185], v140 offset:34816
	ds_read_b128 v[186:189], v140 offset:35840
	ds_read_b128 v[190:193], v140 offset:36864
	ds_read_b128 v[194:197], v140 offset:37888
	ds_read_b128 v[198:201], v140 offset:38912
	ds_read_b128 v[202:205], v140 offset:39936
	global_load_lds_dwordx4 v[214:215], off
	v_lshl_add_u64 v[214:215], s[40:41], 0, v[134:135]
	s_mov_b32 m0, s35
	s_nop 0
	global_load_lds_dwordx4 v[214:215], off
	s_waitcnt vmcnt(8)
	s_waitcnt lgkmcnt(0)
	s_barrier
	s_waitcnt lgkmcnt(0)
	v_mfma_f32_16x16x32_bf16 v[124:127], v[142:145], v[174:177], v[124:127]
	v_mfma_f32_16x16x32_bf16 v[124:127], v[146:149], v[178:181], v[124:127]
	v_mfma_f32_16x16x32_bf16 v[120:123], v[150:153], v[174:177], v[120:123]
	v_mfma_f32_16x16x32_bf16 v[120:123], v[154:157], v[178:181], v[120:123]
	v_mfma_f32_16x16x32_bf16 v[116:119], v[142:145], v[182:185], v[116:119]
	v_mfma_f32_16x16x32_bf16 v[116:119], v[146:149], v[186:189], v[116:119]
	v_mfma_f32_16x16x32_bf16 v[112:115], v[150:153], v[182:185], v[112:115]
	v_mfma_f32_16x16x32_bf16 v[112:115], v[154:157], v[186:189], v[112:115]
	v_mfma_f32_16x16x32_bf16 v[104:107], v[142:145], v[190:193], v[104:107]
	v_mfma_f32_16x16x32_bf16 v[104:107], v[146:149], v[194:197], v[104:107]
	v_mfma_f32_16x16x32_bf16 v[96:99], v[150:153], v[190:193], v[96:99]
	v_mfma_f32_16x16x32_bf16 v[96:99], v[154:157], v[194:197], v[96:99]
	v_mfma_f32_16x16x32_bf16 v[88:91], v[142:145], v[198:201], v[88:91]
	v_mfma_f32_16x16x32_bf16 v[88:91], v[146:149], v[202:205], v[88:91]
	v_mfma_f32_16x16x32_bf16 v[80:83], v[150:153], v[198:201], v[80:83]
	v_mfma_f32_16x16x32_bf16 v[80:83], v[154:157], v[202:205], v[80:83]
	v_mfma_f32_16x16x32_bf16 v[108:111], v[158:161], v[174:177], v[108:111]
	v_mfma_f32_16x16x32_bf16 v[108:111], v[162:165], v[178:181], v[108:111]
	v_mfma_f32_16x16x32_bf16 v[100:103], v[166:169], v[174:177], v[100:103]
	v_mfma_f32_16x16x32_bf16 v[100:103], v[170:173], v[178:181], v[100:103]
	v_mfma_f32_16x16x32_bf16 v[92:95], v[158:161], v[182:185], v[92:95]
	v_mfma_f32_16x16x32_bf16 v[92:95], v[162:165], v[186:189], v[92:95]
	v_mfma_f32_16x16x32_bf16 v[84:87], v[166:169], v[182:185], v[84:87]
	v_mfma_f32_16x16x32_bf16 v[84:87], v[170:173], v[186:189], v[84:87]
	v_mfma_f32_16x16x32_bf16 v[76:79], v[158:161], v[190:193], v[76:79]
	v_mfma_f32_16x16x32_bf16 v[76:79], v[162:165], v[194:197], v[76:79]
	v_mfma_f32_16x16x32_bf16 v[72:75], v[166:169], v[190:193], v[72:75]
	v_mfma_f32_16x16x32_bf16 v[72:75], v[170:173], v[194:197], v[72:75]
	v_mfma_f32_16x16x32_bf16 v[68:71], v[158:161], v[198:201], v[68:71]
	v_mfma_f32_16x16x32_bf16 v[68:71], v[162:165], v[202:205], v[68:71]
	v_mfma_f32_16x16x32_bf16 v[64:67], v[166:169], v[198:201], v[64:67]
	v_mfma_f32_16x16x32_bf16 v[64:67], v[170:173], v[202:205], v[64:67]
	s_barrier
; #define PG8_STAGE(bufoff, gbase, voff) do { _Pragma("unroll") for (int _i = 0; _i < 2; ++_i) \
;         __builtin_amdgcn_global_load_lds((const unsigned*)((const char*)(gbase) + (voff)[_i]), (LAS unsigned*)(lds + (bufoff) + ldsw + _i * 8192), 16, 0, 0); } while (0)
; #define PG8_LDA(dst, b, h) do { _Pragma("unroll") for (int m = 0; m < 4; ++m) _Pragma("unroll") for (int k = 0; k < 2; ++k) dst[m][k] = *(const LAS bf16x8*)(lds + PG8_SA(b, h) + aoff + m * 2048 + k * 1024); } while (0)
; #define PG8_MMA(ai, bj, At, Bt) do { __builtin_amdgcn_s_setprio(1); _Pragma("unroll") for (int m = 0; m < 4; ++m) _Pragma("unroll") for (int n = 0; n < 2; ++n) _Pragma("unroll") for (int k = 0; k < 2; ++k) \
;         acc[ai][bj][m][n] = __builtin_amdgcn_mfma_f32_16x16x32_bf16(Bt[n][k], At[m][k], acc[ai][bj][m][n], 0, 0, 0); __builtin_amdgcn_s_setprio(0); } while (0)
; #define PG8_WAIT_V(n) asm volatile("s_waitcnt vmcnt(" #n ")" ::: "memory")
; #define PG8_WAIT_L(n) asm volatile("s_waitcnt lgkmcnt(" #n ")" ::: "memory")
; #define PG8_BAR __builtin_amdgcn_s_barrier()
; #define PG8_SCHED __builtin_amdgcn_sched_barrier(0)
; template <class Epi>
; __device__ __forceinline__ void gemm_phase(LAS unsigned char* lds, const Gemm g, const Order& S, const Epi& E, const int wid) {
;     ...
;             PG8_LDA(At, 1, 1); PG8_STAGE(PG8_SB(1, 0), b3, voffB); PG8_STAGE(PG8_SB(1, 1), b3 + hB, voffB); PG8_STAGE(PG8_SA(1, 0), a3, voffA);
;             PG8_WAIT_V(8); PG8_WAIT_L(0); PG8_BAR; PG8_MMA(1, 0, At, B0); PG8_MMA(1, 1, At, B1); PG8_BAR; PG8_SCHED;
	s_add_i32 s40, s61, s26
	v_lshl_add_u64 v[206:207], v[206:207], 0, s[12:13]
	s_mov_b32 m0, s40
	ds_read_b128 v[174:177], v140 offset:49152
	ds_read_b128 v[178:181], v140 offset:50176
	ds_read_b128 v[182:185], v140 offset:51200
	ds_read_b128 v[186:189], v140 offset:52224
	ds_read_b128 v[190:193], v140 offset:53248
	ds_read_b128 v[194:197], v140 offset:54272
	ds_read_b128 v[198:201], v140 offset:55296
	ds_read_b128 v[202:205], v140 offset:56320
	global_load_lds_dwordx4 v[206:207], off
	s_add_i32 m0, s40, 0x2000
	s_add_u32 s38, s38, 0x100080
	v_lshl_add_u64 v[206:207], v[208:209], 0, s[12:13]
	s_addc_u32 s39, s39, 0
	s_add_i32 s40, s62, s26
	global_load_lds_dwordx4 v[206:207], off
	v_lshl_add_u64 v[206:207], s[38:39], 0, v[128:129]
	s_mov_b32 m0, s40
	s_nop 0
	global_load_lds_dwordx4 v[206:207], off
	v_lshl_add_u64 v[206:207], s[38:39], 0, v[134:135]
	s_add_i32 m0, s40, 0x2000
	s_nop 0
	global_load_lds_dwordx4 v[206:207], off
	v_lshl_add_u64 v[206:207], v[210:211], 0, s[12:13]
	s_mov_b32 m0, s50
	s_nop 0
	global_load_lds_dwordx4 v[206:207], off
	v_lshl_add_u64 v[206:207], v[212:213], 0, s[12:13]
	s_mov_b32 m0, s51
	s_nop 0
	global_load_lds_dwordx4 v[206:207], off
	s_waitcnt vmcnt(8)
	s_waitcnt lgkmcnt(0)
	s_barrier
	s_waitcnt lgkmcnt(0)
	v_mfma_f32_16x16x32_bf16 v[60:63], v[142:145], v[174:177], v[60:63]
	v_mfma_f32_16x16x32_bf16 v[60:63], v[146:149], v[178:181], v[60:63]
	v_mfma_f32_16x16x32_bf16 v[56:59], v[150:153], v[174:177], v[56:59]
	v_mfma_f32_16x16x32_bf16 v[56:59], v[154:157], v[178:181], v[56:59]
	v_mfma_f32_16x16x32_bf16 v[52:55], v[142:145], v[182:185], v[52:55]
	v_mfma_f32_16x16x32_bf16 v[52:55], v[146:149], v[186:189], v[52:55]
	v_mfma_f32_16x16x32_bf16 v[48:51], v[150:153], v[182:185], v[48:51]
	v_mfma_f32_16x16x32_bf16 v[48:51], v[154:157], v[186:189], v[48:51]
	v_mfma_f32_16x16x32_bf16 v[40:43], v[142:145], v[190:193], v[40:43]
	v_mfma_f32_16x16x32_bf16 v[40:43], v[146:149], v[194:197], v[40:43]
	v_mfma_f32_16x16x32_bf16 v[32:35], v[150:153], v[190:193], v[32:35]
	v_mfma_f32_16x16x32_bf16 v[32:35], v[154:157], v[194:197], v[32:35]
	v_mfma_f32_16x16x32_bf16 v[24:27], v[142:145], v[198:201], v[24:27]
	v_mfma_f32_16x16x32_bf16 v[24:27], v[146:149], v[202:205], v[24:27]
	v_mfma_f32_16x16x32_bf16 v[16:19], v[150:153], v[198:201], v[16:19]
	v_mfma_f32_16x16x32_bf16 v[16:19], v[154:157], v[202:205], v[16:19]
	v_mfma_f32_16x16x32_bf16 v[44:47], v[158:161], v[174:177], v[44:47]
	v_mfma_f32_16x16x32_bf16 v[44:47], v[162:165], v[178:181], v[44:47]
	v_mfma_f32_16x16x32_bf16 v[36:39], v[166:169], v[174:177], v[36:39]
	v_mfma_f32_16x16x32_bf16 v[36:39], v[170:173], v[178:181], v[36:39]
	v_mfma_f32_16x16x32_bf16 v[28:31], v[158:161], v[182:185], v[28:31]
	v_mfma_f32_16x16x32_bf16 v[28:31], v[162:165], v[186:189], v[28:31]
	v_mfma_f32_16x16x32_bf16 v[20:23], v[166:169], v[182:185], v[20:23]
	v_mfma_f32_16x16x32_bf16 v[20:23], v[170:173], v[186:189], v[20:23]
	v_mfma_f32_16x16x32_bf16 v[12:15], v[158:161], v[190:193], v[12:15]
	v_mfma_f32_16x16x32_bf16 v[12:15], v[162:165], v[194:197], v[12:15]
	v_mfma_f32_16x16x32_bf16 v[8:11], v[166:169], v[190:193], v[8:11]
	v_mfma_f32_16x16x32_bf16 v[8:11], v[170:173], v[194:197], v[8:11]
	v_mfma_f32_16x16x32_bf16 v[4:7], v[158:161], v[198:201], v[4:7]
	v_mfma_f32_16x16x32_bf16 v[4:7], v[162:165], v[202:205], v[4:7]
	v_mfma_f32_16x16x32_bf16 v[0:3], v[166:169], v[198:201], v[0:3]
	v_mfma_f32_16x16x32_bf16 v[0:3], v[170:173], v[202:205], v[0:3]
	s_barrier
	s_add_i32 s60, s60, 2
	s_add_u32 s36, s36, 0x100
	s_addc_u32 s37, s37, 0
	s_add_u32 s21, s21, 0x100
	s_addc_u32 s23, s23, 0
	s_cmp_gt_u32 s60, 29
	s_cbranch_scc0 .LBB0_1145
	s_and_b64 vcc, exec, s[10:11]
	s_cbranch_vccz .LBB0_1148
	s_barrier

; #define PG8_STAGE(bufoff, gbase, voff) do { _Pragma("unroll") for (int _i = 0; _i < 2; ++_i) \
;         __builtin_amdgcn_global_load_lds((const unsigned*)((const char*)(gbase) + (voff)[_i]), (LAS unsigned*)(lds + (bufoff) + ldsw + _i * 8192), 16, 0, 0); } while (0)
; #define PG8_LDA(dst, b, h) do { _Pragma("unroll") for (int m = 0; m < 4; ++m) _Pragma("unroll") for (int k = 0; k < 2; ++k) dst[m][k] = *(const LAS bf16x8*)(lds + PG8_SA(b, h) + aoff + m * 2048 + k * 1024); } while (0)
; #define PG8_LDB(dst, b, h) do { _Pragma("unroll") for (int n = 0; n < 2; ++n) _Pragma("unroll") for (int k = 0; k < 2; ++k) dst[n][k] = *(const LAS bf16x8*)(lds + PG8_SB(b, h) + boff + n * 2048 + k * 1024); } while (0)
; #define PG8_MMA(ai, bj, At, Bt) do { __builtin_amdgcn_s_setprio(1); _Pragma("unroll") for (int m = 0; m < 4; ++m) _Pragma("unroll") for (int n = 0; n < 2; ++n) _Pragma("unroll") for (int k = 0; k < 2; ++k) \
;         acc[ai][bj][m][n] = __builtin_amdgcn_mfma_f32_16x16x32_bf16(Bt[n][k], At[m][k], acc[ai][bj][m][n], 0, 0, 0); __builtin_amdgcn_s_setprio(0); } while (0)
; #define PG8_WAIT_V(n) asm volatile("s_waitcnt vmcnt(" #n ")" ::: "memory")
; #define PG8_WAIT_L(n) asm volatile("s_waitcnt lgkmcnt(" #n ")" ::: "memory")
; #define PG8_BAR __builtin_amdgcn_s_barrier()
; #define PG8_SCHED __builtin_amdgcn_sched_barrier(0)
; template <class Epi>
; __device__ __forceinline__ void gemm_phase(LAS unsigned char* lds, const Gemm g, const Order& S, const Epi& E, const int wid) {
;     ...
;             const bool last = (t == nt - 2);
;             const char* a1 = cA + (size_t)(t + 1) * kstep;
;             const char* a2 = last ? nA : cA + (size_t)(t + 2) * kstep; const char* b2 = last ? nB : cB + (size_t)(t + 2) * kstep;
;             const char* a3 = a2 + kstep; const char* b3 = b2 + kstep;
;     ...
;             PG8_LDB(B0, 0, 0); PG8_LDB(B1, 0, 1); PG8_SCHED; PG8_LDA(At, 0, 0); PG8_STAGE(PG8_SA(1, 1), a1 + hA, voffA);
;             PG8_WAIT_V(8); PG8_WAIT_L(0); PG8_BAR; PG8_MMA(0, 0, At, B0); PG8_MMA(0, 1, At, B1); PG8_BAR; PG8_SCHED;
;             PG8_LDA(At, 0, 1); PG8_STAGE(PG8_SB(0, 0), b2, voffB); PG8_STAGE(PG8_SB(0, 1), b2 + hB, voffB); PG8_STAGE(PG8_SA(0, 0), a2, voffA);
;             PG8_WAIT_V(8); PG8_WAIT_L(0); PG8_BAR; PG8_MMA(1, 0, At, B0); PG8_MMA(1, 1, At, B1); PG8_BAR; PG8_SCHED;
.LBB0_1289:
	ds_read_b128 v[74:77], v71
	ds_read_b128 v[78:81], v71 offset:1024
	ds_read_b128 v[82:85], v71 offset:2048
	ds_read_b128 v[86:89], v71 offset:3072
	ds_read_b128 v[90:93], v72
	ds_read_b128 v[160:163], v72 offset:1024
	ds_read_b128 v[164:167], v72 offset:2048
	ds_read_b128 v[174:177], v72 offset:3072
	s_add_u32 s43, s4, 0xfffc0080
	s_addc_u32 s56, s5, -1
	s_cmp_eq_u32 s41, 12
	s_cselect_b32 s59, s69, s56
	s_cselect_b32 s58, s68, s43
	s_cselect_b32 s57, s71, s39
	s_cselect_b32 s56, s70, s7
	v_lshl_add_u64 v[94:95], s[4:5], 0, v[168:169]
	s_add_i32 m0, s27, 0xc000
	ds_read_b128 v[178:181], v73
	ds_read_b128 v[182:185], v73 offset:1024
	ds_read_b128 v[186:189], v73 offset:2048
	ds_read_b128 v[192:195], v73 offset:3072
	ds_read_b128 v[196:199], v73 offset:4096
	ds_read_b128 v[200:203], v73 offset:5120
	ds_read_b128 v[204:207], v73 offset:6144
	ds_read_b128 v[208:211], v73 offset:7168
	global_load_lds_dwordx4 v[94:95], off
	v_lshl_add_u64 v[94:95], s[4:5], 0, v[68:69]
	s_add_i32 m0, s27, 0xe000
	s_nop 0
	global_load_lds_dwordx4 v[94:95], off
	s_waitcnt vmcnt(8)
	s_waitcnt lgkmcnt(0)
	s_barrier
	s_waitcnt lgkmcnt(0)
	v_mfma_f32_16x16x32_bf16 v[156:159], v[74:77], v[178:181], v[156:159]
	v_mfma_f32_16x16x32_bf16 v[156:159], v[78:81], v[182:185], v[156:159]
	v_mfma_f32_16x16x32_bf16 v[152:155], v[82:85], v[178:181], v[152:155]
	v_mfma_f32_16x16x32_bf16 v[152:155], v[86:89], v[182:185], v[152:155]
	v_mfma_f32_16x16x32_bf16 v[140:143], v[74:77], v[186:189], v[140:143]
	v_mfma_f32_16x16x32_bf16 v[140:143], v[78:81], v[192:195], v[140:143]
	v_mfma_f32_16x16x32_bf16 v[136:139], v[82:85], v[186:189], v[136:139]
	v_mfma_f32_16x16x32_bf16 v[136:139], v[86:89], v[192:195], v[136:139]
	v_mfma_f32_16x16x32_bf16 v[124:127], v[74:77], v[196:199], v[124:127]
	v_mfma_f32_16x16x32_bf16 v[124:127], v[78:81], v[200:203], v[124:127]
	v_mfma_f32_16x16x32_bf16 v[120:123], v[82:85], v[196:199], v[120:123]
	v_mfma_f32_16x16x32_bf16 v[120:123], v[86:89], v[200:203], v[120:123]
	v_mfma_f32_16x16x32_bf16 v[108:111], v[74:77], v[204:207], v[108:111]
	v_mfma_f32_16x16x32_bf16 v[108:111], v[78:81], v[208:211], v[108:111]
	v_mfma_f32_16x16x32_bf16 v[104:107], v[82:85], v[204:207], v[104:107]
	v_mfma_f32_16x16x32_bf16 v[104:107], v[86:89], v[208:211], v[104:107]
	v_mfma_f32_16x16x32_bf16 v[148:151], v[90:93], v[178:181], v[148:151]
	v_mfma_f32_16x16x32_bf16 v[144:147], v[164:167], v[178:181], v[144:147]
	v_mfma_f32_16x16x32_bf16 v[132:135], v[90:93], v[186:189], v[132:135]
	v_mfma_f32_16x16x32_bf16 v[128:131], v[164:167], v[186:189], v[128:131]
	v_mfma_f32_16x16x32_bf16 v[116:119], v[90:93], v[196:199], v[116:119]
	v_mfma_f32_16x16x32_bf16 v[112:115], v[164:167], v[196:199], v[112:115]
	v_mfma_f32_16x16x32_bf16 v[100:103], v[90:93], v[204:207], v[100:103]
	v_mfma_f32_16x16x32_bf16 v[94:97], v[164:167], v[204:207], v[96:99]
	v_mfma_f32_16x16x32_bf16 v[148:151], v[160:163], v[182:185], v[148:151]
	v_mfma_f32_16x16x32_bf16 v[144:147], v[174:177], v[182:185], v[144:147]
	v_mfma_f32_16x16x32_bf16 v[132:135], v[160:163], v[192:195], v[132:135]
	v_mfma_f32_16x16x32_bf16 v[128:131], v[174:177], v[192:195], v[128:131]
	v_mfma_f32_16x16x32_bf16 v[116:119], v[160:163], v[200:203], v[116:119]
	v_mfma_f32_16x16x32_bf16 v[112:115], v[174:177], v[200:203], v[112:115]
	v_mfma_f32_16x16x32_bf16 v[100:103], v[160:163], v[208:211], v[100:103]
	v_mfma_f32_16x16x32_bf16 v[94:97], v[174:177], v[208:211], v[94:97]
	s_barrier
	s_add_i32 s43, s62, s26
	v_lshl_add_u64 v[212:213], s[56:57], 0, v[64:65]
	s_mov_b32 m0, s43
	ds_read_b128 v[178:181], v73 offset:16384
	ds_read_b128 v[182:185], v73 offset:17408
	ds_read_b128 v[186:189], v73 offset:18432
	ds_read_b128 v[192:195], v73 offset:19456
	ds_read_b128 v[196:199], v73 offset:20480
	ds_read_b128 v[200:203], v73 offset:21504
	ds_read_b128 v[204:207], v73 offset:22528
	ds_read_b128 v[208:211], v73 offset:23552
	global_load_lds_dwordx4 v[212:213], off
	s_add_i32 m0, s43, 0x2000
	s_add_u32 s66, s56, 0x40000
	v_lshl_add_u64 v[214:215], s[56:57], 0, v[66:67]
	s_addc_u32 s67, s57, 0
	s_add_i32 s43, s63, s26
	global_load_lds_dwordx4 v[214:215], off
	v_lshl_add_u64 v[98:99], s[66:67], 0, v[64:65]
	s_mov_b32 m0, s43
	v_lshl_add_u64 v[216:217], s[58:59], 0, v[168:169]
	global_load_lds_dwordx4 v[98:99], off
	v_lshl_add_u64 v[98:99], s[66:67], 0, v[66:67]
	s_add_i32 m0, s43, 0x2000
	v_lshl_add_u64 v[218:219], s[58:59], 0, v[68:69]
	global_load_lds_dwordx4 v[98:99], off
	s_mov_b32 m0, s27
	s_nop 0
	global_load_lds_dwordx4 v[216:217], off
	s_mov_b32 m0, s29
	s_nop 0
	global_load_lds_dwordx4 v[218:219], off
	s_waitcnt vmcnt(8)
	s_waitcnt lgkmcnt(0)
	s_barrier
; #define PG8_STAGE(bufoff, gbase, voff) do { _Pragma("unroll") for (int _i = 0; _i < 2; ++_i) \
;         __builtin_amdgcn_global_load_lds((const unsigned*)((const char*)(gbase) + (voff)[_i]), (LAS unsigned*)(lds + (bufoff) + ldsw + _i * 8192), 16, 0, 0); } while (0)
; #define PG8_LDA(dst, b, h) do { _Pragma("unroll") for (int m = 0; m < 4; ++m) _Pragma("unroll") for (int k = 0; k < 2; ++k) dst[m][k] = *(const LAS bf16x8*)(lds + PG8_SA(b, h) + aoff + m * 2048 + k * 1024); } while (0)
; #define PG8_LDB(dst, b, h) do { _Pragma("unroll") for (int n = 0; n < 2; ++n) _Pragma("unroll") for (int k = 0; k < 2; ++k) dst[n][k] = *(const LAS bf16x8*)(lds + PG8_SB(b, h) + boff + n * 2048 + k * 1024); } while (0)
; #define PG8_MMA(ai, bj, At, Bt) do { __builtin_amdgcn_s_setprio(1); _Pragma("unroll") for (int m = 0; m < 4; ++m) _Pragma("unroll") for (int n = 0; n < 2; ++n) _Pragma("unroll") for (int k = 0; k < 2; ++k) \
;         acc[ai][bj][m][n] = __builtin_amdgcn_mfma_f32_16x16x32_bf16(Bt[n][k], At[m][k], acc[ai][bj][m][n], 0, 0, 0); __builtin_amdgcn_s_setprio(0); } while (0)
; #define PG8_WAIT_V(n) asm volatile("s_waitcnt vmcnt(" #n ")" ::: "memory")
; #define PG8_WAIT_L(n) asm volatile("s_waitcnt lgkmcnt(" #n ")" ::: "memory")
; #define PG8_BAR __builtin_amdgcn_s_barrier()
; #define PG8_SCHED __builtin_amdgcn_sched_barrier(0)
; template <class Epi>
; __device__ __forceinline__ void gemm_phase(LAS unsigned char* lds, const Gemm g, const Order& S, const Epi& E, const int wid) {
;     ...
;             PG8_WAIT_V(8); PG8_WAIT_L(0); PG8_BAR; PG8_MMA(1, 0, At, B0); PG8_MMA(1, 1, At, B1); PG8_BAR; PG8_SCHED;
;             PG8_LDB(B0, 1, 0); PG8_LDB(B1, 1, 1); PG8_SCHED; PG8_LDA(At, 1, 0); PG8_STAGE(PG8_SA(0, 1), a2 + hA, voffA);
;             PG8_WAIT_V(8); PG8_WAIT_L(0); PG8_BAR; PG8_MMA(0, 0, At, B0); PG8_MMA(0, 1, At, B1); PG8_BAR; PG8_SCHED;
;             PG8_LDA(At, 1, 1); PG8_STAGE(PG8_SB(1, 0), b3, voffB); PG8_STAGE(PG8_SB(1, 1), b3 + hB, voffB); PG8_STAGE(PG8_SA(1, 0), a3, voffA);
	s_waitcnt lgkmcnt(0)
	v_mfma_f32_16x16x32_bf16 v[60:63], v[74:77], v[178:181], v[60:63]
	v_mfma_f32_16x16x32_bf16 v[60:63], v[78:81], v[182:185], v[60:63]
	v_mfma_f32_16x16x32_bf16 v[56:59], v[82:85], v[178:181], v[56:59]
	v_mfma_f32_16x16x32_bf16 v[56:59], v[86:89], v[182:185], v[56:59]
	v_mfma_f32_16x16x32_bf16 v[44:47], v[74:77], v[186:189], v[44:47]
	v_mfma_f32_16x16x32_bf16 v[44:47], v[78:81], v[192:195], v[44:47]
	v_mfma_f32_16x16x32_bf16 v[40:43], v[82:85], v[186:189], v[40:43]
	v_mfma_f32_16x16x32_bf16 v[40:43], v[86:89], v[192:195], v[40:43]
	v_mfma_f32_16x16x32_bf16 v[28:31], v[74:77], v[196:199], v[28:31]
	v_mfma_f32_16x16x32_bf16 v[28:31], v[78:81], v[200:203], v[28:31]
	v_mfma_f32_16x16x32_bf16 v[24:27], v[82:85], v[196:199], v[24:27]
	v_mfma_f32_16x16x32_bf16 v[24:27], v[86:89], v[200:203], v[24:27]
	v_mfma_f32_16x16x32_bf16 v[12:15], v[74:77], v[204:207], v[12:15]
	v_mfma_f32_16x16x32_bf16 v[12:15], v[78:81], v[208:211], v[12:15]
	v_mfma_f32_16x16x32_bf16 v[8:11], v[82:85], v[204:207], v[8:11]
	v_mfma_f32_16x16x32_bf16 v[8:11], v[86:89], v[208:211], v[8:11]
	v_mfma_f32_16x16x32_bf16 v[52:55], v[90:93], v[178:181], v[52:55]
	v_mfma_f32_16x16x32_bf16 v[52:55], v[160:163], v[182:185], v[52:55]
	v_mfma_f32_16x16x32_bf16 v[48:51], v[164:167], v[178:181], v[48:51]
	v_mfma_f32_16x16x32_bf16 v[48:51], v[174:177], v[182:185], v[48:51]
	v_mfma_f32_16x16x32_bf16 v[36:39], v[90:93], v[186:189], v[36:39]
	v_mfma_f32_16x16x32_bf16 v[36:39], v[160:163], v[192:195], v[36:39]
	v_mfma_f32_16x16x32_bf16 v[32:35], v[164:167], v[186:189], v[32:35]
	v_mfma_f32_16x16x32_bf16 v[32:35], v[174:177], v[192:195], v[32:35]
	v_mfma_f32_16x16x32_bf16 v[20:23], v[90:93], v[196:199], v[20:23]
	v_mfma_f32_16x16x32_bf16 v[20:23], v[160:163], v[200:203], v[20:23]
	v_mfma_f32_16x16x32_bf16 v[16:19], v[164:167], v[196:199], v[16:19]
	v_mfma_f32_16x16x32_bf16 v[16:19], v[174:177], v[200:203], v[16:19]
	v_mfma_f32_16x16x32_bf16 v[4:7], v[90:93], v[204:207], v[4:7]
	v_mfma_f32_16x16x32_bf16 v[4:7], v[160:163], v[208:211], v[4:7]
	v_mfma_f32_16x16x32_bf16 v[0:3], v[164:167], v[204:207], v[0:3]
	v_mfma_f32_16x16x32_bf16 v[0:3], v[174:177], v[208:211], v[0:3]
	s_barrier
	s_add_i32 s43, 0, 0x18000
	s_add_i32 s65, 0, 0x1c000
	v_add_u32_e32 v86, s43, v70
	v_add_u32_e32 v98, s65, v70
	ds_read_b128 v[74:77], v86
	ds_read_b128 v[78:81], v86 offset:1024
	ds_read_b128 v[82:85], v86 offset:2048
	ds_read_b128 v[86:89], v86 offset:3072
	ds_read_b128 v[90:93], v98
	ds_read_b128 v[160:163], v98 offset:1024
	ds_read_b128 v[164:167], v98 offset:2048
	ds_read_b128 v[174:177], v98 offset:3072
	s_add_u32 s58, s58, 0x40000
	s_addc_u32 s59, s59, 0
	s_mov_b32 m0, s30
	v_lshl_add_u64 v[98:99], s[58:59], 0, v[168:169]
	ds_read_b128 v[178:181], v73 offset:32768
	ds_read_b128 v[182:185], v73 offset:33792
	ds_read_b128 v[186:189], v73 offset:34816
	ds_read_b128 v[192:195], v73 offset:35840
	ds_read_b128 v[196:199], v73 offset:36864
	ds_read_b128 v[200:203], v73 offset:37888
	ds_read_b128 v[204:207], v73 offset:38912
	ds_read_b128 v[208:211], v73 offset:39936
	global_load_lds_dwordx4 v[98:99], off
	v_lshl_add_u64 v[98:99], s[58:59], 0, v[68:69]
	s_mov_b32 m0, s31
	s_nop 0
	global_load_lds_dwordx4 v[98:99], off
	s_waitcnt vmcnt(8)
	s_waitcnt lgkmcnt(0)
	s_barrier
	s_waitcnt lgkmcnt(0)
	v_mfma_f32_16x16x32_bf16 v[156:159], v[74:77], v[178:181], v[156:159]
	v_mfma_f32_16x16x32_bf16 v[156:159], v[78:81], v[182:185], v[156:159]
	v_mfma_f32_16x16x32_bf16 v[152:155], v[82:85], v[178:181], v[152:155]
	v_mfma_f32_16x16x32_bf16 v[152:155], v[86:89], v[182:185], v[152:155]
	v_mfma_f32_16x16x32_bf16 v[140:143], v[74:77], v[186:189], v[140:143]
	v_mfma_f32_16x16x32_bf16 v[140:143], v[78:81], v[192:195], v[140:143]
	v_mfma_f32_16x16x32_bf16 v[136:139], v[82:85], v[186:189], v[136:139]
	v_mfma_f32_16x16x32_bf16 v[136:139], v[86:89], v[192:195], v[136:139]
	v_mfma_f32_16x16x32_bf16 v[124:127], v[74:77], v[196:199], v[124:127]
	v_mfma_f32_16x16x32_bf16 v[124:127], v[78:81], v[200:203], v[124:127]
	v_mfma_f32_16x16x32_bf16 v[120:123], v[82:85], v[196:199], v[120:123]
	v_mfma_f32_16x16x32_bf16 v[120:123], v[86:89], v[200:203], v[120:123]
	v_mfma_f32_16x16x32_bf16 v[108:111], v[74:77], v[204:207], v[108:111]
	v_mfma_f32_16x16x32_bf16 v[108:111], v[78:81], v[208:211], v[108:111]
	v_mfma_f32_16x16x32_bf16 v[104:107], v[82:85], v[204:207], v[104:107]
	v_mfma_f32_16x16x32_bf16 v[104:107], v[86:89], v[208:211], v[104:107]
	v_mfma_f32_16x16x32_bf16 v[148:151], v[90:93], v[178:181], v[148:151]
	v_mfma_f32_16x16x32_bf16 v[144:147], v[164:167], v[178:181], v[144:147]
	v_mfma_f32_16x16x32_bf16 v[132:135], v[90:93], v[186:189], v[132:135]
	v_mfma_f32_16x16x32_bf16 v[128:131], v[164:167], v[186:189], v[128:131]
	v_mfma_f32_16x16x32_bf16 v[116:119], v[90:93], v[196:199], v[116:119]
	v_mfma_f32_16x16x32_bf16 v[112:115], v[164:167], v[196:199], v[112:115]
	v_mfma_f32_16x16x32_bf16 v[98:101], v[90:93], v[204:207], v[100:103]
	v_mfma_f32_16x16x32_bf16 v[94:97], v[164:167], v[204:207], v[94:97]
	v_mfma_f32_16x16x32_bf16 v[148:151], v[160:163], v[182:185], v[148:151]
	v_mfma_f32_16x16x32_bf16 v[144:147], v[174:177], v[182:185], v[144:147]
	v_mfma_f32_16x16x32_bf16 v[132:135], v[160:163], v[192:195], v[132:135]
	v_mfma_f32_16x16x32_bf16 v[128:131], v[174:177], v[192:195], v[128:131]
	v_mfma_f32_16x16x32_bf16 v[116:119], v[160:163], v[200:203], v[116:119]
	v_mfma_f32_16x16x32_bf16 v[112:115], v[174:177], v[200:203], v[112:115]
	v_mfma_f32_16x16x32_bf16 v[100:103], v[160:163], v[208:211], v[98:101]
	v_mfma_f32_16x16x32_bf16 v[96:99], v[174:177], v[208:211], v[94:97]
	s_barrier
; #define PG8_STAGE(bufoff, gbase, voff) do { _Pragma("unroll") for (int _i = 0; _i < 2; ++_i) \
;         __builtin_amdgcn_global_load_lds((const unsigned*)((const char*)(gbase) + (voff)[_i]), (LAS unsigned*)(lds + (bufoff) + ldsw + _i * 8192), 16, 0, 0); } while (0)
; #define PG8_LDA(dst, b, h) do { _Pragma("unroll") for (int m = 0; m < 4; ++m) _Pragma("unroll") for (int k = 0; k < 2; ++k) dst[m][k] = *(const LAS bf16x8*)(lds + PG8_SA(b, h) + aoff + m * 2048 + k * 1024); } while (0)
; #define PG8_MMA(ai, bj, At, Bt) do { __builtin_amdgcn_s_setprio(1); _Pragma("unroll") for (int m = 0; m < 4; ++m) _Pragma("unroll") for (int n = 0; n < 2; ++n) _Pragma("unroll") for (int k = 0; k < 2; ++k) \
;         acc[ai][bj][m][n] = __builtin_amdgcn_mfma_f32_16x16x32_bf16(Bt[n][k], At[m][k], acc[ai][bj][m][n], 0, 0, 0); __builtin_amdgcn_s_setprio(0); } while (0)
; #define PG8_WAIT_V(n) asm volatile("s_waitcnt vmcnt(" #n ")" ::: "memory")
; #define PG8_WAIT_L(n) asm volatile("s_waitcnt lgkmcnt(" #n ")" ::: "memory")
; #define PG8_BAR __builtin_amdgcn_s_barrier()
; #define PG8_SCHED __builtin_amdgcn_sched_barrier(0)
; template <class Epi>
; __device__ __forceinline__ void gemm_phase(LAS unsigned char* lds, const Gemm g, const Order& S, const Epi& E, const int wid) {
;     ...
;             PG8_LDA(At, 1, 1); PG8_STAGE(PG8_SB(1, 0), b3, voffB); PG8_STAGE(PG8_SB(1, 1), b3 + hB, voffB); PG8_STAGE(PG8_SA(1, 0), a3, voffA);
;             PG8_WAIT_V(8); PG8_WAIT_L(0); PG8_BAR; PG8_MMA(1, 0, At, B0); PG8_MMA(1, 1, At, B1); PG8_BAR; PG8_SCHED;
	s_add_i32 s43, s43, s26
	v_lshl_add_u64 v[94:95], v[212:213], 0, s[22:23]
	s_mov_b32 m0, s43
	ds_read_b128 v[178:181], v73 offset:49152
	ds_read_b128 v[182:185], v73 offset:50176
	ds_read_b128 v[186:189], v73 offset:51200
	ds_read_b128 v[192:195], v73 offset:52224
	ds_read_b128 v[196:199], v73 offset:53248
	ds_read_b128 v[200:203], v73 offset:54272
	ds_read_b128 v[204:207], v73 offset:55296
	ds_read_b128 v[208:211], v73 offset:56320
	global_load_lds_dwordx4 v[94:95], off
	s_add_i32 m0, s43, 0x2000
	s_add_u32 s56, s56, 0x40080
	v_lshl_add_u64 v[94:95], v[214:215], 0, s[22:23]
	s_addc_u32 s57, s57, 0
	s_add_i32 s43, s65, s26
	global_load_lds_dwordx4 v[94:95], off
	v_lshl_add_u64 v[94:95], s[56:57], 0, v[64:65]
	s_mov_b32 m0, s43
	s_nop 0
	global_load_lds_dwordx4 v[94:95], off
	v_lshl_add_u64 v[94:95], s[56:57], 0, v[66:67]
	s_add_i32 m0, s43, 0x2000
	s_nop 0
	global_load_lds_dwordx4 v[94:95], off
	v_lshl_add_u64 v[94:95], v[216:217], 0, s[22:23]
	s_mov_b32 m0, s73
	s_nop 0
	global_load_lds_dwordx4 v[94:95], off
	v_lshl_add_u64 v[94:95], v[218:219], 0, s[22:23]
	s_mov_b32 m0, s60
	s_nop 0
	global_load_lds_dwordx4 v[94:95], off
	s_waitcnt vmcnt(8)
	s_waitcnt lgkmcnt(0)
	s_barrier
	s_waitcnt lgkmcnt(0)
	v_mfma_f32_16x16x32_bf16 v[60:63], v[74:77], v[178:181], v[60:63]
	v_mfma_f32_16x16x32_bf16 v[60:63], v[78:81], v[182:185], v[60:63]
	v_mfma_f32_16x16x32_bf16 v[56:59], v[82:85], v[178:181], v[56:59]
	v_mfma_f32_16x16x32_bf16 v[56:59], v[86:89], v[182:185], v[56:59]
	v_mfma_f32_16x16x32_bf16 v[44:47], v[74:77], v[186:189], v[44:47]
	v_mfma_f32_16x16x32_bf16 v[44:47], v[78:81], v[192:195], v[44:47]
	v_mfma_f32_16x16x32_bf16 v[40:43], v[82:85], v[186:189], v[40:43]
	v_mfma_f32_16x16x32_bf16 v[40:43], v[86:89], v[192:195], v[40:43]
	v_mfma_f32_16x16x32_bf16 v[28:31], v[74:77], v[196:199], v[28:31]
	v_mfma_f32_16x16x32_bf16 v[28:31], v[78:81], v[200:203], v[28:31]
	v_mfma_f32_16x16x32_bf16 v[24:27], v[82:85], v[196:199], v[24:27]
	v_mfma_f32_16x16x32_bf16 v[24:27], v[86:89], v[200:203], v[24:27]
	v_mfma_f32_16x16x32_bf16 v[12:15], v[74:77], v[204:207], v[12:15]
	v_mfma_f32_16x16x32_bf16 v[12:15], v[78:81], v[208:211], v[12:15]
	v_mfma_f32_16x16x32_bf16 v[8:11], v[82:85], v[204:207], v[8:11]
	v_mfma_f32_16x16x32_bf16 v[8:11], v[86:89], v[208:211], v[8:11]
	v_mfma_f32_16x16x32_bf16 v[52:55], v[90:93], v[178:181], v[52:55]
	v_mfma_f32_16x16x32_bf16 v[52:55], v[160:163], v[182:185], v[52:55]
	v_mfma_f32_16x16x32_bf16 v[48:51], v[164:167], v[178:181], v[48:51]
	v_mfma_f32_16x16x32_bf16 v[48:51], v[174:177], v[182:185], v[48:51]
	v_mfma_f32_16x16x32_bf16 v[36:39], v[90:93], v[186:189], v[36:39]
	v_mfma_f32_16x16x32_bf16 v[36:39], v[160:163], v[192:195], v[36:39]
	v_mfma_f32_16x16x32_bf16 v[32:35], v[164:167], v[186:189], v[32:35]
	v_mfma_f32_16x16x32_bf16 v[32:35], v[174:177], v[192:195], v[32:35]
	v_mfma_f32_16x16x32_bf16 v[20:23], v[90:93], v[196:199], v[20:23]
	v_mfma_f32_16x16x32_bf16 v[20:23], v[160:163], v[200:203], v[20:23]
	v_mfma_f32_16x16x32_bf16 v[16:19], v[164:167], v[196:199], v[16:19]
	v_mfma_f32_16x16x32_bf16 v[16:19], v[174:177], v[200:203], v[16:19]
	v_mfma_f32_16x16x32_bf16 v[4:7], v[90:93], v[204:207], v[4:7]
	v_mfma_f32_16x16x32_bf16 v[4:7], v[160:163], v[208:211], v[4:7]
	v_mfma_f32_16x16x32_bf16 v[0:3], v[164:167], v[204:207], v[0:3]
	v_mfma_f32_16x16x32_bf16 v[0:3], v[174:177], v[208:211], v[0:3]
	s_barrier
	s_add_i32 s41, s41, 2
	s_add_u32 s4, s4, 0x100
	s_addc_u32 s5, s5, 0
	s_add_u32 s7, s7, 0x100
	s_addc_u32 s39, s39, 0
	s_cmp_gt_u32 s41, 13
	s_cbranch_scc0 .LBB0_1289
	s_and_b64 vcc, exec, s[12:13]
	s_cbranch_vccz .LBB0_1292
	s_barrier

; #define PG8_STAGE(bufoff, gbase, voff) do { _Pragma("unroll") for (int _i = 0; _i < 2; ++_i) \
;         __builtin_amdgcn_global_load_lds((const unsigned*)((const char*)(gbase) + (voff)[_i]), (LAS unsigned*)(lds + (bufoff) + ldsw + _i * 8192), 16, 0, 0); } while (0)
; #define PG8_LDA(dst, b, h) do { _Pragma("unroll") for (int m = 0; m < 4; ++m) _Pragma("unroll") for (int k = 0; k < 2; ++k) dst[m][k] = *(const LAS bf16x8*)(lds + PG8_SA(b, h) + aoff + m * 2048 + k * 1024); } while (0)
; #define PG8_LDB(dst, b, h) do { _Pragma("unroll") for (int n = 0; n < 2; ++n) _Pragma("unroll") for (int k = 0; k < 2; ++k) dst[n][k] = *(const LAS bf16x8*)(lds + PG8_SB(b, h) + boff + n * 2048 + k * 1024); } while (0)
; #define PG8_MMA(ai, bj, At, Bt) do { __builtin_amdgcn_s_setprio(1); _Pragma("unroll") for (int m = 0; m < 4; ++m) _Pragma("unroll") for (int n = 0; n < 2; ++n) _Pragma("unroll") for (int k = 0; k < 2; ++k) \
;         acc[ai][bj][m][n] = __builtin_amdgcn_mfma_f32_16x16x32_bf16(Bt[n][k], At[m][k], acc[ai][bj][m][n], 0, 0, 0); __builtin_amdgcn_s_setprio(0); } while (0)
; #define PG8_WAIT_V(n) asm volatile("s_waitcnt vmcnt(" #n ")" ::: "memory")
; #define PG8_WAIT_L(n) asm volatile("s_waitcnt lgkmcnt(" #n ")" ::: "memory")
; #define PG8_BAR __builtin_amdgcn_s_barrier()
; #define PG8_SCHED __builtin_amdgcn_sched_barrier(0)
; template <class Epi>
; __device__ __forceinline__ void gemm_phase(LAS unsigned char* lds, const Gemm g, const Order& S, const Epi& E, const int wid) {
;     ...
;             const bool last = (t == nt - 2);
;             const char* a1 = cA + (size_t)(t + 1) * kstep;
;             const char* a2 = last ? nA : cA + (size_t)(t + 2) * kstep; const char* b2 = last ? nB : cB + (size_t)(t + 2) * kstep;
;             const char* a3 = a2 + kstep; const char* b3 = b2 + kstep;
;     ...
;             PG8_LDB(B0, 0, 0); PG8_LDB(B1, 0, 1); PG8_SCHED; PG8_LDA(At, 0, 0); PG8_STAGE(PG8_SA(1, 1), a1 + hA, voffA);
;             PG8_WAIT_V(8); PG8_WAIT_L(0); PG8_BAR; PG8_MMA(0, 0, At, B0); PG8_MMA(0, 1, At, B1); PG8_BAR; PG8_SCHED;
;             PG8_LDA(At, 0, 1); PG8_STAGE(PG8_SB(0, 0), b2, voffB); PG8_STAGE(PG8_SB(0, 1), b2 + hB, voffB); PG8_STAGE(PG8_SA(0, 0), a2, voffA);
;             PG8_WAIT_V(8); PG8_WAIT_L(0); PG8_BAR; PG8_MMA(1, 0, At, B0); PG8_MMA(1, 1, At, B1); PG8_BAR; PG8_SCHED;
.LBB0_1378:
	ds_read_b128 v[138:141], v135
	ds_read_b128 v[142:145], v135 offset:1024
	ds_read_b128 v[146:149], v135 offset:2048
	ds_read_b128 v[150:153], v135 offset:3072
	ds_read_b128 v[154:157], v136
	ds_read_b128 v[158:161], v136 offset:1024
	ds_read_b128 v[162:165], v136 offset:2048
	ds_read_b128 v[166:169], v136 offset:3072
	s_add_u32 s8, s6, 0xfff00080
	s_addc_u32 s9, s7, -1
	s_cmp_eq_u32 s55, 60
	s_cselect_b32 s11, s12, s9
	s_cselect_b32 s10, s13, s8
	s_cselect_b32 s9, s16, s31
	s_cselect_b32 s8, s17, s27
	v_lshl_add_u64 v[190:191], s[6:7], 0, v[192:193]
	s_add_i32 m0, s63, 0xc000
	ds_read_b128 v[170:173], v137
	ds_read_b128 v[174:177], v137 offset:1024
	ds_read_b128 v[178:181], v137 offset:2048
	ds_read_b128 v[182:185], v137 offset:3072
	ds_read_b128 v[186:189], v137 offset:4096
	ds_read_b128 v[198:201], v137 offset:5120
	ds_read_b128 v[202:205], v137 offset:6144
	ds_read_b128 v[206:209], v137 offset:7168
	global_load_lds_dwordx4 v[190:191], off
	v_lshl_add_u64 v[190:191], s[6:7], 0, v[132:133]
	s_add_i32 m0, s63, 0xe000
	s_nop 0
	global_load_lds_dwordx4 v[190:191], off
	s_waitcnt vmcnt(8)
	s_waitcnt lgkmcnt(0)
	s_barrier
	s_waitcnt lgkmcnt(0)
	v_mfma_f32_16x16x32_bf16 v[124:127], v[138:141], v[170:173], v[124:127]
	v_mfma_f32_16x16x32_bf16 v[124:127], v[142:145], v[174:177], v[124:127]
	v_mfma_f32_16x16x32_bf16 v[120:123], v[146:149], v[170:173], v[120:123]
	v_mfma_f32_16x16x32_bf16 v[120:123], v[150:153], v[174:177], v[120:123]
	v_mfma_f32_16x16x32_bf16 v[0:3], v[138:141], v[178:181], v[0:3]
	v_mfma_f32_16x16x32_bf16 v[0:3], v[142:145], v[182:185], v[0:3]
	v_mfma_f32_16x16x32_bf16 v[4:7], v[146:149], v[178:181], v[4:7]
	v_mfma_f32_16x16x32_bf16 v[4:7], v[150:153], v[182:185], v[4:7]
	v_mfma_f32_16x16x32_bf16 v[12:15], v[138:141], v[186:189], v[12:15]
	v_mfma_f32_16x16x32_bf16 v[12:15], v[142:145], v[198:201], v[12:15]
	v_mfma_f32_16x16x32_bf16 v[20:23], v[146:149], v[186:189], v[20:23]
	v_mfma_f32_16x16x32_bf16 v[20:23], v[150:153], v[198:201], v[20:23]
	v_mfma_f32_16x16x32_bf16 v[116:119], v[138:141], v[202:205], v[116:119]
	v_mfma_f32_16x16x32_bf16 v[116:119], v[142:145], v[206:209], v[116:119]
	v_mfma_f32_16x16x32_bf16 v[112:115], v[146:149], v[202:205], v[112:115]
	v_mfma_f32_16x16x32_bf16 v[112:115], v[150:153], v[206:209], v[112:115]
	v_mfma_f32_16x16x32_bf16 v[108:111], v[154:157], v[170:173], v[108:111]
	v_mfma_f32_16x16x32_bf16 v[108:111], v[158:161], v[174:177], v[108:111]
	v_mfma_f32_16x16x32_bf16 v[104:107], v[162:165], v[170:173], v[104:107]
	v_mfma_f32_16x16x32_bf16 v[104:107], v[166:169], v[174:177], v[104:107]
	v_mfma_f32_16x16x32_bf16 v[8:11], v[154:157], v[178:181], v[8:11]
	v_mfma_f32_16x16x32_bf16 v[8:11], v[158:161], v[182:185], v[8:11]
	v_mfma_f32_16x16x32_bf16 v[16:19], v[162:165], v[178:181], v[16:19]
	v_mfma_f32_16x16x32_bf16 v[16:19], v[166:169], v[182:185], v[16:19]
	v_mfma_f32_16x16x32_bf16 v[40:43], v[154:157], v[186:189], v[40:43]
	v_mfma_f32_16x16x32_bf16 v[40:43], v[158:161], v[198:201], v[40:43]
	v_mfma_f32_16x16x32_bf16 v[32:35], v[162:165], v[186:189], v[32:35]
	v_mfma_f32_16x16x32_bf16 v[32:35], v[166:169], v[198:201], v[32:35]
	v_mfma_f32_16x16x32_bf16 v[100:103], v[154:157], v[202:205], v[100:103]
	v_mfma_f32_16x16x32_bf16 v[100:103], v[158:161], v[206:209], v[100:103]
	v_mfma_f32_16x16x32_bf16 v[96:99], v[162:165], v[202:205], v[96:99]
	v_mfma_f32_16x16x32_bf16 v[96:99], v[166:169], v[206:209], v[96:99]
	s_barrier
	s_add_i32 s18, s33, s53
	v_lshl_add_u64 v[190:191], s[8:9], 0, v[128:129]
	s_mov_b32 m0, s18
	ds_read_b128 v[170:173], v137 offset:16384
	ds_read_b128 v[174:177], v137 offset:17408
	ds_read_b128 v[178:181], v137 offset:18432
	ds_read_b128 v[182:185], v137 offset:19456
	ds_read_b128 v[186:189], v137 offset:20480
	ds_read_b128 v[198:201], v137 offset:21504
	ds_read_b128 v[202:205], v137 offset:22528
	ds_read_b128 v[206:209], v137 offset:23552
	global_load_lds_dwordx4 v[190:191], off
	s_add_i32 m0, s18, 0x2000
	s_add_u32 s64, s8, 0x100000
	v_lshl_add_u64 v[210:211], s[8:9], 0, v[130:131]
	s_addc_u32 s65, s9, 0
	s_add_i32 s18, s67, s53
	global_load_lds_dwordx4 v[210:211], off
	v_lshl_add_u64 v[212:213], s[64:65], 0, v[128:129]
	s_mov_b32 m0, s18
	v_lshl_add_u64 v[214:215], s[10:11], 0, v[132:133]
	global_load_lds_dwordx4 v[212:213], off
	v_lshl_add_u64 v[212:213], s[64:65], 0, v[130:131]
	s_add_i32 m0, s18, 0x2000
	s_nop 0
	global_load_lds_dwordx4 v[212:213], off
	v_lshl_add_u64 v[212:213], s[10:11], 0, v[192:193]
	s_mov_b32 m0, s63
	s_nop 0
	global_load_lds_dwordx4 v[212:213], off
	s_mov_b32 m0, s68
	s_nop 0
	global_load_lds_dwordx4 v[214:215], off
	s_waitcnt vmcnt(8)
	s_waitcnt lgkmcnt(0)
	s_barrier
; #define PG8_STAGE(bufoff, gbase, voff) do { _Pragma("unroll") for (int _i = 0; _i < 2; ++_i) \
;         __builtin_amdgcn_global_load_lds((const unsigned*)((const char*)(gbase) + (voff)[_i]), (LAS unsigned*)(lds + (bufoff) + ldsw + _i * 8192), 16, 0, 0); } while (0)
; #define PG8_LDA(dst, b, h) do { _Pragma("unroll") for (int m = 0; m < 4; ++m) _Pragma("unroll") for (int k = 0; k < 2; ++k) dst[m][k] = *(const LAS bf16x8*)(lds + PG8_SA(b, h) + aoff + m * 2048 + k * 1024); } while (0)
; #define PG8_LDB(dst, b, h) do { _Pragma("unroll") for (int n = 0; n < 2; ++n) _Pragma("unroll") for (int k = 0; k < 2; ++k) dst[n][k] = *(const LAS bf16x8*)(lds + PG8_SB(b, h) + boff + n * 2048 + k * 1024); } while (0)
; #define PG8_MMA(ai, bj, At, Bt) do { __builtin_amdgcn_s_setprio(1); _Pragma("unroll") for (int m = 0; m < 4; ++m) _Pragma("unroll") for (int n = 0; n < 2; ++n) _Pragma("unroll") for (int k = 0; k < 2; ++k) \
;         acc[ai][bj][m][n] = __builtin_amdgcn_mfma_f32_16x16x32_bf16(Bt[n][k], At[m][k], acc[ai][bj][m][n], 0, 0, 0); __builtin_amdgcn_s_setprio(0); } while (0)
; #define PG8_WAIT_V(n) asm volatile("s_waitcnt vmcnt(" #n ")" ::: "memory")
; #define PG8_WAIT_L(n) asm volatile("s_waitcnt lgkmcnt(" #n ")" ::: "memory")
; #define PG8_BAR __builtin_amdgcn_s_barrier()
; #define PG8_SCHED __builtin_amdgcn_sched_barrier(0)
; template <class Epi>
; __device__ __forceinline__ void gemm_phase(LAS unsigned char* lds, const Gemm g, const Order& S, const Epi& E, const int wid) {
;     ...
;             PG8_WAIT_V(8); PG8_WAIT_L(0); PG8_BAR; PG8_MMA(1, 0, At, B0); PG8_MMA(1, 1, At, B1); PG8_BAR; PG8_SCHED;
;             PG8_LDB(B0, 1, 0); PG8_LDB(B1, 1, 1); PG8_SCHED; PG8_LDA(At, 1, 0); PG8_STAGE(PG8_SA(0, 1), a2 + hA, voffA);
;             PG8_WAIT_V(8); PG8_WAIT_L(0); PG8_BAR; PG8_MMA(0, 0, At, B0); PG8_MMA(0, 1, At, B1); PG8_BAR; PG8_SCHED;
;             PG8_LDA(At, 1, 1); PG8_STAGE(PG8_SB(1, 0), b3, voffB); PG8_STAGE(PG8_SB(1, 1), b3 + hB, voffB); PG8_STAGE(PG8_SA(1, 0), a3, voffA);
	s_waitcnt lgkmcnt(0)
	v_mfma_f32_16x16x32_bf16 v[92:95], v[138:141], v[170:173], v[92:95]
	v_mfma_f32_16x16x32_bf16 v[92:95], v[142:145], v[174:177], v[92:95]
	v_mfma_f32_16x16x32_bf16 v[88:91], v[146:149], v[170:173], v[88:91]
	v_mfma_f32_16x16x32_bf16 v[88:91], v[150:153], v[174:177], v[88:91]
	v_mfma_f32_16x16x32_bf16 v[24:27], v[138:141], v[178:181], v[24:27]
	v_mfma_f32_16x16x32_bf16 v[24:27], v[142:145], v[182:185], v[24:27]
	v_mfma_f32_16x16x32_bf16 v[28:31], v[146:149], v[178:181], v[28:31]
	v_mfma_f32_16x16x32_bf16 v[28:31], v[150:153], v[182:185], v[28:31]
	v_mfma_f32_16x16x32_bf16 v[44:47], v[138:141], v[186:189], v[44:47]
	v_mfma_f32_16x16x32_bf16 v[44:47], v[142:145], v[198:201], v[44:47]
	v_mfma_f32_16x16x32_bf16 v[52:55], v[146:149], v[186:189], v[52:55]
	v_mfma_f32_16x16x32_bf16 v[52:55], v[150:153], v[198:201], v[52:55]
	v_mfma_f32_16x16x32_bf16 v[84:87], v[138:141], v[202:205], v[84:87]
	v_mfma_f32_16x16x32_bf16 v[84:87], v[142:145], v[206:209], v[84:87]
	v_mfma_f32_16x16x32_bf16 v[80:83], v[146:149], v[202:205], v[80:83]
	v_mfma_f32_16x16x32_bf16 v[80:83], v[150:153], v[206:209], v[80:83]
	v_mfma_f32_16x16x32_bf16 v[76:79], v[154:157], v[170:173], v[76:79]
	v_mfma_f32_16x16x32_bf16 v[76:79], v[158:161], v[174:177], v[76:79]
	v_mfma_f32_16x16x32_bf16 v[72:75], v[162:165], v[170:173], v[72:75]
	v_mfma_f32_16x16x32_bf16 v[72:75], v[166:169], v[174:177], v[72:75]
	v_mfma_f32_16x16x32_bf16 v[36:39], v[154:157], v[178:181], v[36:39]
	v_mfma_f32_16x16x32_bf16 v[36:39], v[158:161], v[182:185], v[36:39]
	v_mfma_f32_16x16x32_bf16 v[48:51], v[162:165], v[178:181], v[48:51]
	v_mfma_f32_16x16x32_bf16 v[48:51], v[166:169], v[182:185], v[48:51]
	v_mfma_f32_16x16x32_bf16 v[60:63], v[154:157], v[186:189], v[60:63]
	v_mfma_f32_16x16x32_bf16 v[60:63], v[158:161], v[198:201], v[60:63]
	v_mfma_f32_16x16x32_bf16 v[56:59], v[162:165], v[186:189], v[56:59]
	v_mfma_f32_16x16x32_bf16 v[56:59], v[166:169], v[198:201], v[56:59]
	v_mfma_f32_16x16x32_bf16 v[68:71], v[154:157], v[202:205], v[68:71]
	v_mfma_f32_16x16x32_bf16 v[68:71], v[158:161], v[206:209], v[68:71]
	v_mfma_f32_16x16x32_bf16 v[64:67], v[162:165], v[202:205], v[64:67]
	v_mfma_f32_16x16x32_bf16 v[64:67], v[166:169], v[206:209], v[64:67]
	s_barrier
	s_add_i32 s18, 0, 0x18000
	s_add_i32 s19, 0, 0x1c000
	v_add_u32_e32 v150, s18, v134
	v_add_u32_e32 v166, s19, v134
	ds_read_b128 v[138:141], v150
	ds_read_b128 v[142:145], v150 offset:1024
	ds_read_b128 v[146:149], v150 offset:2048
	ds_read_b128 v[150:153], v150 offset:3072
	ds_read_b128 v[154:157], v166
	ds_read_b128 v[158:161], v166 offset:1024
	ds_read_b128 v[162:165], v166 offset:2048
	ds_read_b128 v[166:169], v166 offset:3072
	s_add_u32 s10, s10, 0x100000
	s_addc_u32 s11, s11, 0
	s_mov_b32 m0, s69
	v_lshl_add_u64 v[216:217], s[10:11], 0, v[192:193]
	ds_read_b128 v[170:173], v137 offset:32768
	ds_read_b128 v[174:177], v137 offset:33792
	ds_read_b128 v[178:181], v137 offset:34816
	ds_read_b128 v[182:185], v137 offset:35840
	ds_read_b128 v[186:189], v137 offset:36864
	ds_read_b128 v[198:201], v137 offset:37888
	ds_read_b128 v[202:205], v137 offset:38912
	ds_read_b128 v[206:209], v137 offset:39936
	global_load_lds_dwordx4 v[216:217], off
	v_lshl_add_u64 v[216:217], s[10:11], 0, v[132:133]
	s_mov_b32 m0, s70
	s_nop 0
	global_load_lds_dwordx4 v[216:217], off
	s_waitcnt vmcnt(8)
	s_waitcnt lgkmcnt(0)
	s_barrier
	s_waitcnt lgkmcnt(0)
	v_mfma_f32_16x16x32_bf16 v[124:127], v[138:141], v[170:173], v[124:127]
	v_mfma_f32_16x16x32_bf16 v[124:127], v[142:145], v[174:177], v[124:127]
	v_mfma_f32_16x16x32_bf16 v[120:123], v[146:149], v[170:173], v[120:123]
	v_mfma_f32_16x16x32_bf16 v[120:123], v[150:153], v[174:177], v[120:123]
	v_mfma_f32_16x16x32_bf16 v[0:3], v[138:141], v[178:181], v[0:3]
	v_mfma_f32_16x16x32_bf16 v[0:3], v[142:145], v[182:185], v[0:3]
	v_mfma_f32_16x16x32_bf16 v[4:7], v[146:149], v[178:181], v[4:7]
	v_mfma_f32_16x16x32_bf16 v[4:7], v[150:153], v[182:185], v[4:7]
	v_mfma_f32_16x16x32_bf16 v[12:15], v[138:141], v[186:189], v[12:15]
	v_mfma_f32_16x16x32_bf16 v[12:15], v[142:145], v[198:201], v[12:15]
	v_mfma_f32_16x16x32_bf16 v[20:23], v[146:149], v[186:189], v[20:23]
	v_mfma_f32_16x16x32_bf16 v[20:23], v[150:153], v[198:201], v[20:23]
	v_mfma_f32_16x16x32_bf16 v[116:119], v[138:141], v[202:205], v[116:119]
	v_mfma_f32_16x16x32_bf16 v[116:119], v[142:145], v[206:209], v[116:119]
	v_mfma_f32_16x16x32_bf16 v[112:115], v[146:149], v[202:205], v[112:115]
	v_mfma_f32_16x16x32_bf16 v[112:115], v[150:153], v[206:209], v[112:115]
	v_mfma_f32_16x16x32_bf16 v[108:111], v[154:157], v[170:173], v[108:111]
	v_mfma_f32_16x16x32_bf16 v[108:111], v[158:161], v[174:177], v[108:111]
	v_mfma_f32_16x16x32_bf16 v[104:107], v[162:165], v[170:173], v[104:107]
	v_mfma_f32_16x16x32_bf16 v[104:107], v[166:169], v[174:177], v[104:107]
	v_mfma_f32_16x16x32_bf16 v[8:11], v[154:157], v[178:181], v[8:11]
	v_mfma_f32_16x16x32_bf16 v[8:11], v[158:161], v[182:185], v[8:11]
	v_mfma_f32_16x16x32_bf16 v[16:19], v[162:165], v[178:181], v[16:19]
	v_mfma_f32_16x16x32_bf16 v[16:19], v[166:169], v[182:185], v[16:19]
	v_mfma_f32_16x16x32_bf16 v[40:43], v[154:157], v[186:189], v[40:43]
	v_mfma_f32_16x16x32_bf16 v[40:43], v[158:161], v[198:201], v[40:43]
	v_mfma_f32_16x16x32_bf16 v[32:35], v[162:165], v[186:189], v[32:35]
	v_mfma_f32_16x16x32_bf16 v[32:35], v[166:169], v[198:201], v[32:35]
	v_mfma_f32_16x16x32_bf16 v[100:103], v[154:157], v[202:205], v[100:103]
	v_mfma_f32_16x16x32_bf16 v[100:103], v[158:161], v[206:209], v[100:103]
	v_mfma_f32_16x16x32_bf16 v[96:99], v[162:165], v[202:205], v[96:99]
	v_mfma_f32_16x16x32_bf16 v[96:99], v[166:169], v[206:209], v[96:99]
	s_barrier
; #define PG8_STAGE(bufoff, gbase, voff) do { _Pragma("unroll") for (int _i = 0; _i < 2; ++_i) \
;         __builtin_amdgcn_global_load_lds((const unsigned*)((const char*)(gbase) + (voff)[_i]), (LAS unsigned*)(lds + (bufoff) + ldsw + _i * 8192), 16, 0, 0); } while (0)
; #define PG8_LDA(dst, b, h) do { _Pragma("unroll") for (int m = 0; m < 4; ++m) _Pragma("unroll") for (int k = 0; k < 2; ++k) dst[m][k] = *(const LAS bf16x8*)(lds + PG8_SA(b, h) + aoff + m * 2048 + k * 1024); } while (0)
; #define PG8_MMA(ai, bj, At, Bt) do { __builtin_amdgcn_s_setprio(1); _Pragma("unroll") for (int m = 0; m < 4; ++m) _Pragma("unroll") for (int n = 0; n < 2; ++n) _Pragma("unroll") for (int k = 0; k < 2; ++k) \
;         acc[ai][bj][m][n] = __builtin_amdgcn_mfma_f32_16x16x32_bf16(Bt[n][k], At[m][k], acc[ai][bj][m][n], 0, 0, 0); __builtin_amdgcn_s_setprio(0); } while (0)
; #define PG8_WAIT_V(n) asm volatile("s_waitcnt vmcnt(" #n ")" ::: "memory")
; #define PG8_WAIT_L(n) asm volatile("s_waitcnt lgkmcnt(" #n ")" ::: "memory")
; #define PG8_BAR __builtin_amdgcn_s_barrier()
; #define PG8_SCHED __builtin_amdgcn_sched_barrier(0)
; template <class Epi>
; __device__ __forceinline__ void gemm_phase(LAS unsigned char* lds, const Gemm g, const Order& S, const Epi& E, const int wid) {
;     ...
;             PG8_LDA(At, 1, 1); PG8_STAGE(PG8_SB(1, 0), b3, voffB); PG8_STAGE(PG8_SB(1, 1), b3 + hB, voffB); PG8_STAGE(PG8_SA(1, 0), a3, voffA);
;             PG8_WAIT_V(8); PG8_WAIT_L(0); PG8_BAR; PG8_MMA(1, 0, At, B0); PG8_MMA(1, 1, At, B1); PG8_BAR; PG8_SCHED;
	s_add_i32 s10, s18, s53
	v_lshl_add_u64 v[190:191], v[190:191], 0, s[48:49]
	s_mov_b32 m0, s10
	ds_read_b128 v[170:173], v137 offset:49152
	ds_read_b128 v[174:177], v137 offset:50176
	ds_read_b128 v[178:181], v137 offset:51200
	ds_read_b128 v[182:185], v137 offset:52224
	ds_read_b128 v[186:189], v137 offset:53248
	ds_read_b128 v[198:201], v137 offset:54272
	ds_read_b128 v[202:205], v137 offset:55296
	ds_read_b128 v[206:209], v137 offset:56320
	global_load_lds_dwordx4 v[190:191], off
	s_add_i32 m0, s10, 0x2000
	s_add_u32 s8, s8, 0x100080
	v_lshl_add_u64 v[190:191], v[210:211], 0, s[48:49]
	s_addc_u32 s9, s9, 0
	s_add_i32 s10, s19, s53
	global_load_lds_dwordx4 v[190:191], off
	v_lshl_add_u64 v[190:191], s[8:9], 0, v[128:129]
	s_mov_b32 m0, s10
	s_nop 0
	global_load_lds_dwordx4 v[190:191], off
	v_lshl_add_u64 v[190:191], s[8:9], 0, v[130:131]
	s_add_i32 m0, s10, 0x2000
	s_nop 0
	global_load_lds_dwordx4 v[190:191], off
	v_lshl_add_u64 v[190:191], v[212:213], 0, s[48:49]
	s_mov_b32 m0, s97
	s_nop 0
	global_load_lds_dwordx4 v[190:191], off
	v_lshl_add_u64 v[190:191], v[214:215], 0, s[48:49]
	s_mov_b32 m0, s74
	s_nop 0
	global_load_lds_dwordx4 v[190:191], off
	s_waitcnt vmcnt(8)
	s_waitcnt lgkmcnt(0)
	s_barrier
	s_waitcnt lgkmcnt(0)
	v_mfma_f32_16x16x32_bf16 v[92:95], v[138:141], v[170:173], v[92:95]
	v_mfma_f32_16x16x32_bf16 v[92:95], v[142:145], v[174:177], v[92:95]
	v_mfma_f32_16x16x32_bf16 v[88:91], v[146:149], v[170:173], v[88:91]
	v_mfma_f32_16x16x32_bf16 v[88:91], v[150:153], v[174:177], v[88:91]
	v_mfma_f32_16x16x32_bf16 v[24:27], v[138:141], v[178:181], v[24:27]
	v_mfma_f32_16x16x32_bf16 v[24:27], v[142:145], v[182:185], v[24:27]
	v_mfma_f32_16x16x32_bf16 v[28:31], v[146:149], v[178:181], v[28:31]
	v_mfma_f32_16x16x32_bf16 v[28:31], v[150:153], v[182:185], v[28:31]
	v_mfma_f32_16x16x32_bf16 v[44:47], v[138:141], v[186:189], v[44:47]
	v_mfma_f32_16x16x32_bf16 v[44:47], v[142:145], v[198:201], v[44:47]
	v_mfma_f32_16x16x32_bf16 v[52:55], v[146:149], v[186:189], v[52:55]
	v_mfma_f32_16x16x32_bf16 v[52:55], v[150:153], v[198:201], v[52:55]
	v_mfma_f32_16x16x32_bf16 v[84:87], v[138:141], v[202:205], v[84:87]
	v_mfma_f32_16x16x32_bf16 v[84:87], v[142:145], v[206:209], v[84:87]
	v_mfma_f32_16x16x32_bf16 v[80:83], v[146:149], v[202:205], v[80:83]
	v_mfma_f32_16x16x32_bf16 v[80:83], v[150:153], v[206:209], v[80:83]
	v_mfma_f32_16x16x32_bf16 v[76:79], v[154:157], v[170:173], v[76:79]
	v_mfma_f32_16x16x32_bf16 v[76:79], v[158:161], v[174:177], v[76:79]
	v_mfma_f32_16x16x32_bf16 v[72:75], v[162:165], v[170:173], v[72:75]
	v_mfma_f32_16x16x32_bf16 v[72:75], v[166:169], v[174:177], v[72:75]
	v_mfma_f32_16x16x32_bf16 v[36:39], v[154:157], v[178:181], v[36:39]
	v_mfma_f32_16x16x32_bf16 v[36:39], v[158:161], v[182:185], v[36:39]
	v_mfma_f32_16x16x32_bf16 v[48:51], v[162:165], v[178:181], v[48:51]
	v_mfma_f32_16x16x32_bf16 v[48:51], v[166:169], v[182:185], v[48:51]
	v_mfma_f32_16x16x32_bf16 v[60:63], v[154:157], v[186:189], v[60:63]
	v_mfma_f32_16x16x32_bf16 v[60:63], v[158:161], v[198:201], v[60:63]
	v_mfma_f32_16x16x32_bf16 v[56:59], v[162:165], v[186:189], v[56:59]
	v_mfma_f32_16x16x32_bf16 v[56:59], v[166:169], v[198:201], v[56:59]
	v_mfma_f32_16x16x32_bf16 v[68:71], v[154:157], v[202:205], v[68:71]
	v_mfma_f32_16x16x32_bf16 v[68:71], v[158:161], v[206:209], v[68:71]
	v_mfma_f32_16x16x32_bf16 v[64:67], v[162:165], v[202:205], v[64:67]
	v_mfma_f32_16x16x32_bf16 v[64:67], v[166:169], v[206:209], v[64:67]
	s_barrier
	s_add_i32 s55, s55, 2
	s_add_u32 s6, s6, 0x100
	s_addc_u32 s7, s7, 0
	s_add_u32 s27, s27, 0x100
	s_addc_u32 s31, s31, 0
	s_cmp_gt_u32 s55, 61
	s_cbranch_scc0 .LBB0_1378
	s_and_b64 vcc, exec, s[2:3]
	s_cbranch_vccz .LBB0_1381
	s_barrier

; #define PG8_STAGE(bufoff, gbase, voff) do { _Pragma("unroll") for (int _i = 0; _i < 2; ++_i) \
;         __builtin_amdgcn_global_load_lds((const unsigned*)((const char*)(gbase) + (voff)[_i]), (LAS unsigned*)(lds + (bufoff) + ldsw + _i * 8192), 16, 0, 0); } while (0)
; #define PG8_LDA(dst, b, h) do { _Pragma("unroll") for (int m = 0; m < 4; ++m) _Pragma("unroll") for (int k = 0; k < 2; ++k) dst[m][k] = *(const LAS bf16x8*)(lds + PG8_SA(b, h) + aoff + m * 2048 + k * 1024); } while (0)
; #define PG8_LDB(dst, b, h) do { _Pragma("unroll") for (int n = 0; n < 2; ++n) _Pragma("unroll") for (int k = 0; k < 2; ++k) dst[n][k] = *(const LAS bf16x8*)(lds + PG8_SB(b, h) + boff + n * 2048 + k * 1024); } while (0)
; #define PG8_MMA(ai, bj, At, Bt) do { __builtin_amdgcn_s_setprio(1); _Pragma("unroll") for (int m = 0; m < 4; ++m) _Pragma("unroll") for (int n = 0; n < 2; ++n) _Pragma("unroll") for (int k = 0; k < 2; ++k) \
;         acc[ai][bj][m][n] = __builtin_amdgcn_mfma_f32_16x16x32_bf16(Bt[n][k], At[m][k], acc[ai][bj][m][n], 0, 0, 0); __builtin_amdgcn_s_setprio(0); } while (0)
; #define PG8_WAIT_V(n) asm volatile("s_waitcnt vmcnt(" #n ")" ::: "memory")
; #define PG8_WAIT_L(n) asm volatile("s_waitcnt lgkmcnt(" #n ")" ::: "memory")
; #define PG8_BAR __builtin_amdgcn_s_barrier()
; #define PG8_SCHED __builtin_amdgcn_sched_barrier(0)
; template <class Epi>
; __device__ __forceinline__ void gemm_phase(LAS unsigned char* lds, const Gemm g, const Order& S, const Epi& E, const int wid) {
;     ...
;             const bool last = (t == nt - 2);
;             const char* a1 = cA + (size_t)(t + 1) * kstep;
;             const char* a2 = last ? nA : cA + (size_t)(t + 2) * kstep; const char* b2 = last ? nB : cB + (size_t)(t + 2) * kstep;
;             const char* a3 = a2 + kstep; const char* b3 = b2 + kstep;
;     ...
;             PG8_LDB(B0, 0, 0); PG8_LDB(B1, 0, 1); PG8_SCHED; PG8_LDA(At, 0, 0); PG8_STAGE(PG8_SA(1, 1), a1 + hA, voffA);
;             PG8_WAIT_V(8); PG8_WAIT_L(0); PG8_BAR; PG8_MMA(0, 0, At, B0); PG8_MMA(0, 1, At, B1); PG8_BAR; PG8_SCHED;
;             PG8_LDA(At, 0, 1); PG8_STAGE(PG8_SB(0, 0), b2, voffB); PG8_STAGE(PG8_SB(0, 1), b2 + hB, voffB); PG8_STAGE(PG8_SA(0, 0), a2, voffA);
;             PG8_WAIT_V(8); PG8_WAIT_L(0); PG8_BAR; PG8_MMA(1, 0, At, B0); PG8_MMA(1, 1, At, B1); PG8_BAR; PG8_SCHED;
.LBB0_1549:
	ds_read_b128 v[114:117], v111
	ds_read_b128 v[128:131], v111 offset:1024
	ds_read_b128 v[132:135], v111 offset:2048
	ds_read_b128 v[140:143], v111 offset:3072
	ds_read_b128 v[144:147], v112
	ds_read_b128 v[166:169], v112 offset:1024
	ds_read_b128 v[170:173], v112 offset:2048
	ds_read_b128 v[176:179], v112 offset:3072
	s_add_u32 s40, s38, 0xffd50080
	s_addc_u32 s41, s39, -1
	s_cmpk_eq_i32 s64, 0xa8
	s_cselect_b32 s43, s5, s41
	s_cselect_b32 s42, s4, s40
	s_cselect_b32 s41, s37, s63
	s_cselect_b32 s40, s36, s62
	v_lshl_add_u64 v[118:119], s[38:39], 0, v[160:161]
	s_add_i32 m0, s26, 0xc000
	ds_read_b128 v[180:183], v113
	ds_read_b128 v[184:187], v113 offset:1024
	ds_read_b128 v[188:191], v113 offset:2048
	ds_read_b128 v[192:195], v113 offset:3072
	ds_read_b128 v[196:199], v113 offset:4096
	ds_read_b128 v[200:203], v113 offset:5120
	ds_read_b128 v[204:207], v113 offset:6144
	ds_read_b128 v[208:211], v113 offset:7168
	global_load_lds_dwordx4 v[118:119], off
	v_lshl_add_u64 v[118:119], s[38:39], 0, v[106:107]
	s_add_i32 m0, s26, 0xe000
	s_nop 0
	global_load_lds_dwordx4 v[118:119], off
	s_waitcnt vmcnt(8)
	s_waitcnt lgkmcnt(0)
	s_barrier
	s_waitcnt lgkmcnt(0)
	v_mfma_f32_16x16x32_bf16 v[156:159], v[114:117], v[180:183], v[156:159]
	v_mfma_f32_16x16x32_bf16 v[152:155], v[132:135], v[180:183], v[152:155]
	v_mfma_f32_16x16x32_bf16 v[124:127], v[114:117], v[188:191], v[124:127]
	v_mfma_f32_16x16x32_bf16 v[118:121], v[132:135], v[188:191], v[120:123]
	v_mfma_f32_16x16x32_bf16 v[92:95], v[114:117], v[196:199], v[92:95]
	v_mfma_f32_16x16x32_bf16 v[88:91], v[132:135], v[196:199], v[88:91]
	v_mfma_f32_16x16x32_bf16 v[76:79], v[114:117], v[204:207], v[76:79]
	v_mfma_f32_16x16x32_bf16 v[72:75], v[132:135], v[204:207], v[72:75]
	v_mfma_f32_16x16x32_bf16 v[156:159], v[128:131], v[184:187], v[156:159]
	v_mfma_f32_16x16x32_bf16 v[152:155], v[140:143], v[184:187], v[152:155]
	v_mfma_f32_16x16x32_bf16 v[124:127], v[128:131], v[192:195], v[124:127]
	v_mfma_f32_16x16x32_bf16 v[118:121], v[140:143], v[192:195], v[118:121]
	v_mfma_f32_16x16x32_bf16 v[92:95], v[128:131], v[200:203], v[92:95]
	v_mfma_f32_16x16x32_bf16 v[88:91], v[140:143], v[200:203], v[88:91]
	v_mfma_f32_16x16x32_bf16 v[76:79], v[128:131], v[208:211], v[76:79]
	v_mfma_f32_16x16x32_bf16 v[72:75], v[140:143], v[208:211], v[72:75]
	v_mfma_f32_16x16x32_bf16 v[148:151], v[144:147], v[180:183], v[148:151]
	v_mfma_f32_16x16x32_bf16 v[148:151], v[166:169], v[184:187], v[148:151]
	v_mfma_f32_16x16x32_bf16 v[136:139], v[170:173], v[180:183], v[136:139]
	v_mfma_f32_16x16x32_bf16 v[136:139], v[176:179], v[184:187], v[136:139]
	v_mfma_f32_16x16x32_bf16 v[100:103], v[144:147], v[188:191], v[100:103]
	v_mfma_f32_16x16x32_bf16 v[100:103], v[166:169], v[192:195], v[100:103]
	v_mfma_f32_16x16x32_bf16 v[96:99], v[170:173], v[188:191], v[96:99]
	v_mfma_f32_16x16x32_bf16 v[96:99], v[176:179], v[192:195], v[96:99]
	v_mfma_f32_16x16x32_bf16 v[84:87], v[144:147], v[196:199], v[84:87]
	v_mfma_f32_16x16x32_bf16 v[84:87], v[166:169], v[200:203], v[84:87]
	v_mfma_f32_16x16x32_bf16 v[80:83], v[170:173], v[196:199], v[80:83]
	v_mfma_f32_16x16x32_bf16 v[80:83], v[176:179], v[200:203], v[80:83]
	v_mfma_f32_16x16x32_bf16 v[68:71], v[144:147], v[204:207], v[68:71]
	v_mfma_f32_16x16x32_bf16 v[68:71], v[166:169], v[208:211], v[68:71]
	v_mfma_f32_16x16x32_bf16 v[64:67], v[170:173], v[204:207], v[64:67]
	v_mfma_f32_16x16x32_bf16 v[64:67], v[176:179], v[208:211], v[64:67]
	s_barrier
	s_add_i32 s65, s69, s24
	v_lshl_add_u64 v[212:213], s[40:41], 0, v[104:105]
	s_mov_b32 m0, s65
	ds_read_b128 v[180:183], v113 offset:16384
	ds_read_b128 v[184:187], v113 offset:17408
	ds_read_b128 v[188:191], v113 offset:18432
	ds_read_b128 v[192:195], v113 offset:19456
	ds_read_b128 v[196:199], v113 offset:20480
	ds_read_b128 v[200:203], v113 offset:21504
	ds_read_b128 v[204:207], v113 offset:22528
	ds_read_b128 v[208:211], v113 offset:23552
	global_load_lds_dwordx4 v[212:213], off
	s_add_i32 m0, s65, 0x2000
	s_add_u32 s66, s40, 0x2b0000
	v_lshl_add_u64 v[214:215], s[40:41], 0, v[108:109]
	s_addc_u32 s67, s41, 0
	s_add_i32 s65, s70, s24
	global_load_lds_dwordx4 v[214:215], off
	v_lshl_add_u64 v[122:123], s[66:67], 0, v[104:105]
	s_mov_b32 m0, s65
	v_lshl_add_u64 v[216:217], s[42:43], 0, v[160:161]
	global_load_lds_dwordx4 v[122:123], off
	v_lshl_add_u64 v[122:123], s[66:67], 0, v[108:109]
	s_add_i32 m0, s65, 0x2000
	v_lshl_add_u64 v[218:219], s[42:43], 0, v[106:107]
	global_load_lds_dwordx4 v[122:123], off
	s_mov_b32 m0, s26
	s_nop 0
	global_load_lds_dwordx4 v[216:217], off
	s_mov_b32 m0, s27
	s_nop 0
	global_load_lds_dwordx4 v[218:219], off
	s_waitcnt vmcnt(8)
	s_waitcnt lgkmcnt(0)
	s_barrier
; #define PG8_STAGE(bufoff, gbase, voff) do { _Pragma("unroll") for (int _i = 0; _i < 2; ++_i) \
;         __builtin_amdgcn_global_load_lds((const unsigned*)((const char*)(gbase) + (voff)[_i]), (LAS unsigned*)(lds + (bufoff) + ldsw + _i * 8192), 16, 0, 0); } while (0)
; #define PG8_LDA(dst, b, h) do { _Pragma("unroll") for (int m = 0; m < 4; ++m) _Pragma("unroll") for (int k = 0; k < 2; ++k) dst[m][k] = *(const LAS bf16x8*)(lds + PG8_SA(b, h) + aoff + m * 2048 + k * 1024); } while (0)
; #define PG8_LDB(dst, b, h) do { _Pragma("unroll") for (int n = 0; n < 2; ++n) _Pragma("unroll") for (int k = 0; k < 2; ++k) dst[n][k] = *(const LAS bf16x8*)(lds + PG8_SB(b, h) + boff + n * 2048 + k * 1024); } while (0)
; #define PG8_MMA(ai, bj, At, Bt) do { __builtin_amdgcn_s_setprio(1); _Pragma("unroll") for (int m = 0; m < 4; ++m) _Pragma("unroll") for (int n = 0; n < 2; ++n) _Pragma("unroll") for (int k = 0; k < 2; ++k) \
;         acc[ai][bj][m][n] = __builtin_amdgcn_mfma_f32_16x16x32_bf16(Bt[n][k], At[m][k], acc[ai][bj][m][n], 0, 0, 0); __builtin_amdgcn_s_setprio(0); } while (0)
; #define PG8_WAIT_V(n) asm volatile("s_waitcnt vmcnt(" #n ")" ::: "memory")
; #define PG8_WAIT_L(n) asm volatile("s_waitcnt lgkmcnt(" #n ")" ::: "memory")
; #define PG8_BAR __builtin_amdgcn_s_barrier()
; #define PG8_SCHED __builtin_amdgcn_sched_barrier(0)
; template <class Epi>
; __device__ __forceinline__ void gemm_phase(LAS unsigned char* lds, const Gemm g, const Order& S, const Epi& E, const int wid) {
;     ...
;             PG8_WAIT_V(8); PG8_WAIT_L(0); PG8_BAR; PG8_MMA(1, 0, At, B0); PG8_MMA(1, 1, At, B1); PG8_BAR; PG8_SCHED;
;             PG8_LDB(B0, 1, 0); PG8_LDB(B1, 1, 1); PG8_SCHED; PG8_LDA(At, 1, 0); PG8_STAGE(PG8_SA(0, 1), a2 + hA, voffA);
;             PG8_WAIT_V(8); PG8_WAIT_L(0); PG8_BAR; PG8_MMA(0, 0, At, B0); PG8_MMA(0, 1, At, B1); PG8_BAR; PG8_SCHED;
;             PG8_LDA(At, 1, 1); PG8_STAGE(PG8_SB(1, 0), b3, voffB); PG8_STAGE(PG8_SB(1, 1), b3 + hB, voffB); PG8_STAGE(PG8_SA(1, 0), a3, voffA);
	s_waitcnt lgkmcnt(0)
	v_mfma_f32_16x16x32_bf16 v[60:63], v[114:117], v[180:183], v[60:63]
	v_mfma_f32_16x16x32_bf16 v[60:63], v[128:131], v[184:187], v[60:63]
	v_mfma_f32_16x16x32_bf16 v[56:59], v[132:135], v[180:183], v[56:59]
	v_mfma_f32_16x16x32_bf16 v[56:59], v[140:143], v[184:187], v[56:59]
	v_mfma_f32_16x16x32_bf16 v[44:47], v[114:117], v[188:191], v[44:47]
	v_mfma_f32_16x16x32_bf16 v[44:47], v[128:131], v[192:195], v[44:47]
	v_mfma_f32_16x16x32_bf16 v[40:43], v[132:135], v[188:191], v[40:43]
	v_mfma_f32_16x16x32_bf16 v[40:43], v[140:143], v[192:195], v[40:43]
	v_mfma_f32_16x16x32_bf16 v[28:31], v[114:117], v[196:199], v[28:31]
	v_mfma_f32_16x16x32_bf16 v[28:31], v[128:131], v[200:203], v[28:31]
	v_mfma_f32_16x16x32_bf16 v[24:27], v[132:135], v[196:199], v[24:27]
	v_mfma_f32_16x16x32_bf16 v[24:27], v[140:143], v[200:203], v[24:27]
	v_mfma_f32_16x16x32_bf16 v[12:15], v[114:117], v[204:207], v[12:15]
	v_mfma_f32_16x16x32_bf16 v[12:15], v[128:131], v[208:211], v[12:15]
	v_mfma_f32_16x16x32_bf16 v[8:11], v[132:135], v[204:207], v[8:11]
	v_mfma_f32_16x16x32_bf16 v[8:11], v[140:143], v[208:211], v[8:11]
	v_mfma_f32_16x16x32_bf16 v[52:55], v[144:147], v[180:183], v[52:55]
	v_mfma_f32_16x16x32_bf16 v[52:55], v[166:169], v[184:187], v[52:55]
	v_mfma_f32_16x16x32_bf16 v[48:51], v[170:173], v[180:183], v[48:51]
	v_mfma_f32_16x16x32_bf16 v[48:51], v[176:179], v[184:187], v[48:51]
	v_mfma_f32_16x16x32_bf16 v[36:39], v[144:147], v[188:191], v[36:39]
	v_mfma_f32_16x16x32_bf16 v[36:39], v[166:169], v[192:195], v[36:39]
	v_mfma_f32_16x16x32_bf16 v[32:35], v[170:173], v[188:191], v[32:35]
	v_mfma_f32_16x16x32_bf16 v[32:35], v[176:179], v[192:195], v[32:35]
	v_mfma_f32_16x16x32_bf16 v[20:23], v[144:147], v[196:199], v[20:23]
	v_mfma_f32_16x16x32_bf16 v[20:23], v[166:169], v[200:203], v[20:23]
	v_mfma_f32_16x16x32_bf16 v[16:19], v[170:173], v[196:199], v[16:19]
	v_mfma_f32_16x16x32_bf16 v[16:19], v[176:179], v[200:203], v[16:19]
	v_mfma_f32_16x16x32_bf16 v[4:7], v[144:147], v[204:207], v[4:7]
	v_mfma_f32_16x16x32_bf16 v[4:7], v[166:169], v[208:211], v[4:7]
	v_mfma_f32_16x16x32_bf16 v[0:3], v[170:173], v[204:207], v[0:3]
	v_mfma_f32_16x16x32_bf16 v[0:3], v[176:179], v[208:211], v[0:3]
	s_barrier
	s_add_i32 s65, 0, 0x18000
	v_add_u32_e32 v122, s65, v110
	s_add_i32 s66, 0, 0x1c000
	ds_read_b128 v[114:117], v122
	ds_read_b128 v[128:131], v122 offset:1024
	ds_read_b128 v[132:135], v122 offset:2048
	ds_read_b128 v[140:143], v122 offset:3072
	v_add_u32_e32 v122, s66, v110
	ds_read_b128 v[144:147], v122
	ds_read_b128 v[166:169], v122 offset:1024
	ds_read_b128 v[170:173], v122 offset:2048
	ds_read_b128 v[176:179], v122 offset:3072
	s_add_u32 s42, s42, 0x2b0000
	s_addc_u32 s43, s43, 0
	s_mov_b32 m0, s29
	v_lshl_add_u64 v[122:123], s[42:43], 0, v[160:161]
	ds_read_b128 v[180:183], v113 offset:32768
	ds_read_b128 v[184:187], v113 offset:33792
	ds_read_b128 v[188:191], v113 offset:34816
	ds_read_b128 v[192:195], v113 offset:35840
	ds_read_b128 v[196:199], v113 offset:36864
	ds_read_b128 v[200:203], v113 offset:37888
	ds_read_b128 v[204:207], v113 offset:38912
	ds_read_b128 v[208:211], v113 offset:39936
	global_load_lds_dwordx4 v[122:123], off
	v_lshl_add_u64 v[122:123], s[42:43], 0, v[106:107]
	s_mov_b32 m0, s33
	s_nop 0
	global_load_lds_dwordx4 v[122:123], off
	s_waitcnt vmcnt(8)
	s_waitcnt lgkmcnt(0)
	s_barrier
	s_waitcnt lgkmcnt(0)
	v_mfma_f32_16x16x32_bf16 v[156:159], v[114:117], v[180:183], v[156:159]
	v_mfma_f32_16x16x32_bf16 v[152:155], v[132:135], v[180:183], v[152:155]
	v_mfma_f32_16x16x32_bf16 v[122:125], v[114:117], v[188:191], v[124:127]
	v_mfma_f32_16x16x32_bf16 v[118:121], v[132:135], v[188:191], v[118:121]
	v_mfma_f32_16x16x32_bf16 v[92:95], v[114:117], v[196:199], v[92:95]
	v_mfma_f32_16x16x32_bf16 v[88:91], v[132:135], v[196:199], v[88:91]
	v_mfma_f32_16x16x32_bf16 v[76:79], v[114:117], v[204:207], v[76:79]
	v_mfma_f32_16x16x32_bf16 v[72:75], v[132:135], v[204:207], v[72:75]
	v_mfma_f32_16x16x32_bf16 v[156:159], v[128:131], v[184:187], v[156:159]
	v_mfma_f32_16x16x32_bf16 v[152:155], v[140:143], v[184:187], v[152:155]
	v_mfma_f32_16x16x32_bf16 v[124:127], v[128:131], v[192:195], v[122:125]
	v_mfma_f32_16x16x32_bf16 v[120:123], v[140:143], v[192:195], v[118:121]
	v_mfma_f32_16x16x32_bf16 v[92:95], v[128:131], v[200:203], v[92:95]
	v_mfma_f32_16x16x32_bf16 v[88:91], v[140:143], v[200:203], v[88:91]
	v_mfma_f32_16x16x32_bf16 v[76:79], v[128:131], v[208:211], v[76:79]
	v_mfma_f32_16x16x32_bf16 v[72:75], v[140:143], v[208:211], v[72:75]
	v_mfma_f32_16x16x32_bf16 v[148:151], v[144:147], v[180:183], v[148:151]
	v_mfma_f32_16x16x32_bf16 v[148:151], v[166:169], v[184:187], v[148:151]
	v_mfma_f32_16x16x32_bf16 v[136:139], v[170:173], v[180:183], v[136:139]
	v_mfma_f32_16x16x32_bf16 v[136:139], v[176:179], v[184:187], v[136:139]
	v_mfma_f32_16x16x32_bf16 v[100:103], v[144:147], v[188:191], v[100:103]
	v_mfma_f32_16x16x32_bf16 v[100:103], v[166:169], v[192:195], v[100:103]
	v_mfma_f32_16x16x32_bf16 v[96:99], v[170:173], v[188:191], v[96:99]
	v_mfma_f32_16x16x32_bf16 v[96:99], v[176:179], v[192:195], v[96:99]
	v_mfma_f32_16x16x32_bf16 v[84:87], v[144:147], v[196:199], v[84:87]
	v_mfma_f32_16x16x32_bf16 v[84:87], v[166:169], v[200:203], v[84:87]
	v_mfma_f32_16x16x32_bf16 v[80:83], v[170:173], v[196:199], v[80:83]
	v_mfma_f32_16x16x32_bf16 v[80:83], v[176:179], v[200:203], v[80:83]
	v_mfma_f32_16x16x32_bf16 v[68:71], v[144:147], v[204:207], v[68:71]
	v_mfma_f32_16x16x32_bf16 v[68:71], v[166:169], v[208:211], v[68:71]
	v_mfma_f32_16x16x32_bf16 v[64:67], v[170:173], v[204:207], v[64:67]
	v_mfma_f32_16x16x32_bf16 v[64:67], v[176:179], v[208:211], v[64:67]
	s_barrier
; #define PG8_STAGE(bufoff, gbase, voff) do { _Pragma("unroll") for (int _i = 0; _i < 2; ++_i) \
;         __builtin_amdgcn_global_load_lds((const unsigned*)((const char*)(gbase) + (voff)[_i]), (LAS unsigned*)(lds + (bufoff) + ldsw + _i * 8192), 16, 0, 0); } while (0)
; #define PG8_LDA(dst, b, h) do { _Pragma("unroll") for (int m = 0; m < 4; ++m) _Pragma("unroll") for (int k = 0; k < 2; ++k) dst[m][k] = *(const LAS bf16x8*)(lds + PG8_SA(b, h) + aoff + m * 2048 + k * 1024); } while (0)
; #define PG8_MMA(ai, bj, At, Bt) do { __builtin_amdgcn_s_setprio(1); _Pragma("unroll") for (int m = 0; m < 4; ++m) _Pragma("unroll") for (int n = 0; n < 2; ++n) _Pragma("unroll") for (int k = 0; k < 2; ++k) \
;         acc[ai][bj][m][n] = __builtin_amdgcn_mfma_f32_16x16x32_bf16(Bt[n][k], At[m][k], acc[ai][bj][m][n], 0, 0, 0); __builtin_amdgcn_s_setprio(0); } while (0)
; #define PG8_WAIT_V(n) asm volatile("s_waitcnt vmcnt(" #n ")" ::: "memory")
; #define PG8_WAIT_L(n) asm volatile("s_waitcnt lgkmcnt(" #n ")" ::: "memory")
; #define PG8_BAR __builtin_amdgcn_s_barrier()
; #define PG8_SCHED __builtin_amdgcn_sched_barrier(0)
; template <class Epi>
; __device__ __forceinline__ void gemm_phase(LAS unsigned char* lds, const Gemm g, const Order& S, const Epi& E, const int wid) {
;     ...
;             PG8_LDA(At, 1, 1); PG8_STAGE(PG8_SB(1, 0), b3, voffB); PG8_STAGE(PG8_SB(1, 1), b3 + hB, voffB); PG8_STAGE(PG8_SA(1, 0), a3, voffA);
;             PG8_WAIT_V(8); PG8_WAIT_L(0); PG8_BAR; PG8_MMA(1, 0, At, B0); PG8_MMA(1, 1, At, B1); PG8_BAR; PG8_SCHED;
	s_add_i32 s42, s65, s24
	v_lshl_add_u64 v[118:119], v[212:213], 0, s[18:19]
	s_mov_b32 m0, s42
	ds_read_b128 v[180:183], v113 offset:49152
	ds_read_b128 v[184:187], v113 offset:50176
	ds_read_b128 v[188:191], v113 offset:51200
	ds_read_b128 v[192:195], v113 offset:52224
	ds_read_b128 v[196:199], v113 offset:53248
	ds_read_b128 v[200:203], v113 offset:54272
	ds_read_b128 v[204:207], v113 offset:55296
	ds_read_b128 v[208:211], v113 offset:56320
	global_load_lds_dwordx4 v[118:119], off
	s_add_i32 m0, s42, 0x2000
	s_add_u32 s40, s40, 0x2b0080
	v_lshl_add_u64 v[118:119], v[214:215], 0, s[18:19]
	s_addc_u32 s41, s41, 0
	s_add_i32 s42, s66, s24
	global_load_lds_dwordx4 v[118:119], off
	v_lshl_add_u64 v[118:119], s[40:41], 0, v[104:105]
	s_mov_b32 m0, s42
	s_nop 0
	global_load_lds_dwordx4 v[118:119], off
	v_lshl_add_u64 v[118:119], s[40:41], 0, v[108:109]
	s_add_i32 m0, s42, 0x2000
	s_nop 0
	global_load_lds_dwordx4 v[118:119], off
	v_lshl_add_u64 v[118:119], v[216:217], 0, s[18:19]
	s_mov_b32 m0, s51
	s_nop 0
	global_load_lds_dwordx4 v[118:119], off
	v_lshl_add_u64 v[118:119], v[218:219], 0, s[18:19]
	s_mov_b32 m0, s68
	s_nop 0
	global_load_lds_dwordx4 v[118:119], off
	s_waitcnt vmcnt(8)
	s_waitcnt lgkmcnt(0)
	s_barrier
	s_waitcnt lgkmcnt(0)
	v_mfma_f32_16x16x32_bf16 v[60:63], v[114:117], v[180:183], v[60:63]
	v_mfma_f32_16x16x32_bf16 v[60:63], v[128:131], v[184:187], v[60:63]
	v_mfma_f32_16x16x32_bf16 v[56:59], v[132:135], v[180:183], v[56:59]
	v_mfma_f32_16x16x32_bf16 v[56:59], v[140:143], v[184:187], v[56:59]
	v_mfma_f32_16x16x32_bf16 v[44:47], v[114:117], v[188:191], v[44:47]
	v_mfma_f32_16x16x32_bf16 v[44:47], v[128:131], v[192:195], v[44:47]
	v_mfma_f32_16x16x32_bf16 v[40:43], v[132:135], v[188:191], v[40:43]
	v_mfma_f32_16x16x32_bf16 v[40:43], v[140:143], v[192:195], v[40:43]
	v_mfma_f32_16x16x32_bf16 v[28:31], v[114:117], v[196:199], v[28:31]
	v_mfma_f32_16x16x32_bf16 v[28:31], v[128:131], v[200:203], v[28:31]
	v_mfma_f32_16x16x32_bf16 v[24:27], v[132:135], v[196:199], v[24:27]
	v_mfma_f32_16x16x32_bf16 v[24:27], v[140:143], v[200:203], v[24:27]
	v_mfma_f32_16x16x32_bf16 v[12:15], v[114:117], v[204:207], v[12:15]
	v_mfma_f32_16x16x32_bf16 v[12:15], v[128:131], v[208:211], v[12:15]
	v_mfma_f32_16x16x32_bf16 v[8:11], v[132:135], v[204:207], v[8:11]
	v_mfma_f32_16x16x32_bf16 v[8:11], v[140:143], v[208:211], v[8:11]
	v_mfma_f32_16x16x32_bf16 v[52:55], v[144:147], v[180:183], v[52:55]
	v_mfma_f32_16x16x32_bf16 v[52:55], v[166:169], v[184:187], v[52:55]
	v_mfma_f32_16x16x32_bf16 v[48:51], v[170:173], v[180:183], v[48:51]
	v_mfma_f32_16x16x32_bf16 v[48:51], v[176:179], v[184:187], v[48:51]
	v_mfma_f32_16x16x32_bf16 v[36:39], v[144:147], v[188:191], v[36:39]
	v_mfma_f32_16x16x32_bf16 v[36:39], v[166:169], v[192:195], v[36:39]
	v_mfma_f32_16x16x32_bf16 v[32:35], v[170:173], v[188:191], v[32:35]
	v_mfma_f32_16x16x32_bf16 v[32:35], v[176:179], v[192:195], v[32:35]
	v_mfma_f32_16x16x32_bf16 v[20:23], v[144:147], v[196:199], v[20:23]
	v_mfma_f32_16x16x32_bf16 v[20:23], v[166:169], v[200:203], v[20:23]
	v_mfma_f32_16x16x32_bf16 v[16:19], v[170:173], v[196:199], v[16:19]
	v_mfma_f32_16x16x32_bf16 v[16:19], v[176:179], v[200:203], v[16:19]
	v_mfma_f32_16x16x32_bf16 v[4:7], v[144:147], v[204:207], v[4:7]
	v_mfma_f32_16x16x32_bf16 v[4:7], v[166:169], v[208:211], v[4:7]
	v_mfma_f32_16x16x32_bf16 v[0:3], v[170:173], v[204:207], v[0:3]
	v_mfma_f32_16x16x32_bf16 v[0:3], v[176:179], v[208:211], v[0:3]
	s_barrier
	s_add_i32 s64, s64, 2
	s_add_u32 s38, s38, 0x100
	s_addc_u32 s39, s39, 0
	s_add_u32 s62, s62, 0x100
	s_addc_u32 s63, s63, 0
	s_cmpk_gt_u32 s64, 0xa9
	s_cbranch_scc0 .LBB0_1549
	s_and_b64 vcc, exec, s[10:11]
	s_cbranch_vccz .LBB0_1552
	s_barrier
